# non-temporal (nt) row loads in the hand-written input/final LayerNorm phases (rows are read exactly once)
# speedup vs baseline: 1.0280x; 1.0280x over previous
.LBB0_94:
	s_add_u32 s100, s48, 0xfffc0000
	s_addc_u32 s101, s49, -1
	v_lshl_add_u64 v[198:199], s[100:101], 0, v[152:153]
	s_mov_b32 m0, s77
	s_nop 0
	global_load_lds_dwordx4 v[198:199], off
	v_lshl_add_u64 v[198:199], s[100:101], 0, v[148:149]
	s_mov_b32 m0, s78
	s_nop 0
	global_load_lds_dwordx4 v[198:199], off
	s_add_u32 s60, s48, 0xfffc0080
	s_addc_u32 s61, s49, -1
	s_add_i32 s88, 0, 0x10000
	s_cmp_eq_u32 s87, 12
	s_cselect_b32 vcc_hi, s59, s61
	s_cselect_b32 vcc_lo, s83, s60
	v_add_u32_e32 v2, s88, v182
	s_cselect_b32 s61, s95, s86
	s_cselect_b32 s60, s84, s85
	s_add_i32 s90, 0, 0x14000
	ds_read_b128 v[132:135], v2
	ds_read_b128 v[136:139], v2 offset:1024
	ds_read_b128 v[140:143], v2 offset:2048
	ds_read_b128 v[144:147], v2 offset:3072
	v_add_u32_e32 v2, s90, v182
	ds_read_b128 v[162:165], v2
	ds_read_b128 v[166:169], v2 offset:1024
	ds_read_b128 v[170:173], v2 offset:2048
	ds_read_b128 v[174:177], v2 offset:3072
	v_lshl_add_u64 v[198:199], s[48:49], 0, v[158:159]
	s_add_i32 m0, s73, 0xc000
	ds_read_b128 v[178:181], v185
	ds_read_b128 v[186:189], v185 offset:1024
	ds_read_b128 v[190:193], v185 offset:2048
	ds_read_b128 v[194:197], v185 offset:3072
	ds_read_b128 v[208:211], v185 offset:4096
	ds_read_b128 v[212:215], v185 offset:5120
	ds_read_b128 v[216:219], v185 offset:6144
	ds_read_b128 v[220:223], v185 offset:7168
	global_load_lds_dwordx4 v[198:199], off
	v_lshl_add_u64 v[198:199], s[48:49], 0, v[160:161]
	s_add_i32 m0, s73, 0xe000
	s_nop 0
	global_load_lds_dwordx4 v[198:199], off
	s_waitcnt vmcnt(8)
	s_waitcnt lgkmcnt(0)
	s_barrier

	s_waitcnt lgkmcnt(0)
	v_mfma_f32_16x16x32_bf16 v[128:131], v[132:135], v[178:181], v[128:131]
	v_mfma_f32_16x16x32_bf16 v[120:123], v[140:143], v[178:181], v[120:123]
	v_mfma_f32_16x16x32_bf16 v[112:115], v[132:135], v[190:193], v[112:115]
	v_mfma_f32_16x16x32_bf16 v[84:87], v[140:143], v[190:193], v[84:87]
	v_mfma_f32_16x16x32_bf16 v[104:107], v[132:135], v[208:211], v[104:107]
	v_mfma_f32_16x16x32_bf16 v[72:75], v[140:143], v[208:211], v[72:75]
	v_mfma_f32_16x16x32_bf16 v[96:99], v[132:135], v[216:219], v[96:99]
	v_mfma_f32_16x16x32_bf16 v[88:91], v[140:143], v[216:219], v[88:91]
	v_mfma_f32_16x16x32_bf16 v[128:131], v[136:139], v[186:189], v[128:131]
	v_mfma_f32_16x16x32_bf16 v[120:123], v[144:147], v[186:189], v[120:123]
	v_mfma_f32_16x16x32_bf16 v[112:115], v[136:139], v[194:197], v[112:115]
	v_mfma_f32_16x16x32_bf16 v[84:87], v[144:147], v[194:197], v[84:87]
	v_mfma_f32_16x16x32_bf16 v[104:107], v[136:139], v[212:215], v[104:107]
	v_mfma_f32_16x16x32_bf16 v[72:75], v[144:147], v[212:215], v[72:75]
	v_mfma_f32_16x16x32_bf16 v[96:99], v[136:139], v[220:223], v[96:99]
	v_mfma_f32_16x16x32_bf16 v[88:91], v[144:147], v[220:223], v[88:91]


	v_mfma_f32_16x16x32_bf16 v[124:127], v[162:165], v[178:181], v[124:127]
	v_mfma_f32_16x16x32_bf16 v[116:119], v[170:173], v[178:181], v[116:119]
	v_mfma_f32_16x16x32_bf16 v[108:111], v[162:165], v[190:193], v[108:111]
	v_mfma_f32_16x16x32_bf16 v[76:79], v[170:173], v[190:193], v[76:79]
	v_mfma_f32_16x16x32_bf16 v[100:103], v[162:165], v[208:211], v[100:103]
	v_mfma_f32_16x16x32_bf16 v[68:71], v[170:173], v[208:211], v[68:71]
	v_mfma_f32_16x16x32_bf16 v[92:95], v[162:165], v[216:219], v[92:95]
	v_mfma_f32_16x16x32_bf16 v[80:83], v[170:173], v[216:219], v[80:83]
	v_mfma_f32_16x16x32_bf16 v[124:127], v[166:169], v[186:189], v[124:127]
	v_mfma_f32_16x16x32_bf16 v[116:119], v[174:177], v[186:189], v[116:119]
	v_mfma_f32_16x16x32_bf16 v[108:111], v[166:169], v[194:197], v[108:111]
	v_mfma_f32_16x16x32_bf16 v[76:79], v[174:177], v[194:197], v[76:79]
	v_mfma_f32_16x16x32_bf16 v[100:103], v[166:169], v[212:215], v[100:103]
	v_mfma_f32_16x16x32_bf16 v[68:71], v[174:177], v[212:215], v[68:71]
	v_mfma_f32_16x16x32_bf16 v[92:95], v[166:169], v[220:223], v[92:95]
	v_mfma_f32_16x16x32_bf16 v[80:83], v[174:177], v[220:223], v[80:83]

	s_barrier
	s_add_i32 s88, s88, s72
	v_lshl_add_u64 v[198:199], s[60:61], 0, v[150:151]
	s_mov_b32 m0, s88
	ds_read_b128 v[178:181], v185 offset:16384
	ds_read_b128 v[186:189], v185 offset:17408
	ds_read_b128 v[190:193], v185 offset:18432
	ds_read_b128 v[194:197], v185 offset:19456
	ds_read_b128 v[208:211], v185 offset:20480
	ds_read_b128 v[212:215], v185 offset:21504
	ds_read_b128 v[216:219], v185 offset:22528
	ds_read_b128 v[220:223], v185 offset:23552
	global_load_lds_dwordx4 v[198:199], off
	s_add_i32 m0, s88, 0x2000
	s_add_u32 s88, s60, 0x40000
	v_lshl_add_u64 v[204:205], s[60:61], 0, v[0:1]
	s_addc_u32 s89, s61, 0
	s_add_i32 s90, s90, s72
	global_load_lds_dwordx4 v[204:205], off
	v_lshl_add_u64 v[206:207], s[88:89], 0, v[150:151]
	s_mov_b32 m0, s90
	v_lshl_add_u64 v[224:225], vcc, 0, v[148:149]
	global_load_lds_dwordx4 v[206:207], off
	v_lshl_add_u64 v[206:207], s[88:89], 0, v[0:1]
	s_add_i32 m0, s90, 0x2000
	s_nop 0
	global_load_lds_dwordx4 v[206:207], off
	v_lshl_add_u64 v[206:207], vcc, 0, v[152:153]


	s_waitcnt vmcnt(6)
	s_waitcnt lgkmcnt(0)
	s_barrier

	s_waitcnt lgkmcnt(0)
	v_mfma_f32_16x16x32_bf16 v[64:67], v[132:135], v[178:181], v[64:67]
	v_mfma_f32_16x16x32_bf16 v[56:59], v[140:143], v[178:181], v[56:59]
	v_mfma_f32_16x16x32_bf16 v[52:55], v[132:135], v[190:193], v[52:55]
	v_mfma_f32_16x16x32_bf16 v[20:23], v[140:143], v[190:193], v[20:23]
	v_mfma_f32_16x16x32_bf16 v[40:43], v[132:135], v[208:211], v[40:43]
	v_mfma_f32_16x16x32_bf16 v[8:11], v[140:143], v[208:211], v[8:11]
	v_mfma_f32_16x16x32_bf16 v[32:35], v[132:135], v[216:219], v[32:35]
	v_mfma_f32_16x16x32_bf16 v[24:27], v[140:143], v[216:219], v[24:27]
	v_mfma_f32_16x16x32_bf16 v[64:67], v[136:139], v[186:189], v[64:67]
	v_mfma_f32_16x16x32_bf16 v[56:59], v[144:147], v[186:189], v[56:59]
	v_mfma_f32_16x16x32_bf16 v[52:55], v[136:139], v[194:197], v[52:55]
	v_mfma_f32_16x16x32_bf16 v[20:23], v[144:147], v[194:197], v[20:23]
	v_mfma_f32_16x16x32_bf16 v[40:43], v[136:139], v[212:215], v[40:43]
	v_mfma_f32_16x16x32_bf16 v[8:11], v[144:147], v[212:215], v[8:11]
	v_mfma_f32_16x16x32_bf16 v[32:35], v[136:139], v[220:223], v[32:35]
	v_mfma_f32_16x16x32_bf16 v[24:27], v[144:147], v[220:223], v[24:27]


	v_mfma_f32_16x16x32_bf16 v[60:63], v[162:165], v[178:181], v[60:63]
	v_mfma_f32_16x16x32_bf16 v[48:51], v[170:173], v[178:181], v[48:51]
	v_mfma_f32_16x16x32_bf16 v[44:47], v[162:165], v[190:193], v[44:47]
	v_mfma_f32_16x16x32_bf16 v[12:15], v[170:173], v[190:193], v[12:15]
	v_mfma_f32_16x16x32_bf16 v[36:39], v[162:165], v[208:211], v[36:39]
	v_mfma_f32_16x16x32_bf16 v[4:7], v[170:173], v[208:211], v[4:7]
	v_mfma_f32_16x16x32_bf16 v[28:31], v[162:165], v[216:219], v[28:31]
	v_mfma_f32_16x16x32_bf16 v[16:19], v[170:173], v[216:219], v[16:19]
	v_mfma_f32_16x16x32_bf16 v[60:63], v[166:169], v[186:189], v[60:63]
	v_mfma_f32_16x16x32_bf16 v[48:51], v[174:177], v[186:189], v[48:51]
	v_mfma_f32_16x16x32_bf16 v[44:47], v[166:169], v[194:197], v[44:47]
	v_mfma_f32_16x16x32_bf16 v[12:15], v[174:177], v[194:197], v[12:15]
	v_mfma_f32_16x16x32_bf16 v[36:39], v[166:169], v[212:215], v[36:39]
	v_mfma_f32_16x16x32_bf16 v[4:7], v[174:177], v[212:215], v[4:7]
	v_mfma_f32_16x16x32_bf16 v[28:31], v[166:169], v[220:223], v[28:31]
	v_mfma_f32_16x16x32_bf16 v[16:19], v[174:177], v[220:223], v[16:19]

	s_barrier
	s_add_i32 s90, 0, 0x18000
	v_add_u32_e32 v2, s90, v182
	s_add_i32 s91, 0, 0x1c000
	ds_read_b128 v[132:135], v2
	ds_read_b128 v[136:139], v2 offset:1024
	ds_read_b128 v[140:143], v2 offset:2048
	ds_read_b128 v[144:147], v2 offset:3072
	v_add_u32_e32 v2, s91, v182
	ds_read_b128 v[162:165], v2
	ds_read_b128 v[166:169], v2 offset:1024
	ds_read_b128 v[170:173], v2 offset:2048
	ds_read_b128 v[174:177], v2 offset:3072
	s_add_u32 s88, vcc_lo, 0x40000
	s_addc_u32 s89, vcc_hi, 0
	s_mov_b32 m0, s73
	s_nop 0
	global_load_lds_dwordx4 v[206:207], off
	s_mov_b32 m0, s74
	s_nop 0
	global_load_lds_dwordx4 v[224:225], off
	s_mov_b32 m0, s75
	v_lshl_add_u64 v[226:227], s[88:89], 0, v[152:153]
	ds_read_b128 v[178:181], v185 offset:32768
	ds_read_b128 v[186:189], v185 offset:33792
	ds_read_b128 v[190:193], v185 offset:34816
	ds_read_b128 v[194:197], v185 offset:35840
	ds_read_b128 v[208:211], v185 offset:36864
	ds_read_b128 v[212:215], v185 offset:37888
	ds_read_b128 v[216:219], v185 offset:38912
	ds_read_b128 v[220:223], v185 offset:39936
	global_load_lds_dwordx4 v[226:227], off
	v_lshl_add_u64 v[226:227], s[88:89], 0, v[148:149]
	s_mov_b32 m0, s76
	s_nop 0
	global_load_lds_dwordx4 v[226:227], off
	s_waitcnt vmcnt(8)
	s_waitcnt lgkmcnt(0)
	s_barrier

	s_waitcnt lgkmcnt(0)
	v_mfma_f32_16x16x32_bf16 v[128:131], v[132:135], v[178:181], v[128:131]
	v_mfma_f32_16x16x32_bf16 v[120:123], v[140:143], v[178:181], v[120:123]
	v_mfma_f32_16x16x32_bf16 v[112:115], v[132:135], v[190:193], v[112:115]
	v_mfma_f32_16x16x32_bf16 v[84:87], v[140:143], v[190:193], v[84:87]
	v_mfma_f32_16x16x32_bf16 v[104:107], v[132:135], v[208:211], v[104:107]
	v_mfma_f32_16x16x32_bf16 v[72:75], v[140:143], v[208:211], v[72:75]
	v_mfma_f32_16x16x32_bf16 v[96:99], v[132:135], v[216:219], v[96:99]
	v_mfma_f32_16x16x32_bf16 v[88:91], v[140:143], v[216:219], v[88:91]
	v_mfma_f32_16x16x32_bf16 v[128:131], v[136:139], v[186:189], v[128:131]
	v_mfma_f32_16x16x32_bf16 v[120:123], v[144:147], v[186:189], v[120:123]
	v_mfma_f32_16x16x32_bf16 v[112:115], v[136:139], v[194:197], v[112:115]
	v_mfma_f32_16x16x32_bf16 v[84:87], v[144:147], v[194:197], v[84:87]
	v_mfma_f32_16x16x32_bf16 v[104:107], v[136:139], v[212:215], v[104:107]
	v_mfma_f32_16x16x32_bf16 v[72:75], v[144:147], v[212:215], v[72:75]
	v_mfma_f32_16x16x32_bf16 v[96:99], v[136:139], v[220:223], v[96:99]
	v_mfma_f32_16x16x32_bf16 v[88:91], v[144:147], v[220:223], v[88:91]


	v_mfma_f32_16x16x32_bf16 v[124:127], v[162:165], v[178:181], v[124:127]
	v_mfma_f32_16x16x32_bf16 v[116:119], v[170:173], v[178:181], v[116:119]
	v_mfma_f32_16x16x32_bf16 v[108:111], v[162:165], v[190:193], v[108:111]
	v_mfma_f32_16x16x32_bf16 v[76:79], v[170:173], v[190:193], v[76:79]
	v_mfma_f32_16x16x32_bf16 v[100:103], v[162:165], v[208:211], v[100:103]
	v_mfma_f32_16x16x32_bf16 v[68:71], v[170:173], v[208:211], v[68:71]
	v_mfma_f32_16x16x32_bf16 v[92:95], v[162:165], v[216:219], v[92:95]
	v_mfma_f32_16x16x32_bf16 v[80:83], v[170:173], v[216:219], v[80:83]
	v_mfma_f32_16x16x32_bf16 v[124:127], v[166:169], v[186:189], v[124:127]
	v_mfma_f32_16x16x32_bf16 v[116:119], v[174:177], v[186:189], v[116:119]
	v_mfma_f32_16x16x32_bf16 v[108:111], v[166:169], v[194:197], v[108:111]
	v_mfma_f32_16x16x32_bf16 v[76:79], v[174:177], v[194:197], v[76:79]
	v_mfma_f32_16x16x32_bf16 v[100:103], v[166:169], v[212:215], v[100:103]
	v_mfma_f32_16x16x32_bf16 v[68:71], v[174:177], v[212:215], v[68:71]
	v_mfma_f32_16x16x32_bf16 v[92:95], v[166:169], v[220:223], v[92:95]
	v_mfma_f32_16x16x32_bf16 v[80:83], v[174:177], v[220:223], v[80:83]

	s_barrier
	s_add_i32 s88, s90, s72
	v_lshl_add_u64 v[198:199], v[198:199], 0, s[12:13]
	s_mov_b32 m0, s88
	ds_read_b128 v[178:181], v185 offset:49152
	ds_read_b128 v[186:189], v185 offset:50176
	ds_read_b128 v[190:193], v185 offset:51200
	ds_read_b128 v[194:197], v185 offset:52224
	ds_read_b128 v[208:211], v185 offset:53248
	ds_read_b128 v[212:215], v185 offset:54272
	ds_read_b128 v[216:219], v185 offset:55296
	ds_read_b128 v[220:223], v185 offset:56320
	global_load_lds_dwordx4 v[198:199], off
	s_add_i32 m0, s88, 0x2000
	s_add_u32 s60, s60, 0x40080
	v_lshl_add_u64 v[198:199], v[204:205], 0, s[12:13]
	s_addc_u32 s61, s61, 0
	s_add_i32 s88, s91, s72
	global_load_lds_dwordx4 v[198:199], off
	v_lshl_add_u64 v[198:199], s[60:61], 0, v[150:151]
	s_mov_b32 m0, s88
	s_nop 0
	global_load_lds_dwordx4 v[198:199], off
	v_lshl_add_u64 v[198:199], s[60:61], 0, v[0:1]
	s_add_i32 m0, s88, 0x2000
	s_nop 0
	global_load_lds_dwordx4 v[198:199], off


	s_waitcnt vmcnt(6)
	s_waitcnt lgkmcnt(0)
	s_barrier

	s_waitcnt lgkmcnt(0)
	v_mfma_f32_16x16x32_bf16 v[64:67], v[132:135], v[178:181], v[64:67]
	v_mfma_f32_16x16x32_bf16 v[56:59], v[140:143], v[178:181], v[56:59]
	v_mfma_f32_16x16x32_bf16 v[52:55], v[132:135], v[190:193], v[52:55]
	v_mfma_f32_16x16x32_bf16 v[20:23], v[140:143], v[190:193], v[20:23]
	v_mfma_f32_16x16x32_bf16 v[40:43], v[132:135], v[208:211], v[40:43]
	v_mfma_f32_16x16x32_bf16 v[8:11], v[140:143], v[208:211], v[8:11]
	v_mfma_f32_16x16x32_bf16 v[32:35], v[132:135], v[216:219], v[32:35]
	v_mfma_f32_16x16x32_bf16 v[24:27], v[140:143], v[216:219], v[24:27]
	v_mfma_f32_16x16x32_bf16 v[64:67], v[136:139], v[186:189], v[64:67]
	v_mfma_f32_16x16x32_bf16 v[56:59], v[144:147], v[186:189], v[56:59]
	v_mfma_f32_16x16x32_bf16 v[52:55], v[136:139], v[194:197], v[52:55]
	v_mfma_f32_16x16x32_bf16 v[20:23], v[144:147], v[194:197], v[20:23]
	v_mfma_f32_16x16x32_bf16 v[40:43], v[136:139], v[212:215], v[40:43]
	v_mfma_f32_16x16x32_bf16 v[8:11], v[144:147], v[212:215], v[8:11]
	v_mfma_f32_16x16x32_bf16 v[32:35], v[136:139], v[220:223], v[32:35]
	v_mfma_f32_16x16x32_bf16 v[24:27], v[144:147], v[220:223], v[24:27]


	v_mfma_f32_16x16x32_bf16 v[60:63], v[162:165], v[178:181], v[60:63]
	v_mfma_f32_16x16x32_bf16 v[48:51], v[170:173], v[178:181], v[48:51]
	v_mfma_f32_16x16x32_bf16 v[44:47], v[162:165], v[190:193], v[44:47]
	v_mfma_f32_16x16x32_bf16 v[12:15], v[170:173], v[190:193], v[12:15]
	v_mfma_f32_16x16x32_bf16 v[36:39], v[162:165], v[208:211], v[36:39]
	v_mfma_f32_16x16x32_bf16 v[4:7], v[170:173], v[208:211], v[4:7]
	v_mfma_f32_16x16x32_bf16 v[28:31], v[162:165], v[216:219], v[28:31]
	v_mfma_f32_16x16x32_bf16 v[16:19], v[170:173], v[216:219], v[16:19]
	v_mfma_f32_16x16x32_bf16 v[60:63], v[166:169], v[186:189], v[60:63]
	v_mfma_f32_16x16x32_bf16 v[48:51], v[174:177], v[186:189], v[48:51]
	v_mfma_f32_16x16x32_bf16 v[44:47], v[166:169], v[194:197], v[44:47]
	v_mfma_f32_16x16x32_bf16 v[12:15], v[174:177], v[194:197], v[12:15]
	v_mfma_f32_16x16x32_bf16 v[36:39], v[166:169], v[212:215], v[36:39]
	v_mfma_f32_16x16x32_bf16 v[4:7], v[174:177], v[212:215], v[4:7]
	v_mfma_f32_16x16x32_bf16 v[28:31], v[166:169], v[220:223], v[28:31]
	v_mfma_f32_16x16x32_bf16 v[16:19], v[174:177], v[220:223], v[16:19]

	s_barrier
	s_add_i32 s87, s87, 2
	s_add_u32 s48, s48, 0x100
	s_addc_u32 s49, s49, 0
	s_add_u32 s85, s85, 0x100
	s_addc_u32 s86, s86, 0
	s_cmp_gt_u32 s87, 13
	s_cbranch_scc0 .LBB0_94
	s_and_b64 vcc, exec, s[20:21]
	s_cbranch_vccz .LBB0_97
	s_barrier

.LBB0_176:
	s_sub_i32 s4, s86, s10
	v_ashrrev_i32_e32 v1, 6, v2
	v_lshl_add_u32 v94, s4, 3, v1
	v_cmp_gt_i32_e32 vcc, s31, v94
	s_and_saveexec_b64 s[4:5], vcc
	s_cbranch_execz .LBB0_187
	s_cmp_eq_u32 s92, 0
	s_movk_i32 s6, 0xa0
	s_cselect_b32 s6, s6, 0xa8
	s_brev_b32 s7, 16
	s_cselect_b32 s11, s7, 0x14e0000
	s_add_u32 s6, s8, s6
	s_addc_u32 s7, s9, 0
	s_load_dwordx2 s[6:7], s[6:7], 0x0
	v_ashrrev_i32_e32 v1, 31, v0
	s_load_dwordx2 s[20:21], s[8:9], 0xa8
	v_lshlrev_b64 v[0:1], 17, v[0:1]
	s_load_dwordx4 s[40:43], s[8:9], 0x10
	s_waitcnt lgkmcnt(0)
	s_add_u32 s6, s6, s11
	s_addc_u32 s7, s7, 0
	v_lshl_add_u64 v[0:1], s[20:21], 0, v[0:1]
	s_mov_b64 s[20:21], 0x1480000
	s_sub_i32 s8, s56, s10
	v_lshl_add_u64 v[0:1], v[0:1], 0, s[20:21]
	s_lshl_b32 s20, s8, 3
	s_lshl_b32 s8, s10, 6
	v_readlane_b32 s9, v254, 27
	s_sub_i32 s21, s9, s8
	s_lshl_b32 s8, s10, 5
	v_readlane_b32 s10, v254, 25
	v_and_b32_e32 v68, 63, v2
	v_lshlrev_b32_e32 v70, 3, v94
	s_waitcnt vmcnt(0)
	v_lshlrev_b32_e32 v72, 2, v94
	s_sub_i32 s34, s10, s8
	s_mov_b64 s[8:9], 0
	v_readlane_b32 s11, v254, 26
	s_cmpk_lg_u32 s56, 0x100
	s_cbranch_scc1 .Lln_generic
	v_readfirstlane_b32 s38, v0
	v_readfirstlane_b32 s39, v1
	v_mbcnt_lo_u32_b32 v0, -1, 0
	v_mbcnt_hi_u32_b32 v0, -1, v0
	v_lshlrev_b32_e32 v1, 4, v0
	v_lshlrev_b32_e32 v5, 3, v0
	v_mov_b32_e32 v2, 0x3a800000
	v_mov_b32_e32 v4, 0x3727c5ac
	s_lshr_b32 s10, s29, 6
	s_cmp_lt_i32 s92, 0
	s_cselect_b32 s11, 0, 64
	s_sub_u32 s11, s86, s11
	s_lshl_b32 s11, s11, 3
	s_add_i32 s10, s10, s11
	s_lshl_b32 s11, s10, 12
	s_add_u32 s4, s0, s11
	s_addc_u32 s5, s1, 0
	s_lshl_b32 s11, s10, 11
	s_add_u32 s8, s6, s11
	s_addc_u32 s9, s7, 0
	s_lshl_b32 s11, s10, 3
	s_add_u32 s38, s38, s11
	s_addc_u32 s39, s39, 0
	s_cmp_lt_i32 s92, 0
	s_cbranch_scc0 .Lln_late
	global_load_dwordx4 v[40:43], v1, s[4:5] nt
	global_load_dwordx4 v[44:47], v1, s[4:5] offset:1024 nt
	global_load_dwordx4 v[48:51], v1, s[4:5] offset:2048 nt
	global_load_dwordx4 v[52:55], v1, s[4:5] offset:3072 nt
	global_load_dwordx4 v[8:11], v1, s[40:41]
	global_load_dwordx4 v[12:15], v1, s[40:41] offset:1024
	global_load_dwordx4 v[16:19], v1, s[40:41] offset:2048
	global_load_dwordx4 v[20:23], v1, s[40:41] offset:3072
	global_load_dwordx4 v[24:27], v1, s[42:43]
	global_load_dwordx4 v[28:31], v1, s[42:43] offset:1024
	global_load_dwordx4 v[32:35], v1, s[42:43] offset:2048
	global_load_dwordx4 v[36:39], v1, s[42:43] offset:3072
	v_add_u32_e32 v170, 0x800000, v1
	global_load_dwordx4 v[56:59], v170, s[4:5] nt
	global_load_dwordx4 v[60:63], v170, s[4:5] offset:1024 nt
	global_load_dwordx4 v[64:67], v170, s[4:5] offset:2048 nt
	global_load_dwordx4 v[68:71], v170, s[4:5] offset:3072 nt
	v_add_u32_e32 v170, 0x1000000, v1
	global_load_dwordx4 v[72:75], v170, s[4:5] nt
	global_load_dwordx4 v[76:79], v170, s[4:5] offset:1024 nt
	global_load_dwordx4 v[80:83], v170, s[4:5] offset:2048 nt
	global_load_dwordx4 v[84:87], v170, s[4:5] offset:3072 nt
	v_add_u32_e32 v170, 0x1800000, v1
	global_load_dwordx4 v[88:91], v170, s[4:5] nt
	global_load_dwordx4 v[92:95], v170, s[4:5] offset:1024 nt
	global_load_dwordx4 v[96:99], v170, s[4:5] offset:2048 nt
	global_load_dwordx4 v[100:103], v170, s[4:5] offset:3072 nt
	v_add_u32_e32 v170, 0x2000000, v1
	global_load_dwordx4 v[104:107], v170, s[4:5] nt
	global_load_dwordx4 v[108:111], v170, s[4:5] offset:1024 nt
	global_load_dwordx4 v[112:115], v170, s[4:5] offset:2048 nt
	global_load_dwordx4 v[116:119], v170, s[4:5] offset:3072 nt
	v_add_u32_e32 v170, 0x2800000, v1
	global_load_dwordx4 v[120:123], v170, s[4:5] nt
	global_load_dwordx4 v[124:127], v170, s[4:5] offset:1024 nt
	global_load_dwordx4 v[128:131], v170, s[4:5] offset:2048 nt
	global_load_dwordx4 v[132:135], v170, s[4:5] offset:3072 nt
	v_add_u32_e32 v170, 0x3000000, v1
	global_load_dwordx4 v[136:139], v170, s[4:5] nt
	global_load_dwordx4 v[140:143], v170, s[4:5] offset:1024 nt
	global_load_dwordx4 v[144:147], v170, s[4:5] offset:2048 nt
	global_load_dwordx4 v[148:151], v170, s[4:5] offset:3072 nt
	v_add_u32_e32 v170, 0x3800000, v1
	global_load_dwordx4 v[152:155], v170, s[4:5] nt
	global_load_dwordx4 v[156:159], v170, s[4:5] offset:1024 nt
	global_load_dwordx4 v[160:163], v170, s[4:5] offset:2048 nt
	global_load_dwordx4 v[164:167], v170, s[4:5] offset:3072 nt
	s_waitcnt vmcnt(36)
	v_add_f32_e32 v180, v40, v41
	v_add_f32_e32 v181, v44, v45
	v_add_f32_e32 v182, v48, v49
	v_add_f32_e32 v183, v52, v53
	v_add_f32_e32 v180, v180, v42
	v_add_f32_e32 v181, v181, v46
	v_add_f32_e32 v182, v182, v50
	v_add_f32_e32 v183, v183, v54
	v_add_f32_e32 v180, v180, v43
	v_add_f32_e32 v181, v181, v47
	v_add_f32_e32 v182, v182, v51
	v_add_f32_e32 v183, v183, v55
	v_add_f32_e32 v180, v180, v181
	v_add_f32_e32 v182, v182, v183
	v_add_f32_e32 v180, v180, v182
	s_nop 1
	v_add_f32_dpp v180, v180, v180 quad_perm:[1,0,3,2] row_mask:0xf bank_mask:0xf
	s_nop 1
	v_add_f32_dpp v180, v180, v180 quad_perm:[2,3,0,1] row_mask:0xf bank_mask:0xf
	s_nop 1
	v_add_f32_dpp v180, v180, v180 row_half_mirror row_mask:0xf bank_mask:0xf
	s_nop 1
	v_add_f32_dpp v180, v180, v180 row_mirror row_mask:0xf bank_mask:0xf
	s_nop 1
	v_add_f32_dpp v180, v180, v180 row_bcast:15 row_mask:0xa bank_mask:0xf
	s_nop 1
	v_add_f32_dpp v180, v180, v180 row_bcast:31 row_mask:0xc bank_mask:0xf
	s_nop 0
	v_readlane_b32 s20, v180, 63
	s_nop 1
	v_mul_f32_e32 v184, s20, v2
	v_sub_f32_e32 v40, v40, v184
	v_sub_f32_e32 v41, v41, v184
	v_sub_f32_e32 v42, v42, v184
	v_sub_f32_e32 v43, v43, v184
	v_sub_f32_e32 v44, v44, v184
	v_sub_f32_e32 v45, v45, v184
	v_sub_f32_e32 v46, v46, v184
	v_sub_f32_e32 v47, v47, v184
	v_sub_f32_e32 v48, v48, v184
	v_sub_f32_e32 v49, v49, v184
	v_sub_f32_e32 v50, v50, v184
	v_sub_f32_e32 v51, v51, v184
	v_sub_f32_e32 v52, v52, v184
	v_sub_f32_e32 v53, v53, v184
	v_sub_f32_e32 v54, v54, v184
	v_sub_f32_e32 v55, v55, v184
	v_mul_f32_e32 v180, v40, v40
	v_mul_f32_e32 v181, v44, v44
	v_mul_f32_e32 v182, v48, v48
	v_mul_f32_e32 v183, v52, v52
	v_fmac_f32_e32 v180, v41, v41
	v_fmac_f32_e32 v181, v45, v45
	v_fmac_f32_e32 v182, v49, v49
	v_fmac_f32_e32 v183, v53, v53
	v_fmac_f32_e32 v180, v42, v42
	v_fmac_f32_e32 v181, v46, v46
	v_fmac_f32_e32 v182, v50, v50
	v_fmac_f32_e32 v183, v54, v54
	v_fmac_f32_e32 v180, v43, v43
	v_fmac_f32_e32 v181, v47, v47
	v_fmac_f32_e32 v182, v51, v51
	v_fmac_f32_e32 v183, v55, v55
	v_add_f32_e32 v180, v180, v181
	v_add_f32_e32 v182, v182, v183
	v_add_f32_e32 v180, v180, v182
	s_nop 1
	v_add_f32_dpp v180, v180, v180 quad_perm:[1,0,3,2] row_mask:0xf bank_mask:0xf
	s_nop 1
	v_add_f32_dpp v180, v180, v180 quad_perm:[2,3,0,1] row_mask:0xf bank_mask:0xf
	s_nop 1
	v_add_f32_dpp v180, v180, v180 row_half_mirror row_mask:0xf bank_mask:0xf
	s_nop 1
	v_add_f32_dpp v180, v180, v180 row_mirror row_mask:0xf bank_mask:0xf
	s_nop 1
	v_add_f32_dpp v180, v180, v180 row_bcast:15 row_mask:0xa bank_mask:0xf
	s_nop 1
	v_add_f32_dpp v180, v180, v180 row_bcast:31 row_mask:0xc bank_mask:0xf
	s_nop 0
	v_readlane_b32 s20, v180, 63
	s_nop 1
	v_mov_b32_e32 v185, s20
	v_fma_f32 v185, v185, v2, v4
	v_rsq_f32_e32 v185, v185
	s_nop 0
	v_mul_f32_e32 v40, v40, v185
	v_mul_f32_e32 v41, v41, v185
	v_mul_f32_e32 v42, v42, v185
	v_mul_f32_e32 v43, v43, v185
	v_mul_f32_e32 v44, v44, v185
	v_mul_f32_e32 v45, v45, v185
	v_mul_f32_e32 v46, v46, v185
	v_mul_f32_e32 v47, v47, v185
	v_mul_f32_e32 v48, v48, v185
	v_mul_f32_e32 v49, v49, v185
	v_mul_f32_e32 v50, v50, v185
	v_mul_f32_e32 v51, v51, v185
	v_mul_f32_e32 v52, v52, v185
	v_mul_f32_e32 v53, v53, v185
	v_mul_f32_e32 v54, v54, v185
	v_mul_f32_e32 v55, v55, v185
	s_waitcnt vmcnt(28)
	v_fma_f32 v40, v40, v8, v24
	v_fma_f32 v41, v41, v9, v25
	v_fma_f32 v42, v42, v10, v26
	v_fma_f32 v43, v43, v11, v27
	v_fma_f32 v44, v44, v12, v28
	v_fma_f32 v45, v45, v13, v29
	v_fma_f32 v46, v46, v14, v30
	v_fma_f32 v47, v47, v15, v31
	v_fma_f32 v48, v48, v16, v32
	v_fma_f32 v49, v49, v17, v33
	v_fma_f32 v50, v50, v18, v34
	v_fma_f32 v51, v51, v19, v35
	v_fma_f32 v52, v52, v20, v36
	v_fma_f32 v53, v53, v21, v37
	v_fma_f32 v54, v54, v22, v38
	v_fma_f32 v55, v55, v23, v39
	v_cvt_pk_bf16_f32 v40, v40, v41
	v_cvt_pk_bf16_f32 v41, v42, v43
	v_cvt_pk_bf16_f32 v44, v44, v45
	v_cvt_pk_bf16_f32 v45, v46, v47
	v_cvt_pk_bf16_f32 v48, v48, v49
	v_cvt_pk_bf16_f32 v49, v50, v51
	v_cvt_pk_bf16_f32 v52, v52, v53
	v_cvt_pk_bf16_f32 v53, v54, v55
	global_store_dwordx2 v5, v[40:41], s[8:9]
	global_store_dwordx2 v5, v[44:45], s[8:9] offset:512
	global_store_dwordx2 v5, v[48:49], s[8:9] offset:1024
	global_store_dwordx2 v5, v[52:53], s[8:9] offset:1536
	v_mov_b32_e32 v172, 0x0
	s_mov_b64 exec, 1
	global_store_dwordx2 v172, v[184:185], s[38:39]
	s_mov_b64 exec, -1
	s_waitcnt vmcnt(29)
	v_add_f32_e32 v180, v56, v57
	v_add_f32_e32 v181, v60, v61
	v_add_f32_e32 v182, v64, v65
	v_add_f32_e32 v183, v68, v69
	v_add_f32_e32 v180, v180, v58
	v_add_f32_e32 v181, v181, v62
	v_add_f32_e32 v182, v182, v66
	v_add_f32_e32 v183, v183, v70
	v_add_f32_e32 v180, v180, v59
	v_add_f32_e32 v181, v181, v63
	v_add_f32_e32 v182, v182, v67
	v_add_f32_e32 v183, v183, v71
	v_add_f32_e32 v180, v180, v181
	v_add_f32_e32 v182, v182, v183
	v_add_f32_e32 v180, v180, v182
	s_nop 1
	v_add_f32_dpp v180, v180, v180 quad_perm:[1,0,3,2] row_mask:0xf bank_mask:0xf
	s_nop 1
	v_add_f32_dpp v180, v180, v180 quad_perm:[2,3,0,1] row_mask:0xf bank_mask:0xf
	s_nop 1
	v_add_f32_dpp v180, v180, v180 row_half_mirror row_mask:0xf bank_mask:0xf
	s_nop 1
	v_add_f32_dpp v180, v180, v180 row_mirror row_mask:0xf bank_mask:0xf
	s_nop 1
	v_add_f32_dpp v180, v180, v180 row_bcast:15 row_mask:0xa bank_mask:0xf
	s_nop 1
	v_add_f32_dpp v180, v180, v180 row_bcast:31 row_mask:0xc bank_mask:0xf
	s_nop 0
	v_readlane_b32 s20, v180, 63
	s_nop 1
	v_mul_f32_e32 v184, s20, v2
	v_sub_f32_e32 v56, v56, v184
	v_sub_f32_e32 v57, v57, v184
	v_sub_f32_e32 v58, v58, v184
	v_sub_f32_e32 v59, v59, v184
	v_sub_f32_e32 v60, v60, v184
	v_sub_f32_e32 v61, v61, v184
	v_sub_f32_e32 v62, v62, v184
	v_sub_f32_e32 v63, v63, v184
	v_sub_f32_e32 v64, v64, v184
	v_sub_f32_e32 v65, v65, v184
	v_sub_f32_e32 v66, v66, v184
	v_sub_f32_e32 v67, v67, v184
	v_sub_f32_e32 v68, v68, v184
	v_sub_f32_e32 v69, v69, v184
	v_sub_f32_e32 v70, v70, v184
	v_sub_f32_e32 v71, v71, v184
	v_mul_f32_e32 v180, v56, v56
	v_mul_f32_e32 v181, v60, v60
	v_mul_f32_e32 v182, v64, v64
	v_mul_f32_e32 v183, v68, v68
	v_fmac_f32_e32 v180, v57, v57
	v_fmac_f32_e32 v181, v61, v61
	v_fmac_f32_e32 v182, v65, v65
	v_fmac_f32_e32 v183, v69, v69
	v_fmac_f32_e32 v180, v58, v58
	v_fmac_f32_e32 v181, v62, v62
	v_fmac_f32_e32 v182, v66, v66
	v_fmac_f32_e32 v183, v70, v70
	v_fmac_f32_e32 v180, v59, v59
	v_fmac_f32_e32 v181, v63, v63
	v_fmac_f32_e32 v182, v67, v67
	v_fmac_f32_e32 v183, v71, v71
	v_add_f32_e32 v180, v180, v181
	v_add_f32_e32 v182, v182, v183
	v_add_f32_e32 v180, v180, v182
	s_nop 1
	v_add_f32_dpp v180, v180, v180 quad_perm:[1,0,3,2] row_mask:0xf bank_mask:0xf
	s_nop 1
	v_add_f32_dpp v180, v180, v180 quad_perm:[2,3,0,1] row_mask:0xf bank_mask:0xf
	s_nop 1
	v_add_f32_dpp v180, v180, v180 row_half_mirror row_mask:0xf bank_mask:0xf
	s_nop 1
	v_add_f32_dpp v180, v180, v180 row_mirror row_mask:0xf bank_mask:0xf
	s_nop 1
	v_add_f32_dpp v180, v180, v180 row_bcast:15 row_mask:0xa bank_mask:0xf
	s_nop 1
	v_add_f32_dpp v180, v180, v180 row_bcast:31 row_mask:0xc bank_mask:0xf
	s_nop 0
	v_readlane_b32 s20, v180, 63
	s_nop 1
	v_mov_b32_e32 v185, s20
	v_fma_f32 v185, v185, v2, v4
	v_rsq_f32_e32 v185, v185
	s_nop 0
	v_mul_f32_e32 v56, v56, v185
	v_mul_f32_e32 v57, v57, v185
	v_mul_f32_e32 v58, v58, v185
	v_mul_f32_e32 v59, v59, v185
	v_mul_f32_e32 v60, v60, v185
	v_mul_f32_e32 v61, v61, v185
	v_mul_f32_e32 v62, v62, v185
	v_mul_f32_e32 v63, v63, v185
	v_mul_f32_e32 v64, v64, v185
	v_mul_f32_e32 v65, v65, v185
	v_mul_f32_e32 v66, v66, v185
	v_mul_f32_e32 v67, v67, v185
	v_mul_f32_e32 v68, v68, v185
	v_mul_f32_e32 v69, v69, v185
	v_mul_f32_e32 v70, v70, v185
	v_mul_f32_e32 v71, v71, v185
	v_fma_f32 v56, v56, v8, v24
	v_fma_f32 v57, v57, v9, v25
	v_fma_f32 v58, v58, v10, v26
	v_fma_f32 v59, v59, v11, v27
	v_fma_f32 v60, v60, v12, v28
	v_fma_f32 v61, v61, v13, v29
	v_fma_f32 v62, v62, v14, v30
	v_fma_f32 v63, v63, v15, v31
	v_fma_f32 v64, v64, v16, v32
	v_fma_f32 v65, v65, v17, v33
	v_fma_f32 v66, v66, v18, v34
	v_fma_f32 v67, v67, v19, v35
	v_fma_f32 v68, v68, v20, v36
	v_fma_f32 v69, v69, v21, v37
	v_fma_f32 v70, v70, v22, v38
	v_fma_f32 v71, v71, v23, v39
	v_cvt_pk_bf16_f32 v56, v56, v57
	v_cvt_pk_bf16_f32 v57, v58, v59
	v_cvt_pk_bf16_f32 v60, v60, v61
	v_cvt_pk_bf16_f32 v61, v62, v63
	v_cvt_pk_bf16_f32 v64, v64, v65
	v_cvt_pk_bf16_f32 v65, v66, v67
	v_cvt_pk_bf16_f32 v68, v68, v69
	v_cvt_pk_bf16_f32 v69, v70, v71
	v_add_u32_e32 v171, 0x400000, v5
	global_store_dwordx2 v171, v[56:57], s[8:9]
	global_store_dwordx2 v171, v[60:61], s[8:9] offset:512
	global_store_dwordx2 v171, v[64:65], s[8:9] offset:1024
	global_store_dwordx2 v171, v[68:69], s[8:9] offset:1536
	v_mov_b32_e32 v172, 0x4000
	s_mov_b64 exec, 1
	global_store_dwordx2 v172, v[184:185], s[38:39]
	s_mov_b64 exec, -1
	s_waitcnt vmcnt(30)
	v_add_f32_e32 v180, v72, v73
	v_add_f32_e32 v181, v76, v77
	v_add_f32_e32 v182, v80, v81
	v_add_f32_e32 v183, v84, v85
	v_add_f32_e32 v180, v180, v74
	v_add_f32_e32 v181, v181, v78
	v_add_f32_e32 v182, v182, v82
	v_add_f32_e32 v183, v183, v86
	v_add_f32_e32 v180, v180, v75
	v_add_f32_e32 v181, v181, v79
	v_add_f32_e32 v182, v182, v83
	v_add_f32_e32 v183, v183, v87
	v_add_f32_e32 v180, v180, v181
	v_add_f32_e32 v182, v182, v183
	v_add_f32_e32 v180, v180, v182
	s_nop 1
	v_add_f32_dpp v180, v180, v180 quad_perm:[1,0,3,2] row_mask:0xf bank_mask:0xf
	s_nop 1
	v_add_f32_dpp v180, v180, v180 quad_perm:[2,3,0,1] row_mask:0xf bank_mask:0xf
	s_nop 1
	v_add_f32_dpp v180, v180, v180 row_half_mirror row_mask:0xf bank_mask:0xf
	s_nop 1
	v_add_f32_dpp v180, v180, v180 row_mirror row_mask:0xf bank_mask:0xf
	s_nop 1
	v_add_f32_dpp v180, v180, v180 row_bcast:15 row_mask:0xa bank_mask:0xf
	s_nop 1
	v_add_f32_dpp v180, v180, v180 row_bcast:31 row_mask:0xc bank_mask:0xf
	s_nop 0
	v_readlane_b32 s20, v180, 63
	s_nop 1
	v_mul_f32_e32 v184, s20, v2
	v_sub_f32_e32 v72, v72, v184
	v_sub_f32_e32 v73, v73, v184
	v_sub_f32_e32 v74, v74, v184
	v_sub_f32_e32 v75, v75, v184
	v_sub_f32_e32 v76, v76, v184
	v_sub_f32_e32 v77, v77, v184
	v_sub_f32_e32 v78, v78, v184
	v_sub_f32_e32 v79, v79, v184
	v_sub_f32_e32 v80, v80, v184
	v_sub_f32_e32 v81, v81, v184
	v_sub_f32_e32 v82, v82, v184
	v_sub_f32_e32 v83, v83, v184
	v_sub_f32_e32 v84, v84, v184
	v_sub_f32_e32 v85, v85, v184
	v_sub_f32_e32 v86, v86, v184
	v_sub_f32_e32 v87, v87, v184
	v_mul_f32_e32 v180, v72, v72
	v_mul_f32_e32 v181, v76, v76
	v_mul_f32_e32 v182, v80, v80
	v_mul_f32_e32 v183, v84, v84
	v_fmac_f32_e32 v180, v73, v73
	v_fmac_f32_e32 v181, v77, v77
	v_fmac_f32_e32 v182, v81, v81
	v_fmac_f32_e32 v183, v85, v85
	v_fmac_f32_e32 v180, v74, v74
	v_fmac_f32_e32 v181, v78, v78
	v_fmac_f32_e32 v182, v82, v82
	v_fmac_f32_e32 v183, v86, v86
	v_fmac_f32_e32 v180, v75, v75
	v_fmac_f32_e32 v181, v79, v79
	v_fmac_f32_e32 v182, v83, v83
	v_fmac_f32_e32 v183, v87, v87
	v_add_f32_e32 v180, v180, v181
	v_add_f32_e32 v182, v182, v183
	v_add_f32_e32 v180, v180, v182
	s_nop 1
	v_add_f32_dpp v180, v180, v180 quad_perm:[1,0,3,2] row_mask:0xf bank_mask:0xf
	s_nop 1
	v_add_f32_dpp v180, v180, v180 quad_perm:[2,3,0,1] row_mask:0xf bank_mask:0xf
	s_nop 1
	v_add_f32_dpp v180, v180, v180 row_half_mirror row_mask:0xf bank_mask:0xf
	s_nop 1
	v_add_f32_dpp v180, v180, v180 row_mirror row_mask:0xf bank_mask:0xf
	s_nop 1
	v_add_f32_dpp v180, v180, v180 row_bcast:15 row_mask:0xa bank_mask:0xf
	s_nop 1
	v_add_f32_dpp v180, v180, v180 row_bcast:31 row_mask:0xc bank_mask:0xf
	s_nop 0
	v_readlane_b32 s20, v180, 63
	s_nop 1
	v_mov_b32_e32 v185, s20
	v_fma_f32 v185, v185, v2, v4
	v_rsq_f32_e32 v185, v185
	s_nop 0
	v_mul_f32_e32 v72, v72, v185
	v_mul_f32_e32 v73, v73, v185
	v_mul_f32_e32 v74, v74, v185
	v_mul_f32_e32 v75, v75, v185
	v_mul_f32_e32 v76, v76, v185
	v_mul_f32_e32 v77, v77, v185
	v_mul_f32_e32 v78, v78, v185
	v_mul_f32_e32 v79, v79, v185
	v_mul_f32_e32 v80, v80, v185
	v_mul_f32_e32 v81, v81, v185
	v_mul_f32_e32 v82, v82, v185
	v_mul_f32_e32 v83, v83, v185
	v_mul_f32_e32 v84, v84, v185
	v_mul_f32_e32 v85, v85, v185
	v_mul_f32_e32 v86, v86, v185
	v_mul_f32_e32 v87, v87, v185
	v_fma_f32 v72, v72, v8, v24
	v_fma_f32 v73, v73, v9, v25
	v_fma_f32 v74, v74, v10, v26
	v_fma_f32 v75, v75, v11, v27
	v_fma_f32 v76, v76, v12, v28
	v_fma_f32 v77, v77, v13, v29
	v_fma_f32 v78, v78, v14, v30
	v_fma_f32 v79, v79, v15, v31
	v_fma_f32 v80, v80, v16, v32
	v_fma_f32 v81, v81, v17, v33
	v_fma_f32 v82, v82, v18, v34
	v_fma_f32 v83, v83, v19, v35
	v_fma_f32 v84, v84, v20, v36
	v_fma_f32 v85, v85, v21, v37
	v_fma_f32 v86, v86, v22, v38
	v_fma_f32 v87, v87, v23, v39
	v_cvt_pk_bf16_f32 v72, v72, v73
	v_cvt_pk_bf16_f32 v73, v74, v75
	v_cvt_pk_bf16_f32 v76, v76, v77
	v_cvt_pk_bf16_f32 v77, v78, v79
	v_cvt_pk_bf16_f32 v80, v80, v81
	v_cvt_pk_bf16_f32 v81, v82, v83
	v_cvt_pk_bf16_f32 v84, v84, v85
	v_cvt_pk_bf16_f32 v85, v86, v87
	v_add_u32_e32 v171, 0x800000, v5
	global_store_dwordx2 v171, v[72:73], s[8:9]
	global_store_dwordx2 v171, v[76:77], s[8:9] offset:512
	global_store_dwordx2 v171, v[80:81], s[8:9] offset:1024
	global_store_dwordx2 v171, v[84:85], s[8:9] offset:1536
	v_mov_b32_e32 v172, 0x8000
	s_mov_b64 exec, 1
	global_store_dwordx2 v172, v[184:185], s[38:39]
	s_mov_b64 exec, -1
	s_waitcnt vmcnt(31)
	v_add_f32_e32 v180, v88, v89
	v_add_f32_e32 v181, v92, v93
	v_add_f32_e32 v182, v96, v97
	v_add_f32_e32 v183, v100, v101
	v_add_f32_e32 v180, v180, v90
	v_add_f32_e32 v181, v181, v94
	v_add_f32_e32 v182, v182, v98
	v_add_f32_e32 v183, v183, v102
	v_add_f32_e32 v180, v180, v91
	v_add_f32_e32 v181, v181, v95
	v_add_f32_e32 v182, v182, v99
	v_add_f32_e32 v183, v183, v103
	v_add_f32_e32 v180, v180, v181
	v_add_f32_e32 v182, v182, v183
	v_add_f32_e32 v180, v180, v182
	s_nop 1
	v_add_f32_dpp v180, v180, v180 quad_perm:[1,0,3,2] row_mask:0xf bank_mask:0xf
	s_nop 1
	v_add_f32_dpp v180, v180, v180 quad_perm:[2,3,0,1] row_mask:0xf bank_mask:0xf
	s_nop 1
	v_add_f32_dpp v180, v180, v180 row_half_mirror row_mask:0xf bank_mask:0xf
	s_nop 1
	v_add_f32_dpp v180, v180, v180 row_mirror row_mask:0xf bank_mask:0xf
	s_nop 1
	v_add_f32_dpp v180, v180, v180 row_bcast:15 row_mask:0xa bank_mask:0xf
	s_nop 1
	v_add_f32_dpp v180, v180, v180 row_bcast:31 row_mask:0xc bank_mask:0xf
	s_nop 0
	v_readlane_b32 s20, v180, 63
	s_nop 1
	v_mul_f32_e32 v184, s20, v2
	v_sub_f32_e32 v88, v88, v184
	v_sub_f32_e32 v89, v89, v184
	v_sub_f32_e32 v90, v90, v184
	v_sub_f32_e32 v91, v91, v184
	v_sub_f32_e32 v92, v92, v184
	v_sub_f32_e32 v93, v93, v184
	v_sub_f32_e32 v94, v94, v184
	v_sub_f32_e32 v95, v95, v184
	v_sub_f32_e32 v96, v96, v184
	v_sub_f32_e32 v97, v97, v184
	v_sub_f32_e32 v98, v98, v184
	v_sub_f32_e32 v99, v99, v184
	v_sub_f32_e32 v100, v100, v184
	v_sub_f32_e32 v101, v101, v184
	v_sub_f32_e32 v102, v102, v184
	v_sub_f32_e32 v103, v103, v184
	v_mul_f32_e32 v180, v88, v88
	v_mul_f32_e32 v181, v92, v92
	v_mul_f32_e32 v182, v96, v96
	v_mul_f32_e32 v183, v100, v100
	v_fmac_f32_e32 v180, v89, v89
	v_fmac_f32_e32 v181, v93, v93
	v_fmac_f32_e32 v182, v97, v97
	v_fmac_f32_e32 v183, v101, v101
	v_fmac_f32_e32 v180, v90, v90
	v_fmac_f32_e32 v181, v94, v94
	v_fmac_f32_e32 v182, v98, v98
	v_fmac_f32_e32 v183, v102, v102
	v_fmac_f32_e32 v180, v91, v91
	v_fmac_f32_e32 v181, v95, v95
	v_fmac_f32_e32 v182, v99, v99
	v_fmac_f32_e32 v183, v103, v103
	v_add_f32_e32 v180, v180, v181
	v_add_f32_e32 v182, v182, v183
	v_add_f32_e32 v180, v180, v182
	s_nop 1
	v_add_f32_dpp v180, v180, v180 quad_perm:[1,0,3,2] row_mask:0xf bank_mask:0xf
	s_nop 1
	v_add_f32_dpp v180, v180, v180 quad_perm:[2,3,0,1] row_mask:0xf bank_mask:0xf
	s_nop 1
	v_add_f32_dpp v180, v180, v180 row_half_mirror row_mask:0xf bank_mask:0xf
	s_nop 1
	v_add_f32_dpp v180, v180, v180 row_mirror row_mask:0xf bank_mask:0xf
	s_nop 1
	v_add_f32_dpp v180, v180, v180 row_bcast:15 row_mask:0xa bank_mask:0xf
	s_nop 1
	v_add_f32_dpp v180, v180, v180 row_bcast:31 row_mask:0xc bank_mask:0xf
	s_nop 0
	v_readlane_b32 s20, v180, 63
	s_nop 1
	v_mov_b32_e32 v185, s20
	v_fma_f32 v185, v185, v2, v4
	v_rsq_f32_e32 v185, v185
	s_nop 0
	v_mul_f32_e32 v88, v88, v185
	v_mul_f32_e32 v89, v89, v185
	v_mul_f32_e32 v90, v90, v185
	v_mul_f32_e32 v91, v91, v185
	v_mul_f32_e32 v92, v92, v185
	v_mul_f32_e32 v93, v93, v185
	v_mul_f32_e32 v94, v94, v185
	v_mul_f32_e32 v95, v95, v185
	v_mul_f32_e32 v96, v96, v185
	v_mul_f32_e32 v97, v97, v185
	v_mul_f32_e32 v98, v98, v185
	v_mul_f32_e32 v99, v99, v185
	v_mul_f32_e32 v100, v100, v185
	v_mul_f32_e32 v101, v101, v185
	v_mul_f32_e32 v102, v102, v185
	v_mul_f32_e32 v103, v103, v185
	v_fma_f32 v88, v88, v8, v24
	v_fma_f32 v89, v89, v9, v25
	v_fma_f32 v90, v90, v10, v26
	v_fma_f32 v91, v91, v11, v27
	v_fma_f32 v92, v92, v12, v28
	v_fma_f32 v93, v93, v13, v29
	v_fma_f32 v94, v94, v14, v30
	v_fma_f32 v95, v95, v15, v31
	v_fma_f32 v96, v96, v16, v32
	v_fma_f32 v97, v97, v17, v33
	v_fma_f32 v98, v98, v18, v34
	v_fma_f32 v99, v99, v19, v35
	v_fma_f32 v100, v100, v20, v36
	v_fma_f32 v101, v101, v21, v37
	v_fma_f32 v102, v102, v22, v38
	v_fma_f32 v103, v103, v23, v39
	v_cvt_pk_bf16_f32 v88, v88, v89
	v_cvt_pk_bf16_f32 v89, v90, v91
	v_cvt_pk_bf16_f32 v92, v92, v93
	v_cvt_pk_bf16_f32 v93, v94, v95
	v_cvt_pk_bf16_f32 v96, v96, v97
	v_cvt_pk_bf16_f32 v97, v98, v99
	v_cvt_pk_bf16_f32 v100, v100, v101
	v_cvt_pk_bf16_f32 v101, v102, v103
	v_add_u32_e32 v171, 0xc00000, v5
	global_store_dwordx2 v171, v[88:89], s[8:9]
	global_store_dwordx2 v171, v[92:93], s[8:9] offset:512
	global_store_dwordx2 v171, v[96:97], s[8:9] offset:1024
	global_store_dwordx2 v171, v[100:101], s[8:9] offset:1536
	v_mov_b32_e32 v172, 0xc000
	s_mov_b64 exec, 1
	global_store_dwordx2 v172, v[184:185], s[38:39]
	s_mov_b64 exec, -1
	s_waitcnt vmcnt(32)
	v_add_f32_e32 v180, v104, v105
	v_add_f32_e32 v181, v108, v109
	v_add_f32_e32 v182, v112, v113
	v_add_f32_e32 v183, v116, v117
	v_add_f32_e32 v180, v180, v106
	v_add_f32_e32 v181, v181, v110
	v_add_f32_e32 v182, v182, v114
	v_add_f32_e32 v183, v183, v118
	v_add_f32_e32 v180, v180, v107
	v_add_f32_e32 v181, v181, v111
	v_add_f32_e32 v182, v182, v115
	v_add_f32_e32 v183, v183, v119
	v_add_f32_e32 v180, v180, v181
	v_add_f32_e32 v182, v182, v183
	v_add_f32_e32 v180, v180, v182
	s_nop 1
	v_add_f32_dpp v180, v180, v180 quad_perm:[1,0,3,2] row_mask:0xf bank_mask:0xf
	s_nop 1
	v_add_f32_dpp v180, v180, v180 quad_perm:[2,3,0,1] row_mask:0xf bank_mask:0xf
	s_nop 1
	v_add_f32_dpp v180, v180, v180 row_half_mirror row_mask:0xf bank_mask:0xf
	s_nop 1
	v_add_f32_dpp v180, v180, v180 row_mirror row_mask:0xf bank_mask:0xf
	s_nop 1
	v_add_f32_dpp v180, v180, v180 row_bcast:15 row_mask:0xa bank_mask:0xf
	s_nop 1
	v_add_f32_dpp v180, v180, v180 row_bcast:31 row_mask:0xc bank_mask:0xf
	s_nop 0
	v_readlane_b32 s20, v180, 63
	s_nop 1
	v_mul_f32_e32 v184, s20, v2
	v_sub_f32_e32 v104, v104, v184
	v_sub_f32_e32 v105, v105, v184
	v_sub_f32_e32 v106, v106, v184
	v_sub_f32_e32 v107, v107, v184
	v_sub_f32_e32 v108, v108, v184
	v_sub_f32_e32 v109, v109, v184
	v_sub_f32_e32 v110, v110, v184
	v_sub_f32_e32 v111, v111, v184
	v_sub_f32_e32 v112, v112, v184
	v_sub_f32_e32 v113, v113, v184
	v_sub_f32_e32 v114, v114, v184
	v_sub_f32_e32 v115, v115, v184
	v_sub_f32_e32 v116, v116, v184
	v_sub_f32_e32 v117, v117, v184
	v_sub_f32_e32 v118, v118, v184
	v_sub_f32_e32 v119, v119, v184
	v_mul_f32_e32 v180, v104, v104
	v_mul_f32_e32 v181, v108, v108
	v_mul_f32_e32 v182, v112, v112
	v_mul_f32_e32 v183, v116, v116
	v_fmac_f32_e32 v180, v105, v105
	v_fmac_f32_e32 v181, v109, v109
	v_fmac_f32_e32 v182, v113, v113
	v_fmac_f32_e32 v183, v117, v117
	v_fmac_f32_e32 v180, v106, v106
	v_fmac_f32_e32 v181, v110, v110
	v_fmac_f32_e32 v182, v114, v114
	v_fmac_f32_e32 v183, v118, v118
	v_fmac_f32_e32 v180, v107, v107
	v_fmac_f32_e32 v181, v111, v111
	v_fmac_f32_e32 v182, v115, v115
	v_fmac_f32_e32 v183, v119, v119
	v_add_f32_e32 v180, v180, v181
	v_add_f32_e32 v182, v182, v183
	v_add_f32_e32 v180, v180, v182
	s_nop 1
	v_add_f32_dpp v180, v180, v180 quad_perm:[1,0,3,2] row_mask:0xf bank_mask:0xf
	s_nop 1
	v_add_f32_dpp v180, v180, v180 quad_perm:[2,3,0,1] row_mask:0xf bank_mask:0xf
	s_nop 1
	v_add_f32_dpp v180, v180, v180 row_half_mirror row_mask:0xf bank_mask:0xf
	s_nop 1
	v_add_f32_dpp v180, v180, v180 row_mirror row_mask:0xf bank_mask:0xf
	s_nop 1
	v_add_f32_dpp v180, v180, v180 row_bcast:15 row_mask:0xa bank_mask:0xf
	s_nop 1
	v_add_f32_dpp v180, v180, v180 row_bcast:31 row_mask:0xc bank_mask:0xf
	s_nop 0
	v_readlane_b32 s20, v180, 63
	s_nop 1
	v_mov_b32_e32 v185, s20
	v_fma_f32 v185, v185, v2, v4
	v_rsq_f32_e32 v185, v185
	s_nop 0
	v_mul_f32_e32 v104, v104, v185
	v_mul_f32_e32 v105, v105, v185
	v_mul_f32_e32 v106, v106, v185
	v_mul_f32_e32 v107, v107, v185
	v_mul_f32_e32 v108, v108, v185
	v_mul_f32_e32 v109, v109, v185
	v_mul_f32_e32 v110, v110, v185
	v_mul_f32_e32 v111, v111, v185
	v_mul_f32_e32 v112, v112, v185
	v_mul_f32_e32 v113, v113, v185
	v_mul_f32_e32 v114, v114, v185
	v_mul_f32_e32 v115, v115, v185
	v_mul_f32_e32 v116, v116, v185
	v_mul_f32_e32 v117, v117, v185
	v_mul_f32_e32 v118, v118, v185
	v_mul_f32_e32 v119, v119, v185
	v_fma_f32 v104, v104, v8, v24
	v_fma_f32 v105, v105, v9, v25
	v_fma_f32 v106, v106, v10, v26
	v_fma_f32 v107, v107, v11, v27
	v_fma_f32 v108, v108, v12, v28
	v_fma_f32 v109, v109, v13, v29
	v_fma_f32 v110, v110, v14, v30
	v_fma_f32 v111, v111, v15, v31
	v_fma_f32 v112, v112, v16, v32
	v_fma_f32 v113, v113, v17, v33
	v_fma_f32 v114, v114, v18, v34
	v_fma_f32 v115, v115, v19, v35
	v_fma_f32 v116, v116, v20, v36
	v_fma_f32 v117, v117, v21, v37
	v_fma_f32 v118, v118, v22, v38
	v_fma_f32 v119, v119, v23, v39
	v_cvt_pk_bf16_f32 v104, v104, v105
	v_cvt_pk_bf16_f32 v105, v106, v107
	v_cvt_pk_bf16_f32 v108, v108, v109
	v_cvt_pk_bf16_f32 v109, v110, v111
	v_cvt_pk_bf16_f32 v112, v112, v113
	v_cvt_pk_bf16_f32 v113, v114, v115
	v_cvt_pk_bf16_f32 v116, v116, v117
	v_cvt_pk_bf16_f32 v117, v118, v119
	v_add_u32_e32 v171, 0x1000000, v5
	global_store_dwordx2 v171, v[104:105], s[8:9]
	global_store_dwordx2 v171, v[108:109], s[8:9] offset:512
	global_store_dwordx2 v171, v[112:113], s[8:9] offset:1024
	global_store_dwordx2 v171, v[116:117], s[8:9] offset:1536
	v_mov_b32_e32 v172, 0x10000
	s_mov_b64 exec, 1
	global_store_dwordx2 v172, v[184:185], s[38:39]
	s_mov_b64 exec, -1
	s_waitcnt vmcnt(33)
	v_add_f32_e32 v180, v120, v121
	v_add_f32_e32 v181, v124, v125
	v_add_f32_e32 v182, v128, v129
	v_add_f32_e32 v183, v132, v133
	v_add_f32_e32 v180, v180, v122
	v_add_f32_e32 v181, v181, v126
	v_add_f32_e32 v182, v182, v130
	v_add_f32_e32 v183, v183, v134
	v_add_f32_e32 v180, v180, v123
	v_add_f32_e32 v181, v181, v127
	v_add_f32_e32 v182, v182, v131
	v_add_f32_e32 v183, v183, v135
	v_add_f32_e32 v180, v180, v181
	v_add_f32_e32 v182, v182, v183
	v_add_f32_e32 v180, v180, v182
	s_nop 1
	v_add_f32_dpp v180, v180, v180 quad_perm:[1,0,3,2] row_mask:0xf bank_mask:0xf
	s_nop 1
	v_add_f32_dpp v180, v180, v180 quad_perm:[2,3,0,1] row_mask:0xf bank_mask:0xf
	s_nop 1
	v_add_f32_dpp v180, v180, v180 row_half_mirror row_mask:0xf bank_mask:0xf
	s_nop 1
	v_add_f32_dpp v180, v180, v180 row_mirror row_mask:0xf bank_mask:0xf
	s_nop 1
	v_add_f32_dpp v180, v180, v180 row_bcast:15 row_mask:0xa bank_mask:0xf
	s_nop 1
	v_add_f32_dpp v180, v180, v180 row_bcast:31 row_mask:0xc bank_mask:0xf
	s_nop 0
	v_readlane_b32 s20, v180, 63
	s_nop 1
	v_mul_f32_e32 v184, s20, v2
	v_sub_f32_e32 v120, v120, v184
	v_sub_f32_e32 v121, v121, v184
	v_sub_f32_e32 v122, v122, v184
	v_sub_f32_e32 v123, v123, v184
	v_sub_f32_e32 v124, v124, v184
	v_sub_f32_e32 v125, v125, v184
	v_sub_f32_e32 v126, v126, v184
	v_sub_f32_e32 v127, v127, v184
	v_sub_f32_e32 v128, v128, v184
	v_sub_f32_e32 v129, v129, v184
	v_sub_f32_e32 v130, v130, v184
	v_sub_f32_e32 v131, v131, v184
	v_sub_f32_e32 v132, v132, v184
	v_sub_f32_e32 v133, v133, v184
	v_sub_f32_e32 v134, v134, v184
	v_sub_f32_e32 v135, v135, v184
	v_mul_f32_e32 v180, v120, v120
	v_mul_f32_e32 v181, v124, v124
	v_mul_f32_e32 v182, v128, v128
	v_mul_f32_e32 v183, v132, v132
	v_fmac_f32_e32 v180, v121, v121
	v_fmac_f32_e32 v181, v125, v125
	v_fmac_f32_e32 v182, v129, v129
	v_fmac_f32_e32 v183, v133, v133
	v_fmac_f32_e32 v180, v122, v122
	v_fmac_f32_e32 v181, v126, v126
	v_fmac_f32_e32 v182, v130, v130
	v_fmac_f32_e32 v183, v134, v134
	v_fmac_f32_e32 v180, v123, v123
	v_fmac_f32_e32 v181, v127, v127
	v_fmac_f32_e32 v182, v131, v131
	v_fmac_f32_e32 v183, v135, v135
	v_add_f32_e32 v180, v180, v181
	v_add_f32_e32 v182, v182, v183
	v_add_f32_e32 v180, v180, v182
	s_nop 1
	v_add_f32_dpp v180, v180, v180 quad_perm:[1,0,3,2] row_mask:0xf bank_mask:0xf
	s_nop 1
	v_add_f32_dpp v180, v180, v180 quad_perm:[2,3,0,1] row_mask:0xf bank_mask:0xf
	s_nop 1
	v_add_f32_dpp v180, v180, v180 row_half_mirror row_mask:0xf bank_mask:0xf
	s_nop 1
	v_add_f32_dpp v180, v180, v180 row_mirror row_mask:0xf bank_mask:0xf
	s_nop 1
	v_add_f32_dpp v180, v180, v180 row_bcast:15 row_mask:0xa bank_mask:0xf
	s_nop 1
	v_add_f32_dpp v180, v180, v180 row_bcast:31 row_mask:0xc bank_mask:0xf
	s_nop 0
	v_readlane_b32 s20, v180, 63
	s_nop 1
	v_mov_b32_e32 v185, s20
	v_fma_f32 v185, v185, v2, v4
	v_rsq_f32_e32 v185, v185
	s_nop 0
	v_mul_f32_e32 v120, v120, v185
	v_mul_f32_e32 v121, v121, v185
	v_mul_f32_e32 v122, v122, v185
	v_mul_f32_e32 v123, v123, v185
	v_mul_f32_e32 v124, v124, v185
	v_mul_f32_e32 v125, v125, v185
	v_mul_f32_e32 v126, v126, v185
	v_mul_f32_e32 v127, v127, v185
	v_mul_f32_e32 v128, v128, v185
	v_mul_f32_e32 v129, v129, v185
	v_mul_f32_e32 v130, v130, v185
	v_mul_f32_e32 v131, v131, v185
	v_mul_f32_e32 v132, v132, v185
	v_mul_f32_e32 v133, v133, v185
	v_mul_f32_e32 v134, v134, v185
	v_mul_f32_e32 v135, v135, v185
	v_fma_f32 v120, v120, v8, v24
	v_fma_f32 v121, v121, v9, v25
	v_fma_f32 v122, v122, v10, v26
	v_fma_f32 v123, v123, v11, v27
	v_fma_f32 v124, v124, v12, v28
	v_fma_f32 v125, v125, v13, v29
	v_fma_f32 v126, v126, v14, v30
	v_fma_f32 v127, v127, v15, v31
	v_fma_f32 v128, v128, v16, v32
	v_fma_f32 v129, v129, v17, v33
	v_fma_f32 v130, v130, v18, v34
	v_fma_f32 v131, v131, v19, v35
	v_fma_f32 v132, v132, v20, v36
	v_fma_f32 v133, v133, v21, v37
	v_fma_f32 v134, v134, v22, v38
	v_fma_f32 v135, v135, v23, v39
	v_cvt_pk_bf16_f32 v120, v120, v121
	v_cvt_pk_bf16_f32 v121, v122, v123
	v_cvt_pk_bf16_f32 v124, v124, v125
	v_cvt_pk_bf16_f32 v125, v126, v127
	v_cvt_pk_bf16_f32 v128, v128, v129
	v_cvt_pk_bf16_f32 v129, v130, v131
	v_cvt_pk_bf16_f32 v132, v132, v133
	v_cvt_pk_bf16_f32 v133, v134, v135
	v_add_u32_e32 v171, 0x1400000, v5
	global_store_dwordx2 v171, v[120:121], s[8:9]
	global_store_dwordx2 v171, v[124:125], s[8:9] offset:512
	global_store_dwordx2 v171, v[128:129], s[8:9] offset:1024
	global_store_dwordx2 v171, v[132:133], s[8:9] offset:1536
	v_mov_b32_e32 v172, 0x14000
	s_mov_b64 exec, 1
	global_store_dwordx2 v172, v[184:185], s[38:39]
	s_mov_b64 exec, -1
	s_waitcnt vmcnt(34)
	v_add_f32_e32 v180, v136, v137
	v_add_f32_e32 v181, v140, v141
	v_add_f32_e32 v182, v144, v145
	v_add_f32_e32 v183, v148, v149
	v_add_f32_e32 v180, v180, v138
	v_add_f32_e32 v181, v181, v142
	v_add_f32_e32 v182, v182, v146
	v_add_f32_e32 v183, v183, v150
	v_add_f32_e32 v180, v180, v139
	v_add_f32_e32 v181, v181, v143
	v_add_f32_e32 v182, v182, v147
	v_add_f32_e32 v183, v183, v151
	v_add_f32_e32 v180, v180, v181
	v_add_f32_e32 v182, v182, v183
	v_add_f32_e32 v180, v180, v182
	s_nop 1
	v_add_f32_dpp v180, v180, v180 quad_perm:[1,0,3,2] row_mask:0xf bank_mask:0xf
	s_nop 1
	v_add_f32_dpp v180, v180, v180 quad_perm:[2,3,0,1] row_mask:0xf bank_mask:0xf
	s_nop 1
	v_add_f32_dpp v180, v180, v180 row_half_mirror row_mask:0xf bank_mask:0xf
	s_nop 1
	v_add_f32_dpp v180, v180, v180 row_mirror row_mask:0xf bank_mask:0xf
	s_nop 1
	v_add_f32_dpp v180, v180, v180 row_bcast:15 row_mask:0xa bank_mask:0xf
	s_nop 1
	v_add_f32_dpp v180, v180, v180 row_bcast:31 row_mask:0xc bank_mask:0xf
	s_nop 0
	v_readlane_b32 s20, v180, 63
	s_nop 1
	v_mul_f32_e32 v184, s20, v2
	v_sub_f32_e32 v136, v136, v184
	v_sub_f32_e32 v137, v137, v184
	v_sub_f32_e32 v138, v138, v184
	v_sub_f32_e32 v139, v139, v184
	v_sub_f32_e32 v140, v140, v184
	v_sub_f32_e32 v141, v141, v184
	v_sub_f32_e32 v142, v142, v184
	v_sub_f32_e32 v143, v143, v184
	v_sub_f32_e32 v144, v144, v184
	v_sub_f32_e32 v145, v145, v184
	v_sub_f32_e32 v146, v146, v184
	v_sub_f32_e32 v147, v147, v184
	v_sub_f32_e32 v148, v148, v184
	v_sub_f32_e32 v149, v149, v184
	v_sub_f32_e32 v150, v150, v184
	v_sub_f32_e32 v151, v151, v184
	v_mul_f32_e32 v180, v136, v136
	v_mul_f32_e32 v181, v140, v140
	v_mul_f32_e32 v182, v144, v144
	v_mul_f32_e32 v183, v148, v148
	v_fmac_f32_e32 v180, v137, v137
	v_fmac_f32_e32 v181, v141, v141
	v_fmac_f32_e32 v182, v145, v145
	v_fmac_f32_e32 v183, v149, v149
	v_fmac_f32_e32 v180, v138, v138
	v_fmac_f32_e32 v181, v142, v142
	v_fmac_f32_e32 v182, v146, v146
	v_fmac_f32_e32 v183, v150, v150
	v_fmac_f32_e32 v180, v139, v139
	v_fmac_f32_e32 v181, v143, v143
	v_fmac_f32_e32 v182, v147, v147
	v_fmac_f32_e32 v183, v151, v151
	v_add_f32_e32 v180, v180, v181
	v_add_f32_e32 v182, v182, v183
	v_add_f32_e32 v180, v180, v182
	s_nop 1
	v_add_f32_dpp v180, v180, v180 quad_perm:[1,0,3,2] row_mask:0xf bank_mask:0xf
	s_nop 1
	v_add_f32_dpp v180, v180, v180 quad_perm:[2,3,0,1] row_mask:0xf bank_mask:0xf
	s_nop 1
	v_add_f32_dpp v180, v180, v180 row_half_mirror row_mask:0xf bank_mask:0xf
	s_nop 1
	v_add_f32_dpp v180, v180, v180 row_mirror row_mask:0xf bank_mask:0xf
	s_nop 1
	v_add_f32_dpp v180, v180, v180 row_bcast:15 row_mask:0xa bank_mask:0xf
	s_nop 1
	v_add_f32_dpp v180, v180, v180 row_bcast:31 row_mask:0xc bank_mask:0xf
	s_nop 0
	v_readlane_b32 s20, v180, 63
	s_nop 1
	v_mov_b32_e32 v185, s20
	v_fma_f32 v185, v185, v2, v4
	v_rsq_f32_e32 v185, v185
	s_nop 0
	v_mul_f32_e32 v136, v136, v185
	v_mul_f32_e32 v137, v137, v185
	v_mul_f32_e32 v138, v138, v185
	v_mul_f32_e32 v139, v139, v185
	v_mul_f32_e32 v140, v140, v185
	v_mul_f32_e32 v141, v141, v185
	v_mul_f32_e32 v142, v142, v185
	v_mul_f32_e32 v143, v143, v185
	v_mul_f32_e32 v144, v144, v185
	v_mul_f32_e32 v145, v145, v185
	v_mul_f32_e32 v146, v146, v185
	v_mul_f32_e32 v147, v147, v185
	v_mul_f32_e32 v148, v148, v185
	v_mul_f32_e32 v149, v149, v185
	v_mul_f32_e32 v150, v150, v185
	v_mul_f32_e32 v151, v151, v185
	v_fma_f32 v136, v136, v8, v24
	v_fma_f32 v137, v137, v9, v25
	v_fma_f32 v138, v138, v10, v26
	v_fma_f32 v139, v139, v11, v27
	v_fma_f32 v140, v140, v12, v28
	v_fma_f32 v141, v141, v13, v29
	v_fma_f32 v142, v142, v14, v30
	v_fma_f32 v143, v143, v15, v31
	v_fma_f32 v144, v144, v16, v32
	v_fma_f32 v145, v145, v17, v33
	v_fma_f32 v146, v146, v18, v34
	v_fma_f32 v147, v147, v19, v35
	v_fma_f32 v148, v148, v20, v36
	v_fma_f32 v149, v149, v21, v37
	v_fma_f32 v150, v150, v22, v38
	v_fma_f32 v151, v151, v23, v39
	v_cvt_pk_bf16_f32 v136, v136, v137
	v_cvt_pk_bf16_f32 v137, v138, v139
	v_cvt_pk_bf16_f32 v140, v140, v141
	v_cvt_pk_bf16_f32 v141, v142, v143
	v_cvt_pk_bf16_f32 v144, v144, v145
	v_cvt_pk_bf16_f32 v145, v146, v147
	v_cvt_pk_bf16_f32 v148, v148, v149
	v_cvt_pk_bf16_f32 v149, v150, v151
	v_add_u32_e32 v171, 0x1800000, v5
	global_store_dwordx2 v171, v[136:137], s[8:9]
	global_store_dwordx2 v171, v[140:141], s[8:9] offset:512
	global_store_dwordx2 v171, v[144:145], s[8:9] offset:1024
	global_store_dwordx2 v171, v[148:149], s[8:9] offset:1536
	v_mov_b32_e32 v172, 0x18000
	s_mov_b64 exec, 1
	global_store_dwordx2 v172, v[184:185], s[38:39]
	s_mov_b64 exec, -1
	s_waitcnt vmcnt(35)
	v_add_f32_e32 v180, v152, v153
	v_add_f32_e32 v181, v156, v157
	v_add_f32_e32 v182, v160, v161
	v_add_f32_e32 v183, v164, v165
	v_add_f32_e32 v180, v180, v154
	v_add_f32_e32 v181, v181, v158
	v_add_f32_e32 v182, v182, v162
	v_add_f32_e32 v183, v183, v166
	v_add_f32_e32 v180, v180, v155
	v_add_f32_e32 v181, v181, v159
	v_add_f32_e32 v182, v182, v163
	v_add_f32_e32 v183, v183, v167
	v_add_f32_e32 v180, v180, v181
	v_add_f32_e32 v182, v182, v183
	v_add_f32_e32 v180, v180, v182
	s_nop 1
	v_add_f32_dpp v180, v180, v180 quad_perm:[1,0,3,2] row_mask:0xf bank_mask:0xf
	s_nop 1
	v_add_f32_dpp v180, v180, v180 quad_perm:[2,3,0,1] row_mask:0xf bank_mask:0xf
	s_nop 1
	v_add_f32_dpp v180, v180, v180 row_half_mirror row_mask:0xf bank_mask:0xf
	s_nop 1
	v_add_f32_dpp v180, v180, v180 row_mirror row_mask:0xf bank_mask:0xf
	s_nop 1
	v_add_f32_dpp v180, v180, v180 row_bcast:15 row_mask:0xa bank_mask:0xf
	s_nop 1
	v_add_f32_dpp v180, v180, v180 row_bcast:31 row_mask:0xc bank_mask:0xf
	s_nop 0
	v_readlane_b32 s20, v180, 63
	s_nop 1
	v_mul_f32_e32 v184, s20, v2
	v_sub_f32_e32 v152, v152, v184
	v_sub_f32_e32 v153, v153, v184
	v_sub_f32_e32 v154, v154, v184
	v_sub_f32_e32 v155, v155, v184
	v_sub_f32_e32 v156, v156, v184
	v_sub_f32_e32 v157, v157, v184
	v_sub_f32_e32 v158, v158, v184
	v_sub_f32_e32 v159, v159, v184
	v_sub_f32_e32 v160, v160, v184
	v_sub_f32_e32 v161, v161, v184
	v_sub_f32_e32 v162, v162, v184
	v_sub_f32_e32 v163, v163, v184
	v_sub_f32_e32 v164, v164, v184
	v_sub_f32_e32 v165, v165, v184
	v_sub_f32_e32 v166, v166, v184
	v_sub_f32_e32 v167, v167, v184
	v_mul_f32_e32 v180, v152, v152
	v_mul_f32_e32 v181, v156, v156
	v_mul_f32_e32 v182, v160, v160
	v_mul_f32_e32 v183, v164, v164
	v_fmac_f32_e32 v180, v153, v153
	v_fmac_f32_e32 v181, v157, v157
	v_fmac_f32_e32 v182, v161, v161
	v_fmac_f32_e32 v183, v165, v165
	v_fmac_f32_e32 v180, v154, v154
	v_fmac_f32_e32 v181, v158, v158
	v_fmac_f32_e32 v182, v162, v162
	v_fmac_f32_e32 v183, v166, v166
	v_fmac_f32_e32 v180, v155, v155
	v_fmac_f32_e32 v181, v159, v159
	v_fmac_f32_e32 v182, v163, v163
	v_fmac_f32_e32 v183, v167, v167
	v_add_f32_e32 v180, v180, v181
	v_add_f32_e32 v182, v182, v183
	v_add_f32_e32 v180, v180, v182
	s_nop 1
	v_add_f32_dpp v180, v180, v180 quad_perm:[1,0,3,2] row_mask:0xf bank_mask:0xf
	s_nop 1
	v_add_f32_dpp v180, v180, v180 quad_perm:[2,3,0,1] row_mask:0xf bank_mask:0xf
	s_nop 1
	v_add_f32_dpp v180, v180, v180 row_half_mirror row_mask:0xf bank_mask:0xf
	s_nop 1
	v_add_f32_dpp v180, v180, v180 row_mirror row_mask:0xf bank_mask:0xf
	s_nop 1
	v_add_f32_dpp v180, v180, v180 row_bcast:15 row_mask:0xa bank_mask:0xf
	s_nop 1
	v_add_f32_dpp v180, v180, v180 row_bcast:31 row_mask:0xc bank_mask:0xf
	s_nop 0
	v_readlane_b32 s20, v180, 63
	s_nop 1
	v_mov_b32_e32 v185, s20
	v_fma_f32 v185, v185, v2, v4
	v_rsq_f32_e32 v185, v185
	s_nop 0
	v_mul_f32_e32 v152, v152, v185
	v_mul_f32_e32 v153, v153, v185
	v_mul_f32_e32 v154, v154, v185
	v_mul_f32_e32 v155, v155, v185
	v_mul_f32_e32 v156, v156, v185
	v_mul_f32_e32 v157, v157, v185
	v_mul_f32_e32 v158, v158, v185
	v_mul_f32_e32 v159, v159, v185
	v_mul_f32_e32 v160, v160, v185
	v_mul_f32_e32 v161, v161, v185
	v_mul_f32_e32 v162, v162, v185
	v_mul_f32_e32 v163, v163, v185
	v_mul_f32_e32 v164, v164, v185
	v_mul_f32_e32 v165, v165, v185
	v_mul_f32_e32 v166, v166, v185
	v_mul_f32_e32 v167, v167, v185
	v_fma_f32 v152, v152, v8, v24
	v_fma_f32 v153, v153, v9, v25
	v_fma_f32 v154, v154, v10, v26
	v_fma_f32 v155, v155, v11, v27
	v_fma_f32 v156, v156, v12, v28
	v_fma_f32 v157, v157, v13, v29
	v_fma_f32 v158, v158, v14, v30
	v_fma_f32 v159, v159, v15, v31
	v_fma_f32 v160, v160, v16, v32
	v_fma_f32 v161, v161, v17, v33
	v_fma_f32 v162, v162, v18, v34
	v_fma_f32 v163, v163, v19, v35
	v_fma_f32 v164, v164, v20, v36
	v_fma_f32 v165, v165, v21, v37
	v_fma_f32 v166, v166, v22, v38
	v_fma_f32 v167, v167, v23, v39
	v_cvt_pk_bf16_f32 v152, v152, v153
	v_cvt_pk_bf16_f32 v153, v154, v155
	v_cvt_pk_bf16_f32 v156, v156, v157
	v_cvt_pk_bf16_f32 v157, v158, v159
	v_cvt_pk_bf16_f32 v160, v160, v161
	v_cvt_pk_bf16_f32 v161, v162, v163
	v_cvt_pk_bf16_f32 v164, v164, v165
	v_cvt_pk_bf16_f32 v165, v166, v167
	v_add_u32_e32 v171, 0x1c00000, v5
	global_store_dwordx2 v171, v[152:153], s[8:9]
	global_store_dwordx2 v171, v[156:157], s[8:9] offset:512
	global_store_dwordx2 v171, v[160:161], s[8:9] offset:1024
	global_store_dwordx2 v171, v[164:165], s[8:9] offset:1536
	v_mov_b32_e32 v172, 0x1c000
	s_mov_b64 exec, 1
	global_store_dwordx2 v172, v[184:185], s[38:39]
	s_mov_b64 exec, -1
	s_branch .LBB0_188
.Lln_late:
	s_cmpk_lt_u32 s10, 0x400
	s_cbranch_scc0 .Lln_r10
	global_load_dwordx4 v[40:43], v1, s[4:5] nt
	global_load_dwordx4 v[44:47], v1, s[4:5] offset:1024 nt
	global_load_dwordx4 v[48:51], v1, s[4:5] offset:2048 nt
	global_load_dwordx4 v[52:55], v1, s[4:5] offset:3072 nt
	global_load_dwordx4 v[8:11], v1, s[40:41]
	global_load_dwordx4 v[12:15], v1, s[40:41] offset:1024
	global_load_dwordx4 v[16:19], v1, s[40:41] offset:2048
	global_load_dwordx4 v[20:23], v1, s[40:41] offset:3072
	global_load_dwordx4 v[24:27], v1, s[42:43]
	global_load_dwordx4 v[28:31], v1, s[42:43] offset:1024
	global_load_dwordx4 v[32:35], v1, s[42:43] offset:2048
	global_load_dwordx4 v[36:39], v1, s[42:43] offset:3072
	v_add_u32_e32 v170, 0x600000, v1
	global_load_dwordx4 v[56:59], v170, s[4:5] nt
	global_load_dwordx4 v[60:63], v170, s[4:5] offset:1024 nt
	global_load_dwordx4 v[64:67], v170, s[4:5] offset:2048 nt
	global_load_dwordx4 v[68:71], v170, s[4:5] offset:3072 nt
	v_add_u32_e32 v170, 0xc00000, v1
	global_load_dwordx4 v[72:75], v170, s[4:5] nt
	global_load_dwordx4 v[76:79], v170, s[4:5] offset:1024 nt
	global_load_dwordx4 v[80:83], v170, s[4:5] offset:2048 nt
	global_load_dwordx4 v[84:87], v170, s[4:5] offset:3072 nt
	v_add_u32_e32 v170, 0x1200000, v1
	global_load_dwordx4 v[88:91], v170, s[4:5] nt
	global_load_dwordx4 v[92:95], v170, s[4:5] offset:1024 nt
	global_load_dwordx4 v[96:99], v170, s[4:5] offset:2048 nt
	global_load_dwordx4 v[100:103], v170, s[4:5] offset:3072 nt
	v_add_u32_e32 v170, 0x1800000, v1
	global_load_dwordx4 v[104:107], v170, s[4:5] nt
	global_load_dwordx4 v[108:111], v170, s[4:5] offset:1024 nt
	global_load_dwordx4 v[112:115], v170, s[4:5] offset:2048 nt
	global_load_dwordx4 v[116:119], v170, s[4:5] offset:3072 nt
	v_add_u32_e32 v170, 0x1e00000, v1
	global_load_dwordx4 v[120:123], v170, s[4:5] nt
	global_load_dwordx4 v[124:127], v170, s[4:5] offset:1024 nt
	global_load_dwordx4 v[128:131], v170, s[4:5] offset:2048 nt
	global_load_dwordx4 v[132:135], v170, s[4:5] offset:3072 nt
	v_add_u32_e32 v170, 0x2400000, v1
	global_load_dwordx4 v[136:139], v170, s[4:5] nt
	global_load_dwordx4 v[140:143], v170, s[4:5] offset:1024 nt
	global_load_dwordx4 v[144:147], v170, s[4:5] offset:2048 nt
	global_load_dwordx4 v[148:151], v170, s[4:5] offset:3072 nt
	v_add_u32_e32 v170, 0x2a00000, v1
	global_load_dwordx4 v[152:155], v170, s[4:5] nt
	global_load_dwordx4 v[156:159], v170, s[4:5] offset:1024 nt
	global_load_dwordx4 v[160:163], v170, s[4:5] offset:2048 nt
	global_load_dwordx4 v[164:167], v170, s[4:5] offset:3072 nt
	s_waitcnt vmcnt(36)
	v_add_f32_e32 v180, v40, v41
	v_add_f32_e32 v181, v44, v45
	v_add_f32_e32 v182, v48, v49
	v_add_f32_e32 v183, v52, v53
	v_add_f32_e32 v180, v180, v42
	v_add_f32_e32 v181, v181, v46
	v_add_f32_e32 v182, v182, v50
	v_add_f32_e32 v183, v183, v54
	v_add_f32_e32 v180, v180, v43
	v_add_f32_e32 v181, v181, v47
	v_add_f32_e32 v182, v182, v51
	v_add_f32_e32 v183, v183, v55
	v_add_f32_e32 v180, v180, v181
	v_add_f32_e32 v182, v182, v183
	v_add_f32_e32 v180, v180, v182
	s_nop 1
	v_add_f32_dpp v180, v180, v180 quad_perm:[1,0,3,2] row_mask:0xf bank_mask:0xf
	s_nop 1
	v_add_f32_dpp v180, v180, v180 quad_perm:[2,3,0,1] row_mask:0xf bank_mask:0xf
	s_nop 1
	v_add_f32_dpp v180, v180, v180 row_half_mirror row_mask:0xf bank_mask:0xf
	s_nop 1
	v_add_f32_dpp v180, v180, v180 row_mirror row_mask:0xf bank_mask:0xf
	s_nop 1
	v_add_f32_dpp v180, v180, v180 row_bcast:15 row_mask:0xa bank_mask:0xf
	s_nop 1
	v_add_f32_dpp v180, v180, v180 row_bcast:31 row_mask:0xc bank_mask:0xf
	s_nop 0
	v_readlane_b32 s20, v180, 63
	s_nop 1
	v_mul_f32_e32 v184, s20, v2
	v_sub_f32_e32 v40, v40, v184
	v_sub_f32_e32 v41, v41, v184
	v_sub_f32_e32 v42, v42, v184
	v_sub_f32_e32 v43, v43, v184
	v_sub_f32_e32 v44, v44, v184
	v_sub_f32_e32 v45, v45, v184
	v_sub_f32_e32 v46, v46, v184
	v_sub_f32_e32 v47, v47, v184
	v_sub_f32_e32 v48, v48, v184
	v_sub_f32_e32 v49, v49, v184
	v_sub_f32_e32 v50, v50, v184
	v_sub_f32_e32 v51, v51, v184
	v_sub_f32_e32 v52, v52, v184
	v_sub_f32_e32 v53, v53, v184
	v_sub_f32_e32 v54, v54, v184
	v_sub_f32_e32 v55, v55, v184
	v_mul_f32_e32 v180, v40, v40
	v_mul_f32_e32 v181, v44, v44
	v_mul_f32_e32 v182, v48, v48
	v_mul_f32_e32 v183, v52, v52
	v_fmac_f32_e32 v180, v41, v41
	v_fmac_f32_e32 v181, v45, v45
	v_fmac_f32_e32 v182, v49, v49
	v_fmac_f32_e32 v183, v53, v53
	v_fmac_f32_e32 v180, v42, v42
	v_fmac_f32_e32 v181, v46, v46
	v_fmac_f32_e32 v182, v50, v50
	v_fmac_f32_e32 v183, v54, v54
	v_fmac_f32_e32 v180, v43, v43
	v_fmac_f32_e32 v181, v47, v47
	v_fmac_f32_e32 v182, v51, v51
	v_fmac_f32_e32 v183, v55, v55
	v_add_f32_e32 v180, v180, v181
	v_add_f32_e32 v182, v182, v183
	v_add_f32_e32 v180, v180, v182
	s_nop 1
	v_add_f32_dpp v180, v180, v180 quad_perm:[1,0,3,2] row_mask:0xf bank_mask:0xf
	s_nop 1
	v_add_f32_dpp v180, v180, v180 quad_perm:[2,3,0,1] row_mask:0xf bank_mask:0xf
	s_nop 1
	v_add_f32_dpp v180, v180, v180 row_half_mirror row_mask:0xf bank_mask:0xf
	s_nop 1
	v_add_f32_dpp v180, v180, v180 row_mirror row_mask:0xf bank_mask:0xf
	s_nop 1
	v_add_f32_dpp v180, v180, v180 row_bcast:15 row_mask:0xa bank_mask:0xf
	s_nop 1
	v_add_f32_dpp v180, v180, v180 row_bcast:31 row_mask:0xc bank_mask:0xf
	s_nop 0
	v_readlane_b32 s20, v180, 63
	s_nop 1
	v_mov_b32_e32 v185, s20
	v_fma_f32 v185, v185, v2, v4
	v_rsq_f32_e32 v185, v185
	s_nop 0
	v_mul_f32_e32 v40, v40, v185
	v_mul_f32_e32 v41, v41, v185
	v_mul_f32_e32 v42, v42, v185
	v_mul_f32_e32 v43, v43, v185
	v_mul_f32_e32 v44, v44, v185
	v_mul_f32_e32 v45, v45, v185
	v_mul_f32_e32 v46, v46, v185
	v_mul_f32_e32 v47, v47, v185
	v_mul_f32_e32 v48, v48, v185
	v_mul_f32_e32 v49, v49, v185
	v_mul_f32_e32 v50, v50, v185
	v_mul_f32_e32 v51, v51, v185
	v_mul_f32_e32 v52, v52, v185
	v_mul_f32_e32 v53, v53, v185
	v_mul_f32_e32 v54, v54, v185
	v_mul_f32_e32 v55, v55, v185
	s_waitcnt vmcnt(28)
	v_fma_f32 v40, v40, v8, v24
	v_fma_f32 v41, v41, v9, v25
	v_fma_f32 v42, v42, v10, v26
	v_fma_f32 v43, v43, v11, v27
	v_fma_f32 v44, v44, v12, v28
	v_fma_f32 v45, v45, v13, v29
	v_fma_f32 v46, v46, v14, v30
	v_fma_f32 v47, v47, v15, v31
	v_fma_f32 v48, v48, v16, v32
	v_fma_f32 v49, v49, v17, v33
	v_fma_f32 v50, v50, v18, v34
	v_fma_f32 v51, v51, v19, v35
	v_fma_f32 v52, v52, v20, v36
	v_fma_f32 v53, v53, v21, v37
	v_fma_f32 v54, v54, v22, v38
	v_fma_f32 v55, v55, v23, v39
	v_cvt_pk_bf16_f32 v40, v40, v41
	v_cvt_pk_bf16_f32 v41, v42, v43
	v_cvt_pk_bf16_f32 v44, v44, v45
	v_cvt_pk_bf16_f32 v45, v46, v47
	v_cvt_pk_bf16_f32 v48, v48, v49
	v_cvt_pk_bf16_f32 v49, v50, v51
	v_cvt_pk_bf16_f32 v52, v52, v53
	v_cvt_pk_bf16_f32 v53, v54, v55
	global_store_dwordx2 v5, v[40:41], s[8:9]
	global_store_dwordx2 v5, v[44:45], s[8:9] offset:512
	global_store_dwordx2 v5, v[48:49], s[8:9] offset:1024
	global_store_dwordx2 v5, v[52:53], s[8:9] offset:1536
	v_mov_b32_e32 v172, 0x0
	s_mov_b64 exec, 1
	global_store_dwordx2 v172, v[184:185], s[38:39]
	s_mov_b64 exec, -1
	s_nop 1
	v_add_u32_e32 v170, 0x3000000, v1
	global_load_dwordx4 v[40:43], v170, s[4:5] nt
	global_load_dwordx4 v[44:47], v170, s[4:5] offset:1024 nt
	global_load_dwordx4 v[48:51], v170, s[4:5] offset:2048 nt
	global_load_dwordx4 v[52:55], v170, s[4:5] offset:3072 nt
	s_waitcnt vmcnt(33)
	v_add_f32_e32 v180, v56, v57
	v_add_f32_e32 v181, v60, v61
	v_add_f32_e32 v182, v64, v65
	v_add_f32_e32 v183, v68, v69
	v_add_f32_e32 v180, v180, v58
	v_add_f32_e32 v181, v181, v62
	v_add_f32_e32 v182, v182, v66
	v_add_f32_e32 v183, v183, v70
	v_add_f32_e32 v180, v180, v59
	v_add_f32_e32 v181, v181, v63
	v_add_f32_e32 v182, v182, v67
	v_add_f32_e32 v183, v183, v71
	v_add_f32_e32 v180, v180, v181
	v_add_f32_e32 v182, v182, v183
	v_add_f32_e32 v180, v180, v182
	s_nop 1
	v_add_f32_dpp v180, v180, v180 quad_perm:[1,0,3,2] row_mask:0xf bank_mask:0xf
	s_nop 1
	v_add_f32_dpp v180, v180, v180 quad_perm:[2,3,0,1] row_mask:0xf bank_mask:0xf
	s_nop 1
	v_add_f32_dpp v180, v180, v180 row_half_mirror row_mask:0xf bank_mask:0xf
	s_nop 1
	v_add_f32_dpp v180, v180, v180 row_mirror row_mask:0xf bank_mask:0xf
	s_nop 1
	v_add_f32_dpp v180, v180, v180 row_bcast:15 row_mask:0xa bank_mask:0xf
	s_nop 1
	v_add_f32_dpp v180, v180, v180 row_bcast:31 row_mask:0xc bank_mask:0xf
	s_nop 0
	v_readlane_b32 s20, v180, 63
	s_nop 1
	v_mul_f32_e32 v184, s20, v2
	v_sub_f32_e32 v56, v56, v184
	v_sub_f32_e32 v57, v57, v184
	v_sub_f32_e32 v58, v58, v184
	v_sub_f32_e32 v59, v59, v184
	v_sub_f32_e32 v60, v60, v184
	v_sub_f32_e32 v61, v61, v184
	v_sub_f32_e32 v62, v62, v184
	v_sub_f32_e32 v63, v63, v184
	v_sub_f32_e32 v64, v64, v184
	v_sub_f32_e32 v65, v65, v184
	v_sub_f32_e32 v66, v66, v184
	v_sub_f32_e32 v67, v67, v184
	v_sub_f32_e32 v68, v68, v184
	v_sub_f32_e32 v69, v69, v184
	v_sub_f32_e32 v70, v70, v184
	v_sub_f32_e32 v71, v71, v184
	v_mul_f32_e32 v180, v56, v56
	v_mul_f32_e32 v181, v60, v60
	v_mul_f32_e32 v182, v64, v64
	v_mul_f32_e32 v183, v68, v68
	v_fmac_f32_e32 v180, v57, v57
	v_fmac_f32_e32 v181, v61, v61
	v_fmac_f32_e32 v182, v65, v65
	v_fmac_f32_e32 v183, v69, v69
	v_fmac_f32_e32 v180, v58, v58
	v_fmac_f32_e32 v181, v62, v62
	v_fmac_f32_e32 v182, v66, v66
	v_fmac_f32_e32 v183, v70, v70
	v_fmac_f32_e32 v180, v59, v59
	v_fmac_f32_e32 v181, v63, v63
	v_fmac_f32_e32 v182, v67, v67
	v_fmac_f32_e32 v183, v71, v71
	v_add_f32_e32 v180, v180, v181
	v_add_f32_e32 v182, v182, v183
	v_add_f32_e32 v180, v180, v182
	s_nop 1
	v_add_f32_dpp v180, v180, v180 quad_perm:[1,0,3,2] row_mask:0xf bank_mask:0xf
	s_nop 1
	v_add_f32_dpp v180, v180, v180 quad_perm:[2,3,0,1] row_mask:0xf bank_mask:0xf
	s_nop 1
	v_add_f32_dpp v180, v180, v180 row_half_mirror row_mask:0xf bank_mask:0xf
	s_nop 1
	v_add_f32_dpp v180, v180, v180 row_mirror row_mask:0xf bank_mask:0xf
	s_nop 1
	v_add_f32_dpp v180, v180, v180 row_bcast:15 row_mask:0xa bank_mask:0xf
	s_nop 1
	v_add_f32_dpp v180, v180, v180 row_bcast:31 row_mask:0xc bank_mask:0xf
	s_nop 0
	v_readlane_b32 s20, v180, 63
	s_nop 1
	v_mov_b32_e32 v185, s20
	v_fma_f32 v185, v185, v2, v4
	v_rsq_f32_e32 v185, v185
	s_nop 0
	v_mul_f32_e32 v56, v56, v185
	v_mul_f32_e32 v57, v57, v185
	v_mul_f32_e32 v58, v58, v185
	v_mul_f32_e32 v59, v59, v185
	v_mul_f32_e32 v60, v60, v185
	v_mul_f32_e32 v61, v61, v185
	v_mul_f32_e32 v62, v62, v185
	v_mul_f32_e32 v63, v63, v185
	v_mul_f32_e32 v64, v64, v185
	v_mul_f32_e32 v65, v65, v185
	v_mul_f32_e32 v66, v66, v185
	v_mul_f32_e32 v67, v67, v185
	v_mul_f32_e32 v68, v68, v185
	v_mul_f32_e32 v69, v69, v185
	v_mul_f32_e32 v70, v70, v185
	v_mul_f32_e32 v71, v71, v185
	v_fma_f32 v56, v56, v8, v24
	v_fma_f32 v57, v57, v9, v25
	v_fma_f32 v58, v58, v10, v26
	v_fma_f32 v59, v59, v11, v27
	v_fma_f32 v60, v60, v12, v28
	v_fma_f32 v61, v61, v13, v29
	v_fma_f32 v62, v62, v14, v30
	v_fma_f32 v63, v63, v15, v31
	v_fma_f32 v64, v64, v16, v32
	v_fma_f32 v65, v65, v17, v33
	v_fma_f32 v66, v66, v18, v34
	v_fma_f32 v67, v67, v19, v35
	v_fma_f32 v68, v68, v20, v36
	v_fma_f32 v69, v69, v21, v37
	v_fma_f32 v70, v70, v22, v38
	v_fma_f32 v71, v71, v23, v39
	v_cvt_pk_bf16_f32 v56, v56, v57
	v_cvt_pk_bf16_f32 v57, v58, v59
	v_cvt_pk_bf16_f32 v60, v60, v61
	v_cvt_pk_bf16_f32 v61, v62, v63
	v_cvt_pk_bf16_f32 v64, v64, v65
	v_cvt_pk_bf16_f32 v65, v66, v67
	v_cvt_pk_bf16_f32 v68, v68, v69
	v_cvt_pk_bf16_f32 v69, v70, v71
	v_add_u32_e32 v171, 0x300000, v5
	global_store_dwordx2 v171, v[56:57], s[8:9]
	global_store_dwordx2 v171, v[60:61], s[8:9] offset:512
	global_store_dwordx2 v171, v[64:65], s[8:9] offset:1024
	global_store_dwordx2 v171, v[68:69], s[8:9] offset:1536
	v_mov_b32_e32 v172, 0x3000
	s_mov_b64 exec, 1
	global_store_dwordx2 v172, v[184:185], s[38:39]
	s_mov_b64 exec, -1
	s_nop 1
	v_add_u32_e32 v170, 0x3600000, v1
	global_load_dwordx4 v[56:59], v170, s[4:5] nt
	global_load_dwordx4 v[60:63], v170, s[4:5] offset:1024 nt
	global_load_dwordx4 v[64:67], v170, s[4:5] offset:2048 nt
	global_load_dwordx4 v[68:71], v170, s[4:5] offset:3072 nt
	s_waitcnt vmcnt(38)
	v_add_f32_e32 v180, v72, v73
	v_add_f32_e32 v181, v76, v77
	v_add_f32_e32 v182, v80, v81
	v_add_f32_e32 v183, v84, v85
	v_add_f32_e32 v180, v180, v74
	v_add_f32_e32 v181, v181, v78
	v_add_f32_e32 v182, v182, v82
	v_add_f32_e32 v183, v183, v86
	v_add_f32_e32 v180, v180, v75
	v_add_f32_e32 v181, v181, v79
	v_add_f32_e32 v182, v182, v83
	v_add_f32_e32 v183, v183, v87
	v_add_f32_e32 v180, v180, v181
	v_add_f32_e32 v182, v182, v183
	v_add_f32_e32 v180, v180, v182
	s_nop 1
	v_add_f32_dpp v180, v180, v180 quad_perm:[1,0,3,2] row_mask:0xf bank_mask:0xf
	s_nop 1
	v_add_f32_dpp v180, v180, v180 quad_perm:[2,3,0,1] row_mask:0xf bank_mask:0xf
	s_nop 1
	v_add_f32_dpp v180, v180, v180 row_half_mirror row_mask:0xf bank_mask:0xf
	s_nop 1
	v_add_f32_dpp v180, v180, v180 row_mirror row_mask:0xf bank_mask:0xf
	s_nop 1
	v_add_f32_dpp v180, v180, v180 row_bcast:15 row_mask:0xa bank_mask:0xf
	s_nop 1
	v_add_f32_dpp v180, v180, v180 row_bcast:31 row_mask:0xc bank_mask:0xf
	s_nop 0
	v_readlane_b32 s20, v180, 63
	s_nop 1
	v_mul_f32_e32 v184, s20, v2
	v_sub_f32_e32 v72, v72, v184
	v_sub_f32_e32 v73, v73, v184
	v_sub_f32_e32 v74, v74, v184
	v_sub_f32_e32 v75, v75, v184
	v_sub_f32_e32 v76, v76, v184
	v_sub_f32_e32 v77, v77, v184
	v_sub_f32_e32 v78, v78, v184
	v_sub_f32_e32 v79, v79, v184
	v_sub_f32_e32 v80, v80, v184
	v_sub_f32_e32 v81, v81, v184
	v_sub_f32_e32 v82, v82, v184
	v_sub_f32_e32 v83, v83, v184
	v_sub_f32_e32 v84, v84, v184
	v_sub_f32_e32 v85, v85, v184
	v_sub_f32_e32 v86, v86, v184
	v_sub_f32_e32 v87, v87, v184
	v_mul_f32_e32 v180, v72, v72
	v_mul_f32_e32 v181, v76, v76
	v_mul_f32_e32 v182, v80, v80
	v_mul_f32_e32 v183, v84, v84
	v_fmac_f32_e32 v180, v73, v73
	v_fmac_f32_e32 v181, v77, v77
	v_fmac_f32_e32 v182, v81, v81
	v_fmac_f32_e32 v183, v85, v85
	v_fmac_f32_e32 v180, v74, v74
	v_fmac_f32_e32 v181, v78, v78
	v_fmac_f32_e32 v182, v82, v82
	v_fmac_f32_e32 v183, v86, v86
	v_fmac_f32_e32 v180, v75, v75
	v_fmac_f32_e32 v181, v79, v79
	v_fmac_f32_e32 v182, v83, v83
	v_fmac_f32_e32 v183, v87, v87
	v_add_f32_e32 v180, v180, v181
	v_add_f32_e32 v182, v182, v183
	v_add_f32_e32 v180, v180, v182
	s_nop 1
	v_add_f32_dpp v180, v180, v180 quad_perm:[1,0,3,2] row_mask:0xf bank_mask:0xf
	s_nop 1
	v_add_f32_dpp v180, v180, v180 quad_perm:[2,3,0,1] row_mask:0xf bank_mask:0xf
	s_nop 1
	v_add_f32_dpp v180, v180, v180 row_half_mirror row_mask:0xf bank_mask:0xf
	s_nop 1
	v_add_f32_dpp v180, v180, v180 row_mirror row_mask:0xf bank_mask:0xf
	s_nop 1
	v_add_f32_dpp v180, v180, v180 row_bcast:15 row_mask:0xa bank_mask:0xf
	s_nop 1
	v_add_f32_dpp v180, v180, v180 row_bcast:31 row_mask:0xc bank_mask:0xf
	s_nop 0
	v_readlane_b32 s20, v180, 63
	s_nop 1
	v_mov_b32_e32 v185, s20
	v_fma_f32 v185, v185, v2, v4
	v_rsq_f32_e32 v185, v185
	s_nop 0
	v_mul_f32_e32 v72, v72, v185
	v_mul_f32_e32 v73, v73, v185
	v_mul_f32_e32 v74, v74, v185
	v_mul_f32_e32 v75, v75, v185
	v_mul_f32_e32 v76, v76, v185
	v_mul_f32_e32 v77, v77, v185
	v_mul_f32_e32 v78, v78, v185
	v_mul_f32_e32 v79, v79, v185
	v_mul_f32_e32 v80, v80, v185
	v_mul_f32_e32 v81, v81, v185
	v_mul_f32_e32 v82, v82, v185
	v_mul_f32_e32 v83, v83, v185
	v_mul_f32_e32 v84, v84, v185
	v_mul_f32_e32 v85, v85, v185
	v_mul_f32_e32 v86, v86, v185
	v_mul_f32_e32 v87, v87, v185
	v_fma_f32 v72, v72, v8, v24
	v_fma_f32 v73, v73, v9, v25
	v_fma_f32 v74, v74, v10, v26
	v_fma_f32 v75, v75, v11, v27
	v_fma_f32 v76, v76, v12, v28
	v_fma_f32 v77, v77, v13, v29
	v_fma_f32 v78, v78, v14, v30
	v_fma_f32 v79, v79, v15, v31
	v_fma_f32 v80, v80, v16, v32
	v_fma_f32 v81, v81, v17, v33
	v_fma_f32 v82, v82, v18, v34
	v_fma_f32 v83, v83, v19, v35
	v_fma_f32 v84, v84, v20, v36
	v_fma_f32 v85, v85, v21, v37
	v_fma_f32 v86, v86, v22, v38
	v_fma_f32 v87, v87, v23, v39
	v_cvt_pk_bf16_f32 v72, v72, v73
	v_cvt_pk_bf16_f32 v73, v74, v75
	v_cvt_pk_bf16_f32 v76, v76, v77
	v_cvt_pk_bf16_f32 v77, v78, v79
	v_cvt_pk_bf16_f32 v80, v80, v81
	v_cvt_pk_bf16_f32 v81, v82, v83
	v_cvt_pk_bf16_f32 v84, v84, v85
	v_cvt_pk_bf16_f32 v85, v86, v87
	v_add_u32_e32 v171, 0x600000, v5
	global_store_dwordx2 v171, v[72:73], s[8:9]
	global_store_dwordx2 v171, v[76:77], s[8:9] offset:512
	global_store_dwordx2 v171, v[80:81], s[8:9] offset:1024
	global_store_dwordx2 v171, v[84:85], s[8:9] offset:1536
	v_mov_b32_e32 v172, 0x6000
	s_mov_b64 exec, 1
	global_store_dwordx2 v172, v[184:185], s[38:39]
	s_mov_b64 exec, -1
	s_nop 1
	v_add_u32_e32 v170, 0x3c00000, v1
	global_load_dwordx4 v[72:75], v170, s[4:5] nt
	global_load_dwordx4 v[76:79], v170, s[4:5] offset:1024 nt
	global_load_dwordx4 v[80:83], v170, s[4:5] offset:2048 nt
	global_load_dwordx4 v[84:87], v170, s[4:5] offset:3072 nt
	s_waitcnt vmcnt(43)
	v_add_f32_e32 v180, v88, v89
	v_add_f32_e32 v181, v92, v93
	v_add_f32_e32 v182, v96, v97
	v_add_f32_e32 v183, v100, v101
	v_add_f32_e32 v180, v180, v90
	v_add_f32_e32 v181, v181, v94
	v_add_f32_e32 v182, v182, v98
	v_add_f32_e32 v183, v183, v102
	v_add_f32_e32 v180, v180, v91
	v_add_f32_e32 v181, v181, v95
	v_add_f32_e32 v182, v182, v99
	v_add_f32_e32 v183, v183, v103
	v_add_f32_e32 v180, v180, v181
	v_add_f32_e32 v182, v182, v183
	v_add_f32_e32 v180, v180, v182
	s_nop 1
	v_add_f32_dpp v180, v180, v180 quad_perm:[1,0,3,2] row_mask:0xf bank_mask:0xf
	s_nop 1
	v_add_f32_dpp v180, v180, v180 quad_perm:[2,3,0,1] row_mask:0xf bank_mask:0xf
	s_nop 1
	v_add_f32_dpp v180, v180, v180 row_half_mirror row_mask:0xf bank_mask:0xf
	s_nop 1
	v_add_f32_dpp v180, v180, v180 row_mirror row_mask:0xf bank_mask:0xf
	s_nop 1
	v_add_f32_dpp v180, v180, v180 row_bcast:15 row_mask:0xa bank_mask:0xf
	s_nop 1
	v_add_f32_dpp v180, v180, v180 row_bcast:31 row_mask:0xc bank_mask:0xf
	s_nop 0
	v_readlane_b32 s20, v180, 63
	s_nop 1
	v_mul_f32_e32 v184, s20, v2
	v_sub_f32_e32 v88, v88, v184
	v_sub_f32_e32 v89, v89, v184
	v_sub_f32_e32 v90, v90, v184
	v_sub_f32_e32 v91, v91, v184
	v_sub_f32_e32 v92, v92, v184
	v_sub_f32_e32 v93, v93, v184
	v_sub_f32_e32 v94, v94, v184
	v_sub_f32_e32 v95, v95, v184
	v_sub_f32_e32 v96, v96, v184
	v_sub_f32_e32 v97, v97, v184
	v_sub_f32_e32 v98, v98, v184
	v_sub_f32_e32 v99, v99, v184
	v_sub_f32_e32 v100, v100, v184
	v_sub_f32_e32 v101, v101, v184
	v_sub_f32_e32 v102, v102, v184
	v_sub_f32_e32 v103, v103, v184
	v_mul_f32_e32 v180, v88, v88
	v_mul_f32_e32 v181, v92, v92
	v_mul_f32_e32 v182, v96, v96
	v_mul_f32_e32 v183, v100, v100
	v_fmac_f32_e32 v180, v89, v89
	v_fmac_f32_e32 v181, v93, v93
	v_fmac_f32_e32 v182, v97, v97
	v_fmac_f32_e32 v183, v101, v101
	v_fmac_f32_e32 v180, v90, v90
	v_fmac_f32_e32 v181, v94, v94
	v_fmac_f32_e32 v182, v98, v98
	v_fmac_f32_e32 v183, v102, v102
	v_fmac_f32_e32 v180, v91, v91
	v_fmac_f32_e32 v181, v95, v95
	v_fmac_f32_e32 v182, v99, v99
	v_fmac_f32_e32 v183, v103, v103
	v_add_f32_e32 v180, v180, v181
	v_add_f32_e32 v182, v182, v183
	v_add_f32_e32 v180, v180, v182
	s_nop 1
	v_add_f32_dpp v180, v180, v180 quad_perm:[1,0,3,2] row_mask:0xf bank_mask:0xf
	s_nop 1
	v_add_f32_dpp v180, v180, v180 quad_perm:[2,3,0,1] row_mask:0xf bank_mask:0xf
	s_nop 1
	v_add_f32_dpp v180, v180, v180 row_half_mirror row_mask:0xf bank_mask:0xf
	s_nop 1
	v_add_f32_dpp v180, v180, v180 row_mirror row_mask:0xf bank_mask:0xf
	s_nop 1
	v_add_f32_dpp v180, v180, v180 row_bcast:15 row_mask:0xa bank_mask:0xf
	s_nop 1
	v_add_f32_dpp v180, v180, v180 row_bcast:31 row_mask:0xc bank_mask:0xf
	s_nop 0
	v_readlane_b32 s20, v180, 63
	s_nop 1
	v_mov_b32_e32 v185, s20
	v_fma_f32 v185, v185, v2, v4
	v_rsq_f32_e32 v185, v185
	s_nop 0
	v_mul_f32_e32 v88, v88, v185
	v_mul_f32_e32 v89, v89, v185
	v_mul_f32_e32 v90, v90, v185
	v_mul_f32_e32 v91, v91, v185
	v_mul_f32_e32 v92, v92, v185
	v_mul_f32_e32 v93, v93, v185
	v_mul_f32_e32 v94, v94, v185
	v_mul_f32_e32 v95, v95, v185
	v_mul_f32_e32 v96, v96, v185
	v_mul_f32_e32 v97, v97, v185
	v_mul_f32_e32 v98, v98, v185
	v_mul_f32_e32 v99, v99, v185
	v_mul_f32_e32 v100, v100, v185
	v_mul_f32_e32 v101, v101, v185
	v_mul_f32_e32 v102, v102, v185
	v_mul_f32_e32 v103, v103, v185
	v_fma_f32 v88, v88, v8, v24
	v_fma_f32 v89, v89, v9, v25
	v_fma_f32 v90, v90, v10, v26
	v_fma_f32 v91, v91, v11, v27
	v_fma_f32 v92, v92, v12, v28
	v_fma_f32 v93, v93, v13, v29
	v_fma_f32 v94, v94, v14, v30
	v_fma_f32 v95, v95, v15, v31
	v_fma_f32 v96, v96, v16, v32
	v_fma_f32 v97, v97, v17, v33
	v_fma_f32 v98, v98, v18, v34
	v_fma_f32 v99, v99, v19, v35
	v_fma_f32 v100, v100, v20, v36
	v_fma_f32 v101, v101, v21, v37
	v_fma_f32 v102, v102, v22, v38
	v_fma_f32 v103, v103, v23, v39
	v_cvt_pk_bf16_f32 v88, v88, v89
	v_cvt_pk_bf16_f32 v89, v90, v91
	v_cvt_pk_bf16_f32 v92, v92, v93
	v_cvt_pk_bf16_f32 v93, v94, v95
	v_cvt_pk_bf16_f32 v96, v96, v97
	v_cvt_pk_bf16_f32 v97, v98, v99
	v_cvt_pk_bf16_f32 v100, v100, v101
	v_cvt_pk_bf16_f32 v101, v102, v103
	v_add_u32_e32 v171, 0x900000, v5
	global_store_dwordx2 v171, v[88:89], s[8:9]
	global_store_dwordx2 v171, v[92:93], s[8:9] offset:512
	global_store_dwordx2 v171, v[96:97], s[8:9] offset:1024
	global_store_dwordx2 v171, v[100:101], s[8:9] offset:1536
	v_mov_b32_e32 v172, 0x9000
	s_mov_b64 exec, 1
	global_store_dwordx2 v172, v[184:185], s[38:39]
	s_mov_b64 exec, -1
	s_waitcnt vmcnt(44)
	v_add_f32_e32 v180, v104, v105
	v_add_f32_e32 v181, v108, v109
	v_add_f32_e32 v182, v112, v113
	v_add_f32_e32 v183, v116, v117
	v_add_f32_e32 v180, v180, v106
	v_add_f32_e32 v181, v181, v110
	v_add_f32_e32 v182, v182, v114
	v_add_f32_e32 v183, v183, v118
	v_add_f32_e32 v180, v180, v107
	v_add_f32_e32 v181, v181, v111
	v_add_f32_e32 v182, v182, v115
	v_add_f32_e32 v183, v183, v119
	v_add_f32_e32 v180, v180, v181
	v_add_f32_e32 v182, v182, v183
	v_add_f32_e32 v180, v180, v182
	s_nop 1
	v_add_f32_dpp v180, v180, v180 quad_perm:[1,0,3,2] row_mask:0xf bank_mask:0xf
	s_nop 1
	v_add_f32_dpp v180, v180, v180 quad_perm:[2,3,0,1] row_mask:0xf bank_mask:0xf
	s_nop 1
	v_add_f32_dpp v180, v180, v180 row_half_mirror row_mask:0xf bank_mask:0xf
	s_nop 1
	v_add_f32_dpp v180, v180, v180 row_mirror row_mask:0xf bank_mask:0xf
	s_nop 1
	v_add_f32_dpp v180, v180, v180 row_bcast:15 row_mask:0xa bank_mask:0xf
	s_nop 1
	v_add_f32_dpp v180, v180, v180 row_bcast:31 row_mask:0xc bank_mask:0xf
	s_nop 0
	v_readlane_b32 s20, v180, 63
	s_nop 1
	v_mul_f32_e32 v184, s20, v2
	v_sub_f32_e32 v104, v104, v184
	v_sub_f32_e32 v105, v105, v184
	v_sub_f32_e32 v106, v106, v184
	v_sub_f32_e32 v107, v107, v184
	v_sub_f32_e32 v108, v108, v184
	v_sub_f32_e32 v109, v109, v184
	v_sub_f32_e32 v110, v110, v184
	v_sub_f32_e32 v111, v111, v184
	v_sub_f32_e32 v112, v112, v184
	v_sub_f32_e32 v113, v113, v184
	v_sub_f32_e32 v114, v114, v184
	v_sub_f32_e32 v115, v115, v184
	v_sub_f32_e32 v116, v116, v184
	v_sub_f32_e32 v117, v117, v184
	v_sub_f32_e32 v118, v118, v184
	v_sub_f32_e32 v119, v119, v184
	v_mul_f32_e32 v180, v104, v104
	v_mul_f32_e32 v181, v108, v108
	v_mul_f32_e32 v182, v112, v112
	v_mul_f32_e32 v183, v116, v116
	v_fmac_f32_e32 v180, v105, v105
	v_fmac_f32_e32 v181, v109, v109
	v_fmac_f32_e32 v182, v113, v113
	v_fmac_f32_e32 v183, v117, v117
	v_fmac_f32_e32 v180, v106, v106
	v_fmac_f32_e32 v181, v110, v110
	v_fmac_f32_e32 v182, v114, v114
	v_fmac_f32_e32 v183, v118, v118
	v_fmac_f32_e32 v180, v107, v107
	v_fmac_f32_e32 v181, v111, v111
	v_fmac_f32_e32 v182, v115, v115
	v_fmac_f32_e32 v183, v119, v119
	v_add_f32_e32 v180, v180, v181
	v_add_f32_e32 v182, v182, v183
	v_add_f32_e32 v180, v180, v182
	s_nop 1
	v_add_f32_dpp v180, v180, v180 quad_perm:[1,0,3,2] row_mask:0xf bank_mask:0xf
	s_nop 1
	v_add_f32_dpp v180, v180, v180 quad_perm:[2,3,0,1] row_mask:0xf bank_mask:0xf
	s_nop 1
	v_add_f32_dpp v180, v180, v180 row_half_mirror row_mask:0xf bank_mask:0xf
	s_nop 1
	v_add_f32_dpp v180, v180, v180 row_mirror row_mask:0xf bank_mask:0xf
	s_nop 1
	v_add_f32_dpp v180, v180, v180 row_bcast:15 row_mask:0xa bank_mask:0xf
	s_nop 1
	v_add_f32_dpp v180, v180, v180 row_bcast:31 row_mask:0xc bank_mask:0xf
	s_nop 0
	v_readlane_b32 s20, v180, 63
	s_nop 1
	v_mov_b32_e32 v185, s20
	v_fma_f32 v185, v185, v2, v4
	v_rsq_f32_e32 v185, v185
	s_nop 0
	v_mul_f32_e32 v104, v104, v185
	v_mul_f32_e32 v105, v105, v185
	v_mul_f32_e32 v106, v106, v185
	v_mul_f32_e32 v107, v107, v185
	v_mul_f32_e32 v108, v108, v185
	v_mul_f32_e32 v109, v109, v185
	v_mul_f32_e32 v110, v110, v185
	v_mul_f32_e32 v111, v111, v185
	v_mul_f32_e32 v112, v112, v185
	v_mul_f32_e32 v113, v113, v185
	v_mul_f32_e32 v114, v114, v185
	v_mul_f32_e32 v115, v115, v185
	v_mul_f32_e32 v116, v116, v185
	v_mul_f32_e32 v117, v117, v185
	v_mul_f32_e32 v118, v118, v185
	v_mul_f32_e32 v119, v119, v185
	v_fma_f32 v104, v104, v8, v24
	v_fma_f32 v105, v105, v9, v25
	v_fma_f32 v106, v106, v10, v26
	v_fma_f32 v107, v107, v11, v27
	v_fma_f32 v108, v108, v12, v28
	v_fma_f32 v109, v109, v13, v29
	v_fma_f32 v110, v110, v14, v30
	v_fma_f32 v111, v111, v15, v31
	v_fma_f32 v112, v112, v16, v32
	v_fma_f32 v113, v113, v17, v33
	v_fma_f32 v114, v114, v18, v34
	v_fma_f32 v115, v115, v19, v35
	v_fma_f32 v116, v116, v20, v36
	v_fma_f32 v117, v117, v21, v37
	v_fma_f32 v118, v118, v22, v38
	v_fma_f32 v119, v119, v23, v39
	v_cvt_pk_bf16_f32 v104, v104, v105
	v_cvt_pk_bf16_f32 v105, v106, v107
	v_cvt_pk_bf16_f32 v108, v108, v109
	v_cvt_pk_bf16_f32 v109, v110, v111
	v_cvt_pk_bf16_f32 v112, v112, v113
	v_cvt_pk_bf16_f32 v113, v114, v115
	v_cvt_pk_bf16_f32 v116, v116, v117
	v_cvt_pk_bf16_f32 v117, v118, v119
	v_add_u32_e32 v171, 0xc00000, v5
	global_store_dwordx2 v171, v[104:105], s[8:9]
	global_store_dwordx2 v171, v[108:109], s[8:9] offset:512
	global_store_dwordx2 v171, v[112:113], s[8:9] offset:1024
	global_store_dwordx2 v171, v[116:117], s[8:9] offset:1536
	v_mov_b32_e32 v172, 0xc000
	s_mov_b64 exec, 1
	global_store_dwordx2 v172, v[184:185], s[38:39]
	s_mov_b64 exec, -1
	s_waitcnt vmcnt(45)
	v_add_f32_e32 v180, v120, v121
	v_add_f32_e32 v181, v124, v125
	v_add_f32_e32 v182, v128, v129
	v_add_f32_e32 v183, v132, v133
	v_add_f32_e32 v180, v180, v122
	v_add_f32_e32 v181, v181, v126
	v_add_f32_e32 v182, v182, v130
	v_add_f32_e32 v183, v183, v134
	v_add_f32_e32 v180, v180, v123
	v_add_f32_e32 v181, v181, v127
	v_add_f32_e32 v182, v182, v131
	v_add_f32_e32 v183, v183, v135
	v_add_f32_e32 v180, v180, v181
	v_add_f32_e32 v182, v182, v183
	v_add_f32_e32 v180, v180, v182
	s_nop 1
	v_add_f32_dpp v180, v180, v180 quad_perm:[1,0,3,2] row_mask:0xf bank_mask:0xf
	s_nop 1
	v_add_f32_dpp v180, v180, v180 quad_perm:[2,3,0,1] row_mask:0xf bank_mask:0xf
	s_nop 1
	v_add_f32_dpp v180, v180, v180 row_half_mirror row_mask:0xf bank_mask:0xf
	s_nop 1
	v_add_f32_dpp v180, v180, v180 row_mirror row_mask:0xf bank_mask:0xf
	s_nop 1
	v_add_f32_dpp v180, v180, v180 row_bcast:15 row_mask:0xa bank_mask:0xf
	s_nop 1
	v_add_f32_dpp v180, v180, v180 row_bcast:31 row_mask:0xc bank_mask:0xf
	s_nop 0
	v_readlane_b32 s20, v180, 63
	s_nop 1
	v_mul_f32_e32 v184, s20, v2
	v_sub_f32_e32 v120, v120, v184
	v_sub_f32_e32 v121, v121, v184
	v_sub_f32_e32 v122, v122, v184
	v_sub_f32_e32 v123, v123, v184
	v_sub_f32_e32 v124, v124, v184
	v_sub_f32_e32 v125, v125, v184
	v_sub_f32_e32 v126, v126, v184
	v_sub_f32_e32 v127, v127, v184
	v_sub_f32_e32 v128, v128, v184
	v_sub_f32_e32 v129, v129, v184
	v_sub_f32_e32 v130, v130, v184
	v_sub_f32_e32 v131, v131, v184
	v_sub_f32_e32 v132, v132, v184
	v_sub_f32_e32 v133, v133, v184
	v_sub_f32_e32 v134, v134, v184
	v_sub_f32_e32 v135, v135, v184
	v_mul_f32_e32 v180, v120, v120
	v_mul_f32_e32 v181, v124, v124
	v_mul_f32_e32 v182, v128, v128
	v_mul_f32_e32 v183, v132, v132
	v_fmac_f32_e32 v180, v121, v121
	v_fmac_f32_e32 v181, v125, v125
	v_fmac_f32_e32 v182, v129, v129
	v_fmac_f32_e32 v183, v133, v133
	v_fmac_f32_e32 v180, v122, v122
	v_fmac_f32_e32 v181, v126, v126
	v_fmac_f32_e32 v182, v130, v130
	v_fmac_f32_e32 v183, v134, v134
	v_fmac_f32_e32 v180, v123, v123
	v_fmac_f32_e32 v181, v127, v127
	v_fmac_f32_e32 v182, v131, v131
	v_fmac_f32_e32 v183, v135, v135
	v_add_f32_e32 v180, v180, v181
	v_add_f32_e32 v182, v182, v183
	v_add_f32_e32 v180, v180, v182
	s_nop 1
	v_add_f32_dpp v180, v180, v180 quad_perm:[1,0,3,2] row_mask:0xf bank_mask:0xf
	s_nop 1
	v_add_f32_dpp v180, v180, v180 quad_perm:[2,3,0,1] row_mask:0xf bank_mask:0xf
	s_nop 1
	v_add_f32_dpp v180, v180, v180 row_half_mirror row_mask:0xf bank_mask:0xf
	s_nop 1
	v_add_f32_dpp v180, v180, v180 row_mirror row_mask:0xf bank_mask:0xf
	s_nop 1
	v_add_f32_dpp v180, v180, v180 row_bcast:15 row_mask:0xa bank_mask:0xf
	s_nop 1
	v_add_f32_dpp v180, v180, v180 row_bcast:31 row_mask:0xc bank_mask:0xf
	s_nop 0
	v_readlane_b32 s20, v180, 63
	s_nop 1
	v_mov_b32_e32 v185, s20
	v_fma_f32 v185, v185, v2, v4
	v_rsq_f32_e32 v185, v185
	s_nop 0
	v_mul_f32_e32 v120, v120, v185
	v_mul_f32_e32 v121, v121, v185
	v_mul_f32_e32 v122, v122, v185
	v_mul_f32_e32 v123, v123, v185
	v_mul_f32_e32 v124, v124, v185
	v_mul_f32_e32 v125, v125, v185
	v_mul_f32_e32 v126, v126, v185
	v_mul_f32_e32 v127, v127, v185
	v_mul_f32_e32 v128, v128, v185
	v_mul_f32_e32 v129, v129, v185
	v_mul_f32_e32 v130, v130, v185
	v_mul_f32_e32 v131, v131, v185
	v_mul_f32_e32 v132, v132, v185
	v_mul_f32_e32 v133, v133, v185
	v_mul_f32_e32 v134, v134, v185
	v_mul_f32_e32 v135, v135, v185
	v_fma_f32 v120, v120, v8, v24
	v_fma_f32 v121, v121, v9, v25
	v_fma_f32 v122, v122, v10, v26
	v_fma_f32 v123, v123, v11, v27
	v_fma_f32 v124, v124, v12, v28
	v_fma_f32 v125, v125, v13, v29
	v_fma_f32 v126, v126, v14, v30
	v_fma_f32 v127, v127, v15, v31
	v_fma_f32 v128, v128, v16, v32
	v_fma_f32 v129, v129, v17, v33
	v_fma_f32 v130, v130, v18, v34
	v_fma_f32 v131, v131, v19, v35
	v_fma_f32 v132, v132, v20, v36
	v_fma_f32 v133, v133, v21, v37
	v_fma_f32 v134, v134, v22, v38
	v_fma_f32 v135, v135, v23, v39
	v_cvt_pk_bf16_f32 v120, v120, v121
	v_cvt_pk_bf16_f32 v121, v122, v123
	v_cvt_pk_bf16_f32 v124, v124, v125
	v_cvt_pk_bf16_f32 v125, v126, v127
	v_cvt_pk_bf16_f32 v128, v128, v129
	v_cvt_pk_bf16_f32 v129, v130, v131
	v_cvt_pk_bf16_f32 v132, v132, v133
	v_cvt_pk_bf16_f32 v133, v134, v135
	v_add_u32_e32 v171, 0xf00000, v5
	global_store_dwordx2 v171, v[120:121], s[8:9]
	global_store_dwordx2 v171, v[124:125], s[8:9] offset:512
	global_store_dwordx2 v171, v[128:129], s[8:9] offset:1024
	global_store_dwordx2 v171, v[132:133], s[8:9] offset:1536
	v_mov_b32_e32 v172, 0xf000
	s_mov_b64 exec, 1
	global_store_dwordx2 v172, v[184:185], s[38:39]
	s_mov_b64 exec, -1
	s_waitcnt vmcnt(46)
	v_add_f32_e32 v180, v136, v137
	v_add_f32_e32 v181, v140, v141
	v_add_f32_e32 v182, v144, v145
	v_add_f32_e32 v183, v148, v149
	v_add_f32_e32 v180, v180, v138
	v_add_f32_e32 v181, v181, v142
	v_add_f32_e32 v182, v182, v146
	v_add_f32_e32 v183, v183, v150
	v_add_f32_e32 v180, v180, v139
	v_add_f32_e32 v181, v181, v143
	v_add_f32_e32 v182, v182, v147
	v_add_f32_e32 v183, v183, v151
	v_add_f32_e32 v180, v180, v181
	v_add_f32_e32 v182, v182, v183
	v_add_f32_e32 v180, v180, v182
	s_nop 1
	v_add_f32_dpp v180, v180, v180 quad_perm:[1,0,3,2] row_mask:0xf bank_mask:0xf
	s_nop 1
	v_add_f32_dpp v180, v180, v180 quad_perm:[2,3,0,1] row_mask:0xf bank_mask:0xf
	s_nop 1
	v_add_f32_dpp v180, v180, v180 row_half_mirror row_mask:0xf bank_mask:0xf
	s_nop 1
	v_add_f32_dpp v180, v180, v180 row_mirror row_mask:0xf bank_mask:0xf
	s_nop 1
	v_add_f32_dpp v180, v180, v180 row_bcast:15 row_mask:0xa bank_mask:0xf
	s_nop 1
	v_add_f32_dpp v180, v180, v180 row_bcast:31 row_mask:0xc bank_mask:0xf
	s_nop 0
	v_readlane_b32 s20, v180, 63
	s_nop 1
	v_mul_f32_e32 v184, s20, v2
	v_sub_f32_e32 v136, v136, v184
	v_sub_f32_e32 v137, v137, v184
	v_sub_f32_e32 v138, v138, v184
	v_sub_f32_e32 v139, v139, v184
	v_sub_f32_e32 v140, v140, v184
	v_sub_f32_e32 v141, v141, v184
	v_sub_f32_e32 v142, v142, v184
	v_sub_f32_e32 v143, v143, v184
	v_sub_f32_e32 v144, v144, v184
	v_sub_f32_e32 v145, v145, v184
	v_sub_f32_e32 v146, v146, v184
	v_sub_f32_e32 v147, v147, v184
	v_sub_f32_e32 v148, v148, v184
	v_sub_f32_e32 v149, v149, v184
	v_sub_f32_e32 v150, v150, v184
	v_sub_f32_e32 v151, v151, v184
	v_mul_f32_e32 v180, v136, v136
	v_mul_f32_e32 v181, v140, v140
	v_mul_f32_e32 v182, v144, v144
	v_mul_f32_e32 v183, v148, v148
	v_fmac_f32_e32 v180, v137, v137
	v_fmac_f32_e32 v181, v141, v141
	v_fmac_f32_e32 v182, v145, v145
	v_fmac_f32_e32 v183, v149, v149
	v_fmac_f32_e32 v180, v138, v138
	v_fmac_f32_e32 v181, v142, v142
	v_fmac_f32_e32 v182, v146, v146
	v_fmac_f32_e32 v183, v150, v150
	v_fmac_f32_e32 v180, v139, v139
	v_fmac_f32_e32 v181, v143, v143
	v_fmac_f32_e32 v182, v147, v147
	v_fmac_f32_e32 v183, v151, v151
	v_add_f32_e32 v180, v180, v181
	v_add_f32_e32 v182, v182, v183
	v_add_f32_e32 v180, v180, v182
	s_nop 1
	v_add_f32_dpp v180, v180, v180 quad_perm:[1,0,3,2] row_mask:0xf bank_mask:0xf
	s_nop 1
	v_add_f32_dpp v180, v180, v180 quad_perm:[2,3,0,1] row_mask:0xf bank_mask:0xf
	s_nop 1
	v_add_f32_dpp v180, v180, v180 row_half_mirror row_mask:0xf bank_mask:0xf
	s_nop 1
	v_add_f32_dpp v180, v180, v180 row_mirror row_mask:0xf bank_mask:0xf
	s_nop 1
	v_add_f32_dpp v180, v180, v180 row_bcast:15 row_mask:0xa bank_mask:0xf
	s_nop 1
	v_add_f32_dpp v180, v180, v180 row_bcast:31 row_mask:0xc bank_mask:0xf
	s_nop 0
	v_readlane_b32 s20, v180, 63
	s_nop 1
	v_mov_b32_e32 v185, s20
	v_fma_f32 v185, v185, v2, v4
	v_rsq_f32_e32 v185, v185
	s_nop 0
	v_mul_f32_e32 v136, v136, v185
	v_mul_f32_e32 v137, v137, v185
	v_mul_f32_e32 v138, v138, v185
	v_mul_f32_e32 v139, v139, v185
	v_mul_f32_e32 v140, v140, v185
	v_mul_f32_e32 v141, v141, v185
	v_mul_f32_e32 v142, v142, v185
	v_mul_f32_e32 v143, v143, v185
	v_mul_f32_e32 v144, v144, v185
	v_mul_f32_e32 v145, v145, v185
	v_mul_f32_e32 v146, v146, v185
	v_mul_f32_e32 v147, v147, v185
	v_mul_f32_e32 v148, v148, v185
	v_mul_f32_e32 v149, v149, v185
	v_mul_f32_e32 v150, v150, v185
	v_mul_f32_e32 v151, v151, v185
	v_fma_f32 v136, v136, v8, v24
	v_fma_f32 v137, v137, v9, v25
	v_fma_f32 v138, v138, v10, v26
	v_fma_f32 v139, v139, v11, v27
	v_fma_f32 v140, v140, v12, v28
	v_fma_f32 v141, v141, v13, v29
	v_fma_f32 v142, v142, v14, v30
	v_fma_f32 v143, v143, v15, v31
	v_fma_f32 v144, v144, v16, v32
	v_fma_f32 v145, v145, v17, v33
	v_fma_f32 v146, v146, v18, v34
	v_fma_f32 v147, v147, v19, v35
	v_fma_f32 v148, v148, v20, v36
	v_fma_f32 v149, v149, v21, v37
	v_fma_f32 v150, v150, v22, v38
	v_fma_f32 v151, v151, v23, v39
	v_cvt_pk_bf16_f32 v136, v136, v137
	v_cvt_pk_bf16_f32 v137, v138, v139
	v_cvt_pk_bf16_f32 v140, v140, v141
	v_cvt_pk_bf16_f32 v141, v142, v143
	v_cvt_pk_bf16_f32 v144, v144, v145
	v_cvt_pk_bf16_f32 v145, v146, v147
	v_cvt_pk_bf16_f32 v148, v148, v149
	v_cvt_pk_bf16_f32 v149, v150, v151
	v_add_u32_e32 v171, 0x1200000, v5
	global_store_dwordx2 v171, v[136:137], s[8:9]
	global_store_dwordx2 v171, v[140:141], s[8:9] offset:512
	global_store_dwordx2 v171, v[144:145], s[8:9] offset:1024
	global_store_dwordx2 v171, v[148:149], s[8:9] offset:1536
	v_mov_b32_e32 v172, 0x12000
	s_mov_b64 exec, 1
	global_store_dwordx2 v172, v[184:185], s[38:39]
	s_mov_b64 exec, -1
	s_waitcnt vmcnt(47)
	v_add_f32_e32 v180, v152, v153
	v_add_f32_e32 v181, v156, v157
	v_add_f32_e32 v182, v160, v161
	v_add_f32_e32 v183, v164, v165
	v_add_f32_e32 v180, v180, v154
	v_add_f32_e32 v181, v181, v158
	v_add_f32_e32 v182, v182, v162
	v_add_f32_e32 v183, v183, v166
	v_add_f32_e32 v180, v180, v155
	v_add_f32_e32 v181, v181, v159
	v_add_f32_e32 v182, v182, v163
	v_add_f32_e32 v183, v183, v167
	v_add_f32_e32 v180, v180, v181
	v_add_f32_e32 v182, v182, v183
	v_add_f32_e32 v180, v180, v182
	s_nop 1
	v_add_f32_dpp v180, v180, v180 quad_perm:[1,0,3,2] row_mask:0xf bank_mask:0xf
	s_nop 1
	v_add_f32_dpp v180, v180, v180 quad_perm:[2,3,0,1] row_mask:0xf bank_mask:0xf
	s_nop 1
	v_add_f32_dpp v180, v180, v180 row_half_mirror row_mask:0xf bank_mask:0xf
	s_nop 1
	v_add_f32_dpp v180, v180, v180 row_mirror row_mask:0xf bank_mask:0xf
	s_nop 1
	v_add_f32_dpp v180, v180, v180 row_bcast:15 row_mask:0xa bank_mask:0xf
	s_nop 1
	v_add_f32_dpp v180, v180, v180 row_bcast:31 row_mask:0xc bank_mask:0xf
	s_nop 0
	v_readlane_b32 s20, v180, 63
	s_nop 1
	v_mul_f32_e32 v184, s20, v2
	v_sub_f32_e32 v152, v152, v184
	v_sub_f32_e32 v153, v153, v184
	v_sub_f32_e32 v154, v154, v184
	v_sub_f32_e32 v155, v155, v184
	v_sub_f32_e32 v156, v156, v184
	v_sub_f32_e32 v157, v157, v184
	v_sub_f32_e32 v158, v158, v184
	v_sub_f32_e32 v159, v159, v184
	v_sub_f32_e32 v160, v160, v184
	v_sub_f32_e32 v161, v161, v184
	v_sub_f32_e32 v162, v162, v184
	v_sub_f32_e32 v163, v163, v184
	v_sub_f32_e32 v164, v164, v184
	v_sub_f32_e32 v165, v165, v184
	v_sub_f32_e32 v166, v166, v184
	v_sub_f32_e32 v167, v167, v184
	v_mul_f32_e32 v180, v152, v152
	v_mul_f32_e32 v181, v156, v156
	v_mul_f32_e32 v182, v160, v160
	v_mul_f32_e32 v183, v164, v164
	v_fmac_f32_e32 v180, v153, v153
	v_fmac_f32_e32 v181, v157, v157
	v_fmac_f32_e32 v182, v161, v161
	v_fmac_f32_e32 v183, v165, v165
	v_fmac_f32_e32 v180, v154, v154
	v_fmac_f32_e32 v181, v158, v158
	v_fmac_f32_e32 v182, v162, v162
	v_fmac_f32_e32 v183, v166, v166
	v_fmac_f32_e32 v180, v155, v155
	v_fmac_f32_e32 v181, v159, v159
	v_fmac_f32_e32 v182, v163, v163
	v_fmac_f32_e32 v183, v167, v167
	v_add_f32_e32 v180, v180, v181
	v_add_f32_e32 v182, v182, v183
	v_add_f32_e32 v180, v180, v182
	s_nop 1
	v_add_f32_dpp v180, v180, v180 quad_perm:[1,0,3,2] row_mask:0xf bank_mask:0xf
	s_nop 1
	v_add_f32_dpp v180, v180, v180 quad_perm:[2,3,0,1] row_mask:0xf bank_mask:0xf
	s_nop 1
	v_add_f32_dpp v180, v180, v180 row_half_mirror row_mask:0xf bank_mask:0xf
	s_nop 1
	v_add_f32_dpp v180, v180, v180 row_mirror row_mask:0xf bank_mask:0xf
	s_nop 1
	v_add_f32_dpp v180, v180, v180 row_bcast:15 row_mask:0xa bank_mask:0xf
	s_nop 1
	v_add_f32_dpp v180, v180, v180 row_bcast:31 row_mask:0xc bank_mask:0xf
	s_nop 0
	v_readlane_b32 s20, v180, 63
	s_nop 1
	v_mov_b32_e32 v185, s20
	v_fma_f32 v185, v185, v2, v4
	v_rsq_f32_e32 v185, v185
	s_nop 0
	v_mul_f32_e32 v152, v152, v185
	v_mul_f32_e32 v153, v153, v185
	v_mul_f32_e32 v154, v154, v185
	v_mul_f32_e32 v155, v155, v185
	v_mul_f32_e32 v156, v156, v185
	v_mul_f32_e32 v157, v157, v185
	v_mul_f32_e32 v158, v158, v185
	v_mul_f32_e32 v159, v159, v185
	v_mul_f32_e32 v160, v160, v185
	v_mul_f32_e32 v161, v161, v185
	v_mul_f32_e32 v162, v162, v185
	v_mul_f32_e32 v163, v163, v185
	v_mul_f32_e32 v164, v164, v185
	v_mul_f32_e32 v165, v165, v185
	v_mul_f32_e32 v166, v166, v185
	v_mul_f32_e32 v167, v167, v185
	v_fma_f32 v152, v152, v8, v24
	v_fma_f32 v153, v153, v9, v25
	v_fma_f32 v154, v154, v10, v26
	v_fma_f32 v155, v155, v11, v27
	v_fma_f32 v156, v156, v12, v28
	v_fma_f32 v157, v157, v13, v29
	v_fma_f32 v158, v158, v14, v30
	v_fma_f32 v159, v159, v15, v31
	v_fma_f32 v160, v160, v16, v32
	v_fma_f32 v161, v161, v17, v33
	v_fma_f32 v162, v162, v18, v34
	v_fma_f32 v163, v163, v19, v35
	v_fma_f32 v164, v164, v20, v36
	v_fma_f32 v165, v165, v21, v37
	v_fma_f32 v166, v166, v22, v38
	v_fma_f32 v167, v167, v23, v39
	v_cvt_pk_bf16_f32 v152, v152, v153
	v_cvt_pk_bf16_f32 v153, v154, v155
	v_cvt_pk_bf16_f32 v156, v156, v157
	v_cvt_pk_bf16_f32 v157, v158, v159
	v_cvt_pk_bf16_f32 v160, v160, v161
	v_cvt_pk_bf16_f32 v161, v162, v163
	v_cvt_pk_bf16_f32 v164, v164, v165
	v_cvt_pk_bf16_f32 v165, v166, v167
	v_add_u32_e32 v171, 0x1500000, v5
	global_store_dwordx2 v171, v[152:153], s[8:9]
	global_store_dwordx2 v171, v[156:157], s[8:9] offset:512
	global_store_dwordx2 v171, v[160:161], s[8:9] offset:1024
	global_store_dwordx2 v171, v[164:165], s[8:9] offset:1536
	v_mov_b32_e32 v172, 0x15000
	s_mov_b64 exec, 1
	global_store_dwordx2 v172, v[184:185], s[38:39]
	s_mov_b64 exec, -1
	s_waitcnt vmcnt(43)
	v_add_f32_e32 v180, v40, v41
	v_add_f32_e32 v181, v44, v45
	v_add_f32_e32 v182, v48, v49
	v_add_f32_e32 v183, v52, v53
	v_add_f32_e32 v180, v180, v42
	v_add_f32_e32 v181, v181, v46
	v_add_f32_e32 v182, v182, v50
	v_add_f32_e32 v183, v183, v54
	v_add_f32_e32 v180, v180, v43
	v_add_f32_e32 v181, v181, v47
	v_add_f32_e32 v182, v182, v51
	v_add_f32_e32 v183, v183, v55
	v_add_f32_e32 v180, v180, v181
	v_add_f32_e32 v182, v182, v183
	v_add_f32_e32 v180, v180, v182
	s_nop 1
	v_add_f32_dpp v180, v180, v180 quad_perm:[1,0,3,2] row_mask:0xf bank_mask:0xf
	s_nop 1
	v_add_f32_dpp v180, v180, v180 quad_perm:[2,3,0,1] row_mask:0xf bank_mask:0xf
	s_nop 1
	v_add_f32_dpp v180, v180, v180 row_half_mirror row_mask:0xf bank_mask:0xf
	s_nop 1
	v_add_f32_dpp v180, v180, v180 row_mirror row_mask:0xf bank_mask:0xf
	s_nop 1
	v_add_f32_dpp v180, v180, v180 row_bcast:15 row_mask:0xa bank_mask:0xf
	s_nop 1
	v_add_f32_dpp v180, v180, v180 row_bcast:31 row_mask:0xc bank_mask:0xf
	s_nop 0
	v_readlane_b32 s20, v180, 63
	s_nop 1
	v_mul_f32_e32 v184, s20, v2
	v_sub_f32_e32 v40, v40, v184
	v_sub_f32_e32 v41, v41, v184
	v_sub_f32_e32 v42, v42, v184
	v_sub_f32_e32 v43, v43, v184
	v_sub_f32_e32 v44, v44, v184
	v_sub_f32_e32 v45, v45, v184
	v_sub_f32_e32 v46, v46, v184
	v_sub_f32_e32 v47, v47, v184
	v_sub_f32_e32 v48, v48, v184
	v_sub_f32_e32 v49, v49, v184
	v_sub_f32_e32 v50, v50, v184
	v_sub_f32_e32 v51, v51, v184
	v_sub_f32_e32 v52, v52, v184
	v_sub_f32_e32 v53, v53, v184
	v_sub_f32_e32 v54, v54, v184
	v_sub_f32_e32 v55, v55, v184
	v_mul_f32_e32 v180, v40, v40
	v_mul_f32_e32 v181, v44, v44
	v_mul_f32_e32 v182, v48, v48
	v_mul_f32_e32 v183, v52, v52
	v_fmac_f32_e32 v180, v41, v41
	v_fmac_f32_e32 v181, v45, v45
	v_fmac_f32_e32 v182, v49, v49
	v_fmac_f32_e32 v183, v53, v53
	v_fmac_f32_e32 v180, v42, v42
	v_fmac_f32_e32 v181, v46, v46
	v_fmac_f32_e32 v182, v50, v50
	v_fmac_f32_e32 v183, v54, v54
	v_fmac_f32_e32 v180, v43, v43
	v_fmac_f32_e32 v181, v47, v47
	v_fmac_f32_e32 v182, v51, v51
	v_fmac_f32_e32 v183, v55, v55
	v_add_f32_e32 v180, v180, v181
	v_add_f32_e32 v182, v182, v183
	v_add_f32_e32 v180, v180, v182
	s_nop 1
	v_add_f32_dpp v180, v180, v180 quad_perm:[1,0,3,2] row_mask:0xf bank_mask:0xf
	s_nop 1
	v_add_f32_dpp v180, v180, v180 quad_perm:[2,3,0,1] row_mask:0xf bank_mask:0xf
	s_nop 1
	v_add_f32_dpp v180, v180, v180 row_half_mirror row_mask:0xf bank_mask:0xf
	s_nop 1
	v_add_f32_dpp v180, v180, v180 row_mirror row_mask:0xf bank_mask:0xf
	s_nop 1
	v_add_f32_dpp v180, v180, v180 row_bcast:15 row_mask:0xa bank_mask:0xf
	s_nop 1
	v_add_f32_dpp v180, v180, v180 row_bcast:31 row_mask:0xc bank_mask:0xf
	s_nop 0
	v_readlane_b32 s20, v180, 63
	s_nop 1
	v_mov_b32_e32 v185, s20
	v_fma_f32 v185, v185, v2, v4
	v_rsq_f32_e32 v185, v185
	s_nop 0
	v_mul_f32_e32 v40, v40, v185
	v_mul_f32_e32 v41, v41, v185
	v_mul_f32_e32 v42, v42, v185
	v_mul_f32_e32 v43, v43, v185
	v_mul_f32_e32 v44, v44, v185
	v_mul_f32_e32 v45, v45, v185
	v_mul_f32_e32 v46, v46, v185
	v_mul_f32_e32 v47, v47, v185
	v_mul_f32_e32 v48, v48, v185
	v_mul_f32_e32 v49, v49, v185
	v_mul_f32_e32 v50, v50, v185
	v_mul_f32_e32 v51, v51, v185
	v_mul_f32_e32 v52, v52, v185
	v_mul_f32_e32 v53, v53, v185
	v_mul_f32_e32 v54, v54, v185
	v_mul_f32_e32 v55, v55, v185
	v_fma_f32 v40, v40, v8, v24
	v_fma_f32 v41, v41, v9, v25
	v_fma_f32 v42, v42, v10, v26
	v_fma_f32 v43, v43, v11, v27
	v_fma_f32 v44, v44, v12, v28
	v_fma_f32 v45, v45, v13, v29
	v_fma_f32 v46, v46, v14, v30
	v_fma_f32 v47, v47, v15, v31
	v_fma_f32 v48, v48, v16, v32
	v_fma_f32 v49, v49, v17, v33
	v_fma_f32 v50, v50, v18, v34
	v_fma_f32 v51, v51, v19, v35
	v_fma_f32 v52, v52, v20, v36
	v_fma_f32 v53, v53, v21, v37
	v_fma_f32 v54, v54, v22, v38
	v_fma_f32 v55, v55, v23, v39
	v_cvt_pk_bf16_f32 v40, v40, v41
	v_cvt_pk_bf16_f32 v41, v42, v43
	v_cvt_pk_bf16_f32 v44, v44, v45
	v_cvt_pk_bf16_f32 v45, v46, v47
	v_cvt_pk_bf16_f32 v48, v48, v49
	v_cvt_pk_bf16_f32 v49, v50, v51
	v_cvt_pk_bf16_f32 v52, v52, v53
	v_cvt_pk_bf16_f32 v53, v54, v55
	v_add_u32_e32 v171, 0x1800000, v5
	global_store_dwordx2 v171, v[40:41], s[8:9]
	global_store_dwordx2 v171, v[44:45], s[8:9] offset:512
	global_store_dwordx2 v171, v[48:49], s[8:9] offset:1024
	global_store_dwordx2 v171, v[52:53], s[8:9] offset:1536
	v_mov_b32_e32 v172, 0x18000
	s_mov_b64 exec, 1
	global_store_dwordx2 v172, v[184:185], s[38:39]
	s_mov_b64 exec, -1
	s_waitcnt vmcnt(39)
	v_add_f32_e32 v180, v56, v57
	v_add_f32_e32 v181, v60, v61
	v_add_f32_e32 v182, v64, v65
	v_add_f32_e32 v183, v68, v69
	v_add_f32_e32 v180, v180, v58
	v_add_f32_e32 v181, v181, v62
	v_add_f32_e32 v182, v182, v66
	v_add_f32_e32 v183, v183, v70
	v_add_f32_e32 v180, v180, v59
	v_add_f32_e32 v181, v181, v63
	v_add_f32_e32 v182, v182, v67
	v_add_f32_e32 v183, v183, v71
	v_add_f32_e32 v180, v180, v181
	v_add_f32_e32 v182, v182, v183
	v_add_f32_e32 v180, v180, v182
	s_nop 1
	v_add_f32_dpp v180, v180, v180 quad_perm:[1,0,3,2] row_mask:0xf bank_mask:0xf
	s_nop 1
	v_add_f32_dpp v180, v180, v180 quad_perm:[2,3,0,1] row_mask:0xf bank_mask:0xf
	s_nop 1
	v_add_f32_dpp v180, v180, v180 row_half_mirror row_mask:0xf bank_mask:0xf
	s_nop 1
	v_add_f32_dpp v180, v180, v180 row_mirror row_mask:0xf bank_mask:0xf
	s_nop 1
	v_add_f32_dpp v180, v180, v180 row_bcast:15 row_mask:0xa bank_mask:0xf
	s_nop 1
	v_add_f32_dpp v180, v180, v180 row_bcast:31 row_mask:0xc bank_mask:0xf
	s_nop 0
	v_readlane_b32 s20, v180, 63
	s_nop 1
	v_mul_f32_e32 v184, s20, v2
	v_sub_f32_e32 v56, v56, v184
	v_sub_f32_e32 v57, v57, v184
	v_sub_f32_e32 v58, v58, v184
	v_sub_f32_e32 v59, v59, v184
	v_sub_f32_e32 v60, v60, v184
	v_sub_f32_e32 v61, v61, v184
	v_sub_f32_e32 v62, v62, v184
	v_sub_f32_e32 v63, v63, v184
	v_sub_f32_e32 v64, v64, v184
	v_sub_f32_e32 v65, v65, v184
	v_sub_f32_e32 v66, v66, v184
	v_sub_f32_e32 v67, v67, v184
	v_sub_f32_e32 v68, v68, v184
	v_sub_f32_e32 v69, v69, v184
	v_sub_f32_e32 v70, v70, v184
	v_sub_f32_e32 v71, v71, v184
	v_mul_f32_e32 v180, v56, v56
	v_mul_f32_e32 v181, v60, v60
	v_mul_f32_e32 v182, v64, v64
	v_mul_f32_e32 v183, v68, v68
	v_fmac_f32_e32 v180, v57, v57
	v_fmac_f32_e32 v181, v61, v61
	v_fmac_f32_e32 v182, v65, v65
	v_fmac_f32_e32 v183, v69, v69
	v_fmac_f32_e32 v180, v58, v58
	v_fmac_f32_e32 v181, v62, v62
	v_fmac_f32_e32 v182, v66, v66
	v_fmac_f32_e32 v183, v70, v70
	v_fmac_f32_e32 v180, v59, v59
	v_fmac_f32_e32 v181, v63, v63
	v_fmac_f32_e32 v182, v67, v67
	v_fmac_f32_e32 v183, v71, v71
	v_add_f32_e32 v180, v180, v181
	v_add_f32_e32 v182, v182, v183
	v_add_f32_e32 v180, v180, v182
	s_nop 1
	v_add_f32_dpp v180, v180, v180 quad_perm:[1,0,3,2] row_mask:0xf bank_mask:0xf
	s_nop 1
	v_add_f32_dpp v180, v180, v180 quad_perm:[2,3,0,1] row_mask:0xf bank_mask:0xf
	s_nop 1
	v_add_f32_dpp v180, v180, v180 row_half_mirror row_mask:0xf bank_mask:0xf
	s_nop 1
	v_add_f32_dpp v180, v180, v180 row_mirror row_mask:0xf bank_mask:0xf
	s_nop 1
	v_add_f32_dpp v180, v180, v180 row_bcast:15 row_mask:0xa bank_mask:0xf
	s_nop 1
	v_add_f32_dpp v180, v180, v180 row_bcast:31 row_mask:0xc bank_mask:0xf
	s_nop 0
	v_readlane_b32 s20, v180, 63
	s_nop 1
	v_mov_b32_e32 v185, s20
	v_fma_f32 v185, v185, v2, v4
	v_rsq_f32_e32 v185, v185
	s_nop 0
	v_mul_f32_e32 v56, v56, v185
	v_mul_f32_e32 v57, v57, v185
	v_mul_f32_e32 v58, v58, v185
	v_mul_f32_e32 v59, v59, v185
	v_mul_f32_e32 v60, v60, v185
	v_mul_f32_e32 v61, v61, v185
	v_mul_f32_e32 v62, v62, v185
	v_mul_f32_e32 v63, v63, v185
	v_mul_f32_e32 v64, v64, v185
	v_mul_f32_e32 v65, v65, v185
	v_mul_f32_e32 v66, v66, v185
	v_mul_f32_e32 v67, v67, v185
	v_mul_f32_e32 v68, v68, v185
	v_mul_f32_e32 v69, v69, v185
	v_mul_f32_e32 v70, v70, v185
	v_mul_f32_e32 v71, v71, v185
	v_fma_f32 v56, v56, v8, v24
	v_fma_f32 v57, v57, v9, v25
	v_fma_f32 v58, v58, v10, v26
	v_fma_f32 v59, v59, v11, v27
	v_fma_f32 v60, v60, v12, v28
	v_fma_f32 v61, v61, v13, v29
	v_fma_f32 v62, v62, v14, v30
	v_fma_f32 v63, v63, v15, v31
	v_fma_f32 v64, v64, v16, v32
	v_fma_f32 v65, v65, v17, v33
	v_fma_f32 v66, v66, v18, v34
	v_fma_f32 v67, v67, v19, v35
	v_fma_f32 v68, v68, v20, v36
	v_fma_f32 v69, v69, v21, v37
	v_fma_f32 v70, v70, v22, v38
	v_fma_f32 v71, v71, v23, v39
	v_cvt_pk_bf16_f32 v56, v56, v57
	v_cvt_pk_bf16_f32 v57, v58, v59
	v_cvt_pk_bf16_f32 v60, v60, v61
	v_cvt_pk_bf16_f32 v61, v62, v63
	v_cvt_pk_bf16_f32 v64, v64, v65
	v_cvt_pk_bf16_f32 v65, v66, v67
	v_cvt_pk_bf16_f32 v68, v68, v69
	v_cvt_pk_bf16_f32 v69, v70, v71
	v_add_u32_e32 v171, 0x1b00000, v5
	global_store_dwordx2 v171, v[56:57], s[8:9]
	global_store_dwordx2 v171, v[60:61], s[8:9] offset:512
	global_store_dwordx2 v171, v[64:65], s[8:9] offset:1024
	global_store_dwordx2 v171, v[68:69], s[8:9] offset:1536
	v_mov_b32_e32 v172, 0x1b000
	s_mov_b64 exec, 1
	global_store_dwordx2 v172, v[184:185], s[38:39]
	s_mov_b64 exec, -1
	s_waitcnt vmcnt(35)
	v_add_f32_e32 v180, v72, v73
	v_add_f32_e32 v181, v76, v77
	v_add_f32_e32 v182, v80, v81
	v_add_f32_e32 v183, v84, v85
	v_add_f32_e32 v180, v180, v74
	v_add_f32_e32 v181, v181, v78
	v_add_f32_e32 v182, v182, v82
	v_add_f32_e32 v183, v183, v86
	v_add_f32_e32 v180, v180, v75
	v_add_f32_e32 v181, v181, v79
	v_add_f32_e32 v182, v182, v83
	v_add_f32_e32 v183, v183, v87
	v_add_f32_e32 v180, v180, v181
	v_add_f32_e32 v182, v182, v183
	v_add_f32_e32 v180, v180, v182
	s_nop 1
	v_add_f32_dpp v180, v180, v180 quad_perm:[1,0,3,2] row_mask:0xf bank_mask:0xf
	s_nop 1
	v_add_f32_dpp v180, v180, v180 quad_perm:[2,3,0,1] row_mask:0xf bank_mask:0xf
	s_nop 1
	v_add_f32_dpp v180, v180, v180 row_half_mirror row_mask:0xf bank_mask:0xf
	s_nop 1
	v_add_f32_dpp v180, v180, v180 row_mirror row_mask:0xf bank_mask:0xf
	s_nop 1
	v_add_f32_dpp v180, v180, v180 row_bcast:15 row_mask:0xa bank_mask:0xf
	s_nop 1
	v_add_f32_dpp v180, v180, v180 row_bcast:31 row_mask:0xc bank_mask:0xf
	s_nop 0
	v_readlane_b32 s20, v180, 63
	s_nop 1
	v_mul_f32_e32 v184, s20, v2
	v_sub_f32_e32 v72, v72, v184
	v_sub_f32_e32 v73, v73, v184
	v_sub_f32_e32 v74, v74, v184
	v_sub_f32_e32 v75, v75, v184
	v_sub_f32_e32 v76, v76, v184
	v_sub_f32_e32 v77, v77, v184
	v_sub_f32_e32 v78, v78, v184
	v_sub_f32_e32 v79, v79, v184
	v_sub_f32_e32 v80, v80, v184
	v_sub_f32_e32 v81, v81, v184
	v_sub_f32_e32 v82, v82, v184
	v_sub_f32_e32 v83, v83, v184
	v_sub_f32_e32 v84, v84, v184
	v_sub_f32_e32 v85, v85, v184
	v_sub_f32_e32 v86, v86, v184
	v_sub_f32_e32 v87, v87, v184
	v_mul_f32_e32 v180, v72, v72
	v_mul_f32_e32 v181, v76, v76
	v_mul_f32_e32 v182, v80, v80
	v_mul_f32_e32 v183, v84, v84
	v_fmac_f32_e32 v180, v73, v73
	v_fmac_f32_e32 v181, v77, v77
	v_fmac_f32_e32 v182, v81, v81
	v_fmac_f32_e32 v183, v85, v85
	v_fmac_f32_e32 v180, v74, v74
	v_fmac_f32_e32 v181, v78, v78
	v_fmac_f32_e32 v182, v82, v82
	v_fmac_f32_e32 v183, v86, v86
	v_fmac_f32_e32 v180, v75, v75
	v_fmac_f32_e32 v181, v79, v79
	v_fmac_f32_e32 v182, v83, v83
	v_fmac_f32_e32 v183, v87, v87
	v_add_f32_e32 v180, v180, v181
	v_add_f32_e32 v182, v182, v183
	v_add_f32_e32 v180, v180, v182
	s_nop 1
	v_add_f32_dpp v180, v180, v180 quad_perm:[1,0,3,2] row_mask:0xf bank_mask:0xf
	s_nop 1
	v_add_f32_dpp v180, v180, v180 quad_perm:[2,3,0,1] row_mask:0xf bank_mask:0xf
	s_nop 1
	v_add_f32_dpp v180, v180, v180 row_half_mirror row_mask:0xf bank_mask:0xf
	s_nop 1
	v_add_f32_dpp v180, v180, v180 row_mirror row_mask:0xf bank_mask:0xf
	s_nop 1
	v_add_f32_dpp v180, v180, v180 row_bcast:15 row_mask:0xa bank_mask:0xf
	s_nop 1
	v_add_f32_dpp v180, v180, v180 row_bcast:31 row_mask:0xc bank_mask:0xf
	s_nop 0
	v_readlane_b32 s20, v180, 63
	s_nop 1
	v_mov_b32_e32 v185, s20
	v_fma_f32 v185, v185, v2, v4
	v_rsq_f32_e32 v185, v185
	s_nop 0
	v_mul_f32_e32 v72, v72, v185
	v_mul_f32_e32 v73, v73, v185
	v_mul_f32_e32 v74, v74, v185
	v_mul_f32_e32 v75, v75, v185
	v_mul_f32_e32 v76, v76, v185
	v_mul_f32_e32 v77, v77, v185
	v_mul_f32_e32 v78, v78, v185
	v_mul_f32_e32 v79, v79, v185
	v_mul_f32_e32 v80, v80, v185
	v_mul_f32_e32 v81, v81, v185
	v_mul_f32_e32 v82, v82, v185
	v_mul_f32_e32 v83, v83, v185
	v_mul_f32_e32 v84, v84, v185
	v_mul_f32_e32 v85, v85, v185
	v_mul_f32_e32 v86, v86, v185
	v_mul_f32_e32 v87, v87, v185
	v_fma_f32 v72, v72, v8, v24
	v_fma_f32 v73, v73, v9, v25
	v_fma_f32 v74, v74, v10, v26
	v_fma_f32 v75, v75, v11, v27
	v_fma_f32 v76, v76, v12, v28
	v_fma_f32 v77, v77, v13, v29
	v_fma_f32 v78, v78, v14, v30
	v_fma_f32 v79, v79, v15, v31
	v_fma_f32 v80, v80, v16, v32
	v_fma_f32 v81, v81, v17, v33
	v_fma_f32 v82, v82, v18, v34
	v_fma_f32 v83, v83, v19, v35
	v_fma_f32 v84, v84, v20, v36
	v_fma_f32 v85, v85, v21, v37
	v_fma_f32 v86, v86, v22, v38
	v_fma_f32 v87, v87, v23, v39
	v_cvt_pk_bf16_f32 v72, v72, v73
	v_cvt_pk_bf16_f32 v73, v74, v75
	v_cvt_pk_bf16_f32 v76, v76, v77
	v_cvt_pk_bf16_f32 v77, v78, v79
	v_cvt_pk_bf16_f32 v80, v80, v81
	v_cvt_pk_bf16_f32 v81, v82, v83
	v_cvt_pk_bf16_f32 v84, v84, v85
	v_cvt_pk_bf16_f32 v85, v86, v87
	v_add_u32_e32 v171, 0x1e00000, v5
	global_store_dwordx2 v171, v[72:73], s[8:9]
	global_store_dwordx2 v171, v[76:77], s[8:9] offset:512
	global_store_dwordx2 v171, v[80:81], s[8:9] offset:1024
	global_store_dwordx2 v171, v[84:85], s[8:9] offset:1536
	v_mov_b32_e32 v172, 0x1e000
	s_mov_b64 exec, 1
	global_store_dwordx2 v172, v[184:185], s[38:39]
	s_mov_b64 exec, -1
	s_branch .LBB0_188
.Lln_r10:
	global_load_dwordx4 v[40:43], v1, s[4:5] nt
	global_load_dwordx4 v[44:47], v1, s[4:5] offset:1024 nt
	global_load_dwordx4 v[48:51], v1, s[4:5] offset:2048 nt
	global_load_dwordx4 v[52:55], v1, s[4:5] offset:3072 nt
	global_load_dwordx4 v[8:11], v1, s[40:41]
	global_load_dwordx4 v[12:15], v1, s[40:41] offset:1024
	global_load_dwordx4 v[16:19], v1, s[40:41] offset:2048
	global_load_dwordx4 v[20:23], v1, s[40:41] offset:3072
	global_load_dwordx4 v[24:27], v1, s[42:43]
	global_load_dwordx4 v[28:31], v1, s[42:43] offset:1024
	global_load_dwordx4 v[32:35], v1, s[42:43] offset:2048
	global_load_dwordx4 v[36:39], v1, s[42:43] offset:3072
	v_add_u32_e32 v170, 0x600000, v1
	global_load_dwordx4 v[56:59], v170, s[4:5] nt
	global_load_dwordx4 v[60:63], v170, s[4:5] offset:1024 nt
	global_load_dwordx4 v[64:67], v170, s[4:5] offset:2048 nt
	global_load_dwordx4 v[68:71], v170, s[4:5] offset:3072 nt
	v_add_u32_e32 v170, 0xc00000, v1
	global_load_dwordx4 v[72:75], v170, s[4:5] nt
	global_load_dwordx4 v[76:79], v170, s[4:5] offset:1024 nt
	global_load_dwordx4 v[80:83], v170, s[4:5] offset:2048 nt
	global_load_dwordx4 v[84:87], v170, s[4:5] offset:3072 nt
	v_add_u32_e32 v170, 0x1200000, v1
	global_load_dwordx4 v[88:91], v170, s[4:5] nt
	global_load_dwordx4 v[92:95], v170, s[4:5] offset:1024 nt
	global_load_dwordx4 v[96:99], v170, s[4:5] offset:2048 nt
	global_load_dwordx4 v[100:103], v170, s[4:5] offset:3072 nt
	v_add_u32_e32 v170, 0x1800000, v1
	global_load_dwordx4 v[104:107], v170, s[4:5] nt
	global_load_dwordx4 v[108:111], v170, s[4:5] offset:1024 nt
	global_load_dwordx4 v[112:115], v170, s[4:5] offset:2048 nt
	global_load_dwordx4 v[116:119], v170, s[4:5] offset:3072 nt
	v_add_u32_e32 v170, 0x1e00000, v1
	global_load_dwordx4 v[120:123], v170, s[4:5] nt
	global_load_dwordx4 v[124:127], v170, s[4:5] offset:1024 nt
	global_load_dwordx4 v[128:131], v170, s[4:5] offset:2048 nt
	global_load_dwordx4 v[132:135], v170, s[4:5] offset:3072 nt
	v_add_u32_e32 v170, 0x2400000, v1
	global_load_dwordx4 v[136:139], v170, s[4:5] nt
	global_load_dwordx4 v[140:143], v170, s[4:5] offset:1024 nt
	global_load_dwordx4 v[144:147], v170, s[4:5] offset:2048 nt
	global_load_dwordx4 v[148:151], v170, s[4:5] offset:3072 nt
	v_add_u32_e32 v170, 0x2a00000, v1
	global_load_dwordx4 v[152:155], v170, s[4:5] nt
	global_load_dwordx4 v[156:159], v170, s[4:5] offset:1024 nt
	global_load_dwordx4 v[160:163], v170, s[4:5] offset:2048 nt
	global_load_dwordx4 v[164:167], v170, s[4:5] offset:3072 nt
	s_waitcnt vmcnt(36)
	v_add_f32_e32 v180, v40, v41
	v_add_f32_e32 v181, v44, v45
	v_add_f32_e32 v182, v48, v49
	v_add_f32_e32 v183, v52, v53
	v_add_f32_e32 v180, v180, v42
	v_add_f32_e32 v181, v181, v46
	v_add_f32_e32 v182, v182, v50
	v_add_f32_e32 v183, v183, v54
	v_add_f32_e32 v180, v180, v43
	v_add_f32_e32 v181, v181, v47
	v_add_f32_e32 v182, v182, v51
	v_add_f32_e32 v183, v183, v55
	v_add_f32_e32 v180, v180, v181
	v_add_f32_e32 v182, v182, v183
	v_add_f32_e32 v180, v180, v182
	s_nop 1
	v_add_f32_dpp v180, v180, v180 quad_perm:[1,0,3,2] row_mask:0xf bank_mask:0xf
	s_nop 1
	v_add_f32_dpp v180, v180, v180 quad_perm:[2,3,0,1] row_mask:0xf bank_mask:0xf
	s_nop 1
	v_add_f32_dpp v180, v180, v180 row_half_mirror row_mask:0xf bank_mask:0xf
	s_nop 1
	v_add_f32_dpp v180, v180, v180 row_mirror row_mask:0xf bank_mask:0xf
	s_nop 1
	v_add_f32_dpp v180, v180, v180 row_bcast:15 row_mask:0xa bank_mask:0xf
	s_nop 1
	v_add_f32_dpp v180, v180, v180 row_bcast:31 row_mask:0xc bank_mask:0xf
	s_nop 0
	v_readlane_b32 s20, v180, 63
	s_nop 1
	v_mul_f32_e32 v184, s20, v2
	v_sub_f32_e32 v40, v40, v184
	v_sub_f32_e32 v41, v41, v184
	v_sub_f32_e32 v42, v42, v184
	v_sub_f32_e32 v43, v43, v184
	v_sub_f32_e32 v44, v44, v184
	v_sub_f32_e32 v45, v45, v184
	v_sub_f32_e32 v46, v46, v184
	v_sub_f32_e32 v47, v47, v184
	v_sub_f32_e32 v48, v48, v184
	v_sub_f32_e32 v49, v49, v184
	v_sub_f32_e32 v50, v50, v184
	v_sub_f32_e32 v51, v51, v184
	v_sub_f32_e32 v52, v52, v184
	v_sub_f32_e32 v53, v53, v184
	v_sub_f32_e32 v54, v54, v184
	v_sub_f32_e32 v55, v55, v184
	v_mul_f32_e32 v180, v40, v40
	v_mul_f32_e32 v181, v44, v44
	v_mul_f32_e32 v182, v48, v48
	v_mul_f32_e32 v183, v52, v52
	v_fmac_f32_e32 v180, v41, v41
	v_fmac_f32_e32 v181, v45, v45
	v_fmac_f32_e32 v182, v49, v49
	v_fmac_f32_e32 v183, v53, v53
	v_fmac_f32_e32 v180, v42, v42
	v_fmac_f32_e32 v181, v46, v46
	v_fmac_f32_e32 v182, v50, v50
	v_fmac_f32_e32 v183, v54, v54
	v_fmac_f32_e32 v180, v43, v43
	v_fmac_f32_e32 v181, v47, v47
	v_fmac_f32_e32 v182, v51, v51
	v_fmac_f32_e32 v183, v55, v55
	v_add_f32_e32 v180, v180, v181
	v_add_f32_e32 v182, v182, v183
	v_add_f32_e32 v180, v180, v182
	s_nop 1
	v_add_f32_dpp v180, v180, v180 quad_perm:[1,0,3,2] row_mask:0xf bank_mask:0xf
	s_nop 1
	v_add_f32_dpp v180, v180, v180 quad_perm:[2,3,0,1] row_mask:0xf bank_mask:0xf
	s_nop 1
	v_add_f32_dpp v180, v180, v180 row_half_mirror row_mask:0xf bank_mask:0xf
	s_nop 1
	v_add_f32_dpp v180, v180, v180 row_mirror row_mask:0xf bank_mask:0xf
	s_nop 1
	v_add_f32_dpp v180, v180, v180 row_bcast:15 row_mask:0xa bank_mask:0xf
	s_nop 1
	v_add_f32_dpp v180, v180, v180 row_bcast:31 row_mask:0xc bank_mask:0xf
	s_nop 0
	v_readlane_b32 s20, v180, 63
	s_nop 1
	v_mov_b32_e32 v185, s20
	v_fma_f32 v185, v185, v2, v4
	v_rsq_f32_e32 v185, v185
	s_nop 0
	v_mul_f32_e32 v40, v40, v185
	v_mul_f32_e32 v41, v41, v185
	v_mul_f32_e32 v42, v42, v185
	v_mul_f32_e32 v43, v43, v185
	v_mul_f32_e32 v44, v44, v185
	v_mul_f32_e32 v45, v45, v185
	v_mul_f32_e32 v46, v46, v185
	v_mul_f32_e32 v47, v47, v185
	v_mul_f32_e32 v48, v48, v185
	v_mul_f32_e32 v49, v49, v185
	v_mul_f32_e32 v50, v50, v185
	v_mul_f32_e32 v51, v51, v185
	v_mul_f32_e32 v52, v52, v185
	v_mul_f32_e32 v53, v53, v185
	v_mul_f32_e32 v54, v54, v185
	v_mul_f32_e32 v55, v55, v185
	s_waitcnt vmcnt(28)
	v_fma_f32 v40, v40, v8, v24
	v_fma_f32 v41, v41, v9, v25
	v_fma_f32 v42, v42, v10, v26
	v_fma_f32 v43, v43, v11, v27
	v_fma_f32 v44, v44, v12, v28
	v_fma_f32 v45, v45, v13, v29
	v_fma_f32 v46, v46, v14, v30
	v_fma_f32 v47, v47, v15, v31
	v_fma_f32 v48, v48, v16, v32
	v_fma_f32 v49, v49, v17, v33
	v_fma_f32 v50, v50, v18, v34
	v_fma_f32 v51, v51, v19, v35
	v_fma_f32 v52, v52, v20, v36
	v_fma_f32 v53, v53, v21, v37
	v_fma_f32 v54, v54, v22, v38
	v_fma_f32 v55, v55, v23, v39
	v_cvt_pk_bf16_f32 v40, v40, v41
	v_cvt_pk_bf16_f32 v41, v42, v43
	v_cvt_pk_bf16_f32 v44, v44, v45
	v_cvt_pk_bf16_f32 v45, v46, v47
	v_cvt_pk_bf16_f32 v48, v48, v49
	v_cvt_pk_bf16_f32 v49, v50, v51
	v_cvt_pk_bf16_f32 v52, v52, v53
	v_cvt_pk_bf16_f32 v53, v54, v55
	global_store_dwordx2 v5, v[40:41], s[8:9]
	global_store_dwordx2 v5, v[44:45], s[8:9] offset:512
	global_store_dwordx2 v5, v[48:49], s[8:9] offset:1024
	global_store_dwordx2 v5, v[52:53], s[8:9] offset:1536
	v_mov_b32_e32 v172, 0x0
	s_mov_b64 exec, 1
	global_store_dwordx2 v172, v[184:185], s[38:39]
	s_mov_b64 exec, -1
	s_nop 1
	v_add_u32_e32 v170, 0x3000000, v1
	global_load_dwordx4 v[40:43], v170, s[4:5] nt
	global_load_dwordx4 v[44:47], v170, s[4:5] offset:1024 nt
	global_load_dwordx4 v[48:51], v170, s[4:5] offset:2048 nt
	global_load_dwordx4 v[52:55], v170, s[4:5] offset:3072 nt
	s_waitcnt vmcnt(33)
	v_add_f32_e32 v180, v56, v57
	v_add_f32_e32 v181, v60, v61
	v_add_f32_e32 v182, v64, v65
	v_add_f32_e32 v183, v68, v69
	v_add_f32_e32 v180, v180, v58
	v_add_f32_e32 v181, v181, v62
	v_add_f32_e32 v182, v182, v66
	v_add_f32_e32 v183, v183, v70
	v_add_f32_e32 v180, v180, v59
	v_add_f32_e32 v181, v181, v63
	v_add_f32_e32 v182, v182, v67
	v_add_f32_e32 v183, v183, v71
	v_add_f32_e32 v180, v180, v181
	v_add_f32_e32 v182, v182, v183
	v_add_f32_e32 v180, v180, v182
	s_nop 1
	v_add_f32_dpp v180, v180, v180 quad_perm:[1,0,3,2] row_mask:0xf bank_mask:0xf
	s_nop 1
	v_add_f32_dpp v180, v180, v180 quad_perm:[2,3,0,1] row_mask:0xf bank_mask:0xf
	s_nop 1
	v_add_f32_dpp v180, v180, v180 row_half_mirror row_mask:0xf bank_mask:0xf
	s_nop 1
	v_add_f32_dpp v180, v180, v180 row_mirror row_mask:0xf bank_mask:0xf
	s_nop 1
	v_add_f32_dpp v180, v180, v180 row_bcast:15 row_mask:0xa bank_mask:0xf
	s_nop 1
	v_add_f32_dpp v180, v180, v180 row_bcast:31 row_mask:0xc bank_mask:0xf
	s_nop 0
	v_readlane_b32 s20, v180, 63
	s_nop 1
	v_mul_f32_e32 v184, s20, v2
	v_sub_f32_e32 v56, v56, v184
	v_sub_f32_e32 v57, v57, v184
	v_sub_f32_e32 v58, v58, v184
	v_sub_f32_e32 v59, v59, v184
	v_sub_f32_e32 v60, v60, v184
	v_sub_f32_e32 v61, v61, v184
	v_sub_f32_e32 v62, v62, v184
	v_sub_f32_e32 v63, v63, v184
	v_sub_f32_e32 v64, v64, v184
	v_sub_f32_e32 v65, v65, v184
	v_sub_f32_e32 v66, v66, v184
	v_sub_f32_e32 v67, v67, v184
	v_sub_f32_e32 v68, v68, v184
	v_sub_f32_e32 v69, v69, v184
	v_sub_f32_e32 v70, v70, v184
	v_sub_f32_e32 v71, v71, v184
	v_mul_f32_e32 v180, v56, v56
	v_mul_f32_e32 v181, v60, v60
	v_mul_f32_e32 v182, v64, v64
	v_mul_f32_e32 v183, v68, v68
	v_fmac_f32_e32 v180, v57, v57
	v_fmac_f32_e32 v181, v61, v61
	v_fmac_f32_e32 v182, v65, v65
	v_fmac_f32_e32 v183, v69, v69
	v_fmac_f32_e32 v180, v58, v58
	v_fmac_f32_e32 v181, v62, v62
	v_fmac_f32_e32 v182, v66, v66
	v_fmac_f32_e32 v183, v70, v70
	v_fmac_f32_e32 v180, v59, v59
	v_fmac_f32_e32 v181, v63, v63
	v_fmac_f32_e32 v182, v67, v67
	v_fmac_f32_e32 v183, v71, v71
	v_add_f32_e32 v180, v180, v181
	v_add_f32_e32 v182, v182, v183
	v_add_f32_e32 v180, v180, v182
	s_nop 1
	v_add_f32_dpp v180, v180, v180 quad_perm:[1,0,3,2] row_mask:0xf bank_mask:0xf
	s_nop 1
	v_add_f32_dpp v180, v180, v180 quad_perm:[2,3,0,1] row_mask:0xf bank_mask:0xf
	s_nop 1
	v_add_f32_dpp v180, v180, v180 row_half_mirror row_mask:0xf bank_mask:0xf
	s_nop 1
	v_add_f32_dpp v180, v180, v180 row_mirror row_mask:0xf bank_mask:0xf
	s_nop 1
	v_add_f32_dpp v180, v180, v180 row_bcast:15 row_mask:0xa bank_mask:0xf
	s_nop 1
	v_add_f32_dpp v180, v180, v180 row_bcast:31 row_mask:0xc bank_mask:0xf
	s_nop 0
	v_readlane_b32 s20, v180, 63
	s_nop 1
	v_mov_b32_e32 v185, s20
	v_fma_f32 v185, v185, v2, v4
	v_rsq_f32_e32 v185, v185
	s_nop 0
	v_mul_f32_e32 v56, v56, v185
	v_mul_f32_e32 v57, v57, v185
	v_mul_f32_e32 v58, v58, v185
	v_mul_f32_e32 v59, v59, v185
	v_mul_f32_e32 v60, v60, v185
	v_mul_f32_e32 v61, v61, v185
	v_mul_f32_e32 v62, v62, v185
	v_mul_f32_e32 v63, v63, v185
	v_mul_f32_e32 v64, v64, v185
	v_mul_f32_e32 v65, v65, v185
	v_mul_f32_e32 v66, v66, v185
	v_mul_f32_e32 v67, v67, v185
	v_mul_f32_e32 v68, v68, v185
	v_mul_f32_e32 v69, v69, v185
	v_mul_f32_e32 v70, v70, v185
	v_mul_f32_e32 v71, v71, v185
	v_fma_f32 v56, v56, v8, v24
	v_fma_f32 v57, v57, v9, v25
	v_fma_f32 v58, v58, v10, v26
	v_fma_f32 v59, v59, v11, v27
	v_fma_f32 v60, v60, v12, v28
	v_fma_f32 v61, v61, v13, v29
	v_fma_f32 v62, v62, v14, v30
	v_fma_f32 v63, v63, v15, v31
	v_fma_f32 v64, v64, v16, v32
	v_fma_f32 v65, v65, v17, v33
	v_fma_f32 v66, v66, v18, v34
	v_fma_f32 v67, v67, v19, v35
	v_fma_f32 v68, v68, v20, v36
	v_fma_f32 v69, v69, v21, v37
	v_fma_f32 v70, v70, v22, v38
	v_fma_f32 v71, v71, v23, v39
	v_cvt_pk_bf16_f32 v56, v56, v57
	v_cvt_pk_bf16_f32 v57, v58, v59
	v_cvt_pk_bf16_f32 v60, v60, v61
	v_cvt_pk_bf16_f32 v61, v62, v63
	v_cvt_pk_bf16_f32 v64, v64, v65
	v_cvt_pk_bf16_f32 v65, v66, v67
	v_cvt_pk_bf16_f32 v68, v68, v69
	v_cvt_pk_bf16_f32 v69, v70, v71
	v_add_u32_e32 v171, 0x300000, v5
	global_store_dwordx2 v171, v[56:57], s[8:9]
	global_store_dwordx2 v171, v[60:61], s[8:9] offset:512
	global_store_dwordx2 v171, v[64:65], s[8:9] offset:1024
	global_store_dwordx2 v171, v[68:69], s[8:9] offset:1536
	v_mov_b32_e32 v172, 0x3000
	s_mov_b64 exec, 1
	global_store_dwordx2 v172, v[184:185], s[38:39]
	s_mov_b64 exec, -1
	s_nop 1
	v_add_u32_e32 v170, 0x3600000, v1
	global_load_dwordx4 v[56:59], v170, s[4:5] nt
	global_load_dwordx4 v[60:63], v170, s[4:5] offset:1024 nt
	global_load_dwordx4 v[64:67], v170, s[4:5] offset:2048 nt
	global_load_dwordx4 v[68:71], v170, s[4:5] offset:3072 nt
	s_waitcnt vmcnt(38)
	v_add_f32_e32 v180, v72, v73
	v_add_f32_e32 v181, v76, v77
	v_add_f32_e32 v182, v80, v81
	v_add_f32_e32 v183, v84, v85
	v_add_f32_e32 v180, v180, v74
	v_add_f32_e32 v181, v181, v78
	v_add_f32_e32 v182, v182, v82
	v_add_f32_e32 v183, v183, v86
	v_add_f32_e32 v180, v180, v75
	v_add_f32_e32 v181, v181, v79
	v_add_f32_e32 v182, v182, v83
	v_add_f32_e32 v183, v183, v87
	v_add_f32_e32 v180, v180, v181
	v_add_f32_e32 v182, v182, v183
	v_add_f32_e32 v180, v180, v182
	s_nop 1
	v_add_f32_dpp v180, v180, v180 quad_perm:[1,0,3,2] row_mask:0xf bank_mask:0xf
	s_nop 1
	v_add_f32_dpp v180, v180, v180 quad_perm:[2,3,0,1] row_mask:0xf bank_mask:0xf
	s_nop 1
	v_add_f32_dpp v180, v180, v180 row_half_mirror row_mask:0xf bank_mask:0xf
	s_nop 1
	v_add_f32_dpp v180, v180, v180 row_mirror row_mask:0xf bank_mask:0xf
	s_nop 1
	v_add_f32_dpp v180, v180, v180 row_bcast:15 row_mask:0xa bank_mask:0xf
	s_nop 1
	v_add_f32_dpp v180, v180, v180 row_bcast:31 row_mask:0xc bank_mask:0xf
	s_nop 0
	v_readlane_b32 s20, v180, 63
	s_nop 1
	v_mul_f32_e32 v184, s20, v2
	v_sub_f32_e32 v72, v72, v184
	v_sub_f32_e32 v73, v73, v184
	v_sub_f32_e32 v74, v74, v184
	v_sub_f32_e32 v75, v75, v184
	v_sub_f32_e32 v76, v76, v184
	v_sub_f32_e32 v77, v77, v184
	v_sub_f32_e32 v78, v78, v184
	v_sub_f32_e32 v79, v79, v184
	v_sub_f32_e32 v80, v80, v184
	v_sub_f32_e32 v81, v81, v184
	v_sub_f32_e32 v82, v82, v184
	v_sub_f32_e32 v83, v83, v184
	v_sub_f32_e32 v84, v84, v184
	v_sub_f32_e32 v85, v85, v184
	v_sub_f32_e32 v86, v86, v184
	v_sub_f32_e32 v87, v87, v184
	v_mul_f32_e32 v180, v72, v72
	v_mul_f32_e32 v181, v76, v76
	v_mul_f32_e32 v182, v80, v80
	v_mul_f32_e32 v183, v84, v84
	v_fmac_f32_e32 v180, v73, v73
	v_fmac_f32_e32 v181, v77, v77
	v_fmac_f32_e32 v182, v81, v81
	v_fmac_f32_e32 v183, v85, v85
	v_fmac_f32_e32 v180, v74, v74
	v_fmac_f32_e32 v181, v78, v78
	v_fmac_f32_e32 v182, v82, v82
	v_fmac_f32_e32 v183, v86, v86
	v_fmac_f32_e32 v180, v75, v75
	v_fmac_f32_e32 v181, v79, v79
	v_fmac_f32_e32 v182, v83, v83
	v_fmac_f32_e32 v183, v87, v87
	v_add_f32_e32 v180, v180, v181
	v_add_f32_e32 v182, v182, v183
	v_add_f32_e32 v180, v180, v182
	s_nop 1
	v_add_f32_dpp v180, v180, v180 quad_perm:[1,0,3,2] row_mask:0xf bank_mask:0xf
	s_nop 1
	v_add_f32_dpp v180, v180, v180 quad_perm:[2,3,0,1] row_mask:0xf bank_mask:0xf
	s_nop 1
	v_add_f32_dpp v180, v180, v180 row_half_mirror row_mask:0xf bank_mask:0xf
	s_nop 1
	v_add_f32_dpp v180, v180, v180 row_mirror row_mask:0xf bank_mask:0xf
	s_nop 1
	v_add_f32_dpp v180, v180, v180 row_bcast:15 row_mask:0xa bank_mask:0xf
	s_nop 1
	v_add_f32_dpp v180, v180, v180 row_bcast:31 row_mask:0xc bank_mask:0xf
	s_nop 0
	v_readlane_b32 s20, v180, 63
	s_nop 1
	v_mov_b32_e32 v185, s20
	v_fma_f32 v185, v185, v2, v4
	v_rsq_f32_e32 v185, v185
	s_nop 0
	v_mul_f32_e32 v72, v72, v185
	v_mul_f32_e32 v73, v73, v185
	v_mul_f32_e32 v74, v74, v185
	v_mul_f32_e32 v75, v75, v185
	v_mul_f32_e32 v76, v76, v185
	v_mul_f32_e32 v77, v77, v185
	v_mul_f32_e32 v78, v78, v185
	v_mul_f32_e32 v79, v79, v185
	v_mul_f32_e32 v80, v80, v185
	v_mul_f32_e32 v81, v81, v185
	v_mul_f32_e32 v82, v82, v185
	v_mul_f32_e32 v83, v83, v185
	v_mul_f32_e32 v84, v84, v185
	v_mul_f32_e32 v85, v85, v185
	v_mul_f32_e32 v86, v86, v185
	v_mul_f32_e32 v87, v87, v185
	v_fma_f32 v72, v72, v8, v24
	v_fma_f32 v73, v73, v9, v25
	v_fma_f32 v74, v74, v10, v26
	v_fma_f32 v75, v75, v11, v27
	v_fma_f32 v76, v76, v12, v28
	v_fma_f32 v77, v77, v13, v29
	v_fma_f32 v78, v78, v14, v30
	v_fma_f32 v79, v79, v15, v31
	v_fma_f32 v80, v80, v16, v32
	v_fma_f32 v81, v81, v17, v33
	v_fma_f32 v82, v82, v18, v34
	v_fma_f32 v83, v83, v19, v35
	v_fma_f32 v84, v84, v20, v36
	v_fma_f32 v85, v85, v21, v37
	v_fma_f32 v86, v86, v22, v38
	v_fma_f32 v87, v87, v23, v39
	v_cvt_pk_bf16_f32 v72, v72, v73
	v_cvt_pk_bf16_f32 v73, v74, v75
	v_cvt_pk_bf16_f32 v76, v76, v77
	v_cvt_pk_bf16_f32 v77, v78, v79
	v_cvt_pk_bf16_f32 v80, v80, v81
	v_cvt_pk_bf16_f32 v81, v82, v83
	v_cvt_pk_bf16_f32 v84, v84, v85
	v_cvt_pk_bf16_f32 v85, v86, v87
	v_add_u32_e32 v171, 0x600000, v5
	global_store_dwordx2 v171, v[72:73], s[8:9]
	global_store_dwordx2 v171, v[76:77], s[8:9] offset:512
	global_store_dwordx2 v171, v[80:81], s[8:9] offset:1024
	global_store_dwordx2 v171, v[84:85], s[8:9] offset:1536
	v_mov_b32_e32 v172, 0x6000
	s_mov_b64 exec, 1
	global_store_dwordx2 v172, v[184:185], s[38:39]
	s_mov_b64 exec, -1
	s_waitcnt vmcnt(39)
	v_add_f32_e32 v180, v88, v89
	v_add_f32_e32 v181, v92, v93
	v_add_f32_e32 v182, v96, v97
	v_add_f32_e32 v183, v100, v101
	v_add_f32_e32 v180, v180, v90
	v_add_f32_e32 v181, v181, v94
	v_add_f32_e32 v182, v182, v98
	v_add_f32_e32 v183, v183, v102
	v_add_f32_e32 v180, v180, v91
	v_add_f32_e32 v181, v181, v95
	v_add_f32_e32 v182, v182, v99
	v_add_f32_e32 v183, v183, v103
	v_add_f32_e32 v180, v180, v181
	v_add_f32_e32 v182, v182, v183
	v_add_f32_e32 v180, v180, v182
	s_nop 1
	v_add_f32_dpp v180, v180, v180 quad_perm:[1,0,3,2] row_mask:0xf bank_mask:0xf
	s_nop 1
	v_add_f32_dpp v180, v180, v180 quad_perm:[2,3,0,1] row_mask:0xf bank_mask:0xf
	s_nop 1
	v_add_f32_dpp v180, v180, v180 row_half_mirror row_mask:0xf bank_mask:0xf
	s_nop 1
	v_add_f32_dpp v180, v180, v180 row_mirror row_mask:0xf bank_mask:0xf
	s_nop 1
	v_add_f32_dpp v180, v180, v180 row_bcast:15 row_mask:0xa bank_mask:0xf
	s_nop 1
	v_add_f32_dpp v180, v180, v180 row_bcast:31 row_mask:0xc bank_mask:0xf
	s_nop 0
	v_readlane_b32 s20, v180, 63
	s_nop 1
	v_mul_f32_e32 v184, s20, v2
	v_sub_f32_e32 v88, v88, v184
	v_sub_f32_e32 v89, v89, v184
	v_sub_f32_e32 v90, v90, v184
	v_sub_f32_e32 v91, v91, v184
	v_sub_f32_e32 v92, v92, v184
	v_sub_f32_e32 v93, v93, v184
	v_sub_f32_e32 v94, v94, v184
	v_sub_f32_e32 v95, v95, v184
	v_sub_f32_e32 v96, v96, v184
	v_sub_f32_e32 v97, v97, v184
	v_sub_f32_e32 v98, v98, v184
	v_sub_f32_e32 v99, v99, v184
	v_sub_f32_e32 v100, v100, v184
	v_sub_f32_e32 v101, v101, v184
	v_sub_f32_e32 v102, v102, v184
	v_sub_f32_e32 v103, v103, v184
	v_mul_f32_e32 v180, v88, v88
	v_mul_f32_e32 v181, v92, v92
	v_mul_f32_e32 v182, v96, v96
	v_mul_f32_e32 v183, v100, v100
	v_fmac_f32_e32 v180, v89, v89
	v_fmac_f32_e32 v181, v93, v93
	v_fmac_f32_e32 v182, v97, v97
	v_fmac_f32_e32 v183, v101, v101
	v_fmac_f32_e32 v180, v90, v90
	v_fmac_f32_e32 v181, v94, v94
	v_fmac_f32_e32 v182, v98, v98
	v_fmac_f32_e32 v183, v102, v102
	v_fmac_f32_e32 v180, v91, v91
	v_fmac_f32_e32 v181, v95, v95
	v_fmac_f32_e32 v182, v99, v99
	v_fmac_f32_e32 v183, v103, v103
	v_add_f32_e32 v180, v180, v181
	v_add_f32_e32 v182, v182, v183
	v_add_f32_e32 v180, v180, v182
	s_nop 1
	v_add_f32_dpp v180, v180, v180 quad_perm:[1,0,3,2] row_mask:0xf bank_mask:0xf
	s_nop 1
	v_add_f32_dpp v180, v180, v180 quad_perm:[2,3,0,1] row_mask:0xf bank_mask:0xf
	s_nop 1
	v_add_f32_dpp v180, v180, v180 row_half_mirror row_mask:0xf bank_mask:0xf
	s_nop 1
	v_add_f32_dpp v180, v180, v180 row_mirror row_mask:0xf bank_mask:0xf
	s_nop 1
	v_add_f32_dpp v180, v180, v180 row_bcast:15 row_mask:0xa bank_mask:0xf
	s_nop 1
	v_add_f32_dpp v180, v180, v180 row_bcast:31 row_mask:0xc bank_mask:0xf
	s_nop 0
	v_readlane_b32 s20, v180, 63
	s_nop 1
	v_mov_b32_e32 v185, s20
	v_fma_f32 v185, v185, v2, v4
	v_rsq_f32_e32 v185, v185
	s_nop 0
	v_mul_f32_e32 v88, v88, v185
	v_mul_f32_e32 v89, v89, v185
	v_mul_f32_e32 v90, v90, v185
	v_mul_f32_e32 v91, v91, v185
	v_mul_f32_e32 v92, v92, v185
	v_mul_f32_e32 v93, v93, v185
	v_mul_f32_e32 v94, v94, v185
	v_mul_f32_e32 v95, v95, v185
	v_mul_f32_e32 v96, v96, v185
	v_mul_f32_e32 v97, v97, v185
	v_mul_f32_e32 v98, v98, v185
	v_mul_f32_e32 v99, v99, v185
	v_mul_f32_e32 v100, v100, v185
	v_mul_f32_e32 v101, v101, v185
	v_mul_f32_e32 v102, v102, v185
	v_mul_f32_e32 v103, v103, v185
	v_fma_f32 v88, v88, v8, v24
	v_fma_f32 v89, v89, v9, v25
	v_fma_f32 v90, v90, v10, v26
	v_fma_f32 v91, v91, v11, v27
	v_fma_f32 v92, v92, v12, v28
	v_fma_f32 v93, v93, v13, v29
	v_fma_f32 v94, v94, v14, v30
	v_fma_f32 v95, v95, v15, v31
	v_fma_f32 v96, v96, v16, v32
	v_fma_f32 v97, v97, v17, v33
	v_fma_f32 v98, v98, v18, v34
	v_fma_f32 v99, v99, v19, v35
	v_fma_f32 v100, v100, v20, v36
	v_fma_f32 v101, v101, v21, v37
	v_fma_f32 v102, v102, v22, v38
	v_fma_f32 v103, v103, v23, v39
	v_cvt_pk_bf16_f32 v88, v88, v89
	v_cvt_pk_bf16_f32 v89, v90, v91
	v_cvt_pk_bf16_f32 v92, v92, v93
	v_cvt_pk_bf16_f32 v93, v94, v95
	v_cvt_pk_bf16_f32 v96, v96, v97
	v_cvt_pk_bf16_f32 v97, v98, v99
	v_cvt_pk_bf16_f32 v100, v100, v101
	v_cvt_pk_bf16_f32 v101, v102, v103
	v_add_u32_e32 v171, 0x900000, v5
	global_store_dwordx2 v171, v[88:89], s[8:9]
	global_store_dwordx2 v171, v[92:93], s[8:9] offset:512
	global_store_dwordx2 v171, v[96:97], s[8:9] offset:1024
	global_store_dwordx2 v171, v[100:101], s[8:9] offset:1536
	v_mov_b32_e32 v172, 0x9000
	s_mov_b64 exec, 1
	global_store_dwordx2 v172, v[184:185], s[38:39]
	s_mov_b64 exec, -1
	s_waitcnt vmcnt(40)
	v_add_f32_e32 v180, v104, v105
	v_add_f32_e32 v181, v108, v109
	v_add_f32_e32 v182, v112, v113
	v_add_f32_e32 v183, v116, v117
	v_add_f32_e32 v180, v180, v106
	v_add_f32_e32 v181, v181, v110
	v_add_f32_e32 v182, v182, v114
	v_add_f32_e32 v183, v183, v118
	v_add_f32_e32 v180, v180, v107
	v_add_f32_e32 v181, v181, v111
	v_add_f32_e32 v182, v182, v115
	v_add_f32_e32 v183, v183, v119
	v_add_f32_e32 v180, v180, v181
	v_add_f32_e32 v182, v182, v183
	v_add_f32_e32 v180, v180, v182
	s_nop 1
	v_add_f32_dpp v180, v180, v180 quad_perm:[1,0,3,2] row_mask:0xf bank_mask:0xf
	s_nop 1
	v_add_f32_dpp v180, v180, v180 quad_perm:[2,3,0,1] row_mask:0xf bank_mask:0xf
	s_nop 1
	v_add_f32_dpp v180, v180, v180 row_half_mirror row_mask:0xf bank_mask:0xf
	s_nop 1
	v_add_f32_dpp v180, v180, v180 row_mirror row_mask:0xf bank_mask:0xf
	s_nop 1
	v_add_f32_dpp v180, v180, v180 row_bcast:15 row_mask:0xa bank_mask:0xf
	s_nop 1
	v_add_f32_dpp v180, v180, v180 row_bcast:31 row_mask:0xc bank_mask:0xf
	s_nop 0
	v_readlane_b32 s20, v180, 63
	s_nop 1
	v_mul_f32_e32 v184, s20, v2
	v_sub_f32_e32 v104, v104, v184
	v_sub_f32_e32 v105, v105, v184
	v_sub_f32_e32 v106, v106, v184
	v_sub_f32_e32 v107, v107, v184
	v_sub_f32_e32 v108, v108, v184
	v_sub_f32_e32 v109, v109, v184
	v_sub_f32_e32 v110, v110, v184
	v_sub_f32_e32 v111, v111, v184
	v_sub_f32_e32 v112, v112, v184
	v_sub_f32_e32 v113, v113, v184
	v_sub_f32_e32 v114, v114, v184
	v_sub_f32_e32 v115, v115, v184
	v_sub_f32_e32 v116, v116, v184
	v_sub_f32_e32 v117, v117, v184
	v_sub_f32_e32 v118, v118, v184
	v_sub_f32_e32 v119, v119, v184
	v_mul_f32_e32 v180, v104, v104
	v_mul_f32_e32 v181, v108, v108
	v_mul_f32_e32 v182, v112, v112
	v_mul_f32_e32 v183, v116, v116
	v_fmac_f32_e32 v180, v105, v105
	v_fmac_f32_e32 v181, v109, v109
	v_fmac_f32_e32 v182, v113, v113
	v_fmac_f32_e32 v183, v117, v117
	v_fmac_f32_e32 v180, v106, v106
	v_fmac_f32_e32 v181, v110, v110
	v_fmac_f32_e32 v182, v114, v114
	v_fmac_f32_e32 v183, v118, v118
	v_fmac_f32_e32 v180, v107, v107
	v_fmac_f32_e32 v181, v111, v111
	v_fmac_f32_e32 v182, v115, v115
	v_fmac_f32_e32 v183, v119, v119
	v_add_f32_e32 v180, v180, v181
	v_add_f32_e32 v182, v182, v183
	v_add_f32_e32 v180, v180, v182
	s_nop 1
	v_add_f32_dpp v180, v180, v180 quad_perm:[1,0,3,2] row_mask:0xf bank_mask:0xf
	s_nop 1
	v_add_f32_dpp v180, v180, v180 quad_perm:[2,3,0,1] row_mask:0xf bank_mask:0xf
	s_nop 1
	v_add_f32_dpp v180, v180, v180 row_half_mirror row_mask:0xf bank_mask:0xf
	s_nop 1
	v_add_f32_dpp v180, v180, v180 row_mirror row_mask:0xf bank_mask:0xf
	s_nop 1
	v_add_f32_dpp v180, v180, v180 row_bcast:15 row_mask:0xa bank_mask:0xf
	s_nop 1
	v_add_f32_dpp v180, v180, v180 row_bcast:31 row_mask:0xc bank_mask:0xf
	s_nop 0
	v_readlane_b32 s20, v180, 63
	s_nop 1
	v_mov_b32_e32 v185, s20
	v_fma_f32 v185, v185, v2, v4
	v_rsq_f32_e32 v185, v185
	s_nop 0
	v_mul_f32_e32 v104, v104, v185
	v_mul_f32_e32 v105, v105, v185
	v_mul_f32_e32 v106, v106, v185
	v_mul_f32_e32 v107, v107, v185
	v_mul_f32_e32 v108, v108, v185
	v_mul_f32_e32 v109, v109, v185
	v_mul_f32_e32 v110, v110, v185
	v_mul_f32_e32 v111, v111, v185
	v_mul_f32_e32 v112, v112, v185
	v_mul_f32_e32 v113, v113, v185
	v_mul_f32_e32 v114, v114, v185
	v_mul_f32_e32 v115, v115, v185
	v_mul_f32_e32 v116, v116, v185
	v_mul_f32_e32 v117, v117, v185
	v_mul_f32_e32 v118, v118, v185
	v_mul_f32_e32 v119, v119, v185
	v_fma_f32 v104, v104, v8, v24
	v_fma_f32 v105, v105, v9, v25
	v_fma_f32 v106, v106, v10, v26
	v_fma_f32 v107, v107, v11, v27
	v_fma_f32 v108, v108, v12, v28
	v_fma_f32 v109, v109, v13, v29
	v_fma_f32 v110, v110, v14, v30
	v_fma_f32 v111, v111, v15, v31
	v_fma_f32 v112, v112, v16, v32
	v_fma_f32 v113, v113, v17, v33
	v_fma_f32 v114, v114, v18, v34
	v_fma_f32 v115, v115, v19, v35
	v_fma_f32 v116, v116, v20, v36
	v_fma_f32 v117, v117, v21, v37
	v_fma_f32 v118, v118, v22, v38
	v_fma_f32 v119, v119, v23, v39
	v_cvt_pk_bf16_f32 v104, v104, v105
	v_cvt_pk_bf16_f32 v105, v106, v107
	v_cvt_pk_bf16_f32 v108, v108, v109
	v_cvt_pk_bf16_f32 v109, v110, v111
	v_cvt_pk_bf16_f32 v112, v112, v113
	v_cvt_pk_bf16_f32 v113, v114, v115
	v_cvt_pk_bf16_f32 v116, v116, v117
	v_cvt_pk_bf16_f32 v117, v118, v119
	v_add_u32_e32 v171, 0xc00000, v5
	global_store_dwordx2 v171, v[104:105], s[8:9]
	global_store_dwordx2 v171, v[108:109], s[8:9] offset:512
	global_store_dwordx2 v171, v[112:113], s[8:9] offset:1024
	global_store_dwordx2 v171, v[116:117], s[8:9] offset:1536
	v_mov_b32_e32 v172, 0xc000
	s_mov_b64 exec, 1
	global_store_dwordx2 v172, v[184:185], s[38:39]
	s_mov_b64 exec, -1
	s_waitcnt vmcnt(41)
	v_add_f32_e32 v180, v120, v121
	v_add_f32_e32 v181, v124, v125
	v_add_f32_e32 v182, v128, v129
	v_add_f32_e32 v183, v132, v133
	v_add_f32_e32 v180, v180, v122
	v_add_f32_e32 v181, v181, v126
	v_add_f32_e32 v182, v182, v130
	v_add_f32_e32 v183, v183, v134
	v_add_f32_e32 v180, v180, v123
	v_add_f32_e32 v181, v181, v127
	v_add_f32_e32 v182, v182, v131
	v_add_f32_e32 v183, v183, v135
	v_add_f32_e32 v180, v180, v181
	v_add_f32_e32 v182, v182, v183
	v_add_f32_e32 v180, v180, v182
	s_nop 1
	v_add_f32_dpp v180, v180, v180 quad_perm:[1,0,3,2] row_mask:0xf bank_mask:0xf
	s_nop 1
	v_add_f32_dpp v180, v180, v180 quad_perm:[2,3,0,1] row_mask:0xf bank_mask:0xf
	s_nop 1
	v_add_f32_dpp v180, v180, v180 row_half_mirror row_mask:0xf bank_mask:0xf
	s_nop 1
	v_add_f32_dpp v180, v180, v180 row_mirror row_mask:0xf bank_mask:0xf
	s_nop 1
	v_add_f32_dpp v180, v180, v180 row_bcast:15 row_mask:0xa bank_mask:0xf
	s_nop 1
	v_add_f32_dpp v180, v180, v180 row_bcast:31 row_mask:0xc bank_mask:0xf
	s_nop 0
	v_readlane_b32 s20, v180, 63
	s_nop 1
	v_mul_f32_e32 v184, s20, v2
	v_sub_f32_e32 v120, v120, v184
	v_sub_f32_e32 v121, v121, v184
	v_sub_f32_e32 v122, v122, v184
	v_sub_f32_e32 v123, v123, v184
	v_sub_f32_e32 v124, v124, v184
	v_sub_f32_e32 v125, v125, v184
	v_sub_f32_e32 v126, v126, v184
	v_sub_f32_e32 v127, v127, v184
	v_sub_f32_e32 v128, v128, v184
	v_sub_f32_e32 v129, v129, v184
	v_sub_f32_e32 v130, v130, v184
	v_sub_f32_e32 v131, v131, v184
	v_sub_f32_e32 v132, v132, v184
	v_sub_f32_e32 v133, v133, v184
	v_sub_f32_e32 v134, v134, v184
	v_sub_f32_e32 v135, v135, v184
	v_mul_f32_e32 v180, v120, v120
	v_mul_f32_e32 v181, v124, v124
	v_mul_f32_e32 v182, v128, v128
	v_mul_f32_e32 v183, v132, v132
	v_fmac_f32_e32 v180, v121, v121
	v_fmac_f32_e32 v181, v125, v125
	v_fmac_f32_e32 v182, v129, v129
	v_fmac_f32_e32 v183, v133, v133
	v_fmac_f32_e32 v180, v122, v122
	v_fmac_f32_e32 v181, v126, v126
	v_fmac_f32_e32 v182, v130, v130
	v_fmac_f32_e32 v183, v134, v134
	v_fmac_f32_e32 v180, v123, v123
	v_fmac_f32_e32 v181, v127, v127
	v_fmac_f32_e32 v182, v131, v131
	v_fmac_f32_e32 v183, v135, v135
	v_add_f32_e32 v180, v180, v181
	v_add_f32_e32 v182, v182, v183
	v_add_f32_e32 v180, v180, v182
	s_nop 1
	v_add_f32_dpp v180, v180, v180 quad_perm:[1,0,3,2] row_mask:0xf bank_mask:0xf
	s_nop 1
	v_add_f32_dpp v180, v180, v180 quad_perm:[2,3,0,1] row_mask:0xf bank_mask:0xf
	s_nop 1
	v_add_f32_dpp v180, v180, v180 row_half_mirror row_mask:0xf bank_mask:0xf
	s_nop 1
	v_add_f32_dpp v180, v180, v180 row_mirror row_mask:0xf bank_mask:0xf
	s_nop 1
	v_add_f32_dpp v180, v180, v180 row_bcast:15 row_mask:0xa bank_mask:0xf
	s_nop 1
	v_add_f32_dpp v180, v180, v180 row_bcast:31 row_mask:0xc bank_mask:0xf
	s_nop 0
	v_readlane_b32 s20, v180, 63
	s_nop 1
	v_mov_b32_e32 v185, s20
	v_fma_f32 v185, v185, v2, v4
	v_rsq_f32_e32 v185, v185
	s_nop 0
	v_mul_f32_e32 v120, v120, v185
	v_mul_f32_e32 v121, v121, v185
	v_mul_f32_e32 v122, v122, v185
	v_mul_f32_e32 v123, v123, v185
	v_mul_f32_e32 v124, v124, v185
	v_mul_f32_e32 v125, v125, v185
	v_mul_f32_e32 v126, v126, v185
	v_mul_f32_e32 v127, v127, v185
	v_mul_f32_e32 v128, v128, v185
	v_mul_f32_e32 v129, v129, v185
	v_mul_f32_e32 v130, v130, v185
	v_mul_f32_e32 v131, v131, v185
	v_mul_f32_e32 v132, v132, v185
	v_mul_f32_e32 v133, v133, v185
	v_mul_f32_e32 v134, v134, v185
	v_mul_f32_e32 v135, v135, v185
	v_fma_f32 v120, v120, v8, v24
	v_fma_f32 v121, v121, v9, v25
	v_fma_f32 v122, v122, v10, v26
	v_fma_f32 v123, v123, v11, v27
	v_fma_f32 v124, v124, v12, v28
	v_fma_f32 v125, v125, v13, v29
	v_fma_f32 v126, v126, v14, v30
	v_fma_f32 v127, v127, v15, v31
	v_fma_f32 v128, v128, v16, v32
	v_fma_f32 v129, v129, v17, v33
	v_fma_f32 v130, v130, v18, v34
	v_fma_f32 v131, v131, v19, v35
	v_fma_f32 v132, v132, v20, v36
	v_fma_f32 v133, v133, v21, v37
	v_fma_f32 v134, v134, v22, v38
	v_fma_f32 v135, v135, v23, v39
	v_cvt_pk_bf16_f32 v120, v120, v121
	v_cvt_pk_bf16_f32 v121, v122, v123
	v_cvt_pk_bf16_f32 v124, v124, v125
	v_cvt_pk_bf16_f32 v125, v126, v127
	v_cvt_pk_bf16_f32 v128, v128, v129
	v_cvt_pk_bf16_f32 v129, v130, v131
	v_cvt_pk_bf16_f32 v132, v132, v133
	v_cvt_pk_bf16_f32 v133, v134, v135
	v_add_u32_e32 v171, 0xf00000, v5
	global_store_dwordx2 v171, v[120:121], s[8:9]
	global_store_dwordx2 v171, v[124:125], s[8:9] offset:512
	global_store_dwordx2 v171, v[128:129], s[8:9] offset:1024
	global_store_dwordx2 v171, v[132:133], s[8:9] offset:1536
	v_mov_b32_e32 v172, 0xf000
	s_mov_b64 exec, 1
	global_store_dwordx2 v172, v[184:185], s[38:39]
	s_mov_b64 exec, -1
	s_waitcnt vmcnt(42)
	v_add_f32_e32 v180, v136, v137
	v_add_f32_e32 v181, v140, v141
	v_add_f32_e32 v182, v144, v145
	v_add_f32_e32 v183, v148, v149
	v_add_f32_e32 v180, v180, v138
	v_add_f32_e32 v181, v181, v142
	v_add_f32_e32 v182, v182, v146
	v_add_f32_e32 v183, v183, v150
	v_add_f32_e32 v180, v180, v139
	v_add_f32_e32 v181, v181, v143
	v_add_f32_e32 v182, v182, v147
	v_add_f32_e32 v183, v183, v151
	v_add_f32_e32 v180, v180, v181
	v_add_f32_e32 v182, v182, v183
	v_add_f32_e32 v180, v180, v182
	s_nop 1
	v_add_f32_dpp v180, v180, v180 quad_perm:[1,0,3,2] row_mask:0xf bank_mask:0xf
	s_nop 1
	v_add_f32_dpp v180, v180, v180 quad_perm:[2,3,0,1] row_mask:0xf bank_mask:0xf
	s_nop 1
	v_add_f32_dpp v180, v180, v180 row_half_mirror row_mask:0xf bank_mask:0xf
	s_nop 1
	v_add_f32_dpp v180, v180, v180 row_mirror row_mask:0xf bank_mask:0xf
	s_nop 1
	v_add_f32_dpp v180, v180, v180 row_bcast:15 row_mask:0xa bank_mask:0xf
	s_nop 1
	v_add_f32_dpp v180, v180, v180 row_bcast:31 row_mask:0xc bank_mask:0xf
	s_nop 0
	v_readlane_b32 s20, v180, 63
	s_nop 1
	v_mul_f32_e32 v184, s20, v2
	v_sub_f32_e32 v136, v136, v184
	v_sub_f32_e32 v137, v137, v184
	v_sub_f32_e32 v138, v138, v184
	v_sub_f32_e32 v139, v139, v184
	v_sub_f32_e32 v140, v140, v184
	v_sub_f32_e32 v141, v141, v184
	v_sub_f32_e32 v142, v142, v184
	v_sub_f32_e32 v143, v143, v184
	v_sub_f32_e32 v144, v144, v184
	v_sub_f32_e32 v145, v145, v184
	v_sub_f32_e32 v146, v146, v184
	v_sub_f32_e32 v147, v147, v184
	v_sub_f32_e32 v148, v148, v184
	v_sub_f32_e32 v149, v149, v184
	v_sub_f32_e32 v150, v150, v184
	v_sub_f32_e32 v151, v151, v184
	v_mul_f32_e32 v180, v136, v136
	v_mul_f32_e32 v181, v140, v140
	v_mul_f32_e32 v182, v144, v144
	v_mul_f32_e32 v183, v148, v148
	v_fmac_f32_e32 v180, v137, v137
	v_fmac_f32_e32 v181, v141, v141
	v_fmac_f32_e32 v182, v145, v145
	v_fmac_f32_e32 v183, v149, v149
	v_fmac_f32_e32 v180, v138, v138
	v_fmac_f32_e32 v181, v142, v142
	v_fmac_f32_e32 v182, v146, v146
	v_fmac_f32_e32 v183, v150, v150
	v_fmac_f32_e32 v180, v139, v139
	v_fmac_f32_e32 v181, v143, v143
	v_fmac_f32_e32 v182, v147, v147
	v_fmac_f32_e32 v183, v151, v151
	v_add_f32_e32 v180, v180, v181
	v_add_f32_e32 v182, v182, v183
	v_add_f32_e32 v180, v180, v182
	s_nop 1
	v_add_f32_dpp v180, v180, v180 quad_perm:[1,0,3,2] row_mask:0xf bank_mask:0xf
	s_nop 1
	v_add_f32_dpp v180, v180, v180 quad_perm:[2,3,0,1] row_mask:0xf bank_mask:0xf
	s_nop 1
	v_add_f32_dpp v180, v180, v180 row_half_mirror row_mask:0xf bank_mask:0xf
	s_nop 1
	v_add_f32_dpp v180, v180, v180 row_mirror row_mask:0xf bank_mask:0xf
	s_nop 1
	v_add_f32_dpp v180, v180, v180 row_bcast:15 row_mask:0xa bank_mask:0xf
	s_nop 1
	v_add_f32_dpp v180, v180, v180 row_bcast:31 row_mask:0xc bank_mask:0xf
	s_nop 0
	v_readlane_b32 s20, v180, 63
	s_nop 1
	v_mov_b32_e32 v185, s20
	v_fma_f32 v185, v185, v2, v4
	v_rsq_f32_e32 v185, v185
	s_nop 0
	v_mul_f32_e32 v136, v136, v185
	v_mul_f32_e32 v137, v137, v185
	v_mul_f32_e32 v138, v138, v185
	v_mul_f32_e32 v139, v139, v185
	v_mul_f32_e32 v140, v140, v185
	v_mul_f32_e32 v141, v141, v185
	v_mul_f32_e32 v142, v142, v185
	v_mul_f32_e32 v143, v143, v185
	v_mul_f32_e32 v144, v144, v185
	v_mul_f32_e32 v145, v145, v185
	v_mul_f32_e32 v146, v146, v185
	v_mul_f32_e32 v147, v147, v185
	v_mul_f32_e32 v148, v148, v185
	v_mul_f32_e32 v149, v149, v185
	v_mul_f32_e32 v150, v150, v185
	v_mul_f32_e32 v151, v151, v185
	v_fma_f32 v136, v136, v8, v24
	v_fma_f32 v137, v137, v9, v25
	v_fma_f32 v138, v138, v10, v26
	v_fma_f32 v139, v139, v11, v27
	v_fma_f32 v140, v140, v12, v28
	v_fma_f32 v141, v141, v13, v29
	v_fma_f32 v142, v142, v14, v30
	v_fma_f32 v143, v143, v15, v31
	v_fma_f32 v144, v144, v16, v32
	v_fma_f32 v145, v145, v17, v33
	v_fma_f32 v146, v146, v18, v34
	v_fma_f32 v147, v147, v19, v35
	v_fma_f32 v148, v148, v20, v36
	v_fma_f32 v149, v149, v21, v37
	v_fma_f32 v150, v150, v22, v38
	v_fma_f32 v151, v151, v23, v39
	v_cvt_pk_bf16_f32 v136, v136, v137
	v_cvt_pk_bf16_f32 v137, v138, v139
	v_cvt_pk_bf16_f32 v140, v140, v141
	v_cvt_pk_bf16_f32 v141, v142, v143
	v_cvt_pk_bf16_f32 v144, v144, v145
	v_cvt_pk_bf16_f32 v145, v146, v147
	v_cvt_pk_bf16_f32 v148, v148, v149
	v_cvt_pk_bf16_f32 v149, v150, v151
	v_add_u32_e32 v171, 0x1200000, v5
	global_store_dwordx2 v171, v[136:137], s[8:9]
	global_store_dwordx2 v171, v[140:141], s[8:9] offset:512
	global_store_dwordx2 v171, v[144:145], s[8:9] offset:1024
	global_store_dwordx2 v171, v[148:149], s[8:9] offset:1536
	v_mov_b32_e32 v172, 0x12000
	s_mov_b64 exec, 1
	global_store_dwordx2 v172, v[184:185], s[38:39]
	s_mov_b64 exec, -1
	s_waitcnt vmcnt(43)
	v_add_f32_e32 v180, v152, v153
	v_add_f32_e32 v181, v156, v157
	v_add_f32_e32 v182, v160, v161
	v_add_f32_e32 v183, v164, v165
	v_add_f32_e32 v180, v180, v154
	v_add_f32_e32 v181, v181, v158
	v_add_f32_e32 v182, v182, v162
	v_add_f32_e32 v183, v183, v166
	v_add_f32_e32 v180, v180, v155
	v_add_f32_e32 v181, v181, v159
	v_add_f32_e32 v182, v182, v163
	v_add_f32_e32 v183, v183, v167
	v_add_f32_e32 v180, v180, v181
	v_add_f32_e32 v182, v182, v183
	v_add_f32_e32 v180, v180, v182
	s_nop 1
	v_add_f32_dpp v180, v180, v180 quad_perm:[1,0,3,2] row_mask:0xf bank_mask:0xf
	s_nop 1
	v_add_f32_dpp v180, v180, v180 quad_perm:[2,3,0,1] row_mask:0xf bank_mask:0xf
	s_nop 1
	v_add_f32_dpp v180, v180, v180 row_half_mirror row_mask:0xf bank_mask:0xf
	s_nop 1
	v_add_f32_dpp v180, v180, v180 row_mirror row_mask:0xf bank_mask:0xf
	s_nop 1
	v_add_f32_dpp v180, v180, v180 row_bcast:15 row_mask:0xa bank_mask:0xf
	s_nop 1
	v_add_f32_dpp v180, v180, v180 row_bcast:31 row_mask:0xc bank_mask:0xf
	s_nop 0
	v_readlane_b32 s20, v180, 63
	s_nop 1
	v_mul_f32_e32 v184, s20, v2
	v_sub_f32_e32 v152, v152, v184
	v_sub_f32_e32 v153, v153, v184
	v_sub_f32_e32 v154, v154, v184
	v_sub_f32_e32 v155, v155, v184
	v_sub_f32_e32 v156, v156, v184
	v_sub_f32_e32 v157, v157, v184
	v_sub_f32_e32 v158, v158, v184
	v_sub_f32_e32 v159, v159, v184
	v_sub_f32_e32 v160, v160, v184
	v_sub_f32_e32 v161, v161, v184
	v_sub_f32_e32 v162, v162, v184
	v_sub_f32_e32 v163, v163, v184
	v_sub_f32_e32 v164, v164, v184
	v_sub_f32_e32 v165, v165, v184
	v_sub_f32_e32 v166, v166, v184
	v_sub_f32_e32 v167, v167, v184
	v_mul_f32_e32 v180, v152, v152
	v_mul_f32_e32 v181, v156, v156
	v_mul_f32_e32 v182, v160, v160
	v_mul_f32_e32 v183, v164, v164
	v_fmac_f32_e32 v180, v153, v153
	v_fmac_f32_e32 v181, v157, v157
	v_fmac_f32_e32 v182, v161, v161
	v_fmac_f32_e32 v183, v165, v165
	v_fmac_f32_e32 v180, v154, v154
	v_fmac_f32_e32 v181, v158, v158
	v_fmac_f32_e32 v182, v162, v162
	v_fmac_f32_e32 v183, v166, v166
	v_fmac_f32_e32 v180, v155, v155
	v_fmac_f32_e32 v181, v159, v159
	v_fmac_f32_e32 v182, v163, v163
	v_fmac_f32_e32 v183, v167, v167
	v_add_f32_e32 v180, v180, v181
	v_add_f32_e32 v182, v182, v183
	v_add_f32_e32 v180, v180, v182
	s_nop 1
	v_add_f32_dpp v180, v180, v180 quad_perm:[1,0,3,2] row_mask:0xf bank_mask:0xf
	s_nop 1
	v_add_f32_dpp v180, v180, v180 quad_perm:[2,3,0,1] row_mask:0xf bank_mask:0xf
	s_nop 1
	v_add_f32_dpp v180, v180, v180 row_half_mirror row_mask:0xf bank_mask:0xf
	s_nop 1
	v_add_f32_dpp v180, v180, v180 row_mirror row_mask:0xf bank_mask:0xf
	s_nop 1
	v_add_f32_dpp v180, v180, v180 row_bcast:15 row_mask:0xa bank_mask:0xf
	s_nop 1
	v_add_f32_dpp v180, v180, v180 row_bcast:31 row_mask:0xc bank_mask:0xf
	s_nop 0
	v_readlane_b32 s20, v180, 63
	s_nop 1
	v_mov_b32_e32 v185, s20
	v_fma_f32 v185, v185, v2, v4
	v_rsq_f32_e32 v185, v185
	s_nop 0
	v_mul_f32_e32 v152, v152, v185
	v_mul_f32_e32 v153, v153, v185
	v_mul_f32_e32 v154, v154, v185
	v_mul_f32_e32 v155, v155, v185
	v_mul_f32_e32 v156, v156, v185
	v_mul_f32_e32 v157, v157, v185
	v_mul_f32_e32 v158, v158, v185
	v_mul_f32_e32 v159, v159, v185
	v_mul_f32_e32 v160, v160, v185
	v_mul_f32_e32 v161, v161, v185
	v_mul_f32_e32 v162, v162, v185
	v_mul_f32_e32 v163, v163, v185
	v_mul_f32_e32 v164, v164, v185
	v_mul_f32_e32 v165, v165, v185
	v_mul_f32_e32 v166, v166, v185
	v_mul_f32_e32 v167, v167, v185
	v_fma_f32 v152, v152, v8, v24
	v_fma_f32 v153, v153, v9, v25
	v_fma_f32 v154, v154, v10, v26
	v_fma_f32 v155, v155, v11, v27
	v_fma_f32 v156, v156, v12, v28
	v_fma_f32 v157, v157, v13, v29
	v_fma_f32 v158, v158, v14, v30
	v_fma_f32 v159, v159, v15, v31
	v_fma_f32 v160, v160, v16, v32
	v_fma_f32 v161, v161, v17, v33
	v_fma_f32 v162, v162, v18, v34
	v_fma_f32 v163, v163, v19, v35
	v_fma_f32 v164, v164, v20, v36
	v_fma_f32 v165, v165, v21, v37
	v_fma_f32 v166, v166, v22, v38
	v_fma_f32 v167, v167, v23, v39
	v_cvt_pk_bf16_f32 v152, v152, v153
	v_cvt_pk_bf16_f32 v153, v154, v155
	v_cvt_pk_bf16_f32 v156, v156, v157
	v_cvt_pk_bf16_f32 v157, v158, v159
	v_cvt_pk_bf16_f32 v160, v160, v161
	v_cvt_pk_bf16_f32 v161, v162, v163
	v_cvt_pk_bf16_f32 v164, v164, v165
	v_cvt_pk_bf16_f32 v165, v166, v167
	v_add_u32_e32 v171, 0x1500000, v5
	global_store_dwordx2 v171, v[152:153], s[8:9]
	global_store_dwordx2 v171, v[156:157], s[8:9] offset:512
	global_store_dwordx2 v171, v[160:161], s[8:9] offset:1024
	global_store_dwordx2 v171, v[164:165], s[8:9] offset:1536
	v_mov_b32_e32 v172, 0x15000
	s_mov_b64 exec, 1
	global_store_dwordx2 v172, v[184:185], s[38:39]
	s_mov_b64 exec, -1
	s_waitcnt vmcnt(39)
	v_add_f32_e32 v180, v40, v41
	v_add_f32_e32 v181, v44, v45
	v_add_f32_e32 v182, v48, v49
	v_add_f32_e32 v183, v52, v53
	v_add_f32_e32 v180, v180, v42
	v_add_f32_e32 v181, v181, v46
	v_add_f32_e32 v182, v182, v50
	v_add_f32_e32 v183, v183, v54
	v_add_f32_e32 v180, v180, v43
	v_add_f32_e32 v181, v181, v47
	v_add_f32_e32 v182, v182, v51
	v_add_f32_e32 v183, v183, v55
	v_add_f32_e32 v180, v180, v181
	v_add_f32_e32 v182, v182, v183
	v_add_f32_e32 v180, v180, v182
	s_nop 1
	v_add_f32_dpp v180, v180, v180 quad_perm:[1,0,3,2] row_mask:0xf bank_mask:0xf
	s_nop 1
	v_add_f32_dpp v180, v180, v180 quad_perm:[2,3,0,1] row_mask:0xf bank_mask:0xf
	s_nop 1
	v_add_f32_dpp v180, v180, v180 row_half_mirror row_mask:0xf bank_mask:0xf
	s_nop 1
	v_add_f32_dpp v180, v180, v180 row_mirror row_mask:0xf bank_mask:0xf
	s_nop 1
	v_add_f32_dpp v180, v180, v180 row_bcast:15 row_mask:0xa bank_mask:0xf
	s_nop 1
	v_add_f32_dpp v180, v180, v180 row_bcast:31 row_mask:0xc bank_mask:0xf
	s_nop 0
	v_readlane_b32 s20, v180, 63
	s_nop 1
	v_mul_f32_e32 v184, s20, v2
	v_sub_f32_e32 v40, v40, v184
	v_sub_f32_e32 v41, v41, v184
	v_sub_f32_e32 v42, v42, v184
	v_sub_f32_e32 v43, v43, v184
	v_sub_f32_e32 v44, v44, v184
	v_sub_f32_e32 v45, v45, v184
	v_sub_f32_e32 v46, v46, v184
	v_sub_f32_e32 v47, v47, v184
	v_sub_f32_e32 v48, v48, v184
	v_sub_f32_e32 v49, v49, v184
	v_sub_f32_e32 v50, v50, v184
	v_sub_f32_e32 v51, v51, v184
	v_sub_f32_e32 v52, v52, v184
	v_sub_f32_e32 v53, v53, v184
	v_sub_f32_e32 v54, v54, v184
	v_sub_f32_e32 v55, v55, v184
	v_mul_f32_e32 v180, v40, v40
	v_mul_f32_e32 v181, v44, v44
	v_mul_f32_e32 v182, v48, v48
	v_mul_f32_e32 v183, v52, v52
	v_fmac_f32_e32 v180, v41, v41
	v_fmac_f32_e32 v181, v45, v45
	v_fmac_f32_e32 v182, v49, v49
	v_fmac_f32_e32 v183, v53, v53
	v_fmac_f32_e32 v180, v42, v42
	v_fmac_f32_e32 v181, v46, v46
	v_fmac_f32_e32 v182, v50, v50
	v_fmac_f32_e32 v183, v54, v54
	v_fmac_f32_e32 v180, v43, v43
	v_fmac_f32_e32 v181, v47, v47
	v_fmac_f32_e32 v182, v51, v51
	v_fmac_f32_e32 v183, v55, v55
	v_add_f32_e32 v180, v180, v181
	v_add_f32_e32 v182, v182, v183
	v_add_f32_e32 v180, v180, v182
	s_nop 1
	v_add_f32_dpp v180, v180, v180 quad_perm:[1,0,3,2] row_mask:0xf bank_mask:0xf
	s_nop 1
	v_add_f32_dpp v180, v180, v180 quad_perm:[2,3,0,1] row_mask:0xf bank_mask:0xf
	s_nop 1
	v_add_f32_dpp v180, v180, v180 row_half_mirror row_mask:0xf bank_mask:0xf
	s_nop 1
	v_add_f32_dpp v180, v180, v180 row_mirror row_mask:0xf bank_mask:0xf
	s_nop 1
	v_add_f32_dpp v180, v180, v180 row_bcast:15 row_mask:0xa bank_mask:0xf
	s_nop 1
	v_add_f32_dpp v180, v180, v180 row_bcast:31 row_mask:0xc bank_mask:0xf
	s_nop 0
	v_readlane_b32 s20, v180, 63
	s_nop 1
	v_mov_b32_e32 v185, s20
	v_fma_f32 v185, v185, v2, v4
	v_rsq_f32_e32 v185, v185
	s_nop 0
	v_mul_f32_e32 v40, v40, v185
	v_mul_f32_e32 v41, v41, v185
	v_mul_f32_e32 v42, v42, v185
	v_mul_f32_e32 v43, v43, v185
	v_mul_f32_e32 v44, v44, v185
	v_mul_f32_e32 v45, v45, v185
	v_mul_f32_e32 v46, v46, v185
	v_mul_f32_e32 v47, v47, v185
	v_mul_f32_e32 v48, v48, v185
	v_mul_f32_e32 v49, v49, v185
	v_mul_f32_e32 v50, v50, v185
	v_mul_f32_e32 v51, v51, v185
	v_mul_f32_e32 v52, v52, v185
	v_mul_f32_e32 v53, v53, v185
	v_mul_f32_e32 v54, v54, v185
	v_mul_f32_e32 v55, v55, v185
	v_fma_f32 v40, v40, v8, v24
	v_fma_f32 v41, v41, v9, v25
	v_fma_f32 v42, v42, v10, v26
	v_fma_f32 v43, v43, v11, v27
	v_fma_f32 v44, v44, v12, v28
	v_fma_f32 v45, v45, v13, v29
	v_fma_f32 v46, v46, v14, v30
	v_fma_f32 v47, v47, v15, v31
	v_fma_f32 v48, v48, v16, v32
	v_fma_f32 v49, v49, v17, v33
	v_fma_f32 v50, v50, v18, v34
	v_fma_f32 v51, v51, v19, v35
	v_fma_f32 v52, v52, v20, v36
	v_fma_f32 v53, v53, v21, v37
	v_fma_f32 v54, v54, v22, v38
	v_fma_f32 v55, v55, v23, v39
	v_cvt_pk_bf16_f32 v40, v40, v41
	v_cvt_pk_bf16_f32 v41, v42, v43
	v_cvt_pk_bf16_f32 v44, v44, v45
	v_cvt_pk_bf16_f32 v45, v46, v47
	v_cvt_pk_bf16_f32 v48, v48, v49
	v_cvt_pk_bf16_f32 v49, v50, v51
	v_cvt_pk_bf16_f32 v52, v52, v53
	v_cvt_pk_bf16_f32 v53, v54, v55
	v_add_u32_e32 v171, 0x1800000, v5
	global_store_dwordx2 v171, v[40:41], s[8:9]
	global_store_dwordx2 v171, v[44:45], s[8:9] offset:512
	global_store_dwordx2 v171, v[48:49], s[8:9] offset:1024
	global_store_dwordx2 v171, v[52:53], s[8:9] offset:1536
	v_mov_b32_e32 v172, 0x18000
	s_mov_b64 exec, 1
	global_store_dwordx2 v172, v[184:185], s[38:39]
	s_mov_b64 exec, -1
	s_waitcnt vmcnt(35)
	v_add_f32_e32 v180, v56, v57
	v_add_f32_e32 v181, v60, v61
	v_add_f32_e32 v182, v64, v65
	v_add_f32_e32 v183, v68, v69
	v_add_f32_e32 v180, v180, v58
	v_add_f32_e32 v181, v181, v62
	v_add_f32_e32 v182, v182, v66
	v_add_f32_e32 v183, v183, v70
	v_add_f32_e32 v180, v180, v59
	v_add_f32_e32 v181, v181, v63
	v_add_f32_e32 v182, v182, v67
	v_add_f32_e32 v183, v183, v71
	v_add_f32_e32 v180, v180, v181
	v_add_f32_e32 v182, v182, v183
	v_add_f32_e32 v180, v180, v182
	s_nop 1
	v_add_f32_dpp v180, v180, v180 quad_perm:[1,0,3,2] row_mask:0xf bank_mask:0xf
	s_nop 1
	v_add_f32_dpp v180, v180, v180 quad_perm:[2,3,0,1] row_mask:0xf bank_mask:0xf
	s_nop 1
	v_add_f32_dpp v180, v180, v180 row_half_mirror row_mask:0xf bank_mask:0xf
	s_nop 1
	v_add_f32_dpp v180, v180, v180 row_mirror row_mask:0xf bank_mask:0xf
	s_nop 1
	v_add_f32_dpp v180, v180, v180 row_bcast:15 row_mask:0xa bank_mask:0xf
	s_nop 1
	v_add_f32_dpp v180, v180, v180 row_bcast:31 row_mask:0xc bank_mask:0xf
	s_nop 0
	v_readlane_b32 s20, v180, 63
	s_nop 1
	v_mul_f32_e32 v184, s20, v2
	v_sub_f32_e32 v56, v56, v184
	v_sub_f32_e32 v57, v57, v184
	v_sub_f32_e32 v58, v58, v184
	v_sub_f32_e32 v59, v59, v184
	v_sub_f32_e32 v60, v60, v184
	v_sub_f32_e32 v61, v61, v184
	v_sub_f32_e32 v62, v62, v184
	v_sub_f32_e32 v63, v63, v184
	v_sub_f32_e32 v64, v64, v184
	v_sub_f32_e32 v65, v65, v184
	v_sub_f32_e32 v66, v66, v184
	v_sub_f32_e32 v67, v67, v184
	v_sub_f32_e32 v68, v68, v184
	v_sub_f32_e32 v69, v69, v184
	v_sub_f32_e32 v70, v70, v184
	v_sub_f32_e32 v71, v71, v184
	v_mul_f32_e32 v180, v56, v56
	v_mul_f32_e32 v181, v60, v60
	v_mul_f32_e32 v182, v64, v64
	v_mul_f32_e32 v183, v68, v68
	v_fmac_f32_e32 v180, v57, v57
	v_fmac_f32_e32 v181, v61, v61
	v_fmac_f32_e32 v182, v65, v65
	v_fmac_f32_e32 v183, v69, v69
	v_fmac_f32_e32 v180, v58, v58
	v_fmac_f32_e32 v181, v62, v62
	v_fmac_f32_e32 v182, v66, v66
	v_fmac_f32_e32 v183, v70, v70
	v_fmac_f32_e32 v180, v59, v59
	v_fmac_f32_e32 v181, v63, v63
	v_fmac_f32_e32 v182, v67, v67
	v_fmac_f32_e32 v183, v71, v71
	v_add_f32_e32 v180, v180, v181
	v_add_f32_e32 v182, v182, v183
	v_add_f32_e32 v180, v180, v182
	s_nop 1
	v_add_f32_dpp v180, v180, v180 quad_perm:[1,0,3,2] row_mask:0xf bank_mask:0xf
	s_nop 1
	v_add_f32_dpp v180, v180, v180 quad_perm:[2,3,0,1] row_mask:0xf bank_mask:0xf
	s_nop 1
	v_add_f32_dpp v180, v180, v180 row_half_mirror row_mask:0xf bank_mask:0xf
	s_nop 1
	v_add_f32_dpp v180, v180, v180 row_mirror row_mask:0xf bank_mask:0xf
	s_nop 1
	v_add_f32_dpp v180, v180, v180 row_bcast:15 row_mask:0xa bank_mask:0xf
	s_nop 1
	v_add_f32_dpp v180, v180, v180 row_bcast:31 row_mask:0xc bank_mask:0xf
	s_nop 0
	v_readlane_b32 s20, v180, 63
	s_nop 1
	v_mov_b32_e32 v185, s20
	v_fma_f32 v185, v185, v2, v4
	v_rsq_f32_e32 v185, v185
	s_nop 0
	v_mul_f32_e32 v56, v56, v185
	v_mul_f32_e32 v57, v57, v185
	v_mul_f32_e32 v58, v58, v185
	v_mul_f32_e32 v59, v59, v185
	v_mul_f32_e32 v60, v60, v185
	v_mul_f32_e32 v61, v61, v185
	v_mul_f32_e32 v62, v62, v185
	v_mul_f32_e32 v63, v63, v185
	v_mul_f32_e32 v64, v64, v185
	v_mul_f32_e32 v65, v65, v185
	v_mul_f32_e32 v66, v66, v185
	v_mul_f32_e32 v67, v67, v185
	v_mul_f32_e32 v68, v68, v185
	v_mul_f32_e32 v69, v69, v185
	v_mul_f32_e32 v70, v70, v185
	v_mul_f32_e32 v71, v71, v185
	v_fma_f32 v56, v56, v8, v24
	v_fma_f32 v57, v57, v9, v25
	v_fma_f32 v58, v58, v10, v26
	v_fma_f32 v59, v59, v11, v27
	v_fma_f32 v60, v60, v12, v28
	v_fma_f32 v61, v61, v13, v29
	v_fma_f32 v62, v62, v14, v30
	v_fma_f32 v63, v63, v15, v31
	v_fma_f32 v64, v64, v16, v32
	v_fma_f32 v65, v65, v17, v33
	v_fma_f32 v66, v66, v18, v34
	v_fma_f32 v67, v67, v19, v35
	v_fma_f32 v68, v68, v20, v36
	v_fma_f32 v69, v69, v21, v37
	v_fma_f32 v70, v70, v22, v38
	v_fma_f32 v71, v71, v23, v39
	v_cvt_pk_bf16_f32 v56, v56, v57
	v_cvt_pk_bf16_f32 v57, v58, v59
	v_cvt_pk_bf16_f32 v60, v60, v61
	v_cvt_pk_bf16_f32 v61, v62, v63
	v_cvt_pk_bf16_f32 v64, v64, v65
	v_cvt_pk_bf16_f32 v65, v66, v67
	v_cvt_pk_bf16_f32 v68, v68, v69
	v_cvt_pk_bf16_f32 v69, v70, v71
	v_add_u32_e32 v171, 0x1b00000, v5
	global_store_dwordx2 v171, v[56:57], s[8:9]
	global_store_dwordx2 v171, v[60:61], s[8:9] offset:512
	global_store_dwordx2 v171, v[64:65], s[8:9] offset:1024
	global_store_dwordx2 v171, v[68:69], s[8:9] offset:1536
	v_mov_b32_e32 v172, 0x1b000
	s_mov_b64 exec, 1
	global_store_dwordx2 v172, v[184:185], s[38:39]
	s_mov_b64 exec, -1
	s_branch .LBB0_188

.LBB0_745:
	s_or_b64 exec, exec, s[0:1]
	s_mov_b64 s[4:5], s[88:89]
	s_waitcnt lgkmcnt(0)
	s_barrier
	s_cmpk_lg_u32 s56, 0x100
	s_cbranch_scc1 .Llo_generic
	s_load_dwordx2 s[6:7], s[4:5], 0xa0
	s_load_dwordx4 s[40:43], s[4:5], 0x90
	v_mbcnt_lo_u32_b32 v0, -1, 0
	v_mbcnt_hi_u32_b32 v0, -1, v0
	v_lshlrev_b32_e32 v1, 4, v0
	s_lshr_b32 s0, s29, 6
	s_lshl_b32 s96, s92, 24
	s_lshl_b64 s[8:9], s[96:97], 2
	v_mov_b32_e32 v2, 0x3a800000
	v_mov_b32_e32 v4, 0x3727c5ac
	s_waitcnt lgkmcnt(0)
	s_add_u32 s4, s6, s8
	s_addc_u32 s5, s7, s9
	s_cmp_eq_u32 s92, 2
	s_cbranch_scc1 .Llo_even
	s_cmp_lt_u32 s86, 64
	s_cbranch_scc1 .Ltr_29
	s_sub_u32 s1, s86, 64
	s_lshl_b32 s1, s1, 3
	s_add_i32 s0, s0, s1
	s_lshl_b32 s1, s0, 12
	s_add_u32 s4, s4, s1
	s_addc_u32 s5, s5, 0
	s_cmpk_lt_u32 s0, 0x400
	s_cbranch_scc0 .Llo_r10
	global_load_dwordx4 v[40:43], v1, s[4:5] nt
	global_load_dwordx4 v[44:47], v1, s[4:5] offset:1024 nt
	global_load_dwordx4 v[48:51], v1, s[4:5] offset:2048 nt
	global_load_dwordx4 v[52:55], v1, s[4:5] offset:3072 nt
	global_load_dwordx4 v[8:11], v1, s[40:41]
	global_load_dwordx4 v[12:15], v1, s[40:41] offset:1024
	global_load_dwordx4 v[16:19], v1, s[40:41] offset:2048
	global_load_dwordx4 v[20:23], v1, s[40:41] offset:3072
	global_load_dwordx4 v[24:27], v1, s[42:43]
	global_load_dwordx4 v[28:31], v1, s[42:43] offset:1024
	global_load_dwordx4 v[32:35], v1, s[42:43] offset:2048
	global_load_dwordx4 v[36:39], v1, s[42:43] offset:3072
	v_add_u32_e32 v170, 0x600000, v1
	global_load_dwordx4 v[56:59], v170, s[4:5] nt
	global_load_dwordx4 v[60:63], v170, s[4:5] offset:1024 nt
	global_load_dwordx4 v[64:67], v170, s[4:5] offset:2048 nt
	global_load_dwordx4 v[68:71], v170, s[4:5] offset:3072 nt
	v_add_u32_e32 v170, 0xc00000, v1
	global_load_dwordx4 v[72:75], v170, s[4:5] nt
	global_load_dwordx4 v[76:79], v170, s[4:5] offset:1024 nt
	global_load_dwordx4 v[80:83], v170, s[4:5] offset:2048 nt
	global_load_dwordx4 v[84:87], v170, s[4:5] offset:3072 nt
	v_add_u32_e32 v170, 0x1200000, v1
	global_load_dwordx4 v[88:91], v170, s[4:5] nt
	global_load_dwordx4 v[92:95], v170, s[4:5] offset:1024 nt
	global_load_dwordx4 v[96:99], v170, s[4:5] offset:2048 nt
	global_load_dwordx4 v[100:103], v170, s[4:5] offset:3072 nt
	v_add_u32_e32 v170, 0x1800000, v1
	global_load_dwordx4 v[104:107], v170, s[4:5] nt
	global_load_dwordx4 v[108:111], v170, s[4:5] offset:1024 nt
	global_load_dwordx4 v[112:115], v170, s[4:5] offset:2048 nt
	global_load_dwordx4 v[116:119], v170, s[4:5] offset:3072 nt
	v_add_u32_e32 v170, 0x1e00000, v1
	global_load_dwordx4 v[120:123], v170, s[4:5] nt
	global_load_dwordx4 v[124:127], v170, s[4:5] offset:1024 nt
	global_load_dwordx4 v[128:131], v170, s[4:5] offset:2048 nt
	global_load_dwordx4 v[132:135], v170, s[4:5] offset:3072 nt
	v_add_u32_e32 v170, 0x2400000, v1
	global_load_dwordx4 v[136:139], v170, s[4:5] nt
	global_load_dwordx4 v[140:143], v170, s[4:5] offset:1024 nt
	global_load_dwordx4 v[144:147], v170, s[4:5] offset:2048 nt
	global_load_dwordx4 v[148:151], v170, s[4:5] offset:3072 nt
	v_add_u32_e32 v170, 0x2a00000, v1
	global_load_dwordx4 v[152:155], v170, s[4:5] nt
	global_load_dwordx4 v[156:159], v170, s[4:5] offset:1024 nt
	global_load_dwordx4 v[160:163], v170, s[4:5] offset:2048 nt
	global_load_dwordx4 v[164:167], v170, s[4:5] offset:3072 nt
	s_waitcnt vmcnt(36)
	v_add_f32_e32 v180, v40, v41
	v_add_f32_e32 v181, v44, v45
	v_add_f32_e32 v182, v48, v49
	v_add_f32_e32 v183, v52, v53
	v_add_f32_e32 v180, v180, v42
	v_add_f32_e32 v181, v181, v46
	v_add_f32_e32 v182, v182, v50
	v_add_f32_e32 v183, v183, v54
	v_add_f32_e32 v180, v180, v43
	v_add_f32_e32 v181, v181, v47
	v_add_f32_e32 v182, v182, v51
	v_add_f32_e32 v183, v183, v55
	v_add_f32_e32 v180, v180, v181
	v_add_f32_e32 v182, v182, v183
	v_add_f32_e32 v180, v180, v182
	s_nop 1
	v_add_f32_dpp v180, v180, v180 quad_perm:[1,0,3,2] row_mask:0xf bank_mask:0xf
	s_nop 1
	v_add_f32_dpp v180, v180, v180 quad_perm:[2,3,0,1] row_mask:0xf bank_mask:0xf
	s_nop 1
	v_add_f32_dpp v180, v180, v180 row_half_mirror row_mask:0xf bank_mask:0xf
	s_nop 1
	v_add_f32_dpp v180, v180, v180 row_mirror row_mask:0xf bank_mask:0xf
	s_nop 1
	v_add_f32_dpp v180, v180, v180 row_bcast:15 row_mask:0xa bank_mask:0xf
	s_nop 1
	v_add_f32_dpp v180, v180, v180 row_bcast:31 row_mask:0xc bank_mask:0xf
	s_nop 0
	v_readlane_b32 s20, v180, 63
	s_nop 1
	v_mul_f32_e32 v184, s20, v2
	v_sub_f32_e32 v40, v40, v184
	v_sub_f32_e32 v41, v41, v184
	v_sub_f32_e32 v42, v42, v184
	v_sub_f32_e32 v43, v43, v184
	v_sub_f32_e32 v44, v44, v184
	v_sub_f32_e32 v45, v45, v184
	v_sub_f32_e32 v46, v46, v184
	v_sub_f32_e32 v47, v47, v184
	v_sub_f32_e32 v48, v48, v184
	v_sub_f32_e32 v49, v49, v184
	v_sub_f32_e32 v50, v50, v184
	v_sub_f32_e32 v51, v51, v184
	v_sub_f32_e32 v52, v52, v184
	v_sub_f32_e32 v53, v53, v184
	v_sub_f32_e32 v54, v54, v184
	v_sub_f32_e32 v55, v55, v184
	v_mul_f32_e32 v180, v40, v40
	v_mul_f32_e32 v181, v44, v44
	v_mul_f32_e32 v182, v48, v48
	v_mul_f32_e32 v183, v52, v52
	v_fmac_f32_e32 v180, v41, v41
	v_fmac_f32_e32 v181, v45, v45
	v_fmac_f32_e32 v182, v49, v49
	v_fmac_f32_e32 v183, v53, v53
	v_fmac_f32_e32 v180, v42, v42
	v_fmac_f32_e32 v181, v46, v46
	v_fmac_f32_e32 v182, v50, v50
	v_fmac_f32_e32 v183, v54, v54
	v_fmac_f32_e32 v180, v43, v43
	v_fmac_f32_e32 v181, v47, v47
	v_fmac_f32_e32 v182, v51, v51
	v_fmac_f32_e32 v183, v55, v55
	v_add_f32_e32 v180, v180, v181
	v_add_f32_e32 v182, v182, v183
	v_add_f32_e32 v180, v180, v182
	s_nop 1
	v_add_f32_dpp v180, v180, v180 quad_perm:[1,0,3,2] row_mask:0xf bank_mask:0xf
	s_nop 1
	v_add_f32_dpp v180, v180, v180 quad_perm:[2,3,0,1] row_mask:0xf bank_mask:0xf
	s_nop 1
	v_add_f32_dpp v180, v180, v180 row_half_mirror row_mask:0xf bank_mask:0xf
	s_nop 1
	v_add_f32_dpp v180, v180, v180 row_mirror row_mask:0xf bank_mask:0xf
	s_nop 1
	v_add_f32_dpp v180, v180, v180 row_bcast:15 row_mask:0xa bank_mask:0xf
	s_nop 1
	v_add_f32_dpp v180, v180, v180 row_bcast:31 row_mask:0xc bank_mask:0xf
	s_nop 0
	v_readlane_b32 s20, v180, 63
	s_nop 1
	v_mov_b32_e32 v185, s20
	v_fma_f32 v185, v185, v2, v4
	v_rsq_f32_e32 v185, v185
	s_nop 0
	v_mul_f32_e32 v40, v40, v185
	v_mul_f32_e32 v41, v41, v185
	v_mul_f32_e32 v42, v42, v185
	v_mul_f32_e32 v43, v43, v185
	v_mul_f32_e32 v44, v44, v185
	v_mul_f32_e32 v45, v45, v185
	v_mul_f32_e32 v46, v46, v185
	v_mul_f32_e32 v47, v47, v185
	v_mul_f32_e32 v48, v48, v185
	v_mul_f32_e32 v49, v49, v185
	v_mul_f32_e32 v50, v50, v185
	v_mul_f32_e32 v51, v51, v185
	v_mul_f32_e32 v52, v52, v185
	v_mul_f32_e32 v53, v53, v185
	v_mul_f32_e32 v54, v54, v185
	v_mul_f32_e32 v55, v55, v185
	s_waitcnt vmcnt(28)
	v_fma_f32 v40, v40, v8, v24
	v_fma_f32 v41, v41, v9, v25
	v_fma_f32 v42, v42, v10, v26
	v_fma_f32 v43, v43, v11, v27
	v_fma_f32 v44, v44, v12, v28
	v_fma_f32 v45, v45, v13, v29
	v_fma_f32 v46, v46, v14, v30
	v_fma_f32 v47, v47, v15, v31
	v_fma_f32 v48, v48, v16, v32
	v_fma_f32 v49, v49, v17, v33
	v_fma_f32 v50, v50, v18, v34
	v_fma_f32 v51, v51, v19, v35
	v_fma_f32 v52, v52, v20, v36
	v_fma_f32 v53, v53, v21, v37
	v_fma_f32 v54, v54, v22, v38
	v_fma_f32 v55, v55, v23, v39
	global_store_dwordx4 v1, v[40:43], s[4:5]
	global_store_dwordx4 v1, v[44:47], s[4:5] offset:1024
	global_store_dwordx4 v1, v[48:51], s[4:5] offset:2048
	global_store_dwordx4 v1, v[52:55], s[4:5] offset:3072
	s_nop 1
	v_add_u32_e32 v170, 0x3000000, v1
	global_load_dwordx4 v[40:43], v170, s[4:5] nt
	global_load_dwordx4 v[44:47], v170, s[4:5] offset:1024 nt
	global_load_dwordx4 v[48:51], v170, s[4:5] offset:2048 nt
	global_load_dwordx4 v[52:55], v170, s[4:5] offset:3072 nt
	s_waitcnt vmcnt(32)
	v_add_f32_e32 v180, v56, v57
	v_add_f32_e32 v181, v60, v61
	v_add_f32_e32 v182, v64, v65
	v_add_f32_e32 v183, v68, v69
	v_add_f32_e32 v180, v180, v58
	v_add_f32_e32 v181, v181, v62
	v_add_f32_e32 v182, v182, v66
	v_add_f32_e32 v183, v183, v70
	v_add_f32_e32 v180, v180, v59
	v_add_f32_e32 v181, v181, v63
	v_add_f32_e32 v182, v182, v67
	v_add_f32_e32 v183, v183, v71
	v_add_f32_e32 v180, v180, v181
	v_add_f32_e32 v182, v182, v183
	v_add_f32_e32 v180, v180, v182
	s_nop 1
	v_add_f32_dpp v180, v180, v180 quad_perm:[1,0,3,2] row_mask:0xf bank_mask:0xf
	s_nop 1
	v_add_f32_dpp v180, v180, v180 quad_perm:[2,3,0,1] row_mask:0xf bank_mask:0xf
	s_nop 1
	v_add_f32_dpp v180, v180, v180 row_half_mirror row_mask:0xf bank_mask:0xf
	s_nop 1
	v_add_f32_dpp v180, v180, v180 row_mirror row_mask:0xf bank_mask:0xf
	s_nop 1
	v_add_f32_dpp v180, v180, v180 row_bcast:15 row_mask:0xa bank_mask:0xf
	s_nop 1
	v_add_f32_dpp v180, v180, v180 row_bcast:31 row_mask:0xc bank_mask:0xf
	s_nop 0
	v_readlane_b32 s20, v180, 63
	s_nop 1
	v_mul_f32_e32 v184, s20, v2
	v_sub_f32_e32 v56, v56, v184
	v_sub_f32_e32 v57, v57, v184
	v_sub_f32_e32 v58, v58, v184
	v_sub_f32_e32 v59, v59, v184
	v_sub_f32_e32 v60, v60, v184
	v_sub_f32_e32 v61, v61, v184
	v_sub_f32_e32 v62, v62, v184
	v_sub_f32_e32 v63, v63, v184
	v_sub_f32_e32 v64, v64, v184
	v_sub_f32_e32 v65, v65, v184
	v_sub_f32_e32 v66, v66, v184
	v_sub_f32_e32 v67, v67, v184
	v_sub_f32_e32 v68, v68, v184
	v_sub_f32_e32 v69, v69, v184
	v_sub_f32_e32 v70, v70, v184
	v_sub_f32_e32 v71, v71, v184
	v_mul_f32_e32 v180, v56, v56
	v_mul_f32_e32 v181, v60, v60
	v_mul_f32_e32 v182, v64, v64
	v_mul_f32_e32 v183, v68, v68
	v_fmac_f32_e32 v180, v57, v57
	v_fmac_f32_e32 v181, v61, v61
	v_fmac_f32_e32 v182, v65, v65
	v_fmac_f32_e32 v183, v69, v69
	v_fmac_f32_e32 v180, v58, v58
	v_fmac_f32_e32 v181, v62, v62
	v_fmac_f32_e32 v182, v66, v66
	v_fmac_f32_e32 v183, v70, v70
	v_fmac_f32_e32 v180, v59, v59
	v_fmac_f32_e32 v181, v63, v63
	v_fmac_f32_e32 v182, v67, v67
	v_fmac_f32_e32 v183, v71, v71
	v_add_f32_e32 v180, v180, v181
	v_add_f32_e32 v182, v182, v183
	v_add_f32_e32 v180, v180, v182
	s_nop 1
	v_add_f32_dpp v180, v180, v180 quad_perm:[1,0,3,2] row_mask:0xf bank_mask:0xf
	s_nop 1
	v_add_f32_dpp v180, v180, v180 quad_perm:[2,3,0,1] row_mask:0xf bank_mask:0xf
	s_nop 1
	v_add_f32_dpp v180, v180, v180 row_half_mirror row_mask:0xf bank_mask:0xf
	s_nop 1
	v_add_f32_dpp v180, v180, v180 row_mirror row_mask:0xf bank_mask:0xf
	s_nop 1
	v_add_f32_dpp v180, v180, v180 row_bcast:15 row_mask:0xa bank_mask:0xf
	s_nop 1
	v_add_f32_dpp v180, v180, v180 row_bcast:31 row_mask:0xc bank_mask:0xf
	s_nop 0
	v_readlane_b32 s20, v180, 63
	s_nop 1
	v_mov_b32_e32 v185, s20
	v_fma_f32 v185, v185, v2, v4
	v_rsq_f32_e32 v185, v185
	s_nop 0
	v_mul_f32_e32 v56, v56, v185
	v_mul_f32_e32 v57, v57, v185
	v_mul_f32_e32 v58, v58, v185
	v_mul_f32_e32 v59, v59, v185
	v_mul_f32_e32 v60, v60, v185
	v_mul_f32_e32 v61, v61, v185
	v_mul_f32_e32 v62, v62, v185
	v_mul_f32_e32 v63, v63, v185
	v_mul_f32_e32 v64, v64, v185
	v_mul_f32_e32 v65, v65, v185
	v_mul_f32_e32 v66, v66, v185
	v_mul_f32_e32 v67, v67, v185
	v_mul_f32_e32 v68, v68, v185
	v_mul_f32_e32 v69, v69, v185
	v_mul_f32_e32 v70, v70, v185
	v_mul_f32_e32 v71, v71, v185
	v_fma_f32 v56, v56, v8, v24
	v_fma_f32 v57, v57, v9, v25
	v_fma_f32 v58, v58, v10, v26
	v_fma_f32 v59, v59, v11, v27
	v_fma_f32 v60, v60, v12, v28
	v_fma_f32 v61, v61, v13, v29
	v_fma_f32 v62, v62, v14, v30
	v_fma_f32 v63, v63, v15, v31
	v_fma_f32 v64, v64, v16, v32
	v_fma_f32 v65, v65, v17, v33
	v_fma_f32 v66, v66, v18, v34
	v_fma_f32 v67, v67, v19, v35
	v_fma_f32 v68, v68, v20, v36
	v_fma_f32 v69, v69, v21, v37
	v_fma_f32 v70, v70, v22, v38
	v_fma_f32 v71, v71, v23, v39
	v_add_u32_e32 v171, 0x600000, v1
	global_store_dwordx4 v171, v[56:59], s[4:5]
	global_store_dwordx4 v171, v[60:63], s[4:5] offset:1024
	global_store_dwordx4 v171, v[64:67], s[4:5] offset:2048
	global_store_dwordx4 v171, v[68:71], s[4:5] offset:3072
	s_nop 1
	v_add_u32_e32 v170, 0x3600000, v1
	global_load_dwordx4 v[56:59], v170, s[4:5] nt
	global_load_dwordx4 v[60:63], v170, s[4:5] offset:1024 nt
	global_load_dwordx4 v[64:67], v170, s[4:5] offset:2048 nt
	global_load_dwordx4 v[68:71], v170, s[4:5] offset:3072 nt
	s_waitcnt vmcnt(36)
	v_add_f32_e32 v180, v72, v73
	v_add_f32_e32 v181, v76, v77
	v_add_f32_e32 v182, v80, v81
	v_add_f32_e32 v183, v84, v85
	v_add_f32_e32 v180, v180, v74
	v_add_f32_e32 v181, v181, v78
	v_add_f32_e32 v182, v182, v82
	v_add_f32_e32 v183, v183, v86
	v_add_f32_e32 v180, v180, v75
	v_add_f32_e32 v181, v181, v79
	v_add_f32_e32 v182, v182, v83
	v_add_f32_e32 v183, v183, v87
	v_add_f32_e32 v180, v180, v181
	v_add_f32_e32 v182, v182, v183
	v_add_f32_e32 v180, v180, v182
	s_nop 1
	v_add_f32_dpp v180, v180, v180 quad_perm:[1,0,3,2] row_mask:0xf bank_mask:0xf
	s_nop 1
	v_add_f32_dpp v180, v180, v180 quad_perm:[2,3,0,1] row_mask:0xf bank_mask:0xf
	s_nop 1
	v_add_f32_dpp v180, v180, v180 row_half_mirror row_mask:0xf bank_mask:0xf
	s_nop 1
	v_add_f32_dpp v180, v180, v180 row_mirror row_mask:0xf bank_mask:0xf
	s_nop 1
	v_add_f32_dpp v180, v180, v180 row_bcast:15 row_mask:0xa bank_mask:0xf
	s_nop 1
	v_add_f32_dpp v180, v180, v180 row_bcast:31 row_mask:0xc bank_mask:0xf
	s_nop 0
	v_readlane_b32 s20, v180, 63
	s_nop 1
	v_mul_f32_e32 v184, s20, v2
	v_sub_f32_e32 v72, v72, v184
	v_sub_f32_e32 v73, v73, v184
	v_sub_f32_e32 v74, v74, v184
	v_sub_f32_e32 v75, v75, v184
	v_sub_f32_e32 v76, v76, v184
	v_sub_f32_e32 v77, v77, v184
	v_sub_f32_e32 v78, v78, v184
	v_sub_f32_e32 v79, v79, v184
	v_sub_f32_e32 v80, v80, v184
	v_sub_f32_e32 v81, v81, v184
	v_sub_f32_e32 v82, v82, v184
	v_sub_f32_e32 v83, v83, v184
	v_sub_f32_e32 v84, v84, v184
	v_sub_f32_e32 v85, v85, v184
	v_sub_f32_e32 v86, v86, v184
	v_sub_f32_e32 v87, v87, v184
	v_mul_f32_e32 v180, v72, v72
	v_mul_f32_e32 v181, v76, v76
	v_mul_f32_e32 v182, v80, v80
	v_mul_f32_e32 v183, v84, v84
	v_fmac_f32_e32 v180, v73, v73
	v_fmac_f32_e32 v181, v77, v77
	v_fmac_f32_e32 v182, v81, v81
	v_fmac_f32_e32 v183, v85, v85
	v_fmac_f32_e32 v180, v74, v74
	v_fmac_f32_e32 v181, v78, v78
	v_fmac_f32_e32 v182, v82, v82
	v_fmac_f32_e32 v183, v86, v86
	v_fmac_f32_e32 v180, v75, v75
	v_fmac_f32_e32 v181, v79, v79
	v_fmac_f32_e32 v182, v83, v83
	v_fmac_f32_e32 v183, v87, v87
	v_add_f32_e32 v180, v180, v181
	v_add_f32_e32 v182, v182, v183
	v_add_f32_e32 v180, v180, v182
	s_nop 1
	v_add_f32_dpp v180, v180, v180 quad_perm:[1,0,3,2] row_mask:0xf bank_mask:0xf
	s_nop 1
	v_add_f32_dpp v180, v180, v180 quad_perm:[2,3,0,1] row_mask:0xf bank_mask:0xf
	s_nop 1
	v_add_f32_dpp v180, v180, v180 row_half_mirror row_mask:0xf bank_mask:0xf
	s_nop 1
	v_add_f32_dpp v180, v180, v180 row_mirror row_mask:0xf bank_mask:0xf
	s_nop 1
	v_add_f32_dpp v180, v180, v180 row_bcast:15 row_mask:0xa bank_mask:0xf
	s_nop 1
	v_add_f32_dpp v180, v180, v180 row_bcast:31 row_mask:0xc bank_mask:0xf
	s_nop 0
	v_readlane_b32 s20, v180, 63
	s_nop 1
	v_mov_b32_e32 v185, s20
	v_fma_f32 v185, v185, v2, v4
	v_rsq_f32_e32 v185, v185
	s_nop 0
	v_mul_f32_e32 v72, v72, v185
	v_mul_f32_e32 v73, v73, v185
	v_mul_f32_e32 v74, v74, v185
	v_mul_f32_e32 v75, v75, v185
	v_mul_f32_e32 v76, v76, v185
	v_mul_f32_e32 v77, v77, v185
	v_mul_f32_e32 v78, v78, v185
	v_mul_f32_e32 v79, v79, v185
	v_mul_f32_e32 v80, v80, v185
	v_mul_f32_e32 v81, v81, v185
	v_mul_f32_e32 v82, v82, v185
	v_mul_f32_e32 v83, v83, v185
	v_mul_f32_e32 v84, v84, v185
	v_mul_f32_e32 v85, v85, v185
	v_mul_f32_e32 v86, v86, v185
	v_mul_f32_e32 v87, v87, v185
	v_fma_f32 v72, v72, v8, v24
	v_fma_f32 v73, v73, v9, v25
	v_fma_f32 v74, v74, v10, v26
	v_fma_f32 v75, v75, v11, v27
	v_fma_f32 v76, v76, v12, v28
	v_fma_f32 v77, v77, v13, v29
	v_fma_f32 v78, v78, v14, v30
	v_fma_f32 v79, v79, v15, v31
	v_fma_f32 v80, v80, v16, v32
	v_fma_f32 v81, v81, v17, v33
	v_fma_f32 v82, v82, v18, v34
	v_fma_f32 v83, v83, v19, v35
	v_fma_f32 v84, v84, v20, v36
	v_fma_f32 v85, v85, v21, v37
	v_fma_f32 v86, v86, v22, v38
	v_fma_f32 v87, v87, v23, v39
	v_add_u32_e32 v171, 0xc00000, v1
	global_store_dwordx4 v171, v[72:75], s[4:5]
	global_store_dwordx4 v171, v[76:79], s[4:5] offset:1024
	global_store_dwordx4 v171, v[80:83], s[4:5] offset:2048
	global_store_dwordx4 v171, v[84:87], s[4:5] offset:3072
	s_nop 1
	v_add_u32_e32 v170, 0x3c00000, v1
	global_load_dwordx4 v[72:75], v170, s[4:5] nt
	global_load_dwordx4 v[76:79], v170, s[4:5] offset:1024 nt
	global_load_dwordx4 v[80:83], v170, s[4:5] offset:2048 nt
	global_load_dwordx4 v[84:87], v170, s[4:5] offset:3072 nt
	s_waitcnt vmcnt(40)
	v_add_f32_e32 v180, v88, v89
	v_add_f32_e32 v181, v92, v93
	v_add_f32_e32 v182, v96, v97
	v_add_f32_e32 v183, v100, v101
	v_add_f32_e32 v180, v180, v90
	v_add_f32_e32 v181, v181, v94
	v_add_f32_e32 v182, v182, v98
	v_add_f32_e32 v183, v183, v102
	v_add_f32_e32 v180, v180, v91
	v_add_f32_e32 v181, v181, v95
	v_add_f32_e32 v182, v182, v99
	v_add_f32_e32 v183, v183, v103
	v_add_f32_e32 v180, v180, v181
	v_add_f32_e32 v182, v182, v183
	v_add_f32_e32 v180, v180, v182
	s_nop 1
	v_add_f32_dpp v180, v180, v180 quad_perm:[1,0,3,2] row_mask:0xf bank_mask:0xf
	s_nop 1
	v_add_f32_dpp v180, v180, v180 quad_perm:[2,3,0,1] row_mask:0xf bank_mask:0xf
	s_nop 1
	v_add_f32_dpp v180, v180, v180 row_half_mirror row_mask:0xf bank_mask:0xf
	s_nop 1
	v_add_f32_dpp v180, v180, v180 row_mirror row_mask:0xf bank_mask:0xf
	s_nop 1
	v_add_f32_dpp v180, v180, v180 row_bcast:15 row_mask:0xa bank_mask:0xf
	s_nop 1
	v_add_f32_dpp v180, v180, v180 row_bcast:31 row_mask:0xc bank_mask:0xf
	s_nop 0
	v_readlane_b32 s20, v180, 63
	s_nop 1
	v_mul_f32_e32 v184, s20, v2
	v_sub_f32_e32 v88, v88, v184
	v_sub_f32_e32 v89, v89, v184
	v_sub_f32_e32 v90, v90, v184
	v_sub_f32_e32 v91, v91, v184
	v_sub_f32_e32 v92, v92, v184
	v_sub_f32_e32 v93, v93, v184
	v_sub_f32_e32 v94, v94, v184
	v_sub_f32_e32 v95, v95, v184
	v_sub_f32_e32 v96, v96, v184
	v_sub_f32_e32 v97, v97, v184
	v_sub_f32_e32 v98, v98, v184
	v_sub_f32_e32 v99, v99, v184
	v_sub_f32_e32 v100, v100, v184
	v_sub_f32_e32 v101, v101, v184
	v_sub_f32_e32 v102, v102, v184
	v_sub_f32_e32 v103, v103, v184
	v_mul_f32_e32 v180, v88, v88
	v_mul_f32_e32 v181, v92, v92
	v_mul_f32_e32 v182, v96, v96
	v_mul_f32_e32 v183, v100, v100
	v_fmac_f32_e32 v180, v89, v89
	v_fmac_f32_e32 v181, v93, v93
	v_fmac_f32_e32 v182, v97, v97
	v_fmac_f32_e32 v183, v101, v101
	v_fmac_f32_e32 v180, v90, v90
	v_fmac_f32_e32 v181, v94, v94
	v_fmac_f32_e32 v182, v98, v98
	v_fmac_f32_e32 v183, v102, v102
	v_fmac_f32_e32 v180, v91, v91
	v_fmac_f32_e32 v181, v95, v95
	v_fmac_f32_e32 v182, v99, v99
	v_fmac_f32_e32 v183, v103, v103
	v_add_f32_e32 v180, v180, v181
	v_add_f32_e32 v182, v182, v183
	v_add_f32_e32 v180, v180, v182
	s_nop 1
	v_add_f32_dpp v180, v180, v180 quad_perm:[1,0,3,2] row_mask:0xf bank_mask:0xf
	s_nop 1
	v_add_f32_dpp v180, v180, v180 quad_perm:[2,3,0,1] row_mask:0xf bank_mask:0xf
	s_nop 1
	v_add_f32_dpp v180, v180, v180 row_half_mirror row_mask:0xf bank_mask:0xf
	s_nop 1
	v_add_f32_dpp v180, v180, v180 row_mirror row_mask:0xf bank_mask:0xf
	s_nop 1
	v_add_f32_dpp v180, v180, v180 row_bcast:15 row_mask:0xa bank_mask:0xf
	s_nop 1
	v_add_f32_dpp v180, v180, v180 row_bcast:31 row_mask:0xc bank_mask:0xf
	s_nop 0
	v_readlane_b32 s20, v180, 63
	s_nop 1
	v_mov_b32_e32 v185, s20
	v_fma_f32 v185, v185, v2, v4
	v_rsq_f32_e32 v185, v185
	s_nop 0
	v_mul_f32_e32 v88, v88, v185
	v_mul_f32_e32 v89, v89, v185
	v_mul_f32_e32 v90, v90, v185
	v_mul_f32_e32 v91, v91, v185
	v_mul_f32_e32 v92, v92, v185
	v_mul_f32_e32 v93, v93, v185
	v_mul_f32_e32 v94, v94, v185
	v_mul_f32_e32 v95, v95, v185
	v_mul_f32_e32 v96, v96, v185
	v_mul_f32_e32 v97, v97, v185
	v_mul_f32_e32 v98, v98, v185
	v_mul_f32_e32 v99, v99, v185
	v_mul_f32_e32 v100, v100, v185
	v_mul_f32_e32 v101, v101, v185
	v_mul_f32_e32 v102, v102, v185
	v_mul_f32_e32 v103, v103, v185
	v_fma_f32 v88, v88, v8, v24
	v_fma_f32 v89, v89, v9, v25
	v_fma_f32 v90, v90, v10, v26
	v_fma_f32 v91, v91, v11, v27
	v_fma_f32 v92, v92, v12, v28
	v_fma_f32 v93, v93, v13, v29
	v_fma_f32 v94, v94, v14, v30
	v_fma_f32 v95, v95, v15, v31
	v_fma_f32 v96, v96, v16, v32
	v_fma_f32 v97, v97, v17, v33
	v_fma_f32 v98, v98, v18, v34
	v_fma_f32 v99, v99, v19, v35
	v_fma_f32 v100, v100, v20, v36
	v_fma_f32 v101, v101, v21, v37
	v_fma_f32 v102, v102, v22, v38
	v_fma_f32 v103, v103, v23, v39
	v_add_u32_e32 v171, 0x1200000, v1
	global_store_dwordx4 v171, v[88:91], s[4:5]
	global_store_dwordx4 v171, v[92:95], s[4:5] offset:1024
	global_store_dwordx4 v171, v[96:99], s[4:5] offset:2048
	global_store_dwordx4 v171, v[100:103], s[4:5] offset:3072
	s_waitcnt vmcnt(40)
	v_add_f32_e32 v180, v104, v105
	v_add_f32_e32 v181, v108, v109
	v_add_f32_e32 v182, v112, v113
	v_add_f32_e32 v183, v116, v117
	v_add_f32_e32 v180, v180, v106
	v_add_f32_e32 v181, v181, v110
	v_add_f32_e32 v182, v182, v114
	v_add_f32_e32 v183, v183, v118
	v_add_f32_e32 v180, v180, v107
	v_add_f32_e32 v181, v181, v111
	v_add_f32_e32 v182, v182, v115
	v_add_f32_e32 v183, v183, v119
	v_add_f32_e32 v180, v180, v181
	v_add_f32_e32 v182, v182, v183
	v_add_f32_e32 v180, v180, v182
	s_nop 1
	v_add_f32_dpp v180, v180, v180 quad_perm:[1,0,3,2] row_mask:0xf bank_mask:0xf
	s_nop 1
	v_add_f32_dpp v180, v180, v180 quad_perm:[2,3,0,1] row_mask:0xf bank_mask:0xf
	s_nop 1
	v_add_f32_dpp v180, v180, v180 row_half_mirror row_mask:0xf bank_mask:0xf
	s_nop 1
	v_add_f32_dpp v180, v180, v180 row_mirror row_mask:0xf bank_mask:0xf
	s_nop 1
	v_add_f32_dpp v180, v180, v180 row_bcast:15 row_mask:0xa bank_mask:0xf
	s_nop 1
	v_add_f32_dpp v180, v180, v180 row_bcast:31 row_mask:0xc bank_mask:0xf
	s_nop 0
	v_readlane_b32 s20, v180, 63
	s_nop 1
	v_mul_f32_e32 v184, s20, v2
	v_sub_f32_e32 v104, v104, v184
	v_sub_f32_e32 v105, v105, v184
	v_sub_f32_e32 v106, v106, v184
	v_sub_f32_e32 v107, v107, v184
	v_sub_f32_e32 v108, v108, v184
	v_sub_f32_e32 v109, v109, v184
	v_sub_f32_e32 v110, v110, v184
	v_sub_f32_e32 v111, v111, v184
	v_sub_f32_e32 v112, v112, v184
	v_sub_f32_e32 v113, v113, v184
	v_sub_f32_e32 v114, v114, v184
	v_sub_f32_e32 v115, v115, v184
	v_sub_f32_e32 v116, v116, v184
	v_sub_f32_e32 v117, v117, v184
	v_sub_f32_e32 v118, v118, v184
	v_sub_f32_e32 v119, v119, v184
	v_mul_f32_e32 v180, v104, v104
	v_mul_f32_e32 v181, v108, v108
	v_mul_f32_e32 v182, v112, v112
	v_mul_f32_e32 v183, v116, v116
	v_fmac_f32_e32 v180, v105, v105
	v_fmac_f32_e32 v181, v109, v109
	v_fmac_f32_e32 v182, v113, v113
	v_fmac_f32_e32 v183, v117, v117
	v_fmac_f32_e32 v180, v106, v106
	v_fmac_f32_e32 v181, v110, v110
	v_fmac_f32_e32 v182, v114, v114
	v_fmac_f32_e32 v183, v118, v118
	v_fmac_f32_e32 v180, v107, v107
	v_fmac_f32_e32 v181, v111, v111
	v_fmac_f32_e32 v182, v115, v115
	v_fmac_f32_e32 v183, v119, v119
	v_add_f32_e32 v180, v180, v181
	v_add_f32_e32 v182, v182, v183
	v_add_f32_e32 v180, v180, v182
	s_nop 1
	v_add_f32_dpp v180, v180, v180 quad_perm:[1,0,3,2] row_mask:0xf bank_mask:0xf
	s_nop 1
	v_add_f32_dpp v180, v180, v180 quad_perm:[2,3,0,1] row_mask:0xf bank_mask:0xf
	s_nop 1
	v_add_f32_dpp v180, v180, v180 row_half_mirror row_mask:0xf bank_mask:0xf
	s_nop 1
	v_add_f32_dpp v180, v180, v180 row_mirror row_mask:0xf bank_mask:0xf
	s_nop 1
	v_add_f32_dpp v180, v180, v180 row_bcast:15 row_mask:0xa bank_mask:0xf
	s_nop 1
	v_add_f32_dpp v180, v180, v180 row_bcast:31 row_mask:0xc bank_mask:0xf
	s_nop 0
	v_readlane_b32 s20, v180, 63
	s_nop 1
	v_mov_b32_e32 v185, s20
	v_fma_f32 v185, v185, v2, v4
	v_rsq_f32_e32 v185, v185
	s_nop 0
	v_mul_f32_e32 v104, v104, v185
	v_mul_f32_e32 v105, v105, v185
	v_mul_f32_e32 v106, v106, v185
	v_mul_f32_e32 v107, v107, v185
	v_mul_f32_e32 v108, v108, v185
	v_mul_f32_e32 v109, v109, v185
	v_mul_f32_e32 v110, v110, v185
	v_mul_f32_e32 v111, v111, v185
	v_mul_f32_e32 v112, v112, v185
	v_mul_f32_e32 v113, v113, v185
	v_mul_f32_e32 v114, v114, v185
	v_mul_f32_e32 v115, v115, v185
	v_mul_f32_e32 v116, v116, v185
	v_mul_f32_e32 v117, v117, v185
	v_mul_f32_e32 v118, v118, v185
	v_mul_f32_e32 v119, v119, v185
	v_fma_f32 v104, v104, v8, v24
	v_fma_f32 v105, v105, v9, v25
	v_fma_f32 v106, v106, v10, v26
	v_fma_f32 v107, v107, v11, v27
	v_fma_f32 v108, v108, v12, v28
	v_fma_f32 v109, v109, v13, v29
	v_fma_f32 v110, v110, v14, v30
	v_fma_f32 v111, v111, v15, v31
	v_fma_f32 v112, v112, v16, v32
	v_fma_f32 v113, v113, v17, v33
	v_fma_f32 v114, v114, v18, v34
	v_fma_f32 v115, v115, v19, v35
	v_fma_f32 v116, v116, v20, v36
	v_fma_f32 v117, v117, v21, v37
	v_fma_f32 v118, v118, v22, v38
	v_fma_f32 v119, v119, v23, v39
	v_add_u32_e32 v171, 0x1800000, v1
	global_store_dwordx4 v171, v[104:107], s[4:5]
	global_store_dwordx4 v171, v[108:111], s[4:5] offset:1024
	global_store_dwordx4 v171, v[112:115], s[4:5] offset:2048
	global_store_dwordx4 v171, v[116:119], s[4:5] offset:3072
	s_waitcnt vmcnt(40)
	v_add_f32_e32 v180, v120, v121
	v_add_f32_e32 v181, v124, v125
	v_add_f32_e32 v182, v128, v129
	v_add_f32_e32 v183, v132, v133
	v_add_f32_e32 v180, v180, v122
	v_add_f32_e32 v181, v181, v126
	v_add_f32_e32 v182, v182, v130
	v_add_f32_e32 v183, v183, v134
	v_add_f32_e32 v180, v180, v123
	v_add_f32_e32 v181, v181, v127
	v_add_f32_e32 v182, v182, v131
	v_add_f32_e32 v183, v183, v135
	v_add_f32_e32 v180, v180, v181
	v_add_f32_e32 v182, v182, v183
	v_add_f32_e32 v180, v180, v182
	s_nop 1
	v_add_f32_dpp v180, v180, v180 quad_perm:[1,0,3,2] row_mask:0xf bank_mask:0xf
	s_nop 1
	v_add_f32_dpp v180, v180, v180 quad_perm:[2,3,0,1] row_mask:0xf bank_mask:0xf
	s_nop 1
	v_add_f32_dpp v180, v180, v180 row_half_mirror row_mask:0xf bank_mask:0xf
	s_nop 1
	v_add_f32_dpp v180, v180, v180 row_mirror row_mask:0xf bank_mask:0xf
	s_nop 1
	v_add_f32_dpp v180, v180, v180 row_bcast:15 row_mask:0xa bank_mask:0xf
	s_nop 1
	v_add_f32_dpp v180, v180, v180 row_bcast:31 row_mask:0xc bank_mask:0xf
	s_nop 0
	v_readlane_b32 s20, v180, 63
	s_nop 1
	v_mul_f32_e32 v184, s20, v2
	v_sub_f32_e32 v120, v120, v184
	v_sub_f32_e32 v121, v121, v184
	v_sub_f32_e32 v122, v122, v184
	v_sub_f32_e32 v123, v123, v184
	v_sub_f32_e32 v124, v124, v184
	v_sub_f32_e32 v125, v125, v184
	v_sub_f32_e32 v126, v126, v184
	v_sub_f32_e32 v127, v127, v184
	v_sub_f32_e32 v128, v128, v184
	v_sub_f32_e32 v129, v129, v184
	v_sub_f32_e32 v130, v130, v184
	v_sub_f32_e32 v131, v131, v184
	v_sub_f32_e32 v132, v132, v184
	v_sub_f32_e32 v133, v133, v184
	v_sub_f32_e32 v134, v134, v184
	v_sub_f32_e32 v135, v135, v184
	v_mul_f32_e32 v180, v120, v120
	v_mul_f32_e32 v181, v124, v124
	v_mul_f32_e32 v182, v128, v128
	v_mul_f32_e32 v183, v132, v132
	v_fmac_f32_e32 v180, v121, v121
	v_fmac_f32_e32 v181, v125, v125
	v_fmac_f32_e32 v182, v129, v129
	v_fmac_f32_e32 v183, v133, v133
	v_fmac_f32_e32 v180, v122, v122
	v_fmac_f32_e32 v181, v126, v126
	v_fmac_f32_e32 v182, v130, v130
	v_fmac_f32_e32 v183, v134, v134
	v_fmac_f32_e32 v180, v123, v123
	v_fmac_f32_e32 v181, v127, v127
	v_fmac_f32_e32 v182, v131, v131
	v_fmac_f32_e32 v183, v135, v135
	v_add_f32_e32 v180, v180, v181
	v_add_f32_e32 v182, v182, v183
	v_add_f32_e32 v180, v180, v182
	s_nop 1
	v_add_f32_dpp v180, v180, v180 quad_perm:[1,0,3,2] row_mask:0xf bank_mask:0xf
	s_nop 1
	v_add_f32_dpp v180, v180, v180 quad_perm:[2,3,0,1] row_mask:0xf bank_mask:0xf
	s_nop 1
	v_add_f32_dpp v180, v180, v180 row_half_mirror row_mask:0xf bank_mask:0xf
	s_nop 1
	v_add_f32_dpp v180, v180, v180 row_mirror row_mask:0xf bank_mask:0xf
	s_nop 1
	v_add_f32_dpp v180, v180, v180 row_bcast:15 row_mask:0xa bank_mask:0xf
	s_nop 1
	v_add_f32_dpp v180, v180, v180 row_bcast:31 row_mask:0xc bank_mask:0xf
	s_nop 0
	v_readlane_b32 s20, v180, 63
	s_nop 1
	v_mov_b32_e32 v185, s20
	v_fma_f32 v185, v185, v2, v4
	v_rsq_f32_e32 v185, v185
	s_nop 0
	v_mul_f32_e32 v120, v120, v185
	v_mul_f32_e32 v121, v121, v185
	v_mul_f32_e32 v122, v122, v185
	v_mul_f32_e32 v123, v123, v185
	v_mul_f32_e32 v124, v124, v185
	v_mul_f32_e32 v125, v125, v185
	v_mul_f32_e32 v126, v126, v185
	v_mul_f32_e32 v127, v127, v185
	v_mul_f32_e32 v128, v128, v185
	v_mul_f32_e32 v129, v129, v185
	v_mul_f32_e32 v130, v130, v185
	v_mul_f32_e32 v131, v131, v185
	v_mul_f32_e32 v132, v132, v185
	v_mul_f32_e32 v133, v133, v185
	v_mul_f32_e32 v134, v134, v185
	v_mul_f32_e32 v135, v135, v185
	v_fma_f32 v120, v120, v8, v24
	v_fma_f32 v121, v121, v9, v25
	v_fma_f32 v122, v122, v10, v26
	v_fma_f32 v123, v123, v11, v27
	v_fma_f32 v124, v124, v12, v28
	v_fma_f32 v125, v125, v13, v29
	v_fma_f32 v126, v126, v14, v30
	v_fma_f32 v127, v127, v15, v31
	v_fma_f32 v128, v128, v16, v32
	v_fma_f32 v129, v129, v17, v33
	v_fma_f32 v130, v130, v18, v34
	v_fma_f32 v131, v131, v19, v35
	v_fma_f32 v132, v132, v20, v36
	v_fma_f32 v133, v133, v21, v37
	v_fma_f32 v134, v134, v22, v38
	v_fma_f32 v135, v135, v23, v39
	v_add_u32_e32 v171, 0x1e00000, v1
	global_store_dwordx4 v171, v[120:123], s[4:5]
	global_store_dwordx4 v171, v[124:127], s[4:5] offset:1024
	global_store_dwordx4 v171, v[128:131], s[4:5] offset:2048
	global_store_dwordx4 v171, v[132:135], s[4:5] offset:3072
	s_waitcnt vmcnt(40)
	v_add_f32_e32 v180, v136, v137
	v_add_f32_e32 v181, v140, v141
	v_add_f32_e32 v182, v144, v145
	v_add_f32_e32 v183, v148, v149
	v_add_f32_e32 v180, v180, v138
	v_add_f32_e32 v181, v181, v142
	v_add_f32_e32 v182, v182, v146
	v_add_f32_e32 v183, v183, v150
	v_add_f32_e32 v180, v180, v139
	v_add_f32_e32 v181, v181, v143
	v_add_f32_e32 v182, v182, v147
	v_add_f32_e32 v183, v183, v151
	v_add_f32_e32 v180, v180, v181
	v_add_f32_e32 v182, v182, v183
	v_add_f32_e32 v180, v180, v182
	s_nop 1
	v_add_f32_dpp v180, v180, v180 quad_perm:[1,0,3,2] row_mask:0xf bank_mask:0xf
	s_nop 1
	v_add_f32_dpp v180, v180, v180 quad_perm:[2,3,0,1] row_mask:0xf bank_mask:0xf
	s_nop 1
	v_add_f32_dpp v180, v180, v180 row_half_mirror row_mask:0xf bank_mask:0xf
	s_nop 1
	v_add_f32_dpp v180, v180, v180 row_mirror row_mask:0xf bank_mask:0xf
	s_nop 1
	v_add_f32_dpp v180, v180, v180 row_bcast:15 row_mask:0xa bank_mask:0xf
	s_nop 1
	v_add_f32_dpp v180, v180, v180 row_bcast:31 row_mask:0xc bank_mask:0xf
	s_nop 0
	v_readlane_b32 s20, v180, 63
	s_nop 1
	v_mul_f32_e32 v184, s20, v2
	v_sub_f32_e32 v136, v136, v184
	v_sub_f32_e32 v137, v137, v184
	v_sub_f32_e32 v138, v138, v184
	v_sub_f32_e32 v139, v139, v184
	v_sub_f32_e32 v140, v140, v184
	v_sub_f32_e32 v141, v141, v184
	v_sub_f32_e32 v142, v142, v184
	v_sub_f32_e32 v143, v143, v184
	v_sub_f32_e32 v144, v144, v184
	v_sub_f32_e32 v145, v145, v184
	v_sub_f32_e32 v146, v146, v184
	v_sub_f32_e32 v147, v147, v184
	v_sub_f32_e32 v148, v148, v184
	v_sub_f32_e32 v149, v149, v184
	v_sub_f32_e32 v150, v150, v184
	v_sub_f32_e32 v151, v151, v184
	v_mul_f32_e32 v180, v136, v136
	v_mul_f32_e32 v181, v140, v140
	v_mul_f32_e32 v182, v144, v144
	v_mul_f32_e32 v183, v148, v148
	v_fmac_f32_e32 v180, v137, v137
	v_fmac_f32_e32 v181, v141, v141
	v_fmac_f32_e32 v182, v145, v145
	v_fmac_f32_e32 v183, v149, v149
	v_fmac_f32_e32 v180, v138, v138
	v_fmac_f32_e32 v181, v142, v142
	v_fmac_f32_e32 v182, v146, v146
	v_fmac_f32_e32 v183, v150, v150
	v_fmac_f32_e32 v180, v139, v139
	v_fmac_f32_e32 v181, v143, v143
	v_fmac_f32_e32 v182, v147, v147
	v_fmac_f32_e32 v183, v151, v151
	v_add_f32_e32 v180, v180, v181
	v_add_f32_e32 v182, v182, v183
	v_add_f32_e32 v180, v180, v182
	s_nop 1
	v_add_f32_dpp v180, v180, v180 quad_perm:[1,0,3,2] row_mask:0xf bank_mask:0xf
	s_nop 1
	v_add_f32_dpp v180, v180, v180 quad_perm:[2,3,0,1] row_mask:0xf bank_mask:0xf
	s_nop 1
	v_add_f32_dpp v180, v180, v180 row_half_mirror row_mask:0xf bank_mask:0xf
	s_nop 1
	v_add_f32_dpp v180, v180, v180 row_mirror row_mask:0xf bank_mask:0xf
	s_nop 1
	v_add_f32_dpp v180, v180, v180 row_bcast:15 row_mask:0xa bank_mask:0xf
	s_nop 1
	v_add_f32_dpp v180, v180, v180 row_bcast:31 row_mask:0xc bank_mask:0xf
	s_nop 0
	v_readlane_b32 s20, v180, 63
	s_nop 1
	v_mov_b32_e32 v185, s20
	v_fma_f32 v185, v185, v2, v4
	v_rsq_f32_e32 v185, v185
	s_nop 0
	v_mul_f32_e32 v136, v136, v185
	v_mul_f32_e32 v137, v137, v185
	v_mul_f32_e32 v138, v138, v185
	v_mul_f32_e32 v139, v139, v185
	v_mul_f32_e32 v140, v140, v185
	v_mul_f32_e32 v141, v141, v185
	v_mul_f32_e32 v142, v142, v185
	v_mul_f32_e32 v143, v143, v185
	v_mul_f32_e32 v144, v144, v185
	v_mul_f32_e32 v145, v145, v185
	v_mul_f32_e32 v146, v146, v185
	v_mul_f32_e32 v147, v147, v185
	v_mul_f32_e32 v148, v148, v185
	v_mul_f32_e32 v149, v149, v185
	v_mul_f32_e32 v150, v150, v185
	v_mul_f32_e32 v151, v151, v185
	v_fma_f32 v136, v136, v8, v24
	v_fma_f32 v137, v137, v9, v25
	v_fma_f32 v138, v138, v10, v26
	v_fma_f32 v139, v139, v11, v27
	v_fma_f32 v140, v140, v12, v28
	v_fma_f32 v141, v141, v13, v29
	v_fma_f32 v142, v142, v14, v30
	v_fma_f32 v143, v143, v15, v31
	v_fma_f32 v144, v144, v16, v32
	v_fma_f32 v145, v145, v17, v33
	v_fma_f32 v146, v146, v18, v34
	v_fma_f32 v147, v147, v19, v35
	v_fma_f32 v148, v148, v20, v36
	v_fma_f32 v149, v149, v21, v37
	v_fma_f32 v150, v150, v22, v38
	v_fma_f32 v151, v151, v23, v39
	v_add_u32_e32 v171, 0x2400000, v1
	global_store_dwordx4 v171, v[136:139], s[4:5]
	global_store_dwordx4 v171, v[140:143], s[4:5] offset:1024
	global_store_dwordx4 v171, v[144:147], s[4:5] offset:2048
	global_store_dwordx4 v171, v[148:151], s[4:5] offset:3072
	s_waitcnt vmcnt(40)
	v_add_f32_e32 v180, v152, v153
	v_add_f32_e32 v181, v156, v157
	v_add_f32_e32 v182, v160, v161
	v_add_f32_e32 v183, v164, v165
	v_add_f32_e32 v180, v180, v154
	v_add_f32_e32 v181, v181, v158
	v_add_f32_e32 v182, v182, v162
	v_add_f32_e32 v183, v183, v166
	v_add_f32_e32 v180, v180, v155
	v_add_f32_e32 v181, v181, v159
	v_add_f32_e32 v182, v182, v163
	v_add_f32_e32 v183, v183, v167
	v_add_f32_e32 v180, v180, v181
	v_add_f32_e32 v182, v182, v183
	v_add_f32_e32 v180, v180, v182
	s_nop 1
	v_add_f32_dpp v180, v180, v180 quad_perm:[1,0,3,2] row_mask:0xf bank_mask:0xf
	s_nop 1
	v_add_f32_dpp v180, v180, v180 quad_perm:[2,3,0,1] row_mask:0xf bank_mask:0xf
	s_nop 1
	v_add_f32_dpp v180, v180, v180 row_half_mirror row_mask:0xf bank_mask:0xf
	s_nop 1
	v_add_f32_dpp v180, v180, v180 row_mirror row_mask:0xf bank_mask:0xf
	s_nop 1
	v_add_f32_dpp v180, v180, v180 row_bcast:15 row_mask:0xa bank_mask:0xf
	s_nop 1
	v_add_f32_dpp v180, v180, v180 row_bcast:31 row_mask:0xc bank_mask:0xf
	s_nop 0
	v_readlane_b32 s20, v180, 63
	s_nop 1
	v_mul_f32_e32 v184, s20, v2
	v_sub_f32_e32 v152, v152, v184
	v_sub_f32_e32 v153, v153, v184
	v_sub_f32_e32 v154, v154, v184
	v_sub_f32_e32 v155, v155, v184
	v_sub_f32_e32 v156, v156, v184
	v_sub_f32_e32 v157, v157, v184
	v_sub_f32_e32 v158, v158, v184
	v_sub_f32_e32 v159, v159, v184
	v_sub_f32_e32 v160, v160, v184
	v_sub_f32_e32 v161, v161, v184
	v_sub_f32_e32 v162, v162, v184
	v_sub_f32_e32 v163, v163, v184
	v_sub_f32_e32 v164, v164, v184
	v_sub_f32_e32 v165, v165, v184
	v_sub_f32_e32 v166, v166, v184
	v_sub_f32_e32 v167, v167, v184
	v_mul_f32_e32 v180, v152, v152
	v_mul_f32_e32 v181, v156, v156
	v_mul_f32_e32 v182, v160, v160
	v_mul_f32_e32 v183, v164, v164
	v_fmac_f32_e32 v180, v153, v153
	v_fmac_f32_e32 v181, v157, v157
	v_fmac_f32_e32 v182, v161, v161
	v_fmac_f32_e32 v183, v165, v165
	v_fmac_f32_e32 v180, v154, v154
	v_fmac_f32_e32 v181, v158, v158
	v_fmac_f32_e32 v182, v162, v162
	v_fmac_f32_e32 v183, v166, v166
	v_fmac_f32_e32 v180, v155, v155
	v_fmac_f32_e32 v181, v159, v159
	v_fmac_f32_e32 v182, v163, v163
	v_fmac_f32_e32 v183, v167, v167
	v_add_f32_e32 v180, v180, v181
	v_add_f32_e32 v182, v182, v183
	v_add_f32_e32 v180, v180, v182
	s_nop 1
	v_add_f32_dpp v180, v180, v180 quad_perm:[1,0,3,2] row_mask:0xf bank_mask:0xf
	s_nop 1
	v_add_f32_dpp v180, v180, v180 quad_perm:[2,3,0,1] row_mask:0xf bank_mask:0xf
	s_nop 1
	v_add_f32_dpp v180, v180, v180 row_half_mirror row_mask:0xf bank_mask:0xf
	s_nop 1
	v_add_f32_dpp v180, v180, v180 row_mirror row_mask:0xf bank_mask:0xf
	s_nop 1
	v_add_f32_dpp v180, v180, v180 row_bcast:15 row_mask:0xa bank_mask:0xf
	s_nop 1
	v_add_f32_dpp v180, v180, v180 row_bcast:31 row_mask:0xc bank_mask:0xf
	s_nop 0
	v_readlane_b32 s20, v180, 63
	s_nop 1
	v_mov_b32_e32 v185, s20
	v_fma_f32 v185, v185, v2, v4
	v_rsq_f32_e32 v185, v185
	s_nop 0
	v_mul_f32_e32 v152, v152, v185
	v_mul_f32_e32 v153, v153, v185
	v_mul_f32_e32 v154, v154, v185
	v_mul_f32_e32 v155, v155, v185
	v_mul_f32_e32 v156, v156, v185
	v_mul_f32_e32 v157, v157, v185
	v_mul_f32_e32 v158, v158, v185
	v_mul_f32_e32 v159, v159, v185
	v_mul_f32_e32 v160, v160, v185
	v_mul_f32_e32 v161, v161, v185
	v_mul_f32_e32 v162, v162, v185
	v_mul_f32_e32 v163, v163, v185
	v_mul_f32_e32 v164, v164, v185
	v_mul_f32_e32 v165, v165, v185
	v_mul_f32_e32 v166, v166, v185
	v_mul_f32_e32 v167, v167, v185
	v_fma_f32 v152, v152, v8, v24
	v_fma_f32 v153, v153, v9, v25
	v_fma_f32 v154, v154, v10, v26
	v_fma_f32 v155, v155, v11, v27
	v_fma_f32 v156, v156, v12, v28
	v_fma_f32 v157, v157, v13, v29
	v_fma_f32 v158, v158, v14, v30
	v_fma_f32 v159, v159, v15, v31
	v_fma_f32 v160, v160, v16, v32
	v_fma_f32 v161, v161, v17, v33
	v_fma_f32 v162, v162, v18, v34
	v_fma_f32 v163, v163, v19, v35
	v_fma_f32 v164, v164, v20, v36
	v_fma_f32 v165, v165, v21, v37
	v_fma_f32 v166, v166, v22, v38
	v_fma_f32 v167, v167, v23, v39
	v_add_u32_e32 v171, 0x2a00000, v1
	global_store_dwordx4 v171, v[152:155], s[4:5]
	global_store_dwordx4 v171, v[156:159], s[4:5] offset:1024
	global_store_dwordx4 v171, v[160:163], s[4:5] offset:2048
	global_store_dwordx4 v171, v[164:167], s[4:5] offset:3072
	s_waitcnt vmcnt(36)
	v_add_f32_e32 v180, v40, v41
	v_add_f32_e32 v181, v44, v45
	v_add_f32_e32 v182, v48, v49
	v_add_f32_e32 v183, v52, v53
	v_add_f32_e32 v180, v180, v42
	v_add_f32_e32 v181, v181, v46
	v_add_f32_e32 v182, v182, v50
	v_add_f32_e32 v183, v183, v54
	v_add_f32_e32 v180, v180, v43
	v_add_f32_e32 v181, v181, v47
	v_add_f32_e32 v182, v182, v51
	v_add_f32_e32 v183, v183, v55
	v_add_f32_e32 v180, v180, v181
	v_add_f32_e32 v182, v182, v183
	v_add_f32_e32 v180, v180, v182
	s_nop 1
	v_add_f32_dpp v180, v180, v180 quad_perm:[1,0,3,2] row_mask:0xf bank_mask:0xf
	s_nop 1
	v_add_f32_dpp v180, v180, v180 quad_perm:[2,3,0,1] row_mask:0xf bank_mask:0xf
	s_nop 1
	v_add_f32_dpp v180, v180, v180 row_half_mirror row_mask:0xf bank_mask:0xf
	s_nop 1
	v_add_f32_dpp v180, v180, v180 row_mirror row_mask:0xf bank_mask:0xf
	s_nop 1
	v_add_f32_dpp v180, v180, v180 row_bcast:15 row_mask:0xa bank_mask:0xf
	s_nop 1
	v_add_f32_dpp v180, v180, v180 row_bcast:31 row_mask:0xc bank_mask:0xf
	s_nop 0
	v_readlane_b32 s20, v180, 63
	s_nop 1
	v_mul_f32_e32 v184, s20, v2
	v_sub_f32_e32 v40, v40, v184
	v_sub_f32_e32 v41, v41, v184
	v_sub_f32_e32 v42, v42, v184
	v_sub_f32_e32 v43, v43, v184
	v_sub_f32_e32 v44, v44, v184
	v_sub_f32_e32 v45, v45, v184
	v_sub_f32_e32 v46, v46, v184
	v_sub_f32_e32 v47, v47, v184
	v_sub_f32_e32 v48, v48, v184
	v_sub_f32_e32 v49, v49, v184
	v_sub_f32_e32 v50, v50, v184
	v_sub_f32_e32 v51, v51, v184
	v_sub_f32_e32 v52, v52, v184
	v_sub_f32_e32 v53, v53, v184
	v_sub_f32_e32 v54, v54, v184
	v_sub_f32_e32 v55, v55, v184
	v_mul_f32_e32 v180, v40, v40
	v_mul_f32_e32 v181, v44, v44
	v_mul_f32_e32 v182, v48, v48
	v_mul_f32_e32 v183, v52, v52
	v_fmac_f32_e32 v180, v41, v41
	v_fmac_f32_e32 v181, v45, v45
	v_fmac_f32_e32 v182, v49, v49
	v_fmac_f32_e32 v183, v53, v53
	v_fmac_f32_e32 v180, v42, v42
	v_fmac_f32_e32 v181, v46, v46
	v_fmac_f32_e32 v182, v50, v50
	v_fmac_f32_e32 v183, v54, v54
	v_fmac_f32_e32 v180, v43, v43
	v_fmac_f32_e32 v181, v47, v47
	v_fmac_f32_e32 v182, v51, v51
	v_fmac_f32_e32 v183, v55, v55
	v_add_f32_e32 v180, v180, v181
	v_add_f32_e32 v182, v182, v183
	v_add_f32_e32 v180, v180, v182
	s_nop 1
	v_add_f32_dpp v180, v180, v180 quad_perm:[1,0,3,2] row_mask:0xf bank_mask:0xf
	s_nop 1
	v_add_f32_dpp v180, v180, v180 quad_perm:[2,3,0,1] row_mask:0xf bank_mask:0xf
	s_nop 1
	v_add_f32_dpp v180, v180, v180 row_half_mirror row_mask:0xf bank_mask:0xf
	s_nop 1
	v_add_f32_dpp v180, v180, v180 row_mirror row_mask:0xf bank_mask:0xf
	s_nop 1
	v_add_f32_dpp v180, v180, v180 row_bcast:15 row_mask:0xa bank_mask:0xf
	s_nop 1
	v_add_f32_dpp v180, v180, v180 row_bcast:31 row_mask:0xc bank_mask:0xf
	s_nop 0
	v_readlane_b32 s20, v180, 63
	s_nop 1
	v_mov_b32_e32 v185, s20
	v_fma_f32 v185, v185, v2, v4
	v_rsq_f32_e32 v185, v185
	s_nop 0
	v_mul_f32_e32 v40, v40, v185
	v_mul_f32_e32 v41, v41, v185
	v_mul_f32_e32 v42, v42, v185
	v_mul_f32_e32 v43, v43, v185
	v_mul_f32_e32 v44, v44, v185
	v_mul_f32_e32 v45, v45, v185
	v_mul_f32_e32 v46, v46, v185
	v_mul_f32_e32 v47, v47, v185
	v_mul_f32_e32 v48, v48, v185
	v_mul_f32_e32 v49, v49, v185
	v_mul_f32_e32 v50, v50, v185
	v_mul_f32_e32 v51, v51, v185
	v_mul_f32_e32 v52, v52, v185
	v_mul_f32_e32 v53, v53, v185
	v_mul_f32_e32 v54, v54, v185
	v_mul_f32_e32 v55, v55, v185
	v_fma_f32 v40, v40, v8, v24
	v_fma_f32 v41, v41, v9, v25
	v_fma_f32 v42, v42, v10, v26
	v_fma_f32 v43, v43, v11, v27
	v_fma_f32 v44, v44, v12, v28
	v_fma_f32 v45, v45, v13, v29
	v_fma_f32 v46, v46, v14, v30
	v_fma_f32 v47, v47, v15, v31
	v_fma_f32 v48, v48, v16, v32
	v_fma_f32 v49, v49, v17, v33
	v_fma_f32 v50, v50, v18, v34
	v_fma_f32 v51, v51, v19, v35
	v_fma_f32 v52, v52, v20, v36
	v_fma_f32 v53, v53, v21, v37
	v_fma_f32 v54, v54, v22, v38
	v_fma_f32 v55, v55, v23, v39
	v_add_u32_e32 v171, 0x3000000, v1
	global_store_dwordx4 v171, v[40:43], s[4:5]
	global_store_dwordx4 v171, v[44:47], s[4:5] offset:1024
	global_store_dwordx4 v171, v[48:51], s[4:5] offset:2048
	global_store_dwordx4 v171, v[52:55], s[4:5] offset:3072
	s_waitcnt vmcnt(32)
	v_add_f32_e32 v180, v56, v57
	v_add_f32_e32 v181, v60, v61
	v_add_f32_e32 v182, v64, v65
	v_add_f32_e32 v183, v68, v69
	v_add_f32_e32 v180, v180, v58
	v_add_f32_e32 v181, v181, v62
	v_add_f32_e32 v182, v182, v66
	v_add_f32_e32 v183, v183, v70
	v_add_f32_e32 v180, v180, v59
	v_add_f32_e32 v181, v181, v63
	v_add_f32_e32 v182, v182, v67
	v_add_f32_e32 v183, v183, v71
	v_add_f32_e32 v180, v180, v181
	v_add_f32_e32 v182, v182, v183
	v_add_f32_e32 v180, v180, v182
	s_nop 1
	v_add_f32_dpp v180, v180, v180 quad_perm:[1,0,3,2] row_mask:0xf bank_mask:0xf
	s_nop 1
	v_add_f32_dpp v180, v180, v180 quad_perm:[2,3,0,1] row_mask:0xf bank_mask:0xf
	s_nop 1
	v_add_f32_dpp v180, v180, v180 row_half_mirror row_mask:0xf bank_mask:0xf
	s_nop 1
	v_add_f32_dpp v180, v180, v180 row_mirror row_mask:0xf bank_mask:0xf
	s_nop 1
	v_add_f32_dpp v180, v180, v180 row_bcast:15 row_mask:0xa bank_mask:0xf
	s_nop 1
	v_add_f32_dpp v180, v180, v180 row_bcast:31 row_mask:0xc bank_mask:0xf
	s_nop 0
	v_readlane_b32 s20, v180, 63
	s_nop 1
	v_mul_f32_e32 v184, s20, v2
	v_sub_f32_e32 v56, v56, v184
	v_sub_f32_e32 v57, v57, v184
	v_sub_f32_e32 v58, v58, v184
	v_sub_f32_e32 v59, v59, v184
	v_sub_f32_e32 v60, v60, v184
	v_sub_f32_e32 v61, v61, v184
	v_sub_f32_e32 v62, v62, v184
	v_sub_f32_e32 v63, v63, v184
	v_sub_f32_e32 v64, v64, v184
	v_sub_f32_e32 v65, v65, v184
	v_sub_f32_e32 v66, v66, v184
	v_sub_f32_e32 v67, v67, v184
	v_sub_f32_e32 v68, v68, v184
	v_sub_f32_e32 v69, v69, v184
	v_sub_f32_e32 v70, v70, v184
	v_sub_f32_e32 v71, v71, v184
	v_mul_f32_e32 v180, v56, v56
	v_mul_f32_e32 v181, v60, v60
	v_mul_f32_e32 v182, v64, v64
	v_mul_f32_e32 v183, v68, v68
	v_fmac_f32_e32 v180, v57, v57
	v_fmac_f32_e32 v181, v61, v61
	v_fmac_f32_e32 v182, v65, v65
	v_fmac_f32_e32 v183, v69, v69
	v_fmac_f32_e32 v180, v58, v58
	v_fmac_f32_e32 v181, v62, v62
	v_fmac_f32_e32 v182, v66, v66
	v_fmac_f32_e32 v183, v70, v70
	v_fmac_f32_e32 v180, v59, v59
	v_fmac_f32_e32 v181, v63, v63
	v_fmac_f32_e32 v182, v67, v67
	v_fmac_f32_e32 v183, v71, v71
	v_add_f32_e32 v180, v180, v181
	v_add_f32_e32 v182, v182, v183
	v_add_f32_e32 v180, v180, v182
	s_nop 1
	v_add_f32_dpp v180, v180, v180 quad_perm:[1,0,3,2] row_mask:0xf bank_mask:0xf
	s_nop 1
	v_add_f32_dpp v180, v180, v180 quad_perm:[2,3,0,1] row_mask:0xf bank_mask:0xf
	s_nop 1
	v_add_f32_dpp v180, v180, v180 row_half_mirror row_mask:0xf bank_mask:0xf
	s_nop 1
	v_add_f32_dpp v180, v180, v180 row_mirror row_mask:0xf bank_mask:0xf
	s_nop 1
	v_add_f32_dpp v180, v180, v180 row_bcast:15 row_mask:0xa bank_mask:0xf
	s_nop 1
	v_add_f32_dpp v180, v180, v180 row_bcast:31 row_mask:0xc bank_mask:0xf
	s_nop 0
	v_readlane_b32 s20, v180, 63
	s_nop 1
	v_mov_b32_e32 v185, s20
	v_fma_f32 v185, v185, v2, v4
	v_rsq_f32_e32 v185, v185
	s_nop 0
	v_mul_f32_e32 v56, v56, v185
	v_mul_f32_e32 v57, v57, v185
	v_mul_f32_e32 v58, v58, v185
	v_mul_f32_e32 v59, v59, v185
	v_mul_f32_e32 v60, v60, v185
	v_mul_f32_e32 v61, v61, v185
	v_mul_f32_e32 v62, v62, v185
	v_mul_f32_e32 v63, v63, v185
	v_mul_f32_e32 v64, v64, v185
	v_mul_f32_e32 v65, v65, v185
	v_mul_f32_e32 v66, v66, v185
	v_mul_f32_e32 v67, v67, v185
	v_mul_f32_e32 v68, v68, v185
	v_mul_f32_e32 v69, v69, v185
	v_mul_f32_e32 v70, v70, v185
	v_mul_f32_e32 v71, v71, v185
	v_fma_f32 v56, v56, v8, v24
	v_fma_f32 v57, v57, v9, v25
	v_fma_f32 v58, v58, v10, v26
	v_fma_f32 v59, v59, v11, v27
	v_fma_f32 v60, v60, v12, v28
	v_fma_f32 v61, v61, v13, v29
	v_fma_f32 v62, v62, v14, v30
	v_fma_f32 v63, v63, v15, v31
	v_fma_f32 v64, v64, v16, v32
	v_fma_f32 v65, v65, v17, v33
	v_fma_f32 v66, v66, v18, v34
	v_fma_f32 v67, v67, v19, v35
	v_fma_f32 v68, v68, v20, v36
	v_fma_f32 v69, v69, v21, v37
	v_fma_f32 v70, v70, v22, v38
	v_fma_f32 v71, v71, v23, v39
	v_add_u32_e32 v171, 0x3600000, v1
	global_store_dwordx4 v171, v[56:59], s[4:5]
	global_store_dwordx4 v171, v[60:63], s[4:5] offset:1024
	global_store_dwordx4 v171, v[64:67], s[4:5] offset:2048
	global_store_dwordx4 v171, v[68:71], s[4:5] offset:3072
	s_waitcnt vmcnt(28)
	v_add_f32_e32 v180, v72, v73
	v_add_f32_e32 v181, v76, v77
	v_add_f32_e32 v182, v80, v81
	v_add_f32_e32 v183, v84, v85
	v_add_f32_e32 v180, v180, v74
	v_add_f32_e32 v181, v181, v78
	v_add_f32_e32 v182, v182, v82
	v_add_f32_e32 v183, v183, v86
	v_add_f32_e32 v180, v180, v75
	v_add_f32_e32 v181, v181, v79
	v_add_f32_e32 v182, v182, v83
	v_add_f32_e32 v183, v183, v87
	v_add_f32_e32 v180, v180, v181
	v_add_f32_e32 v182, v182, v183
	v_add_f32_e32 v180, v180, v182
	s_nop 1
	v_add_f32_dpp v180, v180, v180 quad_perm:[1,0,3,2] row_mask:0xf bank_mask:0xf
	s_nop 1
	v_add_f32_dpp v180, v180, v180 quad_perm:[2,3,0,1] row_mask:0xf bank_mask:0xf
	s_nop 1
	v_add_f32_dpp v180, v180, v180 row_half_mirror row_mask:0xf bank_mask:0xf
	s_nop 1
	v_add_f32_dpp v180, v180, v180 row_mirror row_mask:0xf bank_mask:0xf
	s_nop 1
	v_add_f32_dpp v180, v180, v180 row_bcast:15 row_mask:0xa bank_mask:0xf
	s_nop 1
	v_add_f32_dpp v180, v180, v180 row_bcast:31 row_mask:0xc bank_mask:0xf
	s_nop 0
	v_readlane_b32 s20, v180, 63
	s_nop 1
	v_mul_f32_e32 v184, s20, v2
	v_sub_f32_e32 v72, v72, v184
	v_sub_f32_e32 v73, v73, v184
	v_sub_f32_e32 v74, v74, v184
	v_sub_f32_e32 v75, v75, v184
	v_sub_f32_e32 v76, v76, v184
	v_sub_f32_e32 v77, v77, v184
	v_sub_f32_e32 v78, v78, v184
	v_sub_f32_e32 v79, v79, v184
	v_sub_f32_e32 v80, v80, v184
	v_sub_f32_e32 v81, v81, v184
	v_sub_f32_e32 v82, v82, v184
	v_sub_f32_e32 v83, v83, v184
	v_sub_f32_e32 v84, v84, v184
	v_sub_f32_e32 v85, v85, v184
	v_sub_f32_e32 v86, v86, v184
	v_sub_f32_e32 v87, v87, v184
	v_mul_f32_e32 v180, v72, v72
	v_mul_f32_e32 v181, v76, v76
	v_mul_f32_e32 v182, v80, v80
	v_mul_f32_e32 v183, v84, v84
	v_fmac_f32_e32 v180, v73, v73
	v_fmac_f32_e32 v181, v77, v77
	v_fmac_f32_e32 v182, v81, v81
	v_fmac_f32_e32 v183, v85, v85
	v_fmac_f32_e32 v180, v74, v74
	v_fmac_f32_e32 v181, v78, v78
	v_fmac_f32_e32 v182, v82, v82
	v_fmac_f32_e32 v183, v86, v86
	v_fmac_f32_e32 v180, v75, v75
	v_fmac_f32_e32 v181, v79, v79
	v_fmac_f32_e32 v182, v83, v83
	v_fmac_f32_e32 v183, v87, v87
	v_add_f32_e32 v180, v180, v181
	v_add_f32_e32 v182, v182, v183
	v_add_f32_e32 v180, v180, v182
	s_nop 1
	v_add_f32_dpp v180, v180, v180 quad_perm:[1,0,3,2] row_mask:0xf bank_mask:0xf
	s_nop 1
	v_add_f32_dpp v180, v180, v180 quad_perm:[2,3,0,1] row_mask:0xf bank_mask:0xf
	s_nop 1
	v_add_f32_dpp v180, v180, v180 row_half_mirror row_mask:0xf bank_mask:0xf
	s_nop 1
	v_add_f32_dpp v180, v180, v180 row_mirror row_mask:0xf bank_mask:0xf
	s_nop 1
	v_add_f32_dpp v180, v180, v180 row_bcast:15 row_mask:0xa bank_mask:0xf
	s_nop 1
	v_add_f32_dpp v180, v180, v180 row_bcast:31 row_mask:0xc bank_mask:0xf
	s_nop 0
	v_readlane_b32 s20, v180, 63
	s_nop 1
	v_mov_b32_e32 v185, s20
	v_fma_f32 v185, v185, v2, v4
	v_rsq_f32_e32 v185, v185
	s_nop 0
	v_mul_f32_e32 v72, v72, v185
	v_mul_f32_e32 v73, v73, v185
	v_mul_f32_e32 v74, v74, v185
	v_mul_f32_e32 v75, v75, v185
	v_mul_f32_e32 v76, v76, v185
	v_mul_f32_e32 v77, v77, v185
	v_mul_f32_e32 v78, v78, v185
	v_mul_f32_e32 v79, v79, v185
	v_mul_f32_e32 v80, v80, v185
	v_mul_f32_e32 v81, v81, v185
	v_mul_f32_e32 v82, v82, v185
	v_mul_f32_e32 v83, v83, v185
	v_mul_f32_e32 v84, v84, v185
	v_mul_f32_e32 v85, v85, v185
	v_mul_f32_e32 v86, v86, v185
	v_mul_f32_e32 v87, v87, v185
	v_fma_f32 v72, v72, v8, v24
	v_fma_f32 v73, v73, v9, v25
	v_fma_f32 v74, v74, v10, v26
	v_fma_f32 v75, v75, v11, v27
	v_fma_f32 v76, v76, v12, v28
	v_fma_f32 v77, v77, v13, v29
	v_fma_f32 v78, v78, v14, v30
	v_fma_f32 v79, v79, v15, v31
	v_fma_f32 v80, v80, v16, v32
	v_fma_f32 v81, v81, v17, v33
	v_fma_f32 v82, v82, v18, v34
	v_fma_f32 v83, v83, v19, v35
	v_fma_f32 v84, v84, v20, v36
	v_fma_f32 v85, v85, v21, v37
	v_fma_f32 v86, v86, v22, v38
	v_fma_f32 v87, v87, v23, v39
	v_add_u32_e32 v171, 0x3c00000, v1
	global_store_dwordx4 v171, v[72:75], s[4:5]
	global_store_dwordx4 v171, v[76:79], s[4:5] offset:1024
	global_store_dwordx4 v171, v[80:83], s[4:5] offset:2048
	global_store_dwordx4 v171, v[84:87], s[4:5] offset:3072
	s_branch .Ltr_29
.Llo_r10:
	global_load_dwordx4 v[40:43], v1, s[4:5] nt
	global_load_dwordx4 v[44:47], v1, s[4:5] offset:1024 nt
	global_load_dwordx4 v[48:51], v1, s[4:5] offset:2048 nt
	global_load_dwordx4 v[52:55], v1, s[4:5] offset:3072 nt
	global_load_dwordx4 v[8:11], v1, s[40:41]
	global_load_dwordx4 v[12:15], v1, s[40:41] offset:1024
	global_load_dwordx4 v[16:19], v1, s[40:41] offset:2048
	global_load_dwordx4 v[20:23], v1, s[40:41] offset:3072
	global_load_dwordx4 v[24:27], v1, s[42:43]
	global_load_dwordx4 v[28:31], v1, s[42:43] offset:1024
	global_load_dwordx4 v[32:35], v1, s[42:43] offset:2048
	global_load_dwordx4 v[36:39], v1, s[42:43] offset:3072
	v_add_u32_e32 v170, 0x600000, v1
	global_load_dwordx4 v[56:59], v170, s[4:5] nt
	global_load_dwordx4 v[60:63], v170, s[4:5] offset:1024 nt
	global_load_dwordx4 v[64:67], v170, s[4:5] offset:2048 nt
	global_load_dwordx4 v[68:71], v170, s[4:5] offset:3072 nt
	v_add_u32_e32 v170, 0xc00000, v1
	global_load_dwordx4 v[72:75], v170, s[4:5] nt
	global_load_dwordx4 v[76:79], v170, s[4:5] offset:1024 nt
	global_load_dwordx4 v[80:83], v170, s[4:5] offset:2048 nt
	global_load_dwordx4 v[84:87], v170, s[4:5] offset:3072 nt
	v_add_u32_e32 v170, 0x1200000, v1
	global_load_dwordx4 v[88:91], v170, s[4:5] nt
	global_load_dwordx4 v[92:95], v170, s[4:5] offset:1024 nt
	global_load_dwordx4 v[96:99], v170, s[4:5] offset:2048 nt
	global_load_dwordx4 v[100:103], v170, s[4:5] offset:3072 nt
	v_add_u32_e32 v170, 0x1800000, v1
	global_load_dwordx4 v[104:107], v170, s[4:5] nt
	global_load_dwordx4 v[108:111], v170, s[4:5] offset:1024 nt
	global_load_dwordx4 v[112:115], v170, s[4:5] offset:2048 nt
	global_load_dwordx4 v[116:119], v170, s[4:5] offset:3072 nt
	v_add_u32_e32 v170, 0x1e00000, v1
	global_load_dwordx4 v[120:123], v170, s[4:5] nt
	global_load_dwordx4 v[124:127], v170, s[4:5] offset:1024 nt
	global_load_dwordx4 v[128:131], v170, s[4:5] offset:2048 nt
	global_load_dwordx4 v[132:135], v170, s[4:5] offset:3072 nt
	v_add_u32_e32 v170, 0x2400000, v1
	global_load_dwordx4 v[136:139], v170, s[4:5] nt
	global_load_dwordx4 v[140:143], v170, s[4:5] offset:1024 nt
	global_load_dwordx4 v[144:147], v170, s[4:5] offset:2048 nt
	global_load_dwordx4 v[148:151], v170, s[4:5] offset:3072 nt
	v_add_u32_e32 v170, 0x2a00000, v1
	global_load_dwordx4 v[152:155], v170, s[4:5] nt
	global_load_dwordx4 v[156:159], v170, s[4:5] offset:1024 nt
	global_load_dwordx4 v[160:163], v170, s[4:5] offset:2048 nt
	global_load_dwordx4 v[164:167], v170, s[4:5] offset:3072 nt
	s_waitcnt vmcnt(36)
	v_add_f32_e32 v180, v40, v41
	v_add_f32_e32 v181, v44, v45
	v_add_f32_e32 v182, v48, v49
	v_add_f32_e32 v183, v52, v53
	v_add_f32_e32 v180, v180, v42
	v_add_f32_e32 v181, v181, v46
	v_add_f32_e32 v182, v182, v50
	v_add_f32_e32 v183, v183, v54
	v_add_f32_e32 v180, v180, v43
	v_add_f32_e32 v181, v181, v47
	v_add_f32_e32 v182, v182, v51
	v_add_f32_e32 v183, v183, v55
	v_add_f32_e32 v180, v180, v181
	v_add_f32_e32 v182, v182, v183
	v_add_f32_e32 v180, v180, v182
	s_nop 1
	v_add_f32_dpp v180, v180, v180 quad_perm:[1,0,3,2] row_mask:0xf bank_mask:0xf
	s_nop 1
	v_add_f32_dpp v180, v180, v180 quad_perm:[2,3,0,1] row_mask:0xf bank_mask:0xf
	s_nop 1
	v_add_f32_dpp v180, v180, v180 row_half_mirror row_mask:0xf bank_mask:0xf
	s_nop 1
	v_add_f32_dpp v180, v180, v180 row_mirror row_mask:0xf bank_mask:0xf
	s_nop 1
	v_add_f32_dpp v180, v180, v180 row_bcast:15 row_mask:0xa bank_mask:0xf
	s_nop 1
	v_add_f32_dpp v180, v180, v180 row_bcast:31 row_mask:0xc bank_mask:0xf
	s_nop 0
	v_readlane_b32 s20, v180, 63
	s_nop 1
	v_mul_f32_e32 v184, s20, v2
	v_sub_f32_e32 v40, v40, v184
	v_sub_f32_e32 v41, v41, v184
	v_sub_f32_e32 v42, v42, v184
	v_sub_f32_e32 v43, v43, v184
	v_sub_f32_e32 v44, v44, v184
	v_sub_f32_e32 v45, v45, v184
	v_sub_f32_e32 v46, v46, v184
	v_sub_f32_e32 v47, v47, v184
	v_sub_f32_e32 v48, v48, v184
	v_sub_f32_e32 v49, v49, v184
	v_sub_f32_e32 v50, v50, v184
	v_sub_f32_e32 v51, v51, v184
	v_sub_f32_e32 v52, v52, v184
	v_sub_f32_e32 v53, v53, v184
	v_sub_f32_e32 v54, v54, v184
	v_sub_f32_e32 v55, v55, v184
	v_mul_f32_e32 v180, v40, v40
	v_mul_f32_e32 v181, v44, v44
	v_mul_f32_e32 v182, v48, v48
	v_mul_f32_e32 v183, v52, v52
	v_fmac_f32_e32 v180, v41, v41
	v_fmac_f32_e32 v181, v45, v45
	v_fmac_f32_e32 v182, v49, v49
	v_fmac_f32_e32 v183, v53, v53
	v_fmac_f32_e32 v180, v42, v42
	v_fmac_f32_e32 v181, v46, v46
	v_fmac_f32_e32 v182, v50, v50
	v_fmac_f32_e32 v183, v54, v54
	v_fmac_f32_e32 v180, v43, v43
	v_fmac_f32_e32 v181, v47, v47
	v_fmac_f32_e32 v182, v51, v51
	v_fmac_f32_e32 v183, v55, v55
	v_add_f32_e32 v180, v180, v181
	v_add_f32_e32 v182, v182, v183
	v_add_f32_e32 v180, v180, v182
	s_nop 1
	v_add_f32_dpp v180, v180, v180 quad_perm:[1,0,3,2] row_mask:0xf bank_mask:0xf
	s_nop 1
	v_add_f32_dpp v180, v180, v180 quad_perm:[2,3,0,1] row_mask:0xf bank_mask:0xf
	s_nop 1
	v_add_f32_dpp v180, v180, v180 row_half_mirror row_mask:0xf bank_mask:0xf
	s_nop 1
	v_add_f32_dpp v180, v180, v180 row_mirror row_mask:0xf bank_mask:0xf
	s_nop 1
	v_add_f32_dpp v180, v180, v180 row_bcast:15 row_mask:0xa bank_mask:0xf
	s_nop 1
	v_add_f32_dpp v180, v180, v180 row_bcast:31 row_mask:0xc bank_mask:0xf
	s_nop 0
	v_readlane_b32 s20, v180, 63
	s_nop 1
	v_mov_b32_e32 v185, s20
	v_fma_f32 v185, v185, v2, v4
	v_rsq_f32_e32 v185, v185
	s_nop 0
	v_mul_f32_e32 v40, v40, v185
	v_mul_f32_e32 v41, v41, v185
	v_mul_f32_e32 v42, v42, v185
	v_mul_f32_e32 v43, v43, v185
	v_mul_f32_e32 v44, v44, v185
	v_mul_f32_e32 v45, v45, v185
	v_mul_f32_e32 v46, v46, v185
	v_mul_f32_e32 v47, v47, v185
	v_mul_f32_e32 v48, v48, v185
	v_mul_f32_e32 v49, v49, v185
	v_mul_f32_e32 v50, v50, v185
	v_mul_f32_e32 v51, v51, v185
	v_mul_f32_e32 v52, v52, v185
	v_mul_f32_e32 v53, v53, v185
	v_mul_f32_e32 v54, v54, v185
	v_mul_f32_e32 v55, v55, v185
	s_waitcnt vmcnt(28)
	v_fma_f32 v40, v40, v8, v24
	v_fma_f32 v41, v41, v9, v25
	v_fma_f32 v42, v42, v10, v26
	v_fma_f32 v43, v43, v11, v27
	v_fma_f32 v44, v44, v12, v28
	v_fma_f32 v45, v45, v13, v29
	v_fma_f32 v46, v46, v14, v30
	v_fma_f32 v47, v47, v15, v31
	v_fma_f32 v48, v48, v16, v32
	v_fma_f32 v49, v49, v17, v33
	v_fma_f32 v50, v50, v18, v34
	v_fma_f32 v51, v51, v19, v35
	v_fma_f32 v52, v52, v20, v36
	v_fma_f32 v53, v53, v21, v37
	v_fma_f32 v54, v54, v22, v38
	v_fma_f32 v55, v55, v23, v39
	global_store_dwordx4 v1, v[40:43], s[4:5]
	global_store_dwordx4 v1, v[44:47], s[4:5] offset:1024
	global_store_dwordx4 v1, v[48:51], s[4:5] offset:2048
	global_store_dwordx4 v1, v[52:55], s[4:5] offset:3072
	s_nop 1
	v_add_u32_e32 v170, 0x3000000, v1
	global_load_dwordx4 v[40:43], v170, s[4:5] nt
	global_load_dwordx4 v[44:47], v170, s[4:5] offset:1024 nt
	global_load_dwordx4 v[48:51], v170, s[4:5] offset:2048 nt
	global_load_dwordx4 v[52:55], v170, s[4:5] offset:3072 nt
	s_waitcnt vmcnt(32)
	v_add_f32_e32 v180, v56, v57
	v_add_f32_e32 v181, v60, v61
	v_add_f32_e32 v182, v64, v65
	v_add_f32_e32 v183, v68, v69
	v_add_f32_e32 v180, v180, v58
	v_add_f32_e32 v181, v181, v62
	v_add_f32_e32 v182, v182, v66
	v_add_f32_e32 v183, v183, v70
	v_add_f32_e32 v180, v180, v59
	v_add_f32_e32 v181, v181, v63
	v_add_f32_e32 v182, v182, v67
	v_add_f32_e32 v183, v183, v71
	v_add_f32_e32 v180, v180, v181
	v_add_f32_e32 v182, v182, v183
	v_add_f32_e32 v180, v180, v182
	s_nop 1
	v_add_f32_dpp v180, v180, v180 quad_perm:[1,0,3,2] row_mask:0xf bank_mask:0xf
	s_nop 1
	v_add_f32_dpp v180, v180, v180 quad_perm:[2,3,0,1] row_mask:0xf bank_mask:0xf
	s_nop 1
	v_add_f32_dpp v180, v180, v180 row_half_mirror row_mask:0xf bank_mask:0xf
	s_nop 1
	v_add_f32_dpp v180, v180, v180 row_mirror row_mask:0xf bank_mask:0xf
	s_nop 1
	v_add_f32_dpp v180, v180, v180 row_bcast:15 row_mask:0xa bank_mask:0xf
	s_nop 1
	v_add_f32_dpp v180, v180, v180 row_bcast:31 row_mask:0xc bank_mask:0xf
	s_nop 0
	v_readlane_b32 s20, v180, 63
	s_nop 1
	v_mul_f32_e32 v184, s20, v2
	v_sub_f32_e32 v56, v56, v184
	v_sub_f32_e32 v57, v57, v184
	v_sub_f32_e32 v58, v58, v184
	v_sub_f32_e32 v59, v59, v184
	v_sub_f32_e32 v60, v60, v184
	v_sub_f32_e32 v61, v61, v184
	v_sub_f32_e32 v62, v62, v184
	v_sub_f32_e32 v63, v63, v184
	v_sub_f32_e32 v64, v64, v184
	v_sub_f32_e32 v65, v65, v184
	v_sub_f32_e32 v66, v66, v184
	v_sub_f32_e32 v67, v67, v184
	v_sub_f32_e32 v68, v68, v184
	v_sub_f32_e32 v69, v69, v184
	v_sub_f32_e32 v70, v70, v184
	v_sub_f32_e32 v71, v71, v184
	v_mul_f32_e32 v180, v56, v56
	v_mul_f32_e32 v181, v60, v60
	v_mul_f32_e32 v182, v64, v64
	v_mul_f32_e32 v183, v68, v68
	v_fmac_f32_e32 v180, v57, v57
	v_fmac_f32_e32 v181, v61, v61
	v_fmac_f32_e32 v182, v65, v65
	v_fmac_f32_e32 v183, v69, v69
	v_fmac_f32_e32 v180, v58, v58
	v_fmac_f32_e32 v181, v62, v62
	v_fmac_f32_e32 v182, v66, v66
	v_fmac_f32_e32 v183, v70, v70
	v_fmac_f32_e32 v180, v59, v59
	v_fmac_f32_e32 v181, v63, v63
	v_fmac_f32_e32 v182, v67, v67
	v_fmac_f32_e32 v183, v71, v71
	v_add_f32_e32 v180, v180, v181
	v_add_f32_e32 v182, v182, v183
	v_add_f32_e32 v180, v180, v182
	s_nop 1
	v_add_f32_dpp v180, v180, v180 quad_perm:[1,0,3,2] row_mask:0xf bank_mask:0xf
	s_nop 1
	v_add_f32_dpp v180, v180, v180 quad_perm:[2,3,0,1] row_mask:0xf bank_mask:0xf
	s_nop 1
	v_add_f32_dpp v180, v180, v180 row_half_mirror row_mask:0xf bank_mask:0xf
	s_nop 1
	v_add_f32_dpp v180, v180, v180 row_mirror row_mask:0xf bank_mask:0xf
	s_nop 1
	v_add_f32_dpp v180, v180, v180 row_bcast:15 row_mask:0xa bank_mask:0xf
	s_nop 1
	v_add_f32_dpp v180, v180, v180 row_bcast:31 row_mask:0xc bank_mask:0xf
	s_nop 0
	v_readlane_b32 s20, v180, 63
	s_nop 1
	v_mov_b32_e32 v185, s20
	v_fma_f32 v185, v185, v2, v4
	v_rsq_f32_e32 v185, v185
	s_nop 0
	v_mul_f32_e32 v56, v56, v185
	v_mul_f32_e32 v57, v57, v185
	v_mul_f32_e32 v58, v58, v185
	v_mul_f32_e32 v59, v59, v185
	v_mul_f32_e32 v60, v60, v185
	v_mul_f32_e32 v61, v61, v185
	v_mul_f32_e32 v62, v62, v185
	v_mul_f32_e32 v63, v63, v185
	v_mul_f32_e32 v64, v64, v185
	v_mul_f32_e32 v65, v65, v185
	v_mul_f32_e32 v66, v66, v185
	v_mul_f32_e32 v67, v67, v185
	v_mul_f32_e32 v68, v68, v185
	v_mul_f32_e32 v69, v69, v185
	v_mul_f32_e32 v70, v70, v185
	v_mul_f32_e32 v71, v71, v185
	v_fma_f32 v56, v56, v8, v24
	v_fma_f32 v57, v57, v9, v25
	v_fma_f32 v58, v58, v10, v26
	v_fma_f32 v59, v59, v11, v27
	v_fma_f32 v60, v60, v12, v28
	v_fma_f32 v61, v61, v13, v29
	v_fma_f32 v62, v62, v14, v30
	v_fma_f32 v63, v63, v15, v31
	v_fma_f32 v64, v64, v16, v32
	v_fma_f32 v65, v65, v17, v33
	v_fma_f32 v66, v66, v18, v34
	v_fma_f32 v67, v67, v19, v35
	v_fma_f32 v68, v68, v20, v36
	v_fma_f32 v69, v69, v21, v37
	v_fma_f32 v70, v70, v22, v38
	v_fma_f32 v71, v71, v23, v39
	v_add_u32_e32 v171, 0x600000, v1
	global_store_dwordx4 v171, v[56:59], s[4:5]
	global_store_dwordx4 v171, v[60:63], s[4:5] offset:1024
	global_store_dwordx4 v171, v[64:67], s[4:5] offset:2048
	global_store_dwordx4 v171, v[68:71], s[4:5] offset:3072
	s_nop 1
	v_add_u32_e32 v170, 0x3600000, v1
	global_load_dwordx4 v[56:59], v170, s[4:5] nt
	global_load_dwordx4 v[60:63], v170, s[4:5] offset:1024 nt
	global_load_dwordx4 v[64:67], v170, s[4:5] offset:2048 nt
	global_load_dwordx4 v[68:71], v170, s[4:5] offset:3072 nt
	s_waitcnt vmcnt(36)
	v_add_f32_e32 v180, v72, v73
	v_add_f32_e32 v181, v76, v77
	v_add_f32_e32 v182, v80, v81
	v_add_f32_e32 v183, v84, v85
	v_add_f32_e32 v180, v180, v74
	v_add_f32_e32 v181, v181, v78
	v_add_f32_e32 v182, v182, v82
	v_add_f32_e32 v183, v183, v86
	v_add_f32_e32 v180, v180, v75
	v_add_f32_e32 v181, v181, v79
	v_add_f32_e32 v182, v182, v83
	v_add_f32_e32 v183, v183, v87
	v_add_f32_e32 v180, v180, v181
	v_add_f32_e32 v182, v182, v183
	v_add_f32_e32 v180, v180, v182
	s_nop 1
	v_add_f32_dpp v180, v180, v180 quad_perm:[1,0,3,2] row_mask:0xf bank_mask:0xf
	s_nop 1
	v_add_f32_dpp v180, v180, v180 quad_perm:[2,3,0,1] row_mask:0xf bank_mask:0xf
	s_nop 1
	v_add_f32_dpp v180, v180, v180 row_half_mirror row_mask:0xf bank_mask:0xf
	s_nop 1
	v_add_f32_dpp v180, v180, v180 row_mirror row_mask:0xf bank_mask:0xf
	s_nop 1
	v_add_f32_dpp v180, v180, v180 row_bcast:15 row_mask:0xa bank_mask:0xf
	s_nop 1
	v_add_f32_dpp v180, v180, v180 row_bcast:31 row_mask:0xc bank_mask:0xf
	s_nop 0
	v_readlane_b32 s20, v180, 63
	s_nop 1
	v_mul_f32_e32 v184, s20, v2
	v_sub_f32_e32 v72, v72, v184
	v_sub_f32_e32 v73, v73, v184
	v_sub_f32_e32 v74, v74, v184
	v_sub_f32_e32 v75, v75, v184
	v_sub_f32_e32 v76, v76, v184
	v_sub_f32_e32 v77, v77, v184
	v_sub_f32_e32 v78, v78, v184
	v_sub_f32_e32 v79, v79, v184
	v_sub_f32_e32 v80, v80, v184
	v_sub_f32_e32 v81, v81, v184
	v_sub_f32_e32 v82, v82, v184
	v_sub_f32_e32 v83, v83, v184
	v_sub_f32_e32 v84, v84, v184
	v_sub_f32_e32 v85, v85, v184
	v_sub_f32_e32 v86, v86, v184
	v_sub_f32_e32 v87, v87, v184
	v_mul_f32_e32 v180, v72, v72
	v_mul_f32_e32 v181, v76, v76
	v_mul_f32_e32 v182, v80, v80
	v_mul_f32_e32 v183, v84, v84
	v_fmac_f32_e32 v180, v73, v73
	v_fmac_f32_e32 v181, v77, v77
	v_fmac_f32_e32 v182, v81, v81
	v_fmac_f32_e32 v183, v85, v85
	v_fmac_f32_e32 v180, v74, v74
	v_fmac_f32_e32 v181, v78, v78
	v_fmac_f32_e32 v182, v82, v82
	v_fmac_f32_e32 v183, v86, v86
	v_fmac_f32_e32 v180, v75, v75
	v_fmac_f32_e32 v181, v79, v79
	v_fmac_f32_e32 v182, v83, v83
	v_fmac_f32_e32 v183, v87, v87
	v_add_f32_e32 v180, v180, v181
	v_add_f32_e32 v182, v182, v183
	v_add_f32_e32 v180, v180, v182
	s_nop 1
	v_add_f32_dpp v180, v180, v180 quad_perm:[1,0,3,2] row_mask:0xf bank_mask:0xf
	s_nop 1
	v_add_f32_dpp v180, v180, v180 quad_perm:[2,3,0,1] row_mask:0xf bank_mask:0xf
	s_nop 1
	v_add_f32_dpp v180, v180, v180 row_half_mirror row_mask:0xf bank_mask:0xf
	s_nop 1
	v_add_f32_dpp v180, v180, v180 row_mirror row_mask:0xf bank_mask:0xf
	s_nop 1
	v_add_f32_dpp v180, v180, v180 row_bcast:15 row_mask:0xa bank_mask:0xf
	s_nop 1
	v_add_f32_dpp v180, v180, v180 row_bcast:31 row_mask:0xc bank_mask:0xf
	s_nop 0
	v_readlane_b32 s20, v180, 63
	s_nop 1
	v_mov_b32_e32 v185, s20
	v_fma_f32 v185, v185, v2, v4
	v_rsq_f32_e32 v185, v185
	s_nop 0
	v_mul_f32_e32 v72, v72, v185
	v_mul_f32_e32 v73, v73, v185
	v_mul_f32_e32 v74, v74, v185
	v_mul_f32_e32 v75, v75, v185
	v_mul_f32_e32 v76, v76, v185
	v_mul_f32_e32 v77, v77, v185
	v_mul_f32_e32 v78, v78, v185
	v_mul_f32_e32 v79, v79, v185
	v_mul_f32_e32 v80, v80, v185
	v_mul_f32_e32 v81, v81, v185
	v_mul_f32_e32 v82, v82, v185
	v_mul_f32_e32 v83, v83, v185
	v_mul_f32_e32 v84, v84, v185
	v_mul_f32_e32 v85, v85, v185
	v_mul_f32_e32 v86, v86, v185
	v_mul_f32_e32 v87, v87, v185
	v_fma_f32 v72, v72, v8, v24
	v_fma_f32 v73, v73, v9, v25
	v_fma_f32 v74, v74, v10, v26
	v_fma_f32 v75, v75, v11, v27
	v_fma_f32 v76, v76, v12, v28
	v_fma_f32 v77, v77, v13, v29
	v_fma_f32 v78, v78, v14, v30
	v_fma_f32 v79, v79, v15, v31
	v_fma_f32 v80, v80, v16, v32
	v_fma_f32 v81, v81, v17, v33
	v_fma_f32 v82, v82, v18, v34
	v_fma_f32 v83, v83, v19, v35
	v_fma_f32 v84, v84, v20, v36
	v_fma_f32 v85, v85, v21, v37
	v_fma_f32 v86, v86, v22, v38
	v_fma_f32 v87, v87, v23, v39
	v_add_u32_e32 v171, 0xc00000, v1
	global_store_dwordx4 v171, v[72:75], s[4:5]
	global_store_dwordx4 v171, v[76:79], s[4:5] offset:1024
	global_store_dwordx4 v171, v[80:83], s[4:5] offset:2048
	global_store_dwordx4 v171, v[84:87], s[4:5] offset:3072
	s_waitcnt vmcnt(36)
	v_add_f32_e32 v180, v88, v89
	v_add_f32_e32 v181, v92, v93
	v_add_f32_e32 v182, v96, v97
	v_add_f32_e32 v183, v100, v101
	v_add_f32_e32 v180, v180, v90
	v_add_f32_e32 v181, v181, v94
	v_add_f32_e32 v182, v182, v98
	v_add_f32_e32 v183, v183, v102
	v_add_f32_e32 v180, v180, v91
	v_add_f32_e32 v181, v181, v95
	v_add_f32_e32 v182, v182, v99
	v_add_f32_e32 v183, v183, v103
	v_add_f32_e32 v180, v180, v181
	v_add_f32_e32 v182, v182, v183
	v_add_f32_e32 v180, v180, v182
	s_nop 1
	v_add_f32_dpp v180, v180, v180 quad_perm:[1,0,3,2] row_mask:0xf bank_mask:0xf
	s_nop 1
	v_add_f32_dpp v180, v180, v180 quad_perm:[2,3,0,1] row_mask:0xf bank_mask:0xf
	s_nop 1
	v_add_f32_dpp v180, v180, v180 row_half_mirror row_mask:0xf bank_mask:0xf
	s_nop 1
	v_add_f32_dpp v180, v180, v180 row_mirror row_mask:0xf bank_mask:0xf
	s_nop 1
	v_add_f32_dpp v180, v180, v180 row_bcast:15 row_mask:0xa bank_mask:0xf
	s_nop 1
	v_add_f32_dpp v180, v180, v180 row_bcast:31 row_mask:0xc bank_mask:0xf
	s_nop 0
	v_readlane_b32 s20, v180, 63
	s_nop 1
	v_mul_f32_e32 v184, s20, v2
	v_sub_f32_e32 v88, v88, v184
	v_sub_f32_e32 v89, v89, v184
	v_sub_f32_e32 v90, v90, v184
	v_sub_f32_e32 v91, v91, v184
	v_sub_f32_e32 v92, v92, v184
	v_sub_f32_e32 v93, v93, v184
	v_sub_f32_e32 v94, v94, v184
	v_sub_f32_e32 v95, v95, v184
	v_sub_f32_e32 v96, v96, v184
	v_sub_f32_e32 v97, v97, v184
	v_sub_f32_e32 v98, v98, v184
	v_sub_f32_e32 v99, v99, v184
	v_sub_f32_e32 v100, v100, v184
	v_sub_f32_e32 v101, v101, v184
	v_sub_f32_e32 v102, v102, v184
	v_sub_f32_e32 v103, v103, v184
	v_mul_f32_e32 v180, v88, v88
	v_mul_f32_e32 v181, v92, v92
	v_mul_f32_e32 v182, v96, v96
	v_mul_f32_e32 v183, v100, v100
	v_fmac_f32_e32 v180, v89, v89
	v_fmac_f32_e32 v181, v93, v93
	v_fmac_f32_e32 v182, v97, v97
	v_fmac_f32_e32 v183, v101, v101
	v_fmac_f32_e32 v180, v90, v90
	v_fmac_f32_e32 v181, v94, v94
	v_fmac_f32_e32 v182, v98, v98
	v_fmac_f32_e32 v183, v102, v102
	v_fmac_f32_e32 v180, v91, v91
	v_fmac_f32_e32 v181, v95, v95
	v_fmac_f32_e32 v182, v99, v99
	v_fmac_f32_e32 v183, v103, v103
	v_add_f32_e32 v180, v180, v181
	v_add_f32_e32 v182, v182, v183
	v_add_f32_e32 v180, v180, v182
	s_nop 1
	v_add_f32_dpp v180, v180, v180 quad_perm:[1,0,3,2] row_mask:0xf bank_mask:0xf
	s_nop 1
	v_add_f32_dpp v180, v180, v180 quad_perm:[2,3,0,1] row_mask:0xf bank_mask:0xf
	s_nop 1
	v_add_f32_dpp v180, v180, v180 row_half_mirror row_mask:0xf bank_mask:0xf
	s_nop 1
	v_add_f32_dpp v180, v180, v180 row_mirror row_mask:0xf bank_mask:0xf
	s_nop 1
	v_add_f32_dpp v180, v180, v180 row_bcast:15 row_mask:0xa bank_mask:0xf
	s_nop 1
	v_add_f32_dpp v180, v180, v180 row_bcast:31 row_mask:0xc bank_mask:0xf
	s_nop 0
	v_readlane_b32 s20, v180, 63
	s_nop 1
	v_mov_b32_e32 v185, s20
	v_fma_f32 v185, v185, v2, v4
	v_rsq_f32_e32 v185, v185
	s_nop 0
	v_mul_f32_e32 v88, v88, v185
	v_mul_f32_e32 v89, v89, v185
	v_mul_f32_e32 v90, v90, v185
	v_mul_f32_e32 v91, v91, v185
	v_mul_f32_e32 v92, v92, v185
	v_mul_f32_e32 v93, v93, v185
	v_mul_f32_e32 v94, v94, v185
	v_mul_f32_e32 v95, v95, v185
	v_mul_f32_e32 v96, v96, v185
	v_mul_f32_e32 v97, v97, v185
	v_mul_f32_e32 v98, v98, v185
	v_mul_f32_e32 v99, v99, v185
	v_mul_f32_e32 v100, v100, v185
	v_mul_f32_e32 v101, v101, v185
	v_mul_f32_e32 v102, v102, v185
	v_mul_f32_e32 v103, v103, v185
	v_fma_f32 v88, v88, v8, v24
	v_fma_f32 v89, v89, v9, v25
	v_fma_f32 v90, v90, v10, v26
	v_fma_f32 v91, v91, v11, v27
	v_fma_f32 v92, v92, v12, v28
	v_fma_f32 v93, v93, v13, v29
	v_fma_f32 v94, v94, v14, v30
	v_fma_f32 v95, v95, v15, v31
	v_fma_f32 v96, v96, v16, v32
	v_fma_f32 v97, v97, v17, v33
	v_fma_f32 v98, v98, v18, v34
	v_fma_f32 v99, v99, v19, v35
	v_fma_f32 v100, v100, v20, v36
	v_fma_f32 v101, v101, v21, v37
	v_fma_f32 v102, v102, v22, v38
	v_fma_f32 v103, v103, v23, v39
	v_add_u32_e32 v171, 0x1200000, v1
	global_store_dwordx4 v171, v[88:91], s[4:5]
	global_store_dwordx4 v171, v[92:95], s[4:5] offset:1024
	global_store_dwordx4 v171, v[96:99], s[4:5] offset:2048
	global_store_dwordx4 v171, v[100:103], s[4:5] offset:3072
	s_waitcnt vmcnt(36)
	v_add_f32_e32 v180, v104, v105
	v_add_f32_e32 v181, v108, v109
	v_add_f32_e32 v182, v112, v113
	v_add_f32_e32 v183, v116, v117
	v_add_f32_e32 v180, v180, v106
	v_add_f32_e32 v181, v181, v110
	v_add_f32_e32 v182, v182, v114
	v_add_f32_e32 v183, v183, v118
	v_add_f32_e32 v180, v180, v107
	v_add_f32_e32 v181, v181, v111
	v_add_f32_e32 v182, v182, v115
	v_add_f32_e32 v183, v183, v119
	v_add_f32_e32 v180, v180, v181
	v_add_f32_e32 v182, v182, v183
	v_add_f32_e32 v180, v180, v182
	s_nop 1
	v_add_f32_dpp v180, v180, v180 quad_perm:[1,0,3,2] row_mask:0xf bank_mask:0xf
	s_nop 1
	v_add_f32_dpp v180, v180, v180 quad_perm:[2,3,0,1] row_mask:0xf bank_mask:0xf
	s_nop 1
	v_add_f32_dpp v180, v180, v180 row_half_mirror row_mask:0xf bank_mask:0xf
	s_nop 1
	v_add_f32_dpp v180, v180, v180 row_mirror row_mask:0xf bank_mask:0xf
	s_nop 1
	v_add_f32_dpp v180, v180, v180 row_bcast:15 row_mask:0xa bank_mask:0xf
	s_nop 1
	v_add_f32_dpp v180, v180, v180 row_bcast:31 row_mask:0xc bank_mask:0xf
	s_nop 0
	v_readlane_b32 s20, v180, 63
	s_nop 1
	v_mul_f32_e32 v184, s20, v2
	v_sub_f32_e32 v104, v104, v184
	v_sub_f32_e32 v105, v105, v184
	v_sub_f32_e32 v106, v106, v184
	v_sub_f32_e32 v107, v107, v184
	v_sub_f32_e32 v108, v108, v184
	v_sub_f32_e32 v109, v109, v184
	v_sub_f32_e32 v110, v110, v184
	v_sub_f32_e32 v111, v111, v184
	v_sub_f32_e32 v112, v112, v184
	v_sub_f32_e32 v113, v113, v184
	v_sub_f32_e32 v114, v114, v184
	v_sub_f32_e32 v115, v115, v184
	v_sub_f32_e32 v116, v116, v184
	v_sub_f32_e32 v117, v117, v184
	v_sub_f32_e32 v118, v118, v184
	v_sub_f32_e32 v119, v119, v184
	v_mul_f32_e32 v180, v104, v104
	v_mul_f32_e32 v181, v108, v108
	v_mul_f32_e32 v182, v112, v112
	v_mul_f32_e32 v183, v116, v116
	v_fmac_f32_e32 v180, v105, v105
	v_fmac_f32_e32 v181, v109, v109
	v_fmac_f32_e32 v182, v113, v113
	v_fmac_f32_e32 v183, v117, v117
	v_fmac_f32_e32 v180, v106, v106
	v_fmac_f32_e32 v181, v110, v110
	v_fmac_f32_e32 v182, v114, v114
	v_fmac_f32_e32 v183, v118, v118
	v_fmac_f32_e32 v180, v107, v107
	v_fmac_f32_e32 v181, v111, v111
	v_fmac_f32_e32 v182, v115, v115
	v_fmac_f32_e32 v183, v119, v119
	v_add_f32_e32 v180, v180, v181
	v_add_f32_e32 v182, v182, v183
	v_add_f32_e32 v180, v180, v182
	s_nop 1
	v_add_f32_dpp v180, v180, v180 quad_perm:[1,0,3,2] row_mask:0xf bank_mask:0xf
	s_nop 1
	v_add_f32_dpp v180, v180, v180 quad_perm:[2,3,0,1] row_mask:0xf bank_mask:0xf
	s_nop 1
	v_add_f32_dpp v180, v180, v180 row_half_mirror row_mask:0xf bank_mask:0xf
	s_nop 1
	v_add_f32_dpp v180, v180, v180 row_mirror row_mask:0xf bank_mask:0xf
	s_nop 1
	v_add_f32_dpp v180, v180, v180 row_bcast:15 row_mask:0xa bank_mask:0xf
	s_nop 1
	v_add_f32_dpp v180, v180, v180 row_bcast:31 row_mask:0xc bank_mask:0xf
	s_nop 0
	v_readlane_b32 s20, v180, 63
	s_nop 1
	v_mov_b32_e32 v185, s20
	v_fma_f32 v185, v185, v2, v4
	v_rsq_f32_e32 v185, v185
	s_nop 0
	v_mul_f32_e32 v104, v104, v185
	v_mul_f32_e32 v105, v105, v185
	v_mul_f32_e32 v106, v106, v185
	v_mul_f32_e32 v107, v107, v185
	v_mul_f32_e32 v108, v108, v185
	v_mul_f32_e32 v109, v109, v185
	v_mul_f32_e32 v110, v110, v185
	v_mul_f32_e32 v111, v111, v185
	v_mul_f32_e32 v112, v112, v185
	v_mul_f32_e32 v113, v113, v185
	v_mul_f32_e32 v114, v114, v185
	v_mul_f32_e32 v115, v115, v185
	v_mul_f32_e32 v116, v116, v185
	v_mul_f32_e32 v117, v117, v185
	v_mul_f32_e32 v118, v118, v185
	v_mul_f32_e32 v119, v119, v185
	v_fma_f32 v104, v104, v8, v24
	v_fma_f32 v105, v105, v9, v25
	v_fma_f32 v106, v106, v10, v26
	v_fma_f32 v107, v107, v11, v27
	v_fma_f32 v108, v108, v12, v28
	v_fma_f32 v109, v109, v13, v29
	v_fma_f32 v110, v110, v14, v30
	v_fma_f32 v111, v111, v15, v31
	v_fma_f32 v112, v112, v16, v32
	v_fma_f32 v113, v113, v17, v33
	v_fma_f32 v114, v114, v18, v34
	v_fma_f32 v115, v115, v19, v35
	v_fma_f32 v116, v116, v20, v36
	v_fma_f32 v117, v117, v21, v37
	v_fma_f32 v118, v118, v22, v38
	v_fma_f32 v119, v119, v23, v39
	v_add_u32_e32 v171, 0x1800000, v1
	global_store_dwordx4 v171, v[104:107], s[4:5]
	global_store_dwordx4 v171, v[108:111], s[4:5] offset:1024
	global_store_dwordx4 v171, v[112:115], s[4:5] offset:2048
	global_store_dwordx4 v171, v[116:119], s[4:5] offset:3072
	s_waitcnt vmcnt(36)
	v_add_f32_e32 v180, v120, v121
	v_add_f32_e32 v181, v124, v125
	v_add_f32_e32 v182, v128, v129
	v_add_f32_e32 v183, v132, v133
	v_add_f32_e32 v180, v180, v122
	v_add_f32_e32 v181, v181, v126
	v_add_f32_e32 v182, v182, v130
	v_add_f32_e32 v183, v183, v134
	v_add_f32_e32 v180, v180, v123
	v_add_f32_e32 v181, v181, v127
	v_add_f32_e32 v182, v182, v131
	v_add_f32_e32 v183, v183, v135
	v_add_f32_e32 v180, v180, v181
	v_add_f32_e32 v182, v182, v183
	v_add_f32_e32 v180, v180, v182
	s_nop 1
	v_add_f32_dpp v180, v180, v180 quad_perm:[1,0,3,2] row_mask:0xf bank_mask:0xf
	s_nop 1
	v_add_f32_dpp v180, v180, v180 quad_perm:[2,3,0,1] row_mask:0xf bank_mask:0xf
	s_nop 1
	v_add_f32_dpp v180, v180, v180 row_half_mirror row_mask:0xf bank_mask:0xf
	s_nop 1
	v_add_f32_dpp v180, v180, v180 row_mirror row_mask:0xf bank_mask:0xf
	s_nop 1
	v_add_f32_dpp v180, v180, v180 row_bcast:15 row_mask:0xa bank_mask:0xf
	s_nop 1
	v_add_f32_dpp v180, v180, v180 row_bcast:31 row_mask:0xc bank_mask:0xf
	s_nop 0
	v_readlane_b32 s20, v180, 63
	s_nop 1
	v_mul_f32_e32 v184, s20, v2
	v_sub_f32_e32 v120, v120, v184
	v_sub_f32_e32 v121, v121, v184
	v_sub_f32_e32 v122, v122, v184
	v_sub_f32_e32 v123, v123, v184
	v_sub_f32_e32 v124, v124, v184
	v_sub_f32_e32 v125, v125, v184
	v_sub_f32_e32 v126, v126, v184
	v_sub_f32_e32 v127, v127, v184
	v_sub_f32_e32 v128, v128, v184
	v_sub_f32_e32 v129, v129, v184
	v_sub_f32_e32 v130, v130, v184
	v_sub_f32_e32 v131, v131, v184
	v_sub_f32_e32 v132, v132, v184
	v_sub_f32_e32 v133, v133, v184
	v_sub_f32_e32 v134, v134, v184
	v_sub_f32_e32 v135, v135, v184
	v_mul_f32_e32 v180, v120, v120
	v_mul_f32_e32 v181, v124, v124
	v_mul_f32_e32 v182, v128, v128
	v_mul_f32_e32 v183, v132, v132
	v_fmac_f32_e32 v180, v121, v121
	v_fmac_f32_e32 v181, v125, v125
	v_fmac_f32_e32 v182, v129, v129
	v_fmac_f32_e32 v183, v133, v133
	v_fmac_f32_e32 v180, v122, v122
	v_fmac_f32_e32 v181, v126, v126
	v_fmac_f32_e32 v182, v130, v130
	v_fmac_f32_e32 v183, v134, v134
	v_fmac_f32_e32 v180, v123, v123
	v_fmac_f32_e32 v181, v127, v127
	v_fmac_f32_e32 v182, v131, v131
	v_fmac_f32_e32 v183, v135, v135
	v_add_f32_e32 v180, v180, v181
	v_add_f32_e32 v182, v182, v183
	v_add_f32_e32 v180, v180, v182
	s_nop 1
	v_add_f32_dpp v180, v180, v180 quad_perm:[1,0,3,2] row_mask:0xf bank_mask:0xf
	s_nop 1
	v_add_f32_dpp v180, v180, v180 quad_perm:[2,3,0,1] row_mask:0xf bank_mask:0xf
	s_nop 1
	v_add_f32_dpp v180, v180, v180 row_half_mirror row_mask:0xf bank_mask:0xf
	s_nop 1
	v_add_f32_dpp v180, v180, v180 row_mirror row_mask:0xf bank_mask:0xf
	s_nop 1
	v_add_f32_dpp v180, v180, v180 row_bcast:15 row_mask:0xa bank_mask:0xf
	s_nop 1
	v_add_f32_dpp v180, v180, v180 row_bcast:31 row_mask:0xc bank_mask:0xf
	s_nop 0
	v_readlane_b32 s20, v180, 63
	s_nop 1
	v_mov_b32_e32 v185, s20
	v_fma_f32 v185, v185, v2, v4
	v_rsq_f32_e32 v185, v185
	s_nop 0
	v_mul_f32_e32 v120, v120, v185
	v_mul_f32_e32 v121, v121, v185
	v_mul_f32_e32 v122, v122, v185
	v_mul_f32_e32 v123, v123, v185
	v_mul_f32_e32 v124, v124, v185
	v_mul_f32_e32 v125, v125, v185
	v_mul_f32_e32 v126, v126, v185
	v_mul_f32_e32 v127, v127, v185
	v_mul_f32_e32 v128, v128, v185
	v_mul_f32_e32 v129, v129, v185
	v_mul_f32_e32 v130, v130, v185
	v_mul_f32_e32 v131, v131, v185
	v_mul_f32_e32 v132, v132, v185
	v_mul_f32_e32 v133, v133, v185
	v_mul_f32_e32 v134, v134, v185
	v_mul_f32_e32 v135, v135, v185
	v_fma_f32 v120, v120, v8, v24
	v_fma_f32 v121, v121, v9, v25
	v_fma_f32 v122, v122, v10, v26
	v_fma_f32 v123, v123, v11, v27
	v_fma_f32 v124, v124, v12, v28
	v_fma_f32 v125, v125, v13, v29
	v_fma_f32 v126, v126, v14, v30
	v_fma_f32 v127, v127, v15, v31
	v_fma_f32 v128, v128, v16, v32
	v_fma_f32 v129, v129, v17, v33
	v_fma_f32 v130, v130, v18, v34
	v_fma_f32 v131, v131, v19, v35
	v_fma_f32 v132, v132, v20, v36
	v_fma_f32 v133, v133, v21, v37
	v_fma_f32 v134, v134, v22, v38
	v_fma_f32 v135, v135, v23, v39
	v_add_u32_e32 v171, 0x1e00000, v1
	global_store_dwordx4 v171, v[120:123], s[4:5]
	global_store_dwordx4 v171, v[124:127], s[4:5] offset:1024
	global_store_dwordx4 v171, v[128:131], s[4:5] offset:2048
	global_store_dwordx4 v171, v[132:135], s[4:5] offset:3072
	s_waitcnt vmcnt(36)
	v_add_f32_e32 v180, v136, v137
	v_add_f32_e32 v181, v140, v141
	v_add_f32_e32 v182, v144, v145
	v_add_f32_e32 v183, v148, v149
	v_add_f32_e32 v180, v180, v138
	v_add_f32_e32 v181, v181, v142
	v_add_f32_e32 v182, v182, v146
	v_add_f32_e32 v183, v183, v150
	v_add_f32_e32 v180, v180, v139
	v_add_f32_e32 v181, v181, v143
	v_add_f32_e32 v182, v182, v147
	v_add_f32_e32 v183, v183, v151
	v_add_f32_e32 v180, v180, v181
	v_add_f32_e32 v182, v182, v183
	v_add_f32_e32 v180, v180, v182
	s_nop 1
	v_add_f32_dpp v180, v180, v180 quad_perm:[1,0,3,2] row_mask:0xf bank_mask:0xf
	s_nop 1
	v_add_f32_dpp v180, v180, v180 quad_perm:[2,3,0,1] row_mask:0xf bank_mask:0xf
	s_nop 1
	v_add_f32_dpp v180, v180, v180 row_half_mirror row_mask:0xf bank_mask:0xf
	s_nop 1
	v_add_f32_dpp v180, v180, v180 row_mirror row_mask:0xf bank_mask:0xf
	s_nop 1
	v_add_f32_dpp v180, v180, v180 row_bcast:15 row_mask:0xa bank_mask:0xf
	s_nop 1
	v_add_f32_dpp v180, v180, v180 row_bcast:31 row_mask:0xc bank_mask:0xf
	s_nop 0
	v_readlane_b32 s20, v180, 63
	s_nop 1
	v_mul_f32_e32 v184, s20, v2
	v_sub_f32_e32 v136, v136, v184
	v_sub_f32_e32 v137, v137, v184
	v_sub_f32_e32 v138, v138, v184
	v_sub_f32_e32 v139, v139, v184
	v_sub_f32_e32 v140, v140, v184
	v_sub_f32_e32 v141, v141, v184
	v_sub_f32_e32 v142, v142, v184
	v_sub_f32_e32 v143, v143, v184
	v_sub_f32_e32 v144, v144, v184
	v_sub_f32_e32 v145, v145, v184
	v_sub_f32_e32 v146, v146, v184
	v_sub_f32_e32 v147, v147, v184
	v_sub_f32_e32 v148, v148, v184
	v_sub_f32_e32 v149, v149, v184
	v_sub_f32_e32 v150, v150, v184
	v_sub_f32_e32 v151, v151, v184
	v_mul_f32_e32 v180, v136, v136
	v_mul_f32_e32 v181, v140, v140
	v_mul_f32_e32 v182, v144, v144
	v_mul_f32_e32 v183, v148, v148
	v_fmac_f32_e32 v180, v137, v137
	v_fmac_f32_e32 v181, v141, v141
	v_fmac_f32_e32 v182, v145, v145
	v_fmac_f32_e32 v183, v149, v149
	v_fmac_f32_e32 v180, v138, v138
	v_fmac_f32_e32 v181, v142, v142
	v_fmac_f32_e32 v182, v146, v146
	v_fmac_f32_e32 v183, v150, v150
	v_fmac_f32_e32 v180, v139, v139
	v_fmac_f32_e32 v181, v143, v143
	v_fmac_f32_e32 v182, v147, v147
	v_fmac_f32_e32 v183, v151, v151
	v_add_f32_e32 v180, v180, v181
	v_add_f32_e32 v182, v182, v183
	v_add_f32_e32 v180, v180, v182
	s_nop 1
	v_add_f32_dpp v180, v180, v180 quad_perm:[1,0,3,2] row_mask:0xf bank_mask:0xf
	s_nop 1
	v_add_f32_dpp v180, v180, v180 quad_perm:[2,3,0,1] row_mask:0xf bank_mask:0xf
	s_nop 1
	v_add_f32_dpp v180, v180, v180 row_half_mirror row_mask:0xf bank_mask:0xf
	s_nop 1
	v_add_f32_dpp v180, v180, v180 row_mirror row_mask:0xf bank_mask:0xf
	s_nop 1
	v_add_f32_dpp v180, v180, v180 row_bcast:15 row_mask:0xa bank_mask:0xf
	s_nop 1
	v_add_f32_dpp v180, v180, v180 row_bcast:31 row_mask:0xc bank_mask:0xf
	s_nop 0
	v_readlane_b32 s20, v180, 63
	s_nop 1
	v_mov_b32_e32 v185, s20
	v_fma_f32 v185, v185, v2, v4
	v_rsq_f32_e32 v185, v185
	s_nop 0
	v_mul_f32_e32 v136, v136, v185
	v_mul_f32_e32 v137, v137, v185
	v_mul_f32_e32 v138, v138, v185
	v_mul_f32_e32 v139, v139, v185
	v_mul_f32_e32 v140, v140, v185
	v_mul_f32_e32 v141, v141, v185
	v_mul_f32_e32 v142, v142, v185
	v_mul_f32_e32 v143, v143, v185
	v_mul_f32_e32 v144, v144, v185
	v_mul_f32_e32 v145, v145, v185
	v_mul_f32_e32 v146, v146, v185
	v_mul_f32_e32 v147, v147, v185
	v_mul_f32_e32 v148, v148, v185
	v_mul_f32_e32 v149, v149, v185
	v_mul_f32_e32 v150, v150, v185
	v_mul_f32_e32 v151, v151, v185
	v_fma_f32 v136, v136, v8, v24
	v_fma_f32 v137, v137, v9, v25
	v_fma_f32 v138, v138, v10, v26
	v_fma_f32 v139, v139, v11, v27
	v_fma_f32 v140, v140, v12, v28
	v_fma_f32 v141, v141, v13, v29
	v_fma_f32 v142, v142, v14, v30
	v_fma_f32 v143, v143, v15, v31
	v_fma_f32 v144, v144, v16, v32
	v_fma_f32 v145, v145, v17, v33
	v_fma_f32 v146, v146, v18, v34
	v_fma_f32 v147, v147, v19, v35
	v_fma_f32 v148, v148, v20, v36
	v_fma_f32 v149, v149, v21, v37
	v_fma_f32 v150, v150, v22, v38
	v_fma_f32 v151, v151, v23, v39
	v_add_u32_e32 v171, 0x2400000, v1
	global_store_dwordx4 v171, v[136:139], s[4:5]
	global_store_dwordx4 v171, v[140:143], s[4:5] offset:1024
	global_store_dwordx4 v171, v[144:147], s[4:5] offset:2048
	global_store_dwordx4 v171, v[148:151], s[4:5] offset:3072
	s_waitcnt vmcnt(36)
	v_add_f32_e32 v180, v152, v153
	v_add_f32_e32 v181, v156, v157
	v_add_f32_e32 v182, v160, v161
	v_add_f32_e32 v183, v164, v165
	v_add_f32_e32 v180, v180, v154
	v_add_f32_e32 v181, v181, v158
	v_add_f32_e32 v182, v182, v162
	v_add_f32_e32 v183, v183, v166
	v_add_f32_e32 v180, v180, v155
	v_add_f32_e32 v181, v181, v159
	v_add_f32_e32 v182, v182, v163
	v_add_f32_e32 v183, v183, v167
	v_add_f32_e32 v180, v180, v181
	v_add_f32_e32 v182, v182, v183
	v_add_f32_e32 v180, v180, v182
	s_nop 1
	v_add_f32_dpp v180, v180, v180 quad_perm:[1,0,3,2] row_mask:0xf bank_mask:0xf
	s_nop 1
	v_add_f32_dpp v180, v180, v180 quad_perm:[2,3,0,1] row_mask:0xf bank_mask:0xf
	s_nop 1
	v_add_f32_dpp v180, v180, v180 row_half_mirror row_mask:0xf bank_mask:0xf
	s_nop 1
	v_add_f32_dpp v180, v180, v180 row_mirror row_mask:0xf bank_mask:0xf
	s_nop 1
	v_add_f32_dpp v180, v180, v180 row_bcast:15 row_mask:0xa bank_mask:0xf
	s_nop 1
	v_add_f32_dpp v180, v180, v180 row_bcast:31 row_mask:0xc bank_mask:0xf
	s_nop 0
	v_readlane_b32 s20, v180, 63
	s_nop 1
	v_mul_f32_e32 v184, s20, v2
	v_sub_f32_e32 v152, v152, v184
	v_sub_f32_e32 v153, v153, v184
	v_sub_f32_e32 v154, v154, v184
	v_sub_f32_e32 v155, v155, v184
	v_sub_f32_e32 v156, v156, v184
	v_sub_f32_e32 v157, v157, v184
	v_sub_f32_e32 v158, v158, v184
	v_sub_f32_e32 v159, v159, v184
	v_sub_f32_e32 v160, v160, v184
	v_sub_f32_e32 v161, v161, v184
	v_sub_f32_e32 v162, v162, v184
	v_sub_f32_e32 v163, v163, v184
	v_sub_f32_e32 v164, v164, v184
	v_sub_f32_e32 v165, v165, v184
	v_sub_f32_e32 v166, v166, v184
	v_sub_f32_e32 v167, v167, v184
	v_mul_f32_e32 v180, v152, v152
	v_mul_f32_e32 v181, v156, v156
	v_mul_f32_e32 v182, v160, v160
	v_mul_f32_e32 v183, v164, v164
	v_fmac_f32_e32 v180, v153, v153
	v_fmac_f32_e32 v181, v157, v157
	v_fmac_f32_e32 v182, v161, v161
	v_fmac_f32_e32 v183, v165, v165
	v_fmac_f32_e32 v180, v154, v154
	v_fmac_f32_e32 v181, v158, v158
	v_fmac_f32_e32 v182, v162, v162
	v_fmac_f32_e32 v183, v166, v166
	v_fmac_f32_e32 v180, v155, v155
	v_fmac_f32_e32 v181, v159, v159
	v_fmac_f32_e32 v182, v163, v163
	v_fmac_f32_e32 v183, v167, v167
	v_add_f32_e32 v180, v180, v181
	v_add_f32_e32 v182, v182, v183
	v_add_f32_e32 v180, v180, v182
	s_nop 1
	v_add_f32_dpp v180, v180, v180 quad_perm:[1,0,3,2] row_mask:0xf bank_mask:0xf
	s_nop 1
	v_add_f32_dpp v180, v180, v180 quad_perm:[2,3,0,1] row_mask:0xf bank_mask:0xf
	s_nop 1
	v_add_f32_dpp v180, v180, v180 row_half_mirror row_mask:0xf bank_mask:0xf
	s_nop 1
	v_add_f32_dpp v180, v180, v180 row_mirror row_mask:0xf bank_mask:0xf
	s_nop 1
	v_add_f32_dpp v180, v180, v180 row_bcast:15 row_mask:0xa bank_mask:0xf
	s_nop 1
	v_add_f32_dpp v180, v180, v180 row_bcast:31 row_mask:0xc bank_mask:0xf
	s_nop 0
	v_readlane_b32 s20, v180, 63
	s_nop 1
	v_mov_b32_e32 v185, s20
	v_fma_f32 v185, v185, v2, v4
	v_rsq_f32_e32 v185, v185
	s_nop 0
	v_mul_f32_e32 v152, v152, v185
	v_mul_f32_e32 v153, v153, v185
	v_mul_f32_e32 v154, v154, v185
	v_mul_f32_e32 v155, v155, v185
	v_mul_f32_e32 v156, v156, v185
	v_mul_f32_e32 v157, v157, v185
	v_mul_f32_e32 v158, v158, v185
	v_mul_f32_e32 v159, v159, v185
	v_mul_f32_e32 v160, v160, v185
	v_mul_f32_e32 v161, v161, v185
	v_mul_f32_e32 v162, v162, v185
	v_mul_f32_e32 v163, v163, v185
	v_mul_f32_e32 v164, v164, v185
	v_mul_f32_e32 v165, v165, v185
	v_mul_f32_e32 v166, v166, v185
	v_mul_f32_e32 v167, v167, v185
	v_fma_f32 v152, v152, v8, v24
	v_fma_f32 v153, v153, v9, v25
	v_fma_f32 v154, v154, v10, v26
	v_fma_f32 v155, v155, v11, v27
	v_fma_f32 v156, v156, v12, v28
	v_fma_f32 v157, v157, v13, v29
	v_fma_f32 v158, v158, v14, v30
	v_fma_f32 v159, v159, v15, v31
	v_fma_f32 v160, v160, v16, v32
	v_fma_f32 v161, v161, v17, v33
	v_fma_f32 v162, v162, v18, v34
	v_fma_f32 v163, v163, v19, v35
	v_fma_f32 v164, v164, v20, v36
	v_fma_f32 v165, v165, v21, v37
	v_fma_f32 v166, v166, v22, v38
	v_fma_f32 v167, v167, v23, v39
	v_add_u32_e32 v171, 0x2a00000, v1
	global_store_dwordx4 v171, v[152:155], s[4:5]
	global_store_dwordx4 v171, v[156:159], s[4:5] offset:1024
	global_store_dwordx4 v171, v[160:163], s[4:5] offset:2048
	global_store_dwordx4 v171, v[164:167], s[4:5] offset:3072
	s_waitcnt vmcnt(32)
	v_add_f32_e32 v180, v40, v41
	v_add_f32_e32 v181, v44, v45
	v_add_f32_e32 v182, v48, v49
	v_add_f32_e32 v183, v52, v53
	v_add_f32_e32 v180, v180, v42
	v_add_f32_e32 v181, v181, v46
	v_add_f32_e32 v182, v182, v50
	v_add_f32_e32 v183, v183, v54
	v_add_f32_e32 v180, v180, v43
	v_add_f32_e32 v181, v181, v47
	v_add_f32_e32 v182, v182, v51
	v_add_f32_e32 v183, v183, v55
	v_add_f32_e32 v180, v180, v181
	v_add_f32_e32 v182, v182, v183
	v_add_f32_e32 v180, v180, v182
	s_nop 1
	v_add_f32_dpp v180, v180, v180 quad_perm:[1,0,3,2] row_mask:0xf bank_mask:0xf
	s_nop 1
	v_add_f32_dpp v180, v180, v180 quad_perm:[2,3,0,1] row_mask:0xf bank_mask:0xf
	s_nop 1
	v_add_f32_dpp v180, v180, v180 row_half_mirror row_mask:0xf bank_mask:0xf
	s_nop 1
	v_add_f32_dpp v180, v180, v180 row_mirror row_mask:0xf bank_mask:0xf
	s_nop 1
	v_add_f32_dpp v180, v180, v180 row_bcast:15 row_mask:0xa bank_mask:0xf
	s_nop 1
	v_add_f32_dpp v180, v180, v180 row_bcast:31 row_mask:0xc bank_mask:0xf
	s_nop 0
	v_readlane_b32 s20, v180, 63
	s_nop 1
	v_mul_f32_e32 v184, s20, v2
	v_sub_f32_e32 v40, v40, v184
	v_sub_f32_e32 v41, v41, v184
	v_sub_f32_e32 v42, v42, v184
	v_sub_f32_e32 v43, v43, v184
	v_sub_f32_e32 v44, v44, v184
	v_sub_f32_e32 v45, v45, v184
	v_sub_f32_e32 v46, v46, v184
	v_sub_f32_e32 v47, v47, v184
	v_sub_f32_e32 v48, v48, v184
	v_sub_f32_e32 v49, v49, v184
	v_sub_f32_e32 v50, v50, v184
	v_sub_f32_e32 v51, v51, v184
	v_sub_f32_e32 v52, v52, v184
	v_sub_f32_e32 v53, v53, v184
	v_sub_f32_e32 v54, v54, v184
	v_sub_f32_e32 v55, v55, v184
	v_mul_f32_e32 v180, v40, v40
	v_mul_f32_e32 v181, v44, v44
	v_mul_f32_e32 v182, v48, v48
	v_mul_f32_e32 v183, v52, v52
	v_fmac_f32_e32 v180, v41, v41
	v_fmac_f32_e32 v181, v45, v45
	v_fmac_f32_e32 v182, v49, v49
	v_fmac_f32_e32 v183, v53, v53
	v_fmac_f32_e32 v180, v42, v42
	v_fmac_f32_e32 v181, v46, v46
	v_fmac_f32_e32 v182, v50, v50
	v_fmac_f32_e32 v183, v54, v54
	v_fmac_f32_e32 v180, v43, v43
	v_fmac_f32_e32 v181, v47, v47
	v_fmac_f32_e32 v182, v51, v51
	v_fmac_f32_e32 v183, v55, v55
	v_add_f32_e32 v180, v180, v181
	v_add_f32_e32 v182, v182, v183
	v_add_f32_e32 v180, v180, v182
	s_nop 1
	v_add_f32_dpp v180, v180, v180 quad_perm:[1,0,3,2] row_mask:0xf bank_mask:0xf
	s_nop 1
	v_add_f32_dpp v180, v180, v180 quad_perm:[2,3,0,1] row_mask:0xf bank_mask:0xf
	s_nop 1
	v_add_f32_dpp v180, v180, v180 row_half_mirror row_mask:0xf bank_mask:0xf
	s_nop 1
	v_add_f32_dpp v180, v180, v180 row_mirror row_mask:0xf bank_mask:0xf
	s_nop 1
	v_add_f32_dpp v180, v180, v180 row_bcast:15 row_mask:0xa bank_mask:0xf
	s_nop 1
	v_add_f32_dpp v180, v180, v180 row_bcast:31 row_mask:0xc bank_mask:0xf
	s_nop 0
	v_readlane_b32 s20, v180, 63
	s_nop 1
	v_mov_b32_e32 v185, s20
	v_fma_f32 v185, v185, v2, v4
	v_rsq_f32_e32 v185, v185
	s_nop 0
	v_mul_f32_e32 v40, v40, v185
	v_mul_f32_e32 v41, v41, v185
	v_mul_f32_e32 v42, v42, v185
	v_mul_f32_e32 v43, v43, v185
	v_mul_f32_e32 v44, v44, v185
	v_mul_f32_e32 v45, v45, v185
	v_mul_f32_e32 v46, v46, v185
	v_mul_f32_e32 v47, v47, v185
	v_mul_f32_e32 v48, v48, v185
	v_mul_f32_e32 v49, v49, v185
	v_mul_f32_e32 v50, v50, v185
	v_mul_f32_e32 v51, v51, v185
	v_mul_f32_e32 v52, v52, v185
	v_mul_f32_e32 v53, v53, v185
	v_mul_f32_e32 v54, v54, v185
	v_mul_f32_e32 v55, v55, v185
	v_fma_f32 v40, v40, v8, v24
	v_fma_f32 v41, v41, v9, v25
	v_fma_f32 v42, v42, v10, v26
	v_fma_f32 v43, v43, v11, v27
	v_fma_f32 v44, v44, v12, v28
	v_fma_f32 v45, v45, v13, v29
	v_fma_f32 v46, v46, v14, v30
	v_fma_f32 v47, v47, v15, v31
	v_fma_f32 v48, v48, v16, v32
	v_fma_f32 v49, v49, v17, v33
	v_fma_f32 v50, v50, v18, v34
	v_fma_f32 v51, v51, v19, v35
	v_fma_f32 v52, v52, v20, v36
	v_fma_f32 v53, v53, v21, v37
	v_fma_f32 v54, v54, v22, v38
	v_fma_f32 v55, v55, v23, v39
	v_add_u32_e32 v171, 0x3000000, v1
	global_store_dwordx4 v171, v[40:43], s[4:5]
	global_store_dwordx4 v171, v[44:47], s[4:5] offset:1024
	global_store_dwordx4 v171, v[48:51], s[4:5] offset:2048
	global_store_dwordx4 v171, v[52:55], s[4:5] offset:3072
	s_waitcnt vmcnt(28)
	v_add_f32_e32 v180, v56, v57
	v_add_f32_e32 v181, v60, v61
	v_add_f32_e32 v182, v64, v65
	v_add_f32_e32 v183, v68, v69
	v_add_f32_e32 v180, v180, v58
	v_add_f32_e32 v181, v181, v62
	v_add_f32_e32 v182, v182, v66
	v_add_f32_e32 v183, v183, v70
	v_add_f32_e32 v180, v180, v59
	v_add_f32_e32 v181, v181, v63
	v_add_f32_e32 v182, v182, v67
	v_add_f32_e32 v183, v183, v71
	v_add_f32_e32 v180, v180, v181
	v_add_f32_e32 v182, v182, v183
	v_add_f32_e32 v180, v180, v182
	s_nop 1
	v_add_f32_dpp v180, v180, v180 quad_perm:[1,0,3,2] row_mask:0xf bank_mask:0xf
	s_nop 1
	v_add_f32_dpp v180, v180, v180 quad_perm:[2,3,0,1] row_mask:0xf bank_mask:0xf
	s_nop 1
	v_add_f32_dpp v180, v180, v180 row_half_mirror row_mask:0xf bank_mask:0xf
	s_nop 1
	v_add_f32_dpp v180, v180, v180 row_mirror row_mask:0xf bank_mask:0xf
	s_nop 1
	v_add_f32_dpp v180, v180, v180 row_bcast:15 row_mask:0xa bank_mask:0xf
	s_nop 1
	v_add_f32_dpp v180, v180, v180 row_bcast:31 row_mask:0xc bank_mask:0xf
	s_nop 0
	v_readlane_b32 s20, v180, 63
	s_nop 1
	v_mul_f32_e32 v184, s20, v2
	v_sub_f32_e32 v56, v56, v184
	v_sub_f32_e32 v57, v57, v184
	v_sub_f32_e32 v58, v58, v184
	v_sub_f32_e32 v59, v59, v184
	v_sub_f32_e32 v60, v60, v184
	v_sub_f32_e32 v61, v61, v184
	v_sub_f32_e32 v62, v62, v184
	v_sub_f32_e32 v63, v63, v184
	v_sub_f32_e32 v64, v64, v184
	v_sub_f32_e32 v65, v65, v184
	v_sub_f32_e32 v66, v66, v184
	v_sub_f32_e32 v67, v67, v184
	v_sub_f32_e32 v68, v68, v184
	v_sub_f32_e32 v69, v69, v184
	v_sub_f32_e32 v70, v70, v184
	v_sub_f32_e32 v71, v71, v184
	v_mul_f32_e32 v180, v56, v56
	v_mul_f32_e32 v181, v60, v60
	v_mul_f32_e32 v182, v64, v64
	v_mul_f32_e32 v183, v68, v68
	v_fmac_f32_e32 v180, v57, v57
	v_fmac_f32_e32 v181, v61, v61
	v_fmac_f32_e32 v182, v65, v65
	v_fmac_f32_e32 v183, v69, v69
	v_fmac_f32_e32 v180, v58, v58
	v_fmac_f32_e32 v181, v62, v62
	v_fmac_f32_e32 v182, v66, v66
	v_fmac_f32_e32 v183, v70, v70
	v_fmac_f32_e32 v180, v59, v59
	v_fmac_f32_e32 v181, v63, v63
	v_fmac_f32_e32 v182, v67, v67
	v_fmac_f32_e32 v183, v71, v71
	v_add_f32_e32 v180, v180, v181
	v_add_f32_e32 v182, v182, v183
	v_add_f32_e32 v180, v180, v182
	s_nop 1
	v_add_f32_dpp v180, v180, v180 quad_perm:[1,0,3,2] row_mask:0xf bank_mask:0xf
	s_nop 1
	v_add_f32_dpp v180, v180, v180 quad_perm:[2,3,0,1] row_mask:0xf bank_mask:0xf
	s_nop 1
	v_add_f32_dpp v180, v180, v180 row_half_mirror row_mask:0xf bank_mask:0xf
	s_nop 1
	v_add_f32_dpp v180, v180, v180 row_mirror row_mask:0xf bank_mask:0xf
	s_nop 1
	v_add_f32_dpp v180, v180, v180 row_bcast:15 row_mask:0xa bank_mask:0xf
	s_nop 1
	v_add_f32_dpp v180, v180, v180 row_bcast:31 row_mask:0xc bank_mask:0xf
	s_nop 0
	v_readlane_b32 s20, v180, 63
	s_nop 1
	v_mov_b32_e32 v185, s20
	v_fma_f32 v185, v185, v2, v4
	v_rsq_f32_e32 v185, v185
	s_nop 0
	v_mul_f32_e32 v56, v56, v185
	v_mul_f32_e32 v57, v57, v185
	v_mul_f32_e32 v58, v58, v185
	v_mul_f32_e32 v59, v59, v185
	v_mul_f32_e32 v60, v60, v185
	v_mul_f32_e32 v61, v61, v185
	v_mul_f32_e32 v62, v62, v185
	v_mul_f32_e32 v63, v63, v185
	v_mul_f32_e32 v64, v64, v185
	v_mul_f32_e32 v65, v65, v185
	v_mul_f32_e32 v66, v66, v185
	v_mul_f32_e32 v67, v67, v185
	v_mul_f32_e32 v68, v68, v185
	v_mul_f32_e32 v69, v69, v185
	v_mul_f32_e32 v70, v70, v185
	v_mul_f32_e32 v71, v71, v185
	v_fma_f32 v56, v56, v8, v24
	v_fma_f32 v57, v57, v9, v25
	v_fma_f32 v58, v58, v10, v26
	v_fma_f32 v59, v59, v11, v27
	v_fma_f32 v60, v60, v12, v28
	v_fma_f32 v61, v61, v13, v29
	v_fma_f32 v62, v62, v14, v30
	v_fma_f32 v63, v63, v15, v31
	v_fma_f32 v64, v64, v16, v32
	v_fma_f32 v65, v65, v17, v33
	v_fma_f32 v66, v66, v18, v34
	v_fma_f32 v67, v67, v19, v35
	v_fma_f32 v68, v68, v20, v36
	v_fma_f32 v69, v69, v21, v37
	v_fma_f32 v70, v70, v22, v38
	v_fma_f32 v71, v71, v23, v39
	v_add_u32_e32 v171, 0x3600000, v1
	global_store_dwordx4 v171, v[56:59], s[4:5]
	global_store_dwordx4 v171, v[60:63], s[4:5] offset:1024
	global_store_dwordx4 v171, v[64:67], s[4:5] offset:2048
	global_store_dwordx4 v171, v[68:71], s[4:5] offset:3072
	s_branch .Ltr_29
.Llo_even:
	s_lshr_b32 s1, s86, 3
	s_lshl_b32 s1, s1, 6
	s_lshl_b32 s0, s0, 3
	s_add_i32 s0, s0, s1
	s_and_b32 s1, s86, 7
	s_lshl_b32 s1, s1, 11
	s_add_i32 s0, s0, s1
	s_lshl_b32 s0, s0, 12
	s_add_u32 s4, s4, s0
	s_addc_u32 s5, s5, 0
	global_load_dwordx4 v[40:43], v1, s[4:5] nt
	global_load_dwordx4 v[44:47], v1, s[4:5] offset:1024 nt
	global_load_dwordx4 v[48:51], v1, s[4:5] offset:2048 nt
	global_load_dwordx4 v[52:55], v1, s[4:5] offset:3072 nt
	global_load_dwordx4 v[8:11], v1, s[40:41]
	global_load_dwordx4 v[12:15], v1, s[40:41] offset:1024
	global_load_dwordx4 v[16:19], v1, s[40:41] offset:2048
	global_load_dwordx4 v[20:23], v1, s[40:41] offset:3072
	global_load_dwordx4 v[24:27], v1, s[42:43]
	global_load_dwordx4 v[28:31], v1, s[42:43] offset:1024
	global_load_dwordx4 v[32:35], v1, s[42:43] offset:2048
	global_load_dwordx4 v[36:39], v1, s[42:43] offset:3072
	v_add_u32_e32 v170, 0x1000, v1
	global_load_dwordx4 v[56:59], v170, s[4:5] nt
	global_load_dwordx4 v[60:63], v170, s[4:5] offset:1024 nt
	global_load_dwordx4 v[64:67], v170, s[4:5] offset:2048 nt
	global_load_dwordx4 v[68:71], v170, s[4:5] offset:3072 nt
	v_add_u32_e32 v170, 0x2000, v1
	global_load_dwordx4 v[72:75], v170, s[4:5] nt
	global_load_dwordx4 v[76:79], v170, s[4:5] offset:1024 nt
	global_load_dwordx4 v[80:83], v170, s[4:5] offset:2048 nt
	global_load_dwordx4 v[84:87], v170, s[4:5] offset:3072 nt
	v_add_u32_e32 v170, 0x3000, v1
	global_load_dwordx4 v[88:91], v170, s[4:5] nt
	global_load_dwordx4 v[92:95], v170, s[4:5] offset:1024 nt
	global_load_dwordx4 v[96:99], v170, s[4:5] offset:2048 nt
	global_load_dwordx4 v[100:103], v170, s[4:5] offset:3072 nt
	v_add_u32_e32 v170, 0x4000, v1
	global_load_dwordx4 v[104:107], v170, s[4:5] nt
	global_load_dwordx4 v[108:111], v170, s[4:5] offset:1024 nt
	global_load_dwordx4 v[112:115], v170, s[4:5] offset:2048 nt
	global_load_dwordx4 v[116:119], v170, s[4:5] offset:3072 nt
	v_add_u32_e32 v170, 0x5000, v1
	global_load_dwordx4 v[120:123], v170, s[4:5] nt
	global_load_dwordx4 v[124:127], v170, s[4:5] offset:1024 nt
	global_load_dwordx4 v[128:131], v170, s[4:5] offset:2048 nt
	global_load_dwordx4 v[132:135], v170, s[4:5] offset:3072 nt
	v_add_u32_e32 v170, 0x6000, v1
	global_load_dwordx4 v[136:139], v170, s[4:5] nt
	global_load_dwordx4 v[140:143], v170, s[4:5] offset:1024 nt
	global_load_dwordx4 v[144:147], v170, s[4:5] offset:2048 nt
	global_load_dwordx4 v[148:151], v170, s[4:5] offset:3072 nt
	v_add_u32_e32 v170, 0x7000, v1
	global_load_dwordx4 v[152:155], v170, s[4:5] nt
	global_load_dwordx4 v[156:159], v170, s[4:5] offset:1024 nt
	global_load_dwordx4 v[160:163], v170, s[4:5] offset:2048 nt
	global_load_dwordx4 v[164:167], v170, s[4:5] offset:3072 nt
	s_waitcnt vmcnt(36)
	v_add_f32_e32 v180, v40, v41
	v_add_f32_e32 v181, v44, v45
	v_add_f32_e32 v182, v48, v49
	v_add_f32_e32 v183, v52, v53
	v_add_f32_e32 v180, v180, v42
	v_add_f32_e32 v181, v181, v46
	v_add_f32_e32 v182, v182, v50
	v_add_f32_e32 v183, v183, v54
	v_add_f32_e32 v180, v180, v43
	v_add_f32_e32 v181, v181, v47
	v_add_f32_e32 v182, v182, v51
	v_add_f32_e32 v183, v183, v55
	v_add_f32_e32 v180, v180, v181
	v_add_f32_e32 v182, v182, v183
	v_add_f32_e32 v180, v180, v182
	s_nop 1
	v_add_f32_dpp v180, v180, v180 quad_perm:[1,0,3,2] row_mask:0xf bank_mask:0xf
	s_nop 1
	v_add_f32_dpp v180, v180, v180 quad_perm:[2,3,0,1] row_mask:0xf bank_mask:0xf
	s_nop 1
	v_add_f32_dpp v180, v180, v180 row_half_mirror row_mask:0xf bank_mask:0xf
	s_nop 1
	v_add_f32_dpp v180, v180, v180 row_mirror row_mask:0xf bank_mask:0xf
	s_nop 1
	v_add_f32_dpp v180, v180, v180 row_bcast:15 row_mask:0xa bank_mask:0xf
	s_nop 1
	v_add_f32_dpp v180, v180, v180 row_bcast:31 row_mask:0xc bank_mask:0xf
	s_nop 0
	v_readlane_b32 s20, v180, 63
	s_nop 1
	v_mul_f32_e32 v184, s20, v2
	v_sub_f32_e32 v40, v40, v184
	v_sub_f32_e32 v41, v41, v184
	v_sub_f32_e32 v42, v42, v184
	v_sub_f32_e32 v43, v43, v184
	v_sub_f32_e32 v44, v44, v184
	v_sub_f32_e32 v45, v45, v184
	v_sub_f32_e32 v46, v46, v184
	v_sub_f32_e32 v47, v47, v184
	v_sub_f32_e32 v48, v48, v184
	v_sub_f32_e32 v49, v49, v184
	v_sub_f32_e32 v50, v50, v184
	v_sub_f32_e32 v51, v51, v184
	v_sub_f32_e32 v52, v52, v184
	v_sub_f32_e32 v53, v53, v184
	v_sub_f32_e32 v54, v54, v184
	v_sub_f32_e32 v55, v55, v184
	v_mul_f32_e32 v180, v40, v40
	v_mul_f32_e32 v181, v44, v44
	v_mul_f32_e32 v182, v48, v48
	v_mul_f32_e32 v183, v52, v52
	v_fmac_f32_e32 v180, v41, v41
	v_fmac_f32_e32 v181, v45, v45
	v_fmac_f32_e32 v182, v49, v49
	v_fmac_f32_e32 v183, v53, v53
	v_fmac_f32_e32 v180, v42, v42
	v_fmac_f32_e32 v181, v46, v46
	v_fmac_f32_e32 v182, v50, v50
	v_fmac_f32_e32 v183, v54, v54
	v_fmac_f32_e32 v180, v43, v43
	v_fmac_f32_e32 v181, v47, v47
	v_fmac_f32_e32 v182, v51, v51
	v_fmac_f32_e32 v183, v55, v55
	v_add_f32_e32 v180, v180, v181
	v_add_f32_e32 v182, v182, v183
	v_add_f32_e32 v180, v180, v182
	s_nop 1
	v_add_f32_dpp v180, v180, v180 quad_perm:[1,0,3,2] row_mask:0xf bank_mask:0xf
	s_nop 1
	v_add_f32_dpp v180, v180, v180 quad_perm:[2,3,0,1] row_mask:0xf bank_mask:0xf
	s_nop 1
	v_add_f32_dpp v180, v180, v180 row_half_mirror row_mask:0xf bank_mask:0xf
	s_nop 1
	v_add_f32_dpp v180, v180, v180 row_mirror row_mask:0xf bank_mask:0xf
	s_nop 1
	v_add_f32_dpp v180, v180, v180 row_bcast:15 row_mask:0xa bank_mask:0xf
	s_nop 1
	v_add_f32_dpp v180, v180, v180 row_bcast:31 row_mask:0xc bank_mask:0xf
	s_nop 0
	v_readlane_b32 s20, v180, 63
	s_nop 1
	v_mov_b32_e32 v185, s20
	v_fma_f32 v185, v185, v2, v4
	v_rsq_f32_e32 v185, v185
	s_nop 0
	v_mul_f32_e32 v40, v40, v185
	v_mul_f32_e32 v41, v41, v185
	v_mul_f32_e32 v42, v42, v185
	v_mul_f32_e32 v43, v43, v185
	v_mul_f32_e32 v44, v44, v185
	v_mul_f32_e32 v45, v45, v185
	v_mul_f32_e32 v46, v46, v185
	v_mul_f32_e32 v47, v47, v185
	v_mul_f32_e32 v48, v48, v185
	v_mul_f32_e32 v49, v49, v185
	v_mul_f32_e32 v50, v50, v185
	v_mul_f32_e32 v51, v51, v185
	v_mul_f32_e32 v52, v52, v185
	v_mul_f32_e32 v53, v53, v185
	v_mul_f32_e32 v54, v54, v185
	v_mul_f32_e32 v55, v55, v185
	s_waitcnt vmcnt(28)
	v_fma_f32 v40, v40, v8, v24
	v_fma_f32 v41, v41, v9, v25
	v_fma_f32 v42, v42, v10, v26
	v_fma_f32 v43, v43, v11, v27
	v_fma_f32 v44, v44, v12, v28
	v_fma_f32 v45, v45, v13, v29
	v_fma_f32 v46, v46, v14, v30
	v_fma_f32 v47, v47, v15, v31
	v_fma_f32 v48, v48, v16, v32
	v_fma_f32 v49, v49, v17, v33
	v_fma_f32 v50, v50, v18, v34
	v_fma_f32 v51, v51, v19, v35
	v_fma_f32 v52, v52, v20, v36
	v_fma_f32 v53, v53, v21, v37
	v_fma_f32 v54, v54, v22, v38
	v_fma_f32 v55, v55, v23, v39
	global_store_dwordx4 v1, v[40:43], s[4:5]
	global_store_dwordx4 v1, v[44:47], s[4:5] offset:1024
	global_store_dwordx4 v1, v[48:51], s[4:5] offset:2048
	global_store_dwordx4 v1, v[52:55], s[4:5] offset:3072
	s_waitcnt vmcnt(28)
	v_add_f32_e32 v180, v56, v57
	v_add_f32_e32 v181, v60, v61
	v_add_f32_e32 v182, v64, v65
	v_add_f32_e32 v183, v68, v69
	v_add_f32_e32 v180, v180, v58
	v_add_f32_e32 v181, v181, v62
	v_add_f32_e32 v182, v182, v66
	v_add_f32_e32 v183, v183, v70
	v_add_f32_e32 v180, v180, v59
	v_add_f32_e32 v181, v181, v63
	v_add_f32_e32 v182, v182, v67
	v_add_f32_e32 v183, v183, v71
	v_add_f32_e32 v180, v180, v181
	v_add_f32_e32 v182, v182, v183
	v_add_f32_e32 v180, v180, v182
	s_nop 1
	v_add_f32_dpp v180, v180, v180 quad_perm:[1,0,3,2] row_mask:0xf bank_mask:0xf
	s_nop 1
	v_add_f32_dpp v180, v180, v180 quad_perm:[2,3,0,1] row_mask:0xf bank_mask:0xf
	s_nop 1
	v_add_f32_dpp v180, v180, v180 row_half_mirror row_mask:0xf bank_mask:0xf
	s_nop 1
	v_add_f32_dpp v180, v180, v180 row_mirror row_mask:0xf bank_mask:0xf
	s_nop 1
	v_add_f32_dpp v180, v180, v180 row_bcast:15 row_mask:0xa bank_mask:0xf
	s_nop 1
	v_add_f32_dpp v180, v180, v180 row_bcast:31 row_mask:0xc bank_mask:0xf
	s_nop 0
	v_readlane_b32 s20, v180, 63
	s_nop 1
	v_mul_f32_e32 v184, s20, v2
	v_sub_f32_e32 v56, v56, v184
	v_sub_f32_e32 v57, v57, v184
	v_sub_f32_e32 v58, v58, v184
	v_sub_f32_e32 v59, v59, v184
	v_sub_f32_e32 v60, v60, v184
	v_sub_f32_e32 v61, v61, v184
	v_sub_f32_e32 v62, v62, v184
	v_sub_f32_e32 v63, v63, v184
	v_sub_f32_e32 v64, v64, v184
	v_sub_f32_e32 v65, v65, v184
	v_sub_f32_e32 v66, v66, v184
	v_sub_f32_e32 v67, v67, v184
	v_sub_f32_e32 v68, v68, v184
	v_sub_f32_e32 v69, v69, v184
	v_sub_f32_e32 v70, v70, v184
	v_sub_f32_e32 v71, v71, v184
	v_mul_f32_e32 v180, v56, v56
	v_mul_f32_e32 v181, v60, v60
	v_mul_f32_e32 v182, v64, v64
	v_mul_f32_e32 v183, v68, v68
	v_fmac_f32_e32 v180, v57, v57
	v_fmac_f32_e32 v181, v61, v61
	v_fmac_f32_e32 v182, v65, v65
	v_fmac_f32_e32 v183, v69, v69
	v_fmac_f32_e32 v180, v58, v58
	v_fmac_f32_e32 v181, v62, v62
	v_fmac_f32_e32 v182, v66, v66
	v_fmac_f32_e32 v183, v70, v70
	v_fmac_f32_e32 v180, v59, v59
	v_fmac_f32_e32 v181, v63, v63
	v_fmac_f32_e32 v182, v67, v67
	v_fmac_f32_e32 v183, v71, v71
	v_add_f32_e32 v180, v180, v181
	v_add_f32_e32 v182, v182, v183
	v_add_f32_e32 v180, v180, v182
	s_nop 1
	v_add_f32_dpp v180, v180, v180 quad_perm:[1,0,3,2] row_mask:0xf bank_mask:0xf
	s_nop 1
	v_add_f32_dpp v180, v180, v180 quad_perm:[2,3,0,1] row_mask:0xf bank_mask:0xf
	s_nop 1
	v_add_f32_dpp v180, v180, v180 row_half_mirror row_mask:0xf bank_mask:0xf
	s_nop 1
	v_add_f32_dpp v180, v180, v180 row_mirror row_mask:0xf bank_mask:0xf
	s_nop 1
	v_add_f32_dpp v180, v180, v180 row_bcast:15 row_mask:0xa bank_mask:0xf
	s_nop 1
	v_add_f32_dpp v180, v180, v180 row_bcast:31 row_mask:0xc bank_mask:0xf
	s_nop 0
	v_readlane_b32 s20, v180, 63
	s_nop 1
	v_mov_b32_e32 v185, s20
	v_fma_f32 v185, v185, v2, v4
	v_rsq_f32_e32 v185, v185
	s_nop 0
	v_mul_f32_e32 v56, v56, v185
	v_mul_f32_e32 v57, v57, v185
	v_mul_f32_e32 v58, v58, v185
	v_mul_f32_e32 v59, v59, v185
	v_mul_f32_e32 v60, v60, v185
	v_mul_f32_e32 v61, v61, v185
	v_mul_f32_e32 v62, v62, v185
	v_mul_f32_e32 v63, v63, v185
	v_mul_f32_e32 v64, v64, v185
	v_mul_f32_e32 v65, v65, v185
	v_mul_f32_e32 v66, v66, v185
	v_mul_f32_e32 v67, v67, v185
	v_mul_f32_e32 v68, v68, v185
	v_mul_f32_e32 v69, v69, v185
	v_mul_f32_e32 v70, v70, v185
	v_mul_f32_e32 v71, v71, v185
	v_fma_f32 v56, v56, v8, v24
	v_fma_f32 v57, v57, v9, v25
	v_fma_f32 v58, v58, v10, v26
	v_fma_f32 v59, v59, v11, v27
	v_fma_f32 v60, v60, v12, v28
	v_fma_f32 v61, v61, v13, v29
	v_fma_f32 v62, v62, v14, v30
	v_fma_f32 v63, v63, v15, v31
	v_fma_f32 v64, v64, v16, v32
	v_fma_f32 v65, v65, v17, v33
	v_fma_f32 v66, v66, v18, v34
	v_fma_f32 v67, v67, v19, v35
	v_fma_f32 v68, v68, v20, v36
	v_fma_f32 v69, v69, v21, v37
	v_fma_f32 v70, v70, v22, v38
	v_fma_f32 v71, v71, v23, v39
	v_add_u32_e32 v171, 0x1000, v1
	global_store_dwordx4 v171, v[56:59], s[4:5]
	global_store_dwordx4 v171, v[60:63], s[4:5] offset:1024
	global_store_dwordx4 v171, v[64:67], s[4:5] offset:2048
	global_store_dwordx4 v171, v[68:71], s[4:5] offset:3072
	s_waitcnt vmcnt(28)
	v_add_f32_e32 v180, v72, v73
	v_add_f32_e32 v181, v76, v77
	v_add_f32_e32 v182, v80, v81
	v_add_f32_e32 v183, v84, v85
	v_add_f32_e32 v180, v180, v74
	v_add_f32_e32 v181, v181, v78
	v_add_f32_e32 v182, v182, v82
	v_add_f32_e32 v183, v183, v86
	v_add_f32_e32 v180, v180, v75
	v_add_f32_e32 v181, v181, v79
	v_add_f32_e32 v182, v182, v83
	v_add_f32_e32 v183, v183, v87
	v_add_f32_e32 v180, v180, v181
	v_add_f32_e32 v182, v182, v183
	v_add_f32_e32 v180, v180, v182
	s_nop 1
	v_add_f32_dpp v180, v180, v180 quad_perm:[1,0,3,2] row_mask:0xf bank_mask:0xf
	s_nop 1
	v_add_f32_dpp v180, v180, v180 quad_perm:[2,3,0,1] row_mask:0xf bank_mask:0xf
	s_nop 1
	v_add_f32_dpp v180, v180, v180 row_half_mirror row_mask:0xf bank_mask:0xf
	s_nop 1
	v_add_f32_dpp v180, v180, v180 row_mirror row_mask:0xf bank_mask:0xf
	s_nop 1
	v_add_f32_dpp v180, v180, v180 row_bcast:15 row_mask:0xa bank_mask:0xf
	s_nop 1
	v_add_f32_dpp v180, v180, v180 row_bcast:31 row_mask:0xc bank_mask:0xf
	s_nop 0
	v_readlane_b32 s20, v180, 63
	s_nop 1
	v_mul_f32_e32 v184, s20, v2
	v_sub_f32_e32 v72, v72, v184
	v_sub_f32_e32 v73, v73, v184
	v_sub_f32_e32 v74, v74, v184
	v_sub_f32_e32 v75, v75, v184
	v_sub_f32_e32 v76, v76, v184
	v_sub_f32_e32 v77, v77, v184
	v_sub_f32_e32 v78, v78, v184
	v_sub_f32_e32 v79, v79, v184
	v_sub_f32_e32 v80, v80, v184
	v_sub_f32_e32 v81, v81, v184
	v_sub_f32_e32 v82, v82, v184
	v_sub_f32_e32 v83, v83, v184
	v_sub_f32_e32 v84, v84, v184
	v_sub_f32_e32 v85, v85, v184
	v_sub_f32_e32 v86, v86, v184
	v_sub_f32_e32 v87, v87, v184
	v_mul_f32_e32 v180, v72, v72
	v_mul_f32_e32 v181, v76, v76
	v_mul_f32_e32 v182, v80, v80
	v_mul_f32_e32 v183, v84, v84
	v_fmac_f32_e32 v180, v73, v73
	v_fmac_f32_e32 v181, v77, v77
	v_fmac_f32_e32 v182, v81, v81
	v_fmac_f32_e32 v183, v85, v85
	v_fmac_f32_e32 v180, v74, v74
	v_fmac_f32_e32 v181, v78, v78
	v_fmac_f32_e32 v182, v82, v82
	v_fmac_f32_e32 v183, v86, v86
	v_fmac_f32_e32 v180, v75, v75
	v_fmac_f32_e32 v181, v79, v79
	v_fmac_f32_e32 v182, v83, v83
	v_fmac_f32_e32 v183, v87, v87
	v_add_f32_e32 v180, v180, v181
	v_add_f32_e32 v182, v182, v183
	v_add_f32_e32 v180, v180, v182
	s_nop 1
	v_add_f32_dpp v180, v180, v180 quad_perm:[1,0,3,2] row_mask:0xf bank_mask:0xf
	s_nop 1
	v_add_f32_dpp v180, v180, v180 quad_perm:[2,3,0,1] row_mask:0xf bank_mask:0xf
	s_nop 1
	v_add_f32_dpp v180, v180, v180 row_half_mirror row_mask:0xf bank_mask:0xf
	s_nop 1
	v_add_f32_dpp v180, v180, v180 row_mirror row_mask:0xf bank_mask:0xf
	s_nop 1
	v_add_f32_dpp v180, v180, v180 row_bcast:15 row_mask:0xa bank_mask:0xf
	s_nop 1
	v_add_f32_dpp v180, v180, v180 row_bcast:31 row_mask:0xc bank_mask:0xf
	s_nop 0
	v_readlane_b32 s20, v180, 63
	s_nop 1
	v_mov_b32_e32 v185, s20
	v_fma_f32 v185, v185, v2, v4
	v_rsq_f32_e32 v185, v185
	s_nop 0
	v_mul_f32_e32 v72, v72, v185
	v_mul_f32_e32 v73, v73, v185
	v_mul_f32_e32 v74, v74, v185
	v_mul_f32_e32 v75, v75, v185
	v_mul_f32_e32 v76, v76, v185
	v_mul_f32_e32 v77, v77, v185
	v_mul_f32_e32 v78, v78, v185
	v_mul_f32_e32 v79, v79, v185
	v_mul_f32_e32 v80, v80, v185
	v_mul_f32_e32 v81, v81, v185
	v_mul_f32_e32 v82, v82, v185
	v_mul_f32_e32 v83, v83, v185
	v_mul_f32_e32 v84, v84, v185
	v_mul_f32_e32 v85, v85, v185
	v_mul_f32_e32 v86, v86, v185
	v_mul_f32_e32 v87, v87, v185
	v_fma_f32 v72, v72, v8, v24
	v_fma_f32 v73, v73, v9, v25
	v_fma_f32 v74, v74, v10, v26
	v_fma_f32 v75, v75, v11, v27
	v_fma_f32 v76, v76, v12, v28
	v_fma_f32 v77, v77, v13, v29
	v_fma_f32 v78, v78, v14, v30
	v_fma_f32 v79, v79, v15, v31
	v_fma_f32 v80, v80, v16, v32
	v_fma_f32 v81, v81, v17, v33
	v_fma_f32 v82, v82, v18, v34
	v_fma_f32 v83, v83, v19, v35
	v_fma_f32 v84, v84, v20, v36
	v_fma_f32 v85, v85, v21, v37
	v_fma_f32 v86, v86, v22, v38
	v_fma_f32 v87, v87, v23, v39
	v_add_u32_e32 v171, 0x2000, v1
	global_store_dwordx4 v171, v[72:75], s[4:5]
	global_store_dwordx4 v171, v[76:79], s[4:5] offset:1024
	global_store_dwordx4 v171, v[80:83], s[4:5] offset:2048
	global_store_dwordx4 v171, v[84:87], s[4:5] offset:3072
	s_waitcnt vmcnt(28)
	v_add_f32_e32 v180, v88, v89
	v_add_f32_e32 v181, v92, v93
	v_add_f32_e32 v182, v96, v97
	v_add_f32_e32 v183, v100, v101
	v_add_f32_e32 v180, v180, v90
	v_add_f32_e32 v181, v181, v94
	v_add_f32_e32 v182, v182, v98
	v_add_f32_e32 v183, v183, v102
	v_add_f32_e32 v180, v180, v91
	v_add_f32_e32 v181, v181, v95
	v_add_f32_e32 v182, v182, v99
	v_add_f32_e32 v183, v183, v103
	v_add_f32_e32 v180, v180, v181
	v_add_f32_e32 v182, v182, v183
	v_add_f32_e32 v180, v180, v182
	s_nop 1
	v_add_f32_dpp v180, v180, v180 quad_perm:[1,0,3,2] row_mask:0xf bank_mask:0xf
	s_nop 1
	v_add_f32_dpp v180, v180, v180 quad_perm:[2,3,0,1] row_mask:0xf bank_mask:0xf
	s_nop 1
	v_add_f32_dpp v180, v180, v180 row_half_mirror row_mask:0xf bank_mask:0xf
	s_nop 1
	v_add_f32_dpp v180, v180, v180 row_mirror row_mask:0xf bank_mask:0xf
	s_nop 1
	v_add_f32_dpp v180, v180, v180 row_bcast:15 row_mask:0xa bank_mask:0xf
	s_nop 1
	v_add_f32_dpp v180, v180, v180 row_bcast:31 row_mask:0xc bank_mask:0xf
	s_nop 0
	v_readlane_b32 s20, v180, 63
	s_nop 1
	v_mul_f32_e32 v184, s20, v2
	v_sub_f32_e32 v88, v88, v184
	v_sub_f32_e32 v89, v89, v184
	v_sub_f32_e32 v90, v90, v184
	v_sub_f32_e32 v91, v91, v184
	v_sub_f32_e32 v92, v92, v184
	v_sub_f32_e32 v93, v93, v184
	v_sub_f32_e32 v94, v94, v184
	v_sub_f32_e32 v95, v95, v184
	v_sub_f32_e32 v96, v96, v184
	v_sub_f32_e32 v97, v97, v184
	v_sub_f32_e32 v98, v98, v184
	v_sub_f32_e32 v99, v99, v184
	v_sub_f32_e32 v100, v100, v184
	v_sub_f32_e32 v101, v101, v184
	v_sub_f32_e32 v102, v102, v184
	v_sub_f32_e32 v103, v103, v184
	v_mul_f32_e32 v180, v88, v88
	v_mul_f32_e32 v181, v92, v92
	v_mul_f32_e32 v182, v96, v96
	v_mul_f32_e32 v183, v100, v100
	v_fmac_f32_e32 v180, v89, v89
	v_fmac_f32_e32 v181, v93, v93
	v_fmac_f32_e32 v182, v97, v97
	v_fmac_f32_e32 v183, v101, v101
	v_fmac_f32_e32 v180, v90, v90
	v_fmac_f32_e32 v181, v94, v94
	v_fmac_f32_e32 v182, v98, v98
	v_fmac_f32_e32 v183, v102, v102
	v_fmac_f32_e32 v180, v91, v91
	v_fmac_f32_e32 v181, v95, v95
	v_fmac_f32_e32 v182, v99, v99
	v_fmac_f32_e32 v183, v103, v103
	v_add_f32_e32 v180, v180, v181
	v_add_f32_e32 v182, v182, v183
	v_add_f32_e32 v180, v180, v182
	s_nop 1
	v_add_f32_dpp v180, v180, v180 quad_perm:[1,0,3,2] row_mask:0xf bank_mask:0xf
	s_nop 1
	v_add_f32_dpp v180, v180, v180 quad_perm:[2,3,0,1] row_mask:0xf bank_mask:0xf
	s_nop 1
	v_add_f32_dpp v180, v180, v180 row_half_mirror row_mask:0xf bank_mask:0xf
	s_nop 1
	v_add_f32_dpp v180, v180, v180 row_mirror row_mask:0xf bank_mask:0xf
	s_nop 1
	v_add_f32_dpp v180, v180, v180 row_bcast:15 row_mask:0xa bank_mask:0xf
	s_nop 1
	v_add_f32_dpp v180, v180, v180 row_bcast:31 row_mask:0xc bank_mask:0xf
	s_nop 0
	v_readlane_b32 s20, v180, 63
	s_nop 1
	v_mov_b32_e32 v185, s20
	v_fma_f32 v185, v185, v2, v4
	v_rsq_f32_e32 v185, v185
	s_nop 0
	v_mul_f32_e32 v88, v88, v185
	v_mul_f32_e32 v89, v89, v185
	v_mul_f32_e32 v90, v90, v185
	v_mul_f32_e32 v91, v91, v185
	v_mul_f32_e32 v92, v92, v185
	v_mul_f32_e32 v93, v93, v185
	v_mul_f32_e32 v94, v94, v185
	v_mul_f32_e32 v95, v95, v185
	v_mul_f32_e32 v96, v96, v185
	v_mul_f32_e32 v97, v97, v185
	v_mul_f32_e32 v98, v98, v185
	v_mul_f32_e32 v99, v99, v185
	v_mul_f32_e32 v100, v100, v185
	v_mul_f32_e32 v101, v101, v185
	v_mul_f32_e32 v102, v102, v185
	v_mul_f32_e32 v103, v103, v185
	v_fma_f32 v88, v88, v8, v24
	v_fma_f32 v89, v89, v9, v25
	v_fma_f32 v90, v90, v10, v26
	v_fma_f32 v91, v91, v11, v27
	v_fma_f32 v92, v92, v12, v28
	v_fma_f32 v93, v93, v13, v29
	v_fma_f32 v94, v94, v14, v30
	v_fma_f32 v95, v95, v15, v31
	v_fma_f32 v96, v96, v16, v32
	v_fma_f32 v97, v97, v17, v33
	v_fma_f32 v98, v98, v18, v34
	v_fma_f32 v99, v99, v19, v35
	v_fma_f32 v100, v100, v20, v36
	v_fma_f32 v101, v101, v21, v37
	v_fma_f32 v102, v102, v22, v38
	v_fma_f32 v103, v103, v23, v39
	v_add_u32_e32 v171, 0x3000, v1
	global_store_dwordx4 v171, v[88:91], s[4:5]
	global_store_dwordx4 v171, v[92:95], s[4:5] offset:1024
	global_store_dwordx4 v171, v[96:99], s[4:5] offset:2048
	global_store_dwordx4 v171, v[100:103], s[4:5] offset:3072
	s_waitcnt vmcnt(28)
	v_add_f32_e32 v180, v104, v105
	v_add_f32_e32 v181, v108, v109
	v_add_f32_e32 v182, v112, v113
	v_add_f32_e32 v183, v116, v117
	v_add_f32_e32 v180, v180, v106
	v_add_f32_e32 v181, v181, v110
	v_add_f32_e32 v182, v182, v114
	v_add_f32_e32 v183, v183, v118
	v_add_f32_e32 v180, v180, v107
	v_add_f32_e32 v181, v181, v111
	v_add_f32_e32 v182, v182, v115
	v_add_f32_e32 v183, v183, v119
	v_add_f32_e32 v180, v180, v181
	v_add_f32_e32 v182, v182, v183
	v_add_f32_e32 v180, v180, v182
	s_nop 1
	v_add_f32_dpp v180, v180, v180 quad_perm:[1,0,3,2] row_mask:0xf bank_mask:0xf
	s_nop 1
	v_add_f32_dpp v180, v180, v180 quad_perm:[2,3,0,1] row_mask:0xf bank_mask:0xf
	s_nop 1
	v_add_f32_dpp v180, v180, v180 row_half_mirror row_mask:0xf bank_mask:0xf
	s_nop 1
	v_add_f32_dpp v180, v180, v180 row_mirror row_mask:0xf bank_mask:0xf
	s_nop 1
	v_add_f32_dpp v180, v180, v180 row_bcast:15 row_mask:0xa bank_mask:0xf
	s_nop 1
	v_add_f32_dpp v180, v180, v180 row_bcast:31 row_mask:0xc bank_mask:0xf
	s_nop 0
	v_readlane_b32 s20, v180, 63
	s_nop 1
	v_mul_f32_e32 v184, s20, v2
	v_sub_f32_e32 v104, v104, v184
	v_sub_f32_e32 v105, v105, v184
	v_sub_f32_e32 v106, v106, v184
	v_sub_f32_e32 v107, v107, v184
	v_sub_f32_e32 v108, v108, v184
	v_sub_f32_e32 v109, v109, v184
	v_sub_f32_e32 v110, v110, v184
	v_sub_f32_e32 v111, v111, v184
	v_sub_f32_e32 v112, v112, v184
	v_sub_f32_e32 v113, v113, v184
	v_sub_f32_e32 v114, v114, v184
	v_sub_f32_e32 v115, v115, v184
	v_sub_f32_e32 v116, v116, v184
	v_sub_f32_e32 v117, v117, v184
	v_sub_f32_e32 v118, v118, v184
	v_sub_f32_e32 v119, v119, v184
	v_mul_f32_e32 v180, v104, v104
	v_mul_f32_e32 v181, v108, v108
	v_mul_f32_e32 v182, v112, v112
	v_mul_f32_e32 v183, v116, v116
	v_fmac_f32_e32 v180, v105, v105
	v_fmac_f32_e32 v181, v109, v109
	v_fmac_f32_e32 v182, v113, v113
	v_fmac_f32_e32 v183, v117, v117
	v_fmac_f32_e32 v180, v106, v106
	v_fmac_f32_e32 v181, v110, v110
	v_fmac_f32_e32 v182, v114, v114
	v_fmac_f32_e32 v183, v118, v118
	v_fmac_f32_e32 v180, v107, v107
	v_fmac_f32_e32 v181, v111, v111
	v_fmac_f32_e32 v182, v115, v115
	v_fmac_f32_e32 v183, v119, v119
	v_add_f32_e32 v180, v180, v181
	v_add_f32_e32 v182, v182, v183
	v_add_f32_e32 v180, v180, v182
	s_nop 1
	v_add_f32_dpp v180, v180, v180 quad_perm:[1,0,3,2] row_mask:0xf bank_mask:0xf
	s_nop 1
	v_add_f32_dpp v180, v180, v180 quad_perm:[2,3,0,1] row_mask:0xf bank_mask:0xf
	s_nop 1
	v_add_f32_dpp v180, v180, v180 row_half_mirror row_mask:0xf bank_mask:0xf
	s_nop 1
	v_add_f32_dpp v180, v180, v180 row_mirror row_mask:0xf bank_mask:0xf
	s_nop 1
	v_add_f32_dpp v180, v180, v180 row_bcast:15 row_mask:0xa bank_mask:0xf
	s_nop 1
	v_add_f32_dpp v180, v180, v180 row_bcast:31 row_mask:0xc bank_mask:0xf
	s_nop 0
	v_readlane_b32 s20, v180, 63
	s_nop 1
	v_mov_b32_e32 v185, s20
	v_fma_f32 v185, v185, v2, v4
	v_rsq_f32_e32 v185, v185
	s_nop 0
	v_mul_f32_e32 v104, v104, v185
	v_mul_f32_e32 v105, v105, v185
	v_mul_f32_e32 v106, v106, v185
	v_mul_f32_e32 v107, v107, v185
	v_mul_f32_e32 v108, v108, v185
	v_mul_f32_e32 v109, v109, v185
	v_mul_f32_e32 v110, v110, v185
	v_mul_f32_e32 v111, v111, v185
	v_mul_f32_e32 v112, v112, v185
	v_mul_f32_e32 v113, v113, v185
	v_mul_f32_e32 v114, v114, v185
	v_mul_f32_e32 v115, v115, v185
	v_mul_f32_e32 v116, v116, v185
	v_mul_f32_e32 v117, v117, v185
	v_mul_f32_e32 v118, v118, v185
	v_mul_f32_e32 v119, v119, v185
	v_fma_f32 v104, v104, v8, v24
	v_fma_f32 v105, v105, v9, v25
	v_fma_f32 v106, v106, v10, v26
	v_fma_f32 v107, v107, v11, v27
	v_fma_f32 v108, v108, v12, v28
	v_fma_f32 v109, v109, v13, v29
	v_fma_f32 v110, v110, v14, v30
	v_fma_f32 v111, v111, v15, v31
	v_fma_f32 v112, v112, v16, v32
	v_fma_f32 v113, v113, v17, v33
	v_fma_f32 v114, v114, v18, v34
	v_fma_f32 v115, v115, v19, v35
	v_fma_f32 v116, v116, v20, v36
	v_fma_f32 v117, v117, v21, v37
	v_fma_f32 v118, v118, v22, v38
	v_fma_f32 v119, v119, v23, v39
	v_add_u32_e32 v171, 0x4000, v1
	global_store_dwordx4 v171, v[104:107], s[4:5]
	global_store_dwordx4 v171, v[108:111], s[4:5] offset:1024
	global_store_dwordx4 v171, v[112:115], s[4:5] offset:2048
	global_store_dwordx4 v171, v[116:119], s[4:5] offset:3072
	s_waitcnt vmcnt(28)
	v_add_f32_e32 v180, v120, v121
	v_add_f32_e32 v181, v124, v125
	v_add_f32_e32 v182, v128, v129
	v_add_f32_e32 v183, v132, v133
	v_add_f32_e32 v180, v180, v122
	v_add_f32_e32 v181, v181, v126
	v_add_f32_e32 v182, v182, v130
	v_add_f32_e32 v183, v183, v134
	v_add_f32_e32 v180, v180, v123
	v_add_f32_e32 v181, v181, v127
	v_add_f32_e32 v182, v182, v131
	v_add_f32_e32 v183, v183, v135
	v_add_f32_e32 v180, v180, v181
	v_add_f32_e32 v182, v182, v183
	v_add_f32_e32 v180, v180, v182
	s_nop 1
	v_add_f32_dpp v180, v180, v180 quad_perm:[1,0,3,2] row_mask:0xf bank_mask:0xf
	s_nop 1
	v_add_f32_dpp v180, v180, v180 quad_perm:[2,3,0,1] row_mask:0xf bank_mask:0xf
	s_nop 1
	v_add_f32_dpp v180, v180, v180 row_half_mirror row_mask:0xf bank_mask:0xf
	s_nop 1
	v_add_f32_dpp v180, v180, v180 row_mirror row_mask:0xf bank_mask:0xf
	s_nop 1
	v_add_f32_dpp v180, v180, v180 row_bcast:15 row_mask:0xa bank_mask:0xf
	s_nop 1
	v_add_f32_dpp v180, v180, v180 row_bcast:31 row_mask:0xc bank_mask:0xf
	s_nop 0
	v_readlane_b32 s20, v180, 63
	s_nop 1
	v_mul_f32_e32 v184, s20, v2
	v_sub_f32_e32 v120, v120, v184
	v_sub_f32_e32 v121, v121, v184
	v_sub_f32_e32 v122, v122, v184
	v_sub_f32_e32 v123, v123, v184
	v_sub_f32_e32 v124, v124, v184
	v_sub_f32_e32 v125, v125, v184
	v_sub_f32_e32 v126, v126, v184
	v_sub_f32_e32 v127, v127, v184
	v_sub_f32_e32 v128, v128, v184
	v_sub_f32_e32 v129, v129, v184
	v_sub_f32_e32 v130, v130, v184
	v_sub_f32_e32 v131, v131, v184
	v_sub_f32_e32 v132, v132, v184
	v_sub_f32_e32 v133, v133, v184
	v_sub_f32_e32 v134, v134, v184
	v_sub_f32_e32 v135, v135, v184
	v_mul_f32_e32 v180, v120, v120
	v_mul_f32_e32 v181, v124, v124
	v_mul_f32_e32 v182, v128, v128
	v_mul_f32_e32 v183, v132, v132
	v_fmac_f32_e32 v180, v121, v121
	v_fmac_f32_e32 v181, v125, v125
	v_fmac_f32_e32 v182, v129, v129
	v_fmac_f32_e32 v183, v133, v133
	v_fmac_f32_e32 v180, v122, v122
	v_fmac_f32_e32 v181, v126, v126
	v_fmac_f32_e32 v182, v130, v130
	v_fmac_f32_e32 v183, v134, v134
	v_fmac_f32_e32 v180, v123, v123
	v_fmac_f32_e32 v181, v127, v127
	v_fmac_f32_e32 v182, v131, v131
	v_fmac_f32_e32 v183, v135, v135
	v_add_f32_e32 v180, v180, v181
	v_add_f32_e32 v182, v182, v183
	v_add_f32_e32 v180, v180, v182
	s_nop 1
	v_add_f32_dpp v180, v180, v180 quad_perm:[1,0,3,2] row_mask:0xf bank_mask:0xf
	s_nop 1
	v_add_f32_dpp v180, v180, v180 quad_perm:[2,3,0,1] row_mask:0xf bank_mask:0xf
	s_nop 1
	v_add_f32_dpp v180, v180, v180 row_half_mirror row_mask:0xf bank_mask:0xf
	s_nop 1
	v_add_f32_dpp v180, v180, v180 row_mirror row_mask:0xf bank_mask:0xf
	s_nop 1
	v_add_f32_dpp v180, v180, v180 row_bcast:15 row_mask:0xa bank_mask:0xf
	s_nop 1
	v_add_f32_dpp v180, v180, v180 row_bcast:31 row_mask:0xc bank_mask:0xf
	s_nop 0
	v_readlane_b32 s20, v180, 63
	s_nop 1
	v_mov_b32_e32 v185, s20
	v_fma_f32 v185, v185, v2, v4
	v_rsq_f32_e32 v185, v185
	s_nop 0
	v_mul_f32_e32 v120, v120, v185
	v_mul_f32_e32 v121, v121, v185
	v_mul_f32_e32 v122, v122, v185
	v_mul_f32_e32 v123, v123, v185
	v_mul_f32_e32 v124, v124, v185
	v_mul_f32_e32 v125, v125, v185
	v_mul_f32_e32 v126, v126, v185
	v_mul_f32_e32 v127, v127, v185
	v_mul_f32_e32 v128, v128, v185
	v_mul_f32_e32 v129, v129, v185
	v_mul_f32_e32 v130, v130, v185
	v_mul_f32_e32 v131, v131, v185
	v_mul_f32_e32 v132, v132, v185
	v_mul_f32_e32 v133, v133, v185
	v_mul_f32_e32 v134, v134, v185
	v_mul_f32_e32 v135, v135, v185
	v_fma_f32 v120, v120, v8, v24
	v_fma_f32 v121, v121, v9, v25
	v_fma_f32 v122, v122, v10, v26
	v_fma_f32 v123, v123, v11, v27
	v_fma_f32 v124, v124, v12, v28
	v_fma_f32 v125, v125, v13, v29
	v_fma_f32 v126, v126, v14, v30
	v_fma_f32 v127, v127, v15, v31
	v_fma_f32 v128, v128, v16, v32
	v_fma_f32 v129, v129, v17, v33
	v_fma_f32 v130, v130, v18, v34
	v_fma_f32 v131, v131, v19, v35
	v_fma_f32 v132, v132, v20, v36
	v_fma_f32 v133, v133, v21, v37
	v_fma_f32 v134, v134, v22, v38
	v_fma_f32 v135, v135, v23, v39
	v_add_u32_e32 v171, 0x5000, v1
	global_store_dwordx4 v171, v[120:123], s[4:5]
	global_store_dwordx4 v171, v[124:127], s[4:5] offset:1024
	global_store_dwordx4 v171, v[128:131], s[4:5] offset:2048
	global_store_dwordx4 v171, v[132:135], s[4:5] offset:3072
	s_waitcnt vmcnt(28)
	v_add_f32_e32 v180, v136, v137
	v_add_f32_e32 v181, v140, v141
	v_add_f32_e32 v182, v144, v145
	v_add_f32_e32 v183, v148, v149
	v_add_f32_e32 v180, v180, v138
	v_add_f32_e32 v181, v181, v142
	v_add_f32_e32 v182, v182, v146
	v_add_f32_e32 v183, v183, v150
	v_add_f32_e32 v180, v180, v139
	v_add_f32_e32 v181, v181, v143
	v_add_f32_e32 v182, v182, v147
	v_add_f32_e32 v183, v183, v151
	v_add_f32_e32 v180, v180, v181
	v_add_f32_e32 v182, v182, v183
	v_add_f32_e32 v180, v180, v182
	s_nop 1
	v_add_f32_dpp v180, v180, v180 quad_perm:[1,0,3,2] row_mask:0xf bank_mask:0xf
	s_nop 1
	v_add_f32_dpp v180, v180, v180 quad_perm:[2,3,0,1] row_mask:0xf bank_mask:0xf
	s_nop 1
	v_add_f32_dpp v180, v180, v180 row_half_mirror row_mask:0xf bank_mask:0xf
	s_nop 1
	v_add_f32_dpp v180, v180, v180 row_mirror row_mask:0xf bank_mask:0xf
	s_nop 1
	v_add_f32_dpp v180, v180, v180 row_bcast:15 row_mask:0xa bank_mask:0xf
	s_nop 1
	v_add_f32_dpp v180, v180, v180 row_bcast:31 row_mask:0xc bank_mask:0xf
	s_nop 0
	v_readlane_b32 s20, v180, 63
	s_nop 1
	v_mul_f32_e32 v184, s20, v2
	v_sub_f32_e32 v136, v136, v184
	v_sub_f32_e32 v137, v137, v184
	v_sub_f32_e32 v138, v138, v184
	v_sub_f32_e32 v139, v139, v184
	v_sub_f32_e32 v140, v140, v184
	v_sub_f32_e32 v141, v141, v184
	v_sub_f32_e32 v142, v142, v184
	v_sub_f32_e32 v143, v143, v184
	v_sub_f32_e32 v144, v144, v184
	v_sub_f32_e32 v145, v145, v184
	v_sub_f32_e32 v146, v146, v184
	v_sub_f32_e32 v147, v147, v184
	v_sub_f32_e32 v148, v148, v184
	v_sub_f32_e32 v149, v149, v184
	v_sub_f32_e32 v150, v150, v184
	v_sub_f32_e32 v151, v151, v184
	v_mul_f32_e32 v180, v136, v136
	v_mul_f32_e32 v181, v140, v140
	v_mul_f32_e32 v182, v144, v144
	v_mul_f32_e32 v183, v148, v148
	v_fmac_f32_e32 v180, v137, v137
	v_fmac_f32_e32 v181, v141, v141
	v_fmac_f32_e32 v182, v145, v145
	v_fmac_f32_e32 v183, v149, v149
	v_fmac_f32_e32 v180, v138, v138
	v_fmac_f32_e32 v181, v142, v142
	v_fmac_f32_e32 v182, v146, v146
	v_fmac_f32_e32 v183, v150, v150
	v_fmac_f32_e32 v180, v139, v139
	v_fmac_f32_e32 v181, v143, v143
	v_fmac_f32_e32 v182, v147, v147
	v_fmac_f32_e32 v183, v151, v151
	v_add_f32_e32 v180, v180, v181
	v_add_f32_e32 v182, v182, v183
	v_add_f32_e32 v180, v180, v182
	s_nop 1
	v_add_f32_dpp v180, v180, v180 quad_perm:[1,0,3,2] row_mask:0xf bank_mask:0xf
	s_nop 1
	v_add_f32_dpp v180, v180, v180 quad_perm:[2,3,0,1] row_mask:0xf bank_mask:0xf
	s_nop 1
	v_add_f32_dpp v180, v180, v180 row_half_mirror row_mask:0xf bank_mask:0xf
	s_nop 1
	v_add_f32_dpp v180, v180, v180 row_mirror row_mask:0xf bank_mask:0xf
	s_nop 1
	v_add_f32_dpp v180, v180, v180 row_bcast:15 row_mask:0xa bank_mask:0xf
	s_nop 1
	v_add_f32_dpp v180, v180, v180 row_bcast:31 row_mask:0xc bank_mask:0xf
	s_nop 0
	v_readlane_b32 s20, v180, 63
	s_nop 1
	v_mov_b32_e32 v185, s20
	v_fma_f32 v185, v185, v2, v4
	v_rsq_f32_e32 v185, v185
	s_nop 0
	v_mul_f32_e32 v136, v136, v185
	v_mul_f32_e32 v137, v137, v185
	v_mul_f32_e32 v138, v138, v185
	v_mul_f32_e32 v139, v139, v185
	v_mul_f32_e32 v140, v140, v185
	v_mul_f32_e32 v141, v141, v185
	v_mul_f32_e32 v142, v142, v185
	v_mul_f32_e32 v143, v143, v185
	v_mul_f32_e32 v144, v144, v185
	v_mul_f32_e32 v145, v145, v185
	v_mul_f32_e32 v146, v146, v185
	v_mul_f32_e32 v147, v147, v185
	v_mul_f32_e32 v148, v148, v185
	v_mul_f32_e32 v149, v149, v185
	v_mul_f32_e32 v150, v150, v185
	v_mul_f32_e32 v151, v151, v185
	v_fma_f32 v136, v136, v8, v24
	v_fma_f32 v137, v137, v9, v25
	v_fma_f32 v138, v138, v10, v26
	v_fma_f32 v139, v139, v11, v27
	v_fma_f32 v140, v140, v12, v28
	v_fma_f32 v141, v141, v13, v29
	v_fma_f32 v142, v142, v14, v30
	v_fma_f32 v143, v143, v15, v31
	v_fma_f32 v144, v144, v16, v32
	v_fma_f32 v145, v145, v17, v33
	v_fma_f32 v146, v146, v18, v34
	v_fma_f32 v147, v147, v19, v35
	v_fma_f32 v148, v148, v20, v36
	v_fma_f32 v149, v149, v21, v37
	v_fma_f32 v150, v150, v22, v38
	v_fma_f32 v151, v151, v23, v39
	v_add_u32_e32 v171, 0x6000, v1
	global_store_dwordx4 v171, v[136:139], s[4:5]
	global_store_dwordx4 v171, v[140:143], s[4:5] offset:1024
	global_store_dwordx4 v171, v[144:147], s[4:5] offset:2048
	global_store_dwordx4 v171, v[148:151], s[4:5] offset:3072
	s_waitcnt vmcnt(28)
	v_add_f32_e32 v180, v152, v153
	v_add_f32_e32 v181, v156, v157
	v_add_f32_e32 v182, v160, v161
	v_add_f32_e32 v183, v164, v165
	v_add_f32_e32 v180, v180, v154
	v_add_f32_e32 v181, v181, v158
	v_add_f32_e32 v182, v182, v162
	v_add_f32_e32 v183, v183, v166
	v_add_f32_e32 v180, v180, v155
	v_add_f32_e32 v181, v181, v159
	v_add_f32_e32 v182, v182, v163
	v_add_f32_e32 v183, v183, v167
	v_add_f32_e32 v180, v180, v181
	v_add_f32_e32 v182, v182, v183
	v_add_f32_e32 v180, v180, v182
	s_nop 1
	v_add_f32_dpp v180, v180, v180 quad_perm:[1,0,3,2] row_mask:0xf bank_mask:0xf
	s_nop 1
	v_add_f32_dpp v180, v180, v180 quad_perm:[2,3,0,1] row_mask:0xf bank_mask:0xf
	s_nop 1
	v_add_f32_dpp v180, v180, v180 row_half_mirror row_mask:0xf bank_mask:0xf
	s_nop 1
	v_add_f32_dpp v180, v180, v180 row_mirror row_mask:0xf bank_mask:0xf
	s_nop 1
	v_add_f32_dpp v180, v180, v180 row_bcast:15 row_mask:0xa bank_mask:0xf
	s_nop 1
	v_add_f32_dpp v180, v180, v180 row_bcast:31 row_mask:0xc bank_mask:0xf
	s_nop 0
	v_readlane_b32 s20, v180, 63
	s_nop 1
	v_mul_f32_e32 v184, s20, v2
	v_sub_f32_e32 v152, v152, v184
	v_sub_f32_e32 v153, v153, v184
	v_sub_f32_e32 v154, v154, v184
	v_sub_f32_e32 v155, v155, v184
	v_sub_f32_e32 v156, v156, v184
	v_sub_f32_e32 v157, v157, v184
	v_sub_f32_e32 v158, v158, v184
	v_sub_f32_e32 v159, v159, v184
	v_sub_f32_e32 v160, v160, v184
	v_sub_f32_e32 v161, v161, v184
	v_sub_f32_e32 v162, v162, v184
	v_sub_f32_e32 v163, v163, v184
	v_sub_f32_e32 v164, v164, v184
	v_sub_f32_e32 v165, v165, v184
	v_sub_f32_e32 v166, v166, v184
	v_sub_f32_e32 v167, v167, v184
	v_mul_f32_e32 v180, v152, v152
	v_mul_f32_e32 v181, v156, v156
	v_mul_f32_e32 v182, v160, v160
	v_mul_f32_e32 v183, v164, v164
	v_fmac_f32_e32 v180, v153, v153
	v_fmac_f32_e32 v181, v157, v157
	v_fmac_f32_e32 v182, v161, v161
	v_fmac_f32_e32 v183, v165, v165
	v_fmac_f32_e32 v180, v154, v154
	v_fmac_f32_e32 v181, v158, v158
	v_fmac_f32_e32 v182, v162, v162
	v_fmac_f32_e32 v183, v166, v166
	v_fmac_f32_e32 v180, v155, v155
	v_fmac_f32_e32 v181, v159, v159
	v_fmac_f32_e32 v182, v163, v163
	v_fmac_f32_e32 v183, v167, v167
	v_add_f32_e32 v180, v180, v181
	v_add_f32_e32 v182, v182, v183
	v_add_f32_e32 v180, v180, v182
	s_nop 1
	v_add_f32_dpp v180, v180, v180 quad_perm:[1,0,3,2] row_mask:0xf bank_mask:0xf
	s_nop 1
	v_add_f32_dpp v180, v180, v180 quad_perm:[2,3,0,1] row_mask:0xf bank_mask:0xf
	s_nop 1
	v_add_f32_dpp v180, v180, v180 row_half_mirror row_mask:0xf bank_mask:0xf
	s_nop 1
	v_add_f32_dpp v180, v180, v180 row_mirror row_mask:0xf bank_mask:0xf
	s_nop 1
	v_add_f32_dpp v180, v180, v180 row_bcast:15 row_mask:0xa bank_mask:0xf
	s_nop 1
	v_add_f32_dpp v180, v180, v180 row_bcast:31 row_mask:0xc bank_mask:0xf
	s_nop 0
	v_readlane_b32 s20, v180, 63
	s_nop 1
	v_mov_b32_e32 v185, s20
	v_fma_f32 v185, v185, v2, v4
	v_rsq_f32_e32 v185, v185
	s_nop 0
	v_mul_f32_e32 v152, v152, v185
	v_mul_f32_e32 v153, v153, v185
	v_mul_f32_e32 v154, v154, v185
	v_mul_f32_e32 v155, v155, v185
	v_mul_f32_e32 v156, v156, v185
	v_mul_f32_e32 v157, v157, v185
	v_mul_f32_e32 v158, v158, v185
	v_mul_f32_e32 v159, v159, v185
	v_mul_f32_e32 v160, v160, v185
	v_mul_f32_e32 v161, v161, v185
	v_mul_f32_e32 v162, v162, v185
	v_mul_f32_e32 v163, v163, v185
	v_mul_f32_e32 v164, v164, v185
	v_mul_f32_e32 v165, v165, v185
	v_mul_f32_e32 v166, v166, v185
	v_mul_f32_e32 v167, v167, v185
	v_fma_f32 v152, v152, v8, v24
	v_fma_f32 v153, v153, v9, v25
	v_fma_f32 v154, v154, v10, v26
	v_fma_f32 v155, v155, v11, v27
	v_fma_f32 v156, v156, v12, v28
	v_fma_f32 v157, v157, v13, v29
	v_fma_f32 v158, v158, v14, v30
	v_fma_f32 v159, v159, v15, v31
	v_fma_f32 v160, v160, v16, v32
	v_fma_f32 v161, v161, v17, v33
	v_fma_f32 v162, v162, v18, v34
	v_fma_f32 v163, v163, v19, v35
	v_fma_f32 v164, v164, v20, v36
	v_fma_f32 v165, v165, v21, v37
	v_fma_f32 v166, v166, v22, v38
	v_fma_f32 v167, v167, v23, v39
	v_add_u32_e32 v171, 0x7000, v1
	global_store_dwordx4 v171, v[152:155], s[4:5]
	global_store_dwordx4 v171, v[156:159], s[4:5] offset:1024
	global_store_dwordx4 v171, v[160:163], s[4:5] offset:2048
	global_store_dwordx4 v171, v[164:167], s[4:5] offset:3072
	s_branch .Ltr_29
